# v29_prio
# speedup vs baseline: 1.0042x; 1.0042x over previous
; #define LDA(dst, b, h)                                                                                    \
;   _Pragma("unroll") for (int m = 0; m < 4; ++m) _Pragma("unroll") for (int k = 0; k < 2; ++k)             \
;       dst[m][k] = *reinterpret_cast<const bf16x8*>((char*)SA(b, h) + lds_byte(wr * 64 + m * 16 + fr, k * 32 + fq * 8))
; #define LDB(dst, b, h)                                                                                    \
;   _Pragma("unroll") for (int n = 0; n < 2; ++n) _Pragma("unroll") for (int k = 0; k < 2; ++k)             \
;       dst[n][k] = *reinterpret_cast<const bf16x8*>((char*)SB(b, h) + lds_byte(wc * 32 + n * 16 + fr, k * 32 + fq * 8))
; #define WAIT_V(n) asm volatile("s_waitcnt vmcnt(" #n ")" ::: "memory")
; #define WAIT_L(n) asm volatile("s_waitcnt lgkmcnt(" #n ")" ::: "memory")
; #define BAR __builtin_amdgcn_s_barrier()
; #define SCHED __builtin_amdgcn_sched_barrier(0)
; template <int EPI> ...
;     ...
;     LDB(B0, 0, 0); SCHED; LDA(At, 0, 0); STAGE(SA(1, 1), A, brow + HALF, t + 1);
;     WAIT_L(8); BAR; WAIT_L(0); MMA(0, 0, At, B0); BAR; SCHED;
;     LDB(B1, 0, 1); STAGE(SB(0, 0), Bt, bcol, t + 2);
;     BAR; WAIT_L(0); MMA(0, 1, At, B1); BAR;
;     LDA(At, 0, 1); STAGE(SA(0, 0), A, brow, t + 2);
;     BAR; WAIT_L(0); MMA(1, 0, At, B0); BAR; SCHED;
;     STAGE(SB(0, 1), Bt, bcol + HALF, t + 2);
;     WAIT_V(6); BAR; MMA(1, 1, At, B1); BAR;
.LBB0_141:
	ds_read_b128 v[160:163], v159
	ds_read_b128 v[164:167], v159 offset:1024
	ds_read_b128 v[178:181], v159 offset:2048
	ds_read_b128 v[182:185], v159 offset:3072
	s_add_u32 s16, s10, s14
	s_addc_u32 s17, s11, s15
	ds_read_b128 v[186:189], v138
	ds_read_b128 v[190:193], v138 offset:1024
	ds_read_b128 v[194:197], v137
	ds_read_b128 v[198:201], v137 offset:1024
	ds_read_b128 v[202:205], v136
	ds_read_b128 v[206:209], v136 offset:1024
	ds_read_b128 v[210:213], v135
	ds_read_b128 v[214:217], v135 offset:1024
	s_add_u32 m0, s32, 0xc000
	s_add_u32 s98, s16, 0x40080
	s_addc_u32 s99, s17, 0
	global_load_lds_dwordx4 v253, s[98:99]
	s_add_u32 m0, s32, 0xe000
	s_nop 0
	global_load_lds_dwordx4 v252, s[98:99]
	s_waitcnt lgkmcnt(8)
	s_setprio 1
	s_barrier
	s_waitcnt lgkmcnt(0)
	v_mfma_f32_16x16x32_bf16 v[124:127], v[186:189], v[160:163], v[124:127]
	v_mfma_f32_16x16x32_bf16 v[120:123], v[186:189], v[178:181], v[120:123]
	v_mfma_f32_16x16x32_bf16 v[116:119], v[194:197], v[160:163], v[116:119]
	v_mfma_f32_16x16x32_bf16 v[112:115], v[194:197], v[178:181], v[112:115]
	v_mfma_f32_16x16x32_bf16 v[108:111], v[202:205], v[160:163], v[108:111]
	v_mfma_f32_16x16x32_bf16 v[104:107], v[202:205], v[178:181], v[104:107]
	v_mfma_f32_16x16x32_bf16 v[100:103], v[210:213], v[160:163], v[100:103]
	v_mfma_f32_16x16x32_bf16 v[96:99], v[210:213], v[178:181], v[96:99]
	v_mfma_f32_16x16x32_bf16 v[124:127], v[190:193], v[164:167], v[124:127]
	v_mfma_f32_16x16x32_bf16 v[120:123], v[190:193], v[182:185], v[120:123]
	v_mfma_f32_16x16x32_bf16 v[116:119], v[198:201], v[164:167], v[116:119]
	v_mfma_f32_16x16x32_bf16 v[112:115], v[198:201], v[182:185], v[112:115]
	v_mfma_f32_16x16x32_bf16 v[108:111], v[206:209], v[164:167], v[108:111]
	v_mfma_f32_16x16x32_bf16 v[104:107], v[206:209], v[182:185], v[104:107]
	v_mfma_f32_16x16x32_bf16 v[100:103], v[214:217], v[164:167], v[100:103]
	v_mfma_f32_16x16x32_bf16 v[96:99], v[214:217], v[182:185], v[96:99]
	s_setprio 0
	s_barrier
	s_add_u32 s18, s8, s14
	s_addc_u32 s19, s9, s15
	ds_read_b128 v[218:221], v155
	ds_read_b128 v[222:225], v155 offset:1024
	ds_read_b128 v[226:229], v155 offset:2048
	ds_read_b128 v[230:233], v155 offset:3072
	s_add_u32 m0, s32, 0x10000
	s_add_u32 s98, s18, 0x100
	s_addc_u32 s99, s19, 0
	global_load_lds_dwordx4 v253, s[98:99]
	s_add_u32 m0, s32, 0x12000
	s_nop 0
	global_load_lds_dwordx4 v252, s[98:99]
	s_setprio 1
	s_barrier
	s_waitcnt lgkmcnt(0)
	v_mfma_f32_16x16x32_bf16 v[92:95], v[186:189], v[218:221], v[92:95]
	v_mfma_f32_16x16x32_bf16 v[88:91], v[186:189], v[226:229], v[88:91]
	v_mfma_f32_16x16x32_bf16 v[84:87], v[194:197], v[218:221], v[84:87]
	v_mfma_f32_16x16x32_bf16 v[80:83], v[194:197], v[226:229], v[80:83]
	v_mfma_f32_16x16x32_bf16 v[76:79], v[202:205], v[218:221], v[76:79]
	v_mfma_f32_16x16x32_bf16 v[72:75], v[202:205], v[226:229], v[72:75]
	v_mfma_f32_16x16x32_bf16 v[68:71], v[210:213], v[218:221], v[68:71]
	v_mfma_f32_16x16x32_bf16 v[64:67], v[210:213], v[226:229], v[64:67]
	v_mfma_f32_16x16x32_bf16 v[92:95], v[190:193], v[222:225], v[92:95]
	v_mfma_f32_16x16x32_bf16 v[88:91], v[190:193], v[230:233], v[88:91]
	v_mfma_f32_16x16x32_bf16 v[84:87], v[198:201], v[222:225], v[84:87]
	v_mfma_f32_16x16x32_bf16 v[80:83], v[198:201], v[230:233], v[80:83]
	v_mfma_f32_16x16x32_bf16 v[76:79], v[206:209], v[222:225], v[76:79]
	v_mfma_f32_16x16x32_bf16 v[72:75], v[206:209], v[230:233], v[72:75]
	v_mfma_f32_16x16x32_bf16 v[68:71], v[214:217], v[222:225], v[68:71]
	v_mfma_f32_16x16x32_bf16 v[64:67], v[214:217], v[230:233], v[64:67]
	s_setprio 0
	s_barrier
	ds_read_b128 v[186:189], v138 offset:16384
	ds_read_b128 v[190:193], v138 offset:17408
	ds_read_b128 v[194:197], v137 offset:16384
	ds_read_b128 v[198:201], v137 offset:17408
	ds_read_b128 v[202:205], v136 offset:16384
	ds_read_b128 v[206:209], v136 offset:17408
	ds_read_b128 v[210:213], v135 offset:16384
	ds_read_b128 v[214:217], v135 offset:17408
	s_mov_b32 m0, s32
	s_add_u32 s98, s16, 0x100
	s_addc_u32 s99, s17, 0
	global_load_lds_dwordx4 v253, s[98:99]
	s_add_u32 m0, s32, 0x2000
	s_nop 0
	global_load_lds_dwordx4 v252, s[98:99]
	s_setprio 1
	s_barrier
	s_waitcnt lgkmcnt(0)
	v_mfma_f32_16x16x32_bf16 v[60:63], v[186:189], v[160:163], v[60:63]
	v_mfma_f32_16x16x32_bf16 v[56:59], v[186:189], v[178:181], v[56:59]
	v_mfma_f32_16x16x32_bf16 v[52:55], v[194:197], v[160:163], v[52:55]
	v_mfma_f32_16x16x32_bf16 v[48:51], v[194:197], v[178:181], v[48:51]
	v_mfma_f32_16x16x32_bf16 v[44:47], v[202:205], v[160:163], v[44:47]
	v_mfma_f32_16x16x32_bf16 v[40:43], v[202:205], v[178:181], v[40:43]
	v_mfma_f32_16x16x32_bf16 v[36:39], v[210:213], v[160:163], v[36:39]
	v_mfma_f32_16x16x32_bf16 v[32:35], v[210:213], v[178:181], v[32:35]
	v_mfma_f32_16x16x32_bf16 v[60:63], v[190:193], v[164:167], v[60:63]
	v_mfma_f32_16x16x32_bf16 v[56:59], v[190:193], v[182:185], v[56:59]
	v_mfma_f32_16x16x32_bf16 v[52:55], v[198:201], v[164:167], v[52:55]
	v_mfma_f32_16x16x32_bf16 v[48:51], v[198:201], v[182:185], v[48:51]
	v_mfma_f32_16x16x32_bf16 v[44:47], v[206:209], v[164:167], v[44:47]
	v_mfma_f32_16x16x32_bf16 v[40:43], v[206:209], v[182:185], v[40:43]
	v_mfma_f32_16x16x32_bf16 v[36:39], v[214:217], v[164:167], v[36:39]
	v_mfma_f32_16x16x32_bf16 v[32:35], v[214:217], v[182:185], v[32:35]
	s_setprio 0
	s_barrier
	s_add_u32 m0, s32, 0x14000
	s_add_u32 s98, s18, 0x40100
	s_addc_u32 s99, s19, 0
	global_load_lds_dwordx4 v253, s[98:99]
	s_add_u32 m0, s32, 0x16000
	s_nop 0
	global_load_lds_dwordx4 v252, s[98:99]
	s_waitcnt vmcnt(6)
	s_barrier
; #define LDA(dst, b, h)                                                                                    \
;   _Pragma("unroll") for (int m = 0; m < 4; ++m) _Pragma("unroll") for (int k = 0; k < 2; ++k)             \
;       dst[m][k] = *reinterpret_cast<const bf16x8*>((char*)SA(b, h) + lds_byte(wr * 64 + m * 16 + fr, k * 32 + fq * 8))
; #define LDB(dst, b, h)                                                                                    \
;   _Pragma("unroll") for (int n = 0; n < 2; ++n) _Pragma("unroll") for (int k = 0; k < 2; ++k)             \
;       dst[n][k] = *reinterpret_cast<const bf16x8*>((char*)SB(b, h) + lds_byte(wc * 32 + n * 16 + fr, k * 32 + fq * 8))
; #define WAIT_V(n) asm volatile("s_waitcnt vmcnt(" #n ")" ::: "memory")
; #define WAIT_L(n) asm volatile("s_waitcnt lgkmcnt(" #n ")" ::: "memory")
; #define BAR __builtin_amdgcn_s_barrier()
; #define SCHED __builtin_amdgcn_sched_barrier(0)
; template <int EPI> ...
;     ...
;     WAIT_V(6); BAR; MMA(1, 1, At, B1); BAR;
;     LDB(B0, 1, 0); SCHED; LDA(At, 1, 0); STAGE(SA(0, 1), A, brow + HALF, t + 2);
;     WAIT_L(8); BAR; WAIT_L(0); MMA(0, 0, At, B0); BAR; SCHED;
;     LDB(B1, 1, 1); STAGE(SB(1, 0), Bt, bcol, t + 3);
;     BAR; WAIT_L(0); MMA(0, 1, At, B1); BAR;
;     LDA(At, 1, 1); STAGE(SA(1, 0), A, brow, t + 3);
	s_setprio 1
	v_mfma_f32_16x16x32_bf16 v[28:31], v[186:189], v[218:221], v[28:31]
	v_mfma_f32_16x16x32_bf16 v[24:27], v[186:189], v[226:229], v[24:27]
	v_mfma_f32_16x16x32_bf16 v[20:23], v[194:197], v[218:221], v[20:23]
	v_mfma_f32_16x16x32_bf16 v[16:19], v[194:197], v[226:229], v[16:19]
	v_mfma_f32_16x16x32_bf16 v[12:15], v[202:205], v[218:221], v[12:15]
	v_mfma_f32_16x16x32_bf16 v[8:11], v[202:205], v[226:229], v[8:11]
	v_mfma_f32_16x16x32_bf16 v[4:7], v[210:213], v[218:221], v[4:7]
	v_mfma_f32_16x16x32_bf16 v[0:3], v[210:213], v[226:229], v[0:3]
	v_mfma_f32_16x16x32_bf16 v[28:31], v[190:193], v[222:225], v[28:31]
	v_mfma_f32_16x16x32_bf16 v[24:27], v[190:193], v[230:233], v[24:27]
	v_mfma_f32_16x16x32_bf16 v[20:23], v[198:201], v[222:225], v[20:23]
	v_mfma_f32_16x16x32_bf16 v[16:19], v[198:201], v[230:233], v[16:19]
	v_mfma_f32_16x16x32_bf16 v[12:15], v[206:209], v[222:225], v[12:15]
	v_mfma_f32_16x16x32_bf16 v[8:11], v[206:209], v[230:233], v[8:11]
	v_mfma_f32_16x16x32_bf16 v[4:7], v[214:217], v[222:225], v[4:7]
	v_mfma_f32_16x16x32_bf16 v[0:3], v[214:217], v[230:233], v[0:3]
	s_setprio 0
	s_barrier
	ds_read_b128 v[160:163], v143
	ds_read_b128 v[164:167], v143 offset:1024
	ds_read_b128 v[178:181], v143 offset:2048
	ds_read_b128 v[182:185], v143 offset:3072
	ds_read_b128 v[186:189], v138 offset:32768
	ds_read_b128 v[190:193], v138 offset:33792
	ds_read_b128 v[194:197], v137 offset:32768
	ds_read_b128 v[198:201], v137 offset:33792
	ds_read_b128 v[202:205], v136 offset:32768
	ds_read_b128 v[206:209], v136 offset:33792
	ds_read_b128 v[210:213], v135 offset:32768
	ds_read_b128 v[214:217], v135 offset:33792
	s_add_u32 m0, s32, 0x4000
	s_add_u32 s98, s16, 0x40100
	s_addc_u32 s99, s17, 0
	global_load_lds_dwordx4 v253, s[98:99]
	s_add_u32 m0, s32, 0x6000
	s_nop 0
	global_load_lds_dwordx4 v252, s[98:99]
	s_waitcnt lgkmcnt(8)
	s_setprio 1
	s_barrier
	s_waitcnt lgkmcnt(0)
	v_mfma_f32_16x16x32_bf16 v[124:127], v[186:189], v[160:163], v[124:127]
	v_mfma_f32_16x16x32_bf16 v[120:123], v[186:189], v[178:181], v[120:123]
	v_mfma_f32_16x16x32_bf16 v[116:119], v[194:197], v[160:163], v[116:119]
	v_mfma_f32_16x16x32_bf16 v[112:115], v[194:197], v[178:181], v[112:115]
	v_mfma_f32_16x16x32_bf16 v[108:111], v[202:205], v[160:163], v[108:111]
	v_mfma_f32_16x16x32_bf16 v[104:107], v[202:205], v[178:181], v[104:107]
	v_mfma_f32_16x16x32_bf16 v[100:103], v[210:213], v[160:163], v[100:103]
	v_mfma_f32_16x16x32_bf16 v[96:99], v[210:213], v[178:181], v[96:99]
	v_mfma_f32_16x16x32_bf16 v[124:127], v[190:193], v[164:167], v[124:127]
	v_mfma_f32_16x16x32_bf16 v[120:123], v[190:193], v[182:185], v[120:123]
	v_mfma_f32_16x16x32_bf16 v[116:119], v[198:201], v[164:167], v[116:119]
	v_mfma_f32_16x16x32_bf16 v[112:115], v[198:201], v[182:185], v[112:115]
	v_mfma_f32_16x16x32_bf16 v[108:111], v[206:209], v[164:167], v[108:111]
	v_mfma_f32_16x16x32_bf16 v[104:107], v[206:209], v[182:185], v[104:107]
	v_mfma_f32_16x16x32_bf16 v[100:103], v[214:217], v[164:167], v[100:103]
	v_mfma_f32_16x16x32_bf16 v[96:99], v[214:217], v[182:185], v[96:99]
	s_setprio 0
	s_barrier
	ds_read_b128 v[218:221], v140
	ds_read_b128 v[222:225], v140 offset:1024
	ds_read_b128 v[226:229], v140 offset:2048
	ds_read_b128 v[230:233], v140 offset:3072
	s_add_u32 m0, s32, 0x18000
	s_add_u32 s98, s18, 0x180
	s_addc_u32 s99, s19, 0
	global_load_lds_dwordx4 v253, s[98:99]
	s_add_u32 m0, s32, 0x1a000
	s_nop 0
	global_load_lds_dwordx4 v252, s[98:99]
	s_setprio 1
	s_barrier
	s_waitcnt lgkmcnt(0)
	v_mfma_f32_16x16x32_bf16 v[92:95], v[186:189], v[218:221], v[92:95]
	v_mfma_f32_16x16x32_bf16 v[88:91], v[186:189], v[226:229], v[88:91]
	v_mfma_f32_16x16x32_bf16 v[84:87], v[194:197], v[218:221], v[84:87]
	v_mfma_f32_16x16x32_bf16 v[80:83], v[194:197], v[226:229], v[80:83]
	v_mfma_f32_16x16x32_bf16 v[76:79], v[202:205], v[218:221], v[76:79]
	v_mfma_f32_16x16x32_bf16 v[72:75], v[202:205], v[226:229], v[72:75]
	v_mfma_f32_16x16x32_bf16 v[68:71], v[210:213], v[218:221], v[68:71]
	v_mfma_f32_16x16x32_bf16 v[64:67], v[210:213], v[226:229], v[64:67]
	v_mfma_f32_16x16x32_bf16 v[92:95], v[190:193], v[222:225], v[92:95]
	v_mfma_f32_16x16x32_bf16 v[88:91], v[190:193], v[230:233], v[88:91]
	v_mfma_f32_16x16x32_bf16 v[84:87], v[198:201], v[222:225], v[84:87]
	v_mfma_f32_16x16x32_bf16 v[80:83], v[198:201], v[230:233], v[80:83]
	v_mfma_f32_16x16x32_bf16 v[76:79], v[206:209], v[222:225], v[76:79]
	v_mfma_f32_16x16x32_bf16 v[72:75], v[206:209], v[230:233], v[72:75]
	v_mfma_f32_16x16x32_bf16 v[68:71], v[214:217], v[222:225], v[68:71]
	v_mfma_f32_16x16x32_bf16 v[64:67], v[214:217], v[230:233], v[64:67]
	s_setprio 0
	s_barrier
	ds_read_b128 v[186:189], v138 offset:49152
	ds_read_b128 v[190:193], v138 offset:50176
	ds_read_b128 v[194:197], v137 offset:49152
	ds_read_b128 v[198:201], v137 offset:50176
	ds_read_b128 v[202:205], v136 offset:49152
	ds_read_b128 v[206:209], v136 offset:50176
	ds_read_b128 v[210:213], v135 offset:49152
	ds_read_b128 v[214:217], v135 offset:50176
	s_add_u32 m0, s32, 0x8000
	s_add_u32 s98, s16, 0x180
	s_addc_u32 s99, s17, 0
	global_load_lds_dwordx4 v253, s[98:99]
	s_nop 0
	s_add_u32 m0, s32, 0xa000
	s_nop 0
	global_load_lds_dwordx4 v252, s[98:99]
	s_setprio 1
	s_barrier
; #define LDA(dst, b, h)                                                                                    \
;   _Pragma("unroll") for (int m = 0; m < 4; ++m) _Pragma("unroll") for (int k = 0; k < 2; ++k)             \
;       dst[m][k] = *reinterpret_cast<const bf16x8*>((char*)SA(b, h) + lds_byte(wr * 64 + m * 16 + fr, k * 32 + fq * 8))
; #define LDB(dst, b, h)                                                                                    \
;   _Pragma("unroll") for (int n = 0; n < 2; ++n) _Pragma("unroll") for (int k = 0; k < 2; ++k)             \
;       dst[n][k] = *reinterpret_cast<const bf16x8*>((char*)SB(b, h) + lds_byte(wc * 32 + n * 16 + fr, k * 32 + fq * 8))
; #define WAIT_V(n) asm volatile("s_waitcnt vmcnt(" #n ")" ::: "memory")
; #define WAIT_L(n) asm volatile("s_waitcnt lgkmcnt(" #n ")" ::: "memory")
; #define BAR __builtin_amdgcn_s_barrier()
; #define SCHED __builtin_amdgcn_sched_barrier(0)
; template <int EPI> ...
;     ...
;     BAR; WAIT_L(0); MMA(1, 0, At, B0); BAR; SCHED;
;     STAGE(SB(1, 1), Bt, bcol + HALF, t + 3);
;     WAIT_V(6); BAR; MMA(1, 1, At, B1); BAR;
;   }
;   {
;     LDB(B0, 0, 0); LDA(At, 0, 0); STAGE(SA(1, 1), A, brow + HALF, nt - 1);
;     BAR; WAIT_L(0); MMA(0, 0, At, B0); BAR;
;     LDB(B1, 0, 1); BAR; WAIT_L(0); MMA(0, 1, At, B1); BAR;
	s_waitcnt lgkmcnt(0)
	v_mfma_f32_16x16x32_bf16 v[60:63], v[186:189], v[160:163], v[60:63]
	v_mfma_f32_16x16x32_bf16 v[56:59], v[186:189], v[178:181], v[56:59]
	v_mfma_f32_16x16x32_bf16 v[52:55], v[194:197], v[160:163], v[52:55]
	v_mfma_f32_16x16x32_bf16 v[48:51], v[194:197], v[178:181], v[48:51]
	v_mfma_f32_16x16x32_bf16 v[44:47], v[202:205], v[160:163], v[44:47]
	v_mfma_f32_16x16x32_bf16 v[40:43], v[202:205], v[178:181], v[40:43]
	v_mfma_f32_16x16x32_bf16 v[36:39], v[210:213], v[160:163], v[36:39]
	v_mfma_f32_16x16x32_bf16 v[32:35], v[210:213], v[178:181], v[32:35]
	v_mfma_f32_16x16x32_bf16 v[60:63], v[190:193], v[164:167], v[60:63]
	v_mfma_f32_16x16x32_bf16 v[56:59], v[190:193], v[182:185], v[56:59]
	v_mfma_f32_16x16x32_bf16 v[52:55], v[198:201], v[164:167], v[52:55]
	v_mfma_f32_16x16x32_bf16 v[48:51], v[198:201], v[182:185], v[48:51]
	v_mfma_f32_16x16x32_bf16 v[44:47], v[206:209], v[164:167], v[44:47]
	v_mfma_f32_16x16x32_bf16 v[40:43], v[206:209], v[182:185], v[40:43]
	v_mfma_f32_16x16x32_bf16 v[36:39], v[214:217], v[164:167], v[36:39]
	v_mfma_f32_16x16x32_bf16 v[32:35], v[214:217], v[182:185], v[32:35]
	s_setprio 0
	s_barrier
	s_add_u32 m0, s32, 0x1c000
	s_add_u32 s98, s18, 0x40180
	s_addc_u32 s99, s19, 0
	global_load_lds_dwordx4 v253, s[98:99]
	s_add_u32 m0, s32, 0x1e000
	s_nop 0
	global_load_lds_dwordx4 v252, s[98:99]
	s_waitcnt vmcnt(6)
	s_barrier
	s_setprio 1
	v_mfma_f32_16x16x32_bf16 v[28:31], v[186:189], v[218:221], v[28:31]
	v_mfma_f32_16x16x32_bf16 v[24:27], v[186:189], v[226:229], v[24:27]
	v_mfma_f32_16x16x32_bf16 v[20:23], v[194:197], v[218:221], v[20:23]
	v_mfma_f32_16x16x32_bf16 v[16:19], v[194:197], v[226:229], v[16:19]
	v_mfma_f32_16x16x32_bf16 v[12:15], v[202:205], v[218:221], v[12:15]
	v_mfma_f32_16x16x32_bf16 v[8:11], v[202:205], v[226:229], v[8:11]
	v_mfma_f32_16x16x32_bf16 v[4:7], v[210:213], v[218:221], v[4:7]
	v_mfma_f32_16x16x32_bf16 v[0:3], v[210:213], v[226:229], v[0:3]
	v_mfma_f32_16x16x32_bf16 v[28:31], v[190:193], v[222:225], v[28:31]
	v_mfma_f32_16x16x32_bf16 v[24:27], v[190:193], v[230:233], v[24:27]
	v_mfma_f32_16x16x32_bf16 v[20:23], v[198:201], v[222:225], v[20:23]
	v_mfma_f32_16x16x32_bf16 v[16:19], v[198:201], v[230:233], v[16:19]
	v_mfma_f32_16x16x32_bf16 v[12:15], v[206:209], v[222:225], v[12:15]
	v_mfma_f32_16x16x32_bf16 v[8:11], v[206:209], v[230:233], v[8:11]
	v_mfma_f32_16x16x32_bf16 v[4:7], v[214:217], v[222:225], v[4:7]
	v_mfma_f32_16x16x32_bf16 v[0:3], v[214:217], v[230:233], v[0:3]
	s_setprio 0
	s_add_i32 s62, s62, 2
	s_add_u32 s14, s14, 0x100
	s_addc_u32 s15, s15, 0
	s_cmp_lt_u32 s62, 12
	s_barrier
	s_cbranch_scc1 .LBB0_141
	ds_read_b128 v[144:147], v159
	ds_read_b128 v[160:163], v159 offset:1024
	ds_read_b128 v[164:167], v159 offset:2048
	ds_read_b128 v[178:181], v159 offset:3072
	ds_read_b128 v[182:185], v138
	ds_read_b128 v[186:189], v138 offset:1024
	ds_read_b128 v[190:193], v137
	ds_read_b128 v[194:197], v137 offset:1024
	ds_read_b128 v[198:201], v136
	ds_read_b128 v[202:205], v136 offset:1024
	ds_read_b128 v[206:209], v135
	ds_read_b128 v[210:213], v135 offset:1024
	v_mov_b32_e32 v129, v149
	v_lshl_add_u64 v[128:129], v[128:129], 1, s[12:13]
	s_mov_b64 s[10:11], 0x780
	v_readfirstlane_b32 s8, v158
	v_lshl_add_u64 v[128:129], v[128:129], 0, s[10:11]
	s_mov_b32 m0, s8
	v_mov_b32_e32 v131, v149
	global_load_lds_dwordx4 v[128:129], off
	v_readfirstlane_b32 s8, v157
	v_lshl_add_u64 v[128:129], v[130:131], 1, s[12:13]
	v_lshl_add_u64 v[128:129], v[128:129], 0, s[10:11]
	s_mov_b32 m0, s8
	s_nop 0
	global_load_lds_dwordx4 v[128:129], off
	s_setprio 1
	s_barrier
	s_waitcnt lgkmcnt(0)
	v_mfma_f32_16x16x32_bf16 v[124:127], v[182:185], v[144:147], v[124:127]
	v_mfma_f32_16x16x32_bf16 v[120:123], v[182:185], v[164:167], v[120:123]
	v_mfma_f32_16x16x32_bf16 v[116:119], v[190:193], v[144:147], v[116:119]
	v_mfma_f32_16x16x32_bf16 v[112:115], v[190:193], v[164:167], v[112:115]
	v_mfma_f32_16x16x32_bf16 v[108:111], v[198:201], v[144:147], v[108:111]
	v_mfma_f32_16x16x32_bf16 v[104:107], v[198:201], v[164:167], v[104:107]
	v_mfma_f32_16x16x32_bf16 v[96:99], v[206:209], v[164:167], v[96:99]
	v_mfma_f32_16x16x32_bf16 v[124:127], v[186:189], v[160:163], v[124:127]
	v_mfma_f32_16x16x32_bf16 v[120:123], v[186:189], v[178:181], v[120:123]
	v_mfma_f32_16x16x32_bf16 v[116:119], v[194:197], v[160:163], v[116:119]
	v_mfma_f32_16x16x32_bf16 v[112:115], v[194:197], v[178:181], v[112:115]
	v_mfma_f32_16x16x32_bf16 v[108:111], v[202:205], v[160:163], v[108:111]
	v_mfma_f32_16x16x32_bf16 v[104:107], v[202:205], v[178:181], v[104:107]
	v_mfma_f32_16x16x32_bf16 v[100:103], v[206:209], v[144:147], v[100:103]
	v_mfma_f32_16x16x32_bf16 v[96:99], v[210:213], v[178:181], v[96:99]
	v_mfma_f32_16x16x32_bf16 v[128:131], v[210:213], v[160:163], v[100:103]
	s_setprio 0
	s_barrier
	s_nop 3
	ds_read_b128 v[100:103], v155
	ds_read_b128 v[156:159], v155 offset:1024
	ds_read_b128 v[214:217], v155 offset:2048
	ds_read_b128 v[152:155], v155 offset:3072
	s_setprio 1
	s_barrier
	s_waitcnt lgkmcnt(0)
	v_mfma_f32_16x16x32_bf16 v[88:91], v[182:185], v[214:217], v[88:91]
	v_mfma_f32_16x16x32_bf16 v[92:95], v[182:185], v[100:103], v[92:95]
	v_mfma_f32_16x16x32_bf16 v[88:91], v[186:189], v[152:155], v[88:91]
	v_mfma_f32_16x16x32_bf16 v[84:87], v[190:193], v[100:103], v[84:87]
	v_mfma_f32_16x16x32_bf16 v[80:83], v[190:193], v[214:217], v[80:83]
	v_mfma_f32_16x16x32_bf16 v[76:79], v[198:201], v[100:103], v[76:79]
	v_mfma_f32_16x16x32_bf16 v[72:75], v[198:201], v[214:217], v[72:75]
	v_mfma_f32_16x16x32_bf16 v[68:71], v[206:209], v[100:103], v[68:71]
	v_mfma_f32_16x16x32_bf16 v[64:67], v[206:209], v[214:217], v[64:67]
	v_mfma_f32_16x16x32_bf16 v[218:221], v[186:189], v[156:159], v[92:95]
	v_mfma_f32_16x16x32_bf16 v[182:185], v[194:197], v[156:159], v[84:87]
	v_mfma_f32_16x16x32_bf16 v[186:189], v[194:197], v[152:155], v[80:83]
	v_mfma_f32_16x16x32_bf16 v[190:193], v[202:205], v[156:159], v[76:79]
	v_mfma_f32_16x16x32_bf16 v[194:197], v[202:205], v[152:155], v[72:75]
	v_mfma_f32_16x16x32_bf16 v[198:201], v[210:213], v[156:159], v[68:71]
	v_mfma_f32_16x16x32_bf16 v[202:205], v[210:213], v[152:155], v[64:67]
	s_setprio 0
	s_barrier
; #define LDA(dst, b, h)                                                                                    \
;   _Pragma("unroll") for (int m = 0; m < 4; ++m) _Pragma("unroll") for (int k = 0; k < 2; ++k)             \
;       dst[m][k] = *reinterpret_cast<const bf16x8*>((char*)SA(b, h) + lds_byte(wr * 64 + m * 16 + fr, k * 32 + fq * 8))
; #define LDB(dst, b, h)                                                                                    \
;   _Pragma("unroll") for (int n = 0; n < 2; ++n) _Pragma("unroll") for (int k = 0; k < 2; ++k)             \
;       dst[n][k] = *reinterpret_cast<const bf16x8*>((char*)SB(b, h) + lds_byte(wc * 32 + n * 16 + fr, k * 32 + fq * 8))
; #define WAIT_V(n) asm volatile("s_waitcnt vmcnt(" #n ")" ::: "memory")
; #define WAIT_L(n) asm volatile("s_waitcnt lgkmcnt(" #n ")" ::: "memory")
; #define BAR __builtin_amdgcn_s_barrier()
; template <int EPI> ...
;     ...
;     LDA(At, 0, 1); WAIT_V(4); BAR; WAIT_L(0); MMA(1, 0, At, B0); MMA(1, 1, At, B1); BAR;
;   }
;   {
;     LDB(B0, 1, 0); LDA(At, 1, 0); WAIT_V(2); BAR; WAIT_L(0); MMA(0, 0, At, B0); BAR;
	s_nop 0
	ds_read_b128 v[64:67], v138 offset:16384
	ds_read_b128 v[68:71], v138 offset:17408
	ds_read_b128 v[72:75], v137 offset:16384
	ds_read_b128 v[76:79], v137 offset:17408
	ds_read_b128 v[80:83], v136 offset:16384
	ds_read_b128 v[84:87], v136 offset:17408
	ds_read_b128 v[92:95], v135 offset:16384
	ds_read_b128 v[206:209], v135 offset:17408
	s_waitcnt vmcnt(4)
	s_setprio 1
	s_barrier
	s_waitcnt lgkmcnt(0)
	v_mfma_f32_16x16x32_bf16 v[60:63], v[64:67], v[144:147], v[60:63]
	v_mfma_f32_16x16x32_bf16 v[56:59], v[64:67], v[164:167], v[56:59]
	v_mfma_f32_16x16x32_bf16 v[52:55], v[72:75], v[144:147], v[52:55]
	v_mfma_f32_16x16x32_bf16 v[48:51], v[72:75], v[164:167], v[48:51]
	v_mfma_f32_16x16x32_bf16 v[44:47], v[80:83], v[144:147], v[44:47]
	v_mfma_f32_16x16x32_bf16 v[40:43], v[80:83], v[164:167], v[40:43]
	v_mfma_f32_16x16x32_bf16 v[36:39], v[92:95], v[144:147], v[36:39]
	v_mfma_f32_16x16x32_bf16 v[32:35], v[92:95], v[164:167], v[32:35]
	v_mfma_f32_16x16x32_bf16 v[60:63], v[68:71], v[160:163], v[60:63]
	v_mfma_f32_16x16x32_bf16 v[56:59], v[68:71], v[178:181], v[56:59]
	v_mfma_f32_16x16x32_bf16 v[52:55], v[76:79], v[160:163], v[52:55]
	v_mfma_f32_16x16x32_bf16 v[48:51], v[76:79], v[178:181], v[48:51]
	v_mfma_f32_16x16x32_bf16 v[44:47], v[84:87], v[160:163], v[44:47]
	v_mfma_f32_16x16x32_bf16 v[40:43], v[84:87], v[178:181], v[40:43]
	v_mfma_f32_16x16x32_bf16 v[36:39], v[206:209], v[160:163], v[36:39]
	v_mfma_f32_16x16x32_bf16 v[32:35], v[206:209], v[178:181], v[32:35]
	s_setprio 0
	s_setprio 1
	v_mfma_f32_16x16x32_bf16 v[28:31], v[64:67], v[100:103], v[28:31]
	v_mfma_f32_16x16x32_bf16 v[24:27], v[64:67], v[214:217], v[24:27]
	v_mfma_f32_16x16x32_bf16 v[20:23], v[72:75], v[100:103], v[20:23]
	v_mfma_f32_16x16x32_bf16 v[16:19], v[72:75], v[214:217], v[16:19]
	v_mfma_f32_16x16x32_bf16 v[12:15], v[80:83], v[100:103], v[12:15]
	v_mfma_f32_16x16x32_bf16 v[8:11], v[80:83], v[214:217], v[8:11]
	v_mfma_f32_16x16x32_bf16 v[4:7], v[92:95], v[100:103], v[4:7]
	v_mfma_f32_16x16x32_bf16 v[0:3], v[92:95], v[214:217], v[0:3]
	v_mfma_f32_16x16x32_bf16 v[144:147], v[68:71], v[156:159], v[28:31]
	v_mfma_f32_16x16x32_bf16 v[160:163], v[68:71], v[152:155], v[24:27]
	v_mfma_f32_16x16x32_bf16 v[164:167], v[76:79], v[156:159], v[20:23]
	v_mfma_f32_16x16x32_bf16 v[178:181], v[76:79], v[152:155], v[16:19]
	v_mfma_f32_16x16x32_bf16 v[210:213], v[84:87], v[156:159], v[12:15]
	v_mfma_f32_16x16x32_bf16 v[222:225], v[84:87], v[152:155], v[8:11]
	v_mfma_f32_16x16x32_bf16 v[156:159], v[206:209], v[156:159], v[4:7]
	v_mfma_f32_16x16x32_bf16 v[152:155], v[206:209], v[152:155], v[0:3]
	s_setprio 0
	s_barrier
	s_nop 0
	ds_read_b128 v[0:3], v143
	ds_read_b128 v[4:7], v143 offset:1024
	ds_read_b128 v[206:209], v143 offset:2048
	ds_read_b128 v[214:217], v143 offset:3072
	ds_read_b128 v[8:11], v138 offset:32768
	ds_read_b128 v[12:15], v138 offset:33792
	ds_read_b128 v[16:19], v137 offset:32768
	ds_read_b128 v[20:23], v137 offset:33792
	ds_read_b128 v[24:27], v136 offset:32768
	ds_read_b128 v[28:31], v136 offset:33792
	ds_read_b128 v[226:229], v135 offset:32768
	ds_read_b128 v[230:233], v135 offset:33792
	s_waitcnt vmcnt(2)
	s_setprio 1
	s_barrier
	s_waitcnt lgkmcnt(0)
	v_mfma_f32_16x16x32_bf16 v[64:67], v[8:11], v[0:3], v[124:127]
	v_mfma_f32_16x16x32_bf16 v[92:95], v[12:15], v[4:7], v[64:67]
	v_mfma_f32_16x16x32_bf16 v[64:67], v[8:11], v[206:209], v[120:123]
	v_mfma_f32_16x16x32_bf16 v[100:103], v[12:15], v[214:217], v[64:67]
	v_mfma_f32_16x16x32_bf16 v[64:67], v[16:19], v[0:3], v[116:119]
	v_mfma_f32_16x16x32_bf16 v[80:83], v[20:23], v[4:7], v[64:67]
	v_mfma_f32_16x16x32_bf16 v[64:67], v[16:19], v[206:209], v[112:115]
	v_mfma_f32_16x16x32_bf16 v[84:87], v[20:23], v[214:217], v[64:67]
	v_mfma_f32_16x16x32_bf16 v[64:67], v[24:27], v[0:3], v[108:111]
	v_mfma_f32_16x16x32_bf16 v[72:75], v[28:31], v[4:7], v[64:67]
	v_mfma_f32_16x16x32_bf16 v[64:67], v[24:27], v[206:209], v[104:107]
	v_mfma_f32_16x16x32_bf16 v[76:79], v[28:31], v[214:217], v[64:67]
	v_mfma_f32_16x16x32_bf16 v[64:67], v[226:229], v[0:3], v[128:131]
	v_mfma_f32_16x16x32_bf16 v[68:71], v[226:229], v[206:209], v[96:99]
	v_mfma_f32_16x16x32_bf16 v[64:67], v[230:233], v[4:7], v[64:67]
	v_mfma_f32_16x16x32_bf16 v[68:71], v[230:233], v[214:217], v[68:71]
	s_setprio 0
	s_barrier
; #define LDA(dst, b, h)                                                                                    \
;   _Pragma("unroll") for (int m = 0; m < 4; ++m) _Pragma("unroll") for (int k = 0; k < 2; ++k)             \
;       dst[m][k] = *reinterpret_cast<const bf16x8*>((char*)SA(b, h) + lds_byte(wr * 64 + m * 16 + fr, k * 32 + fq * 8))
; #define LDB(dst, b, h)                                                                                    \
;   _Pragma("unroll") for (int n = 0; n < 2; ++n) _Pragma("unroll") for (int k = 0; k < 2; ++k)             \
;       dst[n][k] = *reinterpret_cast<const bf16x8*>((char*)SB(b, h) + lds_byte(wc * 32 + n * 16 + fr, k * 32 + fq * 8))
; #define WAIT_V(n) asm volatile("s_waitcnt vmcnt(" #n ")" ::: "memory")
; #define WAIT_L(n) asm volatile("s_waitcnt lgkmcnt(" #n ")" ::: "memory")
; #define BAR __builtin_amdgcn_s_barrier()
; template <int EPI> ...
;     ...
;     LDB(B0, 1, 0); LDA(At, 1, 0); WAIT_V(2); BAR; WAIT_L(0); MMA(0, 0, At, B0); BAR;
;     LDB(B1, 1, 1); WAIT_V(0); BAR; WAIT_L(0); MMA(0, 1, At, B1); BAR;
;     LDA(At, 1, 1); BAR; WAIT_L(0); MMA(1, 0, At, B0); MMA(1, 1, At, B1); BAR;
;   }
;   if (wr == 0) BAR;
	ds_read_b128 v[128:131], v140
	ds_read_b128 v[234:237], v140 offset:1024
	ds_read_b128 v[238:241], v140 offset:2048
	ds_read_b128 v[140:143], v140 offset:3072
	s_waitcnt vmcnt(0)
	s_setprio 1
	s_barrier
	s_waitcnt lgkmcnt(0)
	v_mfma_f32_16x16x32_bf16 v[96:99], v[8:11], v[128:131], v[218:221]
	v_mfma_f32_16x16x32_bf16 v[8:11], v[8:11], v[238:241], v[88:91]
	v_mfma_f32_16x16x32_bf16 v[124:127], v[12:15], v[140:143], v[8:11]
	v_mfma_f32_16x16x32_bf16 v[8:11], v[16:19], v[128:131], v[182:185]
	v_mfma_f32_16x16x32_bf16 v[112:115], v[20:23], v[234:237], v[8:11]
	v_mfma_f32_16x16x32_bf16 v[8:11], v[16:19], v[238:241], v[186:189]
	v_mfma_f32_16x16x32_bf16 v[116:119], v[20:23], v[140:143], v[8:11]
	v_mfma_f32_16x16x32_bf16 v[8:11], v[24:27], v[128:131], v[190:193]
	v_mfma_f32_16x16x32_bf16 v[104:107], v[28:31], v[234:237], v[8:11]
	v_mfma_f32_16x16x32_bf16 v[8:11], v[24:27], v[238:241], v[194:197]
	v_mfma_f32_16x16x32_bf16 v[108:111], v[28:31], v[140:143], v[8:11]
	v_mfma_f32_16x16x32_bf16 v[8:11], v[226:229], v[128:131], v[198:201]
	v_mfma_f32_16x16x32_bf16 v[88:91], v[230:233], v[234:237], v[8:11]
	v_mfma_f32_16x16x32_bf16 v[8:11], v[226:229], v[238:241], v[202:205]
	v_mfma_f32_16x16x32_bf16 v[120:123], v[12:15], v[234:237], v[96:99]
	v_mfma_f32_16x16x32_bf16 v[96:99], v[230:233], v[140:143], v[8:11]
	s_setprio 0
	s_barrier
	ds_read_b128 v[182:185], v138 offset:49152
	ds_read_b128 v[186:189], v138 offset:50176
	ds_read_b128 v[190:193], v137 offset:49152
	ds_read_b128 v[194:197], v137 offset:50176
	ds_read_b128 v[198:201], v136 offset:49152
	ds_read_b128 v[136:139], v136 offset:50176
	ds_read_b128 v[202:205], v135 offset:49152
	ds_read_b128 v[218:221], v135 offset:50176
	s_setprio 1
	s_barrier
	s_waitcnt lgkmcnt(0)
	v_mfma_f32_16x16x32_bf16 v[8:11], v[182:185], v[0:3], v[60:63]
	v_mfma_f32_16x16x32_bf16 v[24:27], v[186:189], v[4:7], v[8:11]
	v_mfma_f32_16x16x32_bf16 v[8:11], v[182:185], v[206:209], v[56:59]
	v_mfma_f32_16x16x32_bf16 v[28:31], v[186:189], v[214:217], v[8:11]
	v_mfma_f32_16x16x32_bf16 v[8:11], v[190:193], v[0:3], v[52:55]
	v_mfma_f32_16x16x32_bf16 v[16:19], v[194:197], v[4:7], v[8:11]
	v_mfma_f32_16x16x32_bf16 v[8:11], v[190:193], v[206:209], v[48:51]
	v_mfma_f32_16x16x32_bf16 v[20:23], v[194:197], v[214:217], v[8:11]
	v_mfma_f32_16x16x32_bf16 v[8:11], v[198:201], v[0:3], v[44:47]
	v_mfma_f32_16x16x32_bf16 v[0:3], v[202:205], v[0:3], v[36:39]
	v_mfma_f32_16x16x32_bf16 v[8:11], v[136:139], v[4:7], v[8:11]
	v_mfma_f32_16x16x32_bf16 v[12:15], v[198:201], v[206:209], v[40:43]
	v_mfma_f32_16x16x32_bf16 v[0:3], v[218:221], v[4:7], v[0:3]
	v_mfma_f32_16x16x32_bf16 v[4:7], v[202:205], v[206:209], v[32:35]
	v_mfma_f32_16x16x32_bf16 v[12:15], v[136:139], v[214:217], v[12:15]
	v_mfma_f32_16x16x32_bf16 v[4:7], v[218:221], v[214:217], v[4:7]
	s_setprio 0
	s_setprio 1
	v_mfma_f32_16x16x32_bf16 v[32:35], v[182:185], v[128:131], v[144:147]
	v_mfma_f32_16x16x32_bf16 v[56:59], v[186:189], v[234:237], v[32:35]
	v_mfma_f32_16x16x32_bf16 v[32:35], v[182:185], v[238:241], v[160:163]
	v_mfma_f32_16x16x32_bf16 v[60:63], v[186:189], v[140:143], v[32:35]
	v_mfma_f32_16x16x32_bf16 v[32:35], v[190:193], v[128:131], v[164:167]
	v_mfma_f32_16x16x32_bf16 v[48:51], v[194:197], v[234:237], v[32:35]
	v_mfma_f32_16x16x32_bf16 v[32:35], v[190:193], v[238:241], v[178:181]
	v_mfma_f32_16x16x32_bf16 v[52:55], v[194:197], v[140:143], v[32:35]
	v_mfma_f32_16x16x32_bf16 v[32:35], v[198:201], v[128:131], v[210:213]
	v_mfma_f32_16x16x32_bf16 v[40:43], v[136:139], v[234:237], v[32:35]
	v_mfma_f32_16x16x32_bf16 v[32:35], v[198:201], v[238:241], v[222:225]
	v_mfma_f32_16x16x32_bf16 v[44:47], v[136:139], v[140:143], v[32:35]
	v_mfma_f32_16x16x32_bf16 v[32:35], v[202:205], v[128:131], v[156:159]
	v_mfma_f32_16x16x32_bf16 v[36:39], v[202:205], v[238:241], v[152:155]
	v_mfma_f32_16x16x32_bf16 v[32:35], v[218:221], v[234:237], v[32:35]
	v_mfma_f32_16x16x32_bf16 v[36:39], v[218:221], v[140:143], v[36:39]
	s_setprio 0
	s_cmpk_gt_u32 s34, 0xff
	s_barrier
	s_cbranch_scc1 .LBB0_135
	s_barrier
	s_branch .LBB0_135

; #define LDA(dst, b, h)                                                                                    \
;   _Pragma("unroll") for (int m = 0; m < 4; ++m) _Pragma("unroll") for (int k = 0; k < 2; ++k)             \
;       dst[m][k] = *reinterpret_cast<const bf16x8*>((char*)SA(b, h) + lds_byte(wr * 64 + m * 16 + fr, k * 32 + fq * 8))
; #define LDB(dst, b, h)                                                                                    \
;   _Pragma("unroll") for (int n = 0; n < 2; ++n) _Pragma("unroll") for (int k = 0; k < 2; ++k)             \
;       dst[n][k] = *reinterpret_cast<const bf16x8*>((char*)SB(b, h) + lds_byte(wc * 32 + n * 16 + fr, k * 32 + fq * 8))
; #define WAIT_V(n) asm volatile("s_waitcnt vmcnt(" #n ")" ::: "memory")
; #define WAIT_L(n) asm volatile("s_waitcnt lgkmcnt(" #n ")" ::: "memory")
; #define BAR __builtin_amdgcn_s_barrier()
; #define SCHED __builtin_amdgcn_sched_barrier(0)
; template <int EPI> ...
;     ...
;     LDB(B0, 0, 0); SCHED; LDA(At, 0, 0); STAGE(SA(1, 1), A, brow + HALF, t + 1);
;     WAIT_L(8); BAR; WAIT_L(0); MMA(0, 0, At, B0); BAR; SCHED;
;     LDB(B1, 0, 1); STAGE(SB(0, 0), Bt, bcol, t + 2);
;     BAR; WAIT_L(0); MMA(0, 1, At, B1); BAR;
;     LDA(At, 0, 1); STAGE(SA(0, 0), A, brow, t + 2);
;     BAR; WAIT_L(0); MMA(1, 0, At, B0); BAR; SCHED;
;     STAGE(SB(0, 1), Bt, bcol + HALF, t + 2);
;     WAIT_V(6); BAR; MMA(1, 1, At, B1); BAR;
.LBB0_166:
	ds_read_b128 v[162:165], v155
	ds_read_b128 v[178:181], v155 offset:1024
	ds_read_b128 v[182:185], v155 offset:2048
	ds_read_b128 v[186:189], v155 offset:3072
	s_add_u32 s22, s4, s20
	v_add_u32_e32 v156, s66, v154
	v_add_u32_e32 v157, s67, v154
	v_add_u32_e32 v158, s69, v154
	s_addc_u32 s23, s5, s21
	v_add_u32_e32 v159, 0xc000, v129
	ds_read_b128 v[190:193], v135
	ds_read_b128 v[194:197], v135 offset:1024
	ds_read_b128 v[198:201], v156
	ds_read_b128 v[202:205], v156 offset:1024
	ds_read_b128 v[206:209], v157
	ds_read_b128 v[210:213], v157 offset:1024
	ds_read_b128 v[214:217], v158
	ds_read_b128 v[218:221], v158 offset:1024
	s_add_u32 m0, s32, 0xc000
	s_add_u32 s98, s22, 0xb0080
	s_addc_u32 s99, s23, 0
	global_load_lds_dwordx4 v253, s[98:99]
	s_nop 0
	v_add_u32_e32 v160, 0xe000, v129
	s_nop 0
	s_add_u32 m0, s32, 0xe000
	s_nop 0
	global_load_lds_dwordx4 v252, s[98:99]
	s_waitcnt lgkmcnt(8)
	s_setprio 1
	s_barrier
	s_waitcnt lgkmcnt(0)
	v_mfma_f32_16x16x32_bf16 v[124:127], v[190:193], v[162:165], v[124:127]
	v_mfma_f32_16x16x32_bf16 v[120:123], v[190:193], v[182:185], v[120:123]
	v_mfma_f32_16x16x32_bf16 v[116:119], v[198:201], v[162:165], v[116:119]
	v_mfma_f32_16x16x32_bf16 v[112:115], v[198:201], v[182:185], v[112:115]
	v_mfma_f32_16x16x32_bf16 v[108:111], v[206:209], v[162:165], v[108:111]
	v_mfma_f32_16x16x32_bf16 v[104:107], v[206:209], v[182:185], v[104:107]
	v_mfma_f32_16x16x32_bf16 v[100:103], v[214:217], v[162:165], v[100:103]
	v_mfma_f32_16x16x32_bf16 v[96:99], v[214:217], v[182:185], v[96:99]
	v_mfma_f32_16x16x32_bf16 v[124:127], v[194:197], v[178:181], v[124:127]
	v_mfma_f32_16x16x32_bf16 v[120:123], v[194:197], v[186:189], v[120:123]
	v_mfma_f32_16x16x32_bf16 v[116:119], v[202:205], v[178:181], v[116:119]
	v_mfma_f32_16x16x32_bf16 v[112:115], v[202:205], v[186:189], v[112:115]
	v_mfma_f32_16x16x32_bf16 v[108:111], v[210:213], v[178:181], v[108:111]
	v_mfma_f32_16x16x32_bf16 v[104:107], v[210:213], v[186:189], v[104:107]
	v_mfma_f32_16x16x32_bf16 v[100:103], v[218:221], v[178:181], v[100:103]
	v_mfma_f32_16x16x32_bf16 v[96:99], v[218:221], v[186:189], v[96:99]
	s_setprio 0
	s_barrier
	s_add_u32 s30, s0, s20
	s_addc_u32 s31, s1, s21
	ds_read_b128 v[222:225], v152
	ds_read_b128 v[226:229], v152 offset:1024
	ds_read_b128 v[230:233], v152 offset:2048
	ds_read_b128 v[234:237], v152 offset:3072
	s_add_u32 m0, s32, 0x10000
	s_add_u32 s98, s30, 0x100
	s_addc_u32 s99, s31, 0
	global_load_lds_dwordx4 v253, s[98:99]
	s_add_u32 m0, s32, 0x12000
	s_nop 0
	global_load_lds_dwordx4 v252, s[98:99]
	s_setprio 1
	s_barrier
	s_waitcnt lgkmcnt(0)
	v_mfma_f32_16x16x32_bf16 v[92:95], v[190:193], v[222:225], v[92:95]
	v_mfma_f32_16x16x32_bf16 v[88:91], v[190:193], v[230:233], v[88:91]
	v_mfma_f32_16x16x32_bf16 v[84:87], v[198:201], v[222:225], v[84:87]
	v_mfma_f32_16x16x32_bf16 v[80:83], v[198:201], v[230:233], v[80:83]
	v_mfma_f32_16x16x32_bf16 v[76:79], v[206:209], v[222:225], v[76:79]
	v_mfma_f32_16x16x32_bf16 v[72:75], v[206:209], v[230:233], v[72:75]
	v_mfma_f32_16x16x32_bf16 v[68:71], v[214:217], v[222:225], v[68:71]
	v_mfma_f32_16x16x32_bf16 v[64:67], v[214:217], v[230:233], v[64:67]
	v_mfma_f32_16x16x32_bf16 v[92:95], v[194:197], v[226:229], v[92:95]
	v_mfma_f32_16x16x32_bf16 v[88:91], v[194:197], v[234:237], v[88:91]
	v_mfma_f32_16x16x32_bf16 v[84:87], v[202:205], v[226:229], v[84:87]
	v_mfma_f32_16x16x32_bf16 v[80:83], v[202:205], v[234:237], v[80:83]
	v_mfma_f32_16x16x32_bf16 v[76:79], v[210:213], v[226:229], v[76:79]
	v_mfma_f32_16x16x32_bf16 v[72:75], v[210:213], v[234:237], v[72:75]
	v_mfma_f32_16x16x32_bf16 v[68:71], v[218:221], v[226:229], v[68:71]
	v_mfma_f32_16x16x32_bf16 v[64:67], v[218:221], v[234:237], v[64:67]
	s_setprio 0
	s_barrier
	ds_read_b128 v[190:193], v135 offset:16384
	ds_read_b128 v[194:197], v135 offset:17408
	ds_read_b128 v[198:201], v156 offset:16384
	ds_read_b128 v[202:205], v156 offset:17408
	ds_read_b128 v[206:209], v157 offset:16384
	ds_read_b128 v[210:213], v157 offset:17408
	ds_read_b128 v[214:217], v158 offset:16384
	ds_read_b128 v[218:221], v158 offset:17408
	s_mov_b32 m0, s32
	s_add_u32 s98, s22, 0x100
	s_addc_u32 s99, s23, 0
	global_load_lds_dwordx4 v253, s[98:99]
	s_add_u32 m0, s32, 0x2000
	s_nop 0
	global_load_lds_dwordx4 v252, s[98:99]
	s_setprio 1
	s_barrier
	s_waitcnt lgkmcnt(0)
	v_mfma_f32_16x16x32_bf16 v[60:63], v[190:193], v[162:165], v[60:63]
	v_mfma_f32_16x16x32_bf16 v[56:59], v[190:193], v[182:185], v[56:59]
	v_mfma_f32_16x16x32_bf16 v[52:55], v[198:201], v[162:165], v[52:55]
	v_mfma_f32_16x16x32_bf16 v[48:51], v[198:201], v[182:185], v[48:51]
	v_mfma_f32_16x16x32_bf16 v[44:47], v[206:209], v[162:165], v[44:47]
	v_mfma_f32_16x16x32_bf16 v[40:43], v[206:209], v[182:185], v[40:43]
	v_mfma_f32_16x16x32_bf16 v[36:39], v[214:217], v[162:165], v[36:39]
	v_mfma_f32_16x16x32_bf16 v[32:35], v[214:217], v[182:185], v[32:35]
	v_mfma_f32_16x16x32_bf16 v[60:63], v[194:197], v[178:181], v[60:63]
	v_mfma_f32_16x16x32_bf16 v[56:59], v[194:197], v[186:189], v[56:59]
	v_mfma_f32_16x16x32_bf16 v[52:55], v[202:205], v[178:181], v[52:55]
	v_mfma_f32_16x16x32_bf16 v[48:51], v[202:205], v[186:189], v[48:51]
	v_mfma_f32_16x16x32_bf16 v[44:47], v[210:213], v[178:181], v[44:47]
	v_mfma_f32_16x16x32_bf16 v[40:43], v[210:213], v[186:189], v[40:43]
	v_mfma_f32_16x16x32_bf16 v[36:39], v[218:221], v[178:181], v[36:39]
	v_mfma_f32_16x16x32_bf16 v[32:35], v[218:221], v[186:189], v[32:35]
	s_setprio 0
	s_barrier
	s_add_u32 m0, s32, 0x14000
	s_add_u32 s98, s30, 0xb0100
	s_addc_u32 s99, s31, 0
	global_load_lds_dwordx4 v253, s[98:99]
	s_add_u32 m0, s32, 0x16000
	s_nop 0
	global_load_lds_dwordx4 v252, s[98:99]
	s_waitcnt vmcnt(6)
	s_barrier
; #define LDA(dst, b, h)                                                                                    \
;   _Pragma("unroll") for (int m = 0; m < 4; ++m) _Pragma("unroll") for (int k = 0; k < 2; ++k)             \
;       dst[m][k] = *reinterpret_cast<const bf16x8*>((char*)SA(b, h) + lds_byte(wr * 64 + m * 16 + fr, k * 32 + fq * 8))
; #define LDB(dst, b, h)                                                                                    \
;   _Pragma("unroll") for (int n = 0; n < 2; ++n) _Pragma("unroll") for (int k = 0; k < 2; ++k)             \
;       dst[n][k] = *reinterpret_cast<const bf16x8*>((char*)SB(b, h) + lds_byte(wc * 32 + n * 16 + fr, k * 32 + fq * 8))
; #define WAIT_V(n) asm volatile("s_waitcnt vmcnt(" #n ")" ::: "memory")
; #define WAIT_L(n) asm volatile("s_waitcnt lgkmcnt(" #n ")" ::: "memory")
; #define BAR __builtin_amdgcn_s_barrier()
; #define SCHED __builtin_amdgcn_sched_barrier(0)
; template <int EPI> ...
;     ...
;     WAIT_V(6); BAR; MMA(1, 1, At, B1); BAR;
;     LDB(B0, 1, 0); SCHED; LDA(At, 1, 0); STAGE(SA(0, 1), A, brow + HALF, t + 2);
;     WAIT_L(8); BAR; WAIT_L(0); MMA(0, 0, At, B0); BAR; SCHED;
;     LDB(B1, 1, 1); STAGE(SB(1, 0), Bt, bcol, t + 3);
;     BAR; WAIT_L(0); MMA(0, 1, At, B1); BAR;
;     LDA(At, 1, 1); STAGE(SA(1, 0), A, brow, t + 3);
	s_setprio 1
	v_mfma_f32_16x16x32_bf16 v[28:31], v[190:193], v[222:225], v[28:31]
	v_mfma_f32_16x16x32_bf16 v[24:27], v[190:193], v[230:233], v[24:27]
	v_mfma_f32_16x16x32_bf16 v[20:23], v[198:201], v[222:225], v[20:23]
	v_mfma_f32_16x16x32_bf16 v[16:19], v[198:201], v[230:233], v[16:19]
	v_mfma_f32_16x16x32_bf16 v[12:15], v[206:209], v[222:225], v[12:15]
	v_mfma_f32_16x16x32_bf16 v[8:11], v[206:209], v[230:233], v[8:11]
	v_mfma_f32_16x16x32_bf16 v[4:7], v[214:217], v[222:225], v[4:7]
	v_mfma_f32_16x16x32_bf16 v[0:3], v[214:217], v[230:233], v[0:3]
	v_mfma_f32_16x16x32_bf16 v[28:31], v[194:197], v[226:229], v[28:31]
	v_mfma_f32_16x16x32_bf16 v[24:27], v[194:197], v[234:237], v[24:27]
	v_mfma_f32_16x16x32_bf16 v[20:23], v[202:205], v[226:229], v[20:23]
	v_mfma_f32_16x16x32_bf16 v[16:19], v[202:205], v[234:237], v[16:19]
	v_mfma_f32_16x16x32_bf16 v[12:15], v[210:213], v[226:229], v[12:15]
	v_mfma_f32_16x16x32_bf16 v[8:11], v[210:213], v[234:237], v[8:11]
	v_mfma_f32_16x16x32_bf16 v[4:7], v[218:221], v[226:229], v[4:7]
	v_mfma_f32_16x16x32_bf16 v[0:3], v[218:221], v[234:237], v[0:3]
	s_setprio 0
	s_barrier
	ds_read_b128 v[162:165], v140
	ds_read_b128 v[178:181], v140 offset:1024
	ds_read_b128 v[182:185], v140 offset:2048
	ds_read_b128 v[186:189], v140 offset:3072
	ds_read_b128 v[190:193], v135 offset:32768
	ds_read_b128 v[194:197], v135 offset:33792
	ds_read_b128 v[198:201], v156 offset:32768
	ds_read_b128 v[202:205], v156 offset:33792
	ds_read_b128 v[206:209], v157 offset:32768
	ds_read_b128 v[210:213], v157 offset:33792
	ds_read_b128 v[214:217], v158 offset:32768
	ds_read_b128 v[218:221], v158 offset:33792
	s_add_u32 m0, s32, 0x4000
	s_add_u32 s98, s22, 0xb0100
	s_addc_u32 s99, s23, 0
	global_load_lds_dwordx4 v253, s[98:99]
	s_add_u32 m0, s32, 0x6000
	s_nop 0
	global_load_lds_dwordx4 v252, s[98:99]
	s_waitcnt lgkmcnt(8)
	s_setprio 1
	s_barrier
	s_waitcnt lgkmcnt(0)
	v_mfma_f32_16x16x32_bf16 v[124:127], v[190:193], v[162:165], v[124:127]
	v_mfma_f32_16x16x32_bf16 v[120:123], v[190:193], v[182:185], v[120:123]
	v_mfma_f32_16x16x32_bf16 v[116:119], v[198:201], v[162:165], v[116:119]
	v_mfma_f32_16x16x32_bf16 v[112:115], v[198:201], v[182:185], v[112:115]
	v_mfma_f32_16x16x32_bf16 v[108:111], v[206:209], v[162:165], v[108:111]
	v_mfma_f32_16x16x32_bf16 v[104:107], v[206:209], v[182:185], v[104:107]
	v_mfma_f32_16x16x32_bf16 v[100:103], v[214:217], v[162:165], v[100:103]
	v_mfma_f32_16x16x32_bf16 v[96:99], v[214:217], v[182:185], v[96:99]
	v_mfma_f32_16x16x32_bf16 v[124:127], v[194:197], v[178:181], v[124:127]
	v_mfma_f32_16x16x32_bf16 v[120:123], v[194:197], v[186:189], v[120:123]
	v_mfma_f32_16x16x32_bf16 v[116:119], v[202:205], v[178:181], v[116:119]
	v_mfma_f32_16x16x32_bf16 v[112:115], v[202:205], v[186:189], v[112:115]
	v_mfma_f32_16x16x32_bf16 v[108:111], v[210:213], v[178:181], v[108:111]
	v_mfma_f32_16x16x32_bf16 v[104:107], v[210:213], v[186:189], v[104:107]
	v_mfma_f32_16x16x32_bf16 v[100:103], v[218:221], v[178:181], v[100:103]
	v_mfma_f32_16x16x32_bf16 v[96:99], v[218:221], v[186:189], v[96:99]
	s_setprio 0
	s_barrier
	ds_read_b128 v[222:225], v137
	ds_read_b128 v[226:229], v137 offset:1024
	ds_read_b128 v[230:233], v137 offset:2048
	ds_read_b128 v[234:237], v137 offset:3072
	s_add_u32 m0, s32, 0x18000
	s_add_u32 s98, s30, 0x180
	s_addc_u32 s99, s31, 0
	global_load_lds_dwordx4 v253, s[98:99]
	s_add_u32 m0, s32, 0x1a000
	s_nop 0
	global_load_lds_dwordx4 v252, s[98:99]
	s_setprio 1
	s_barrier
	s_waitcnt lgkmcnt(0)
	v_mfma_f32_16x16x32_bf16 v[92:95], v[190:193], v[222:225], v[92:95]
	v_mfma_f32_16x16x32_bf16 v[88:91], v[190:193], v[230:233], v[88:91]
	v_mfma_f32_16x16x32_bf16 v[84:87], v[198:201], v[222:225], v[84:87]
	v_mfma_f32_16x16x32_bf16 v[80:83], v[198:201], v[230:233], v[80:83]
	v_mfma_f32_16x16x32_bf16 v[76:79], v[206:209], v[222:225], v[76:79]
	v_mfma_f32_16x16x32_bf16 v[72:75], v[206:209], v[230:233], v[72:75]
	v_mfma_f32_16x16x32_bf16 v[68:71], v[214:217], v[222:225], v[68:71]
	v_mfma_f32_16x16x32_bf16 v[64:67], v[214:217], v[230:233], v[64:67]
	v_mfma_f32_16x16x32_bf16 v[92:95], v[194:197], v[226:229], v[92:95]
	v_mfma_f32_16x16x32_bf16 v[88:91], v[194:197], v[234:237], v[88:91]
	v_mfma_f32_16x16x32_bf16 v[84:87], v[202:205], v[226:229], v[84:87]
	v_mfma_f32_16x16x32_bf16 v[80:83], v[202:205], v[234:237], v[80:83]
	v_mfma_f32_16x16x32_bf16 v[76:79], v[210:213], v[226:229], v[76:79]
	v_mfma_f32_16x16x32_bf16 v[72:75], v[210:213], v[234:237], v[72:75]
	v_mfma_f32_16x16x32_bf16 v[68:71], v[218:221], v[226:229], v[68:71]
	v_mfma_f32_16x16x32_bf16 v[64:67], v[218:221], v[234:237], v[64:67]
	s_setprio 0
	s_barrier
	ds_read_b128 v[190:193], v135 offset:49152
	ds_read_b128 v[194:197], v135 offset:50176
	ds_read_b128 v[198:201], v156 offset:49152
	ds_read_b128 v[202:205], v156 offset:50176
	ds_read_b128 v[206:209], v157 offset:49152
	ds_read_b128 v[210:213], v157 offset:50176
	ds_read_b128 v[214:217], v158 offset:49152
	ds_read_b128 v[218:221], v158 offset:50176
	s_add_u32 m0, s32, 0x8000
	s_add_u32 s98, s22, 0x180
	s_addc_u32 s99, s23, 0
	global_load_lds_dwordx4 v253, s[98:99]
	s_nop 0
	s_add_u32 m0, s32, 0xa000
	s_nop 0
	global_load_lds_dwordx4 v252, s[98:99]
	s_setprio 1
	s_barrier
; #define LDA(dst, b, h)                                                                                    \
;   _Pragma("unroll") for (int m = 0; m < 4; ++m) _Pragma("unroll") for (int k = 0; k < 2; ++k)             \
;       dst[m][k] = *reinterpret_cast<const bf16x8*>((char*)SA(b, h) + lds_byte(wr * 64 + m * 16 + fr, k * 32 + fq * 8))
; #define LDB(dst, b, h)                                                                                    \
;   _Pragma("unroll") for (int n = 0; n < 2; ++n) _Pragma("unroll") for (int k = 0; k < 2; ++k)             \
;       dst[n][k] = *reinterpret_cast<const bf16x8*>((char*)SB(b, h) + lds_byte(wc * 32 + n * 16 + fr, k * 32 + fq * 8))
; #define WAIT_V(n) asm volatile("s_waitcnt vmcnt(" #n ")" ::: "memory")
; #define WAIT_L(n) asm volatile("s_waitcnt lgkmcnt(" #n ")" ::: "memory")
; #define BAR __builtin_amdgcn_s_barrier()
; #define SCHED __builtin_amdgcn_sched_barrier(0)
; template <int EPI> ...
;     ...
;     BAR; WAIT_L(0); MMA(1, 0, At, B0); BAR; SCHED;
;     STAGE(SB(1, 1), Bt, bcol + HALF, t + 3);
;     WAIT_V(6); BAR; MMA(1, 1, At, B1); BAR;
;   }
;   {
;     LDB(B0, 0, 0); LDA(At, 0, 0); STAGE(SA(1, 1), A, brow + HALF, nt - 1);
;     BAR; WAIT_L(0); MMA(0, 0, At, B0); BAR;
;     LDB(B1, 0, 1); BAR; WAIT_L(0); MMA(0, 1, At, B1); BAR;
	s_waitcnt lgkmcnt(0)
	v_mfma_f32_16x16x32_bf16 v[60:63], v[190:193], v[162:165], v[60:63]
	v_mfma_f32_16x16x32_bf16 v[56:59], v[190:193], v[182:185], v[56:59]
	v_mfma_f32_16x16x32_bf16 v[52:55], v[198:201], v[162:165], v[52:55]
	v_mfma_f32_16x16x32_bf16 v[48:51], v[198:201], v[182:185], v[48:51]
	v_mfma_f32_16x16x32_bf16 v[44:47], v[206:209], v[162:165], v[44:47]
	v_mfma_f32_16x16x32_bf16 v[40:43], v[206:209], v[182:185], v[40:43]
	v_mfma_f32_16x16x32_bf16 v[36:39], v[214:217], v[162:165], v[36:39]
	v_mfma_f32_16x16x32_bf16 v[32:35], v[214:217], v[182:185], v[32:35]
	v_mfma_f32_16x16x32_bf16 v[60:63], v[194:197], v[178:181], v[60:63]
	v_mfma_f32_16x16x32_bf16 v[56:59], v[194:197], v[186:189], v[56:59]
	v_mfma_f32_16x16x32_bf16 v[52:55], v[202:205], v[178:181], v[52:55]
	v_mfma_f32_16x16x32_bf16 v[48:51], v[202:205], v[186:189], v[48:51]
	v_mfma_f32_16x16x32_bf16 v[44:47], v[210:213], v[178:181], v[44:47]
	v_mfma_f32_16x16x32_bf16 v[40:43], v[210:213], v[186:189], v[40:43]
	v_mfma_f32_16x16x32_bf16 v[36:39], v[218:221], v[178:181], v[36:39]
	v_mfma_f32_16x16x32_bf16 v[32:35], v[218:221], v[186:189], v[32:35]
	s_setprio 0
	s_barrier
	s_add_u32 m0, s32, 0x1c000
	s_add_u32 s98, s30, 0xb0180
	s_addc_u32 s99, s31, 0
	global_load_lds_dwordx4 v253, s[98:99]
	s_add_u32 m0, s32, 0x1e000
	s_nop 0
	global_load_lds_dwordx4 v252, s[98:99]
	s_waitcnt vmcnt(6)
	s_barrier
	s_setprio 1
	v_mfma_f32_16x16x32_bf16 v[28:31], v[190:193], v[222:225], v[28:31]
	v_mfma_f32_16x16x32_bf16 v[24:27], v[190:193], v[230:233], v[24:27]
	v_mfma_f32_16x16x32_bf16 v[20:23], v[198:201], v[222:225], v[20:23]
	v_mfma_f32_16x16x32_bf16 v[16:19], v[198:201], v[230:233], v[16:19]
	v_mfma_f32_16x16x32_bf16 v[12:15], v[206:209], v[222:225], v[12:15]
	v_mfma_f32_16x16x32_bf16 v[8:11], v[206:209], v[230:233], v[8:11]
	v_mfma_f32_16x16x32_bf16 v[4:7], v[214:217], v[222:225], v[4:7]
	v_mfma_f32_16x16x32_bf16 v[0:3], v[214:217], v[230:233], v[0:3]
	v_mfma_f32_16x16x32_bf16 v[28:31], v[194:197], v[226:229], v[28:31]
	v_mfma_f32_16x16x32_bf16 v[24:27], v[194:197], v[234:237], v[24:27]
	v_mfma_f32_16x16x32_bf16 v[20:23], v[202:205], v[226:229], v[20:23]
	v_mfma_f32_16x16x32_bf16 v[16:19], v[202:205], v[234:237], v[16:19]
	v_mfma_f32_16x16x32_bf16 v[12:15], v[210:213], v[226:229], v[12:15]
	v_mfma_f32_16x16x32_bf16 v[8:11], v[210:213], v[234:237], v[8:11]
	v_mfma_f32_16x16x32_bf16 v[4:7], v[218:221], v[226:229], v[4:7]
	v_mfma_f32_16x16x32_bf16 v[0:3], v[218:221], v[234:237], v[0:3]
	s_setprio 0
	s_add_i32 s70, s70, 2
	s_add_u32 s20, s20, 0x100
	s_addc_u32 s21, s21, 0
	s_cmp_lt_u32 s70, 40
	s_barrier
	s_cbranch_scc1 .LBB0_166
	s_add_u32 s0, s18, 0x1580
	ds_read_b128 v[142:145], v155
	ds_read_b128 v[162:165], v155 offset:1024
	ds_read_b128 v[178:181], v155 offset:2048
	ds_read_b128 v[182:185], v155 offset:3072
	ds_read_b128 v[186:189], v135
	ds_read_b128 v[190:193], v135 offset:1024
	ds_read_b128 v[194:197], v156
	ds_read_b128 v[198:201], v156 offset:1024
	ds_read_b128 v[202:205], v157
	ds_read_b128 v[206:209], v157 offset:1024
	ds_read_b128 v[210:213], v158
	ds_read_b128 v[214:217], v158 offset:1024
	s_addc_u32 s1, s19, 0
	v_mov_b32_e32 v129, v149
	v_readfirstlane_b32 s4, v159
	v_lshl_add_u64 v[128:129], v[128:129], 1, s[0:1]
	s_mov_b32 m0, s4
	v_mov_b32_e32 v131, v149
	global_load_lds_dwordx4 v[128:129], off
	s_nop 0
	v_lshl_add_u64 v[128:129], v[130:131], 1, s[0:1]
	v_readfirstlane_b32 s0, v160
	s_mov_b32 m0, s0
	s_nop 0
	global_load_lds_dwordx4 v[128:129], off
	s_setprio 1
	s_barrier
	s_waitcnt lgkmcnt(0)
	v_mfma_f32_16x16x32_bf16 v[124:127], v[186:189], v[142:145], v[124:127]
	v_mfma_f32_16x16x32_bf16 v[120:123], v[186:189], v[178:181], v[120:123]
	v_mfma_f32_16x16x32_bf16 v[116:119], v[194:197], v[142:145], v[116:119]
	v_mfma_f32_16x16x32_bf16 v[112:115], v[194:197], v[178:181], v[112:115]
	v_mfma_f32_16x16x32_bf16 v[108:111], v[202:205], v[142:145], v[108:111]
	v_mfma_f32_16x16x32_bf16 v[104:107], v[202:205], v[178:181], v[104:107]
	v_mfma_f32_16x16x32_bf16 v[96:99], v[210:213], v[178:181], v[96:99]
	v_mfma_f32_16x16x32_bf16 v[124:127], v[190:193], v[162:165], v[124:127]
	v_mfma_f32_16x16x32_bf16 v[120:123], v[190:193], v[182:185], v[120:123]
	v_mfma_f32_16x16x32_bf16 v[116:119], v[198:201], v[162:165], v[116:119]
	v_mfma_f32_16x16x32_bf16 v[112:115], v[198:201], v[182:185], v[112:115]
	v_mfma_f32_16x16x32_bf16 v[108:111], v[206:209], v[162:165], v[108:111]
	v_mfma_f32_16x16x32_bf16 v[104:107], v[206:209], v[182:185], v[104:107]
	v_mfma_f32_16x16x32_bf16 v[100:103], v[210:213], v[142:145], v[100:103]
	v_mfma_f32_16x16x32_bf16 v[96:99], v[214:217], v[182:185], v[96:99]
	v_mfma_f32_16x16x32_bf16 v[128:131], v[214:217], v[162:165], v[100:103]
	s_setprio 0
	s_barrier
	s_nop 3
	ds_read_b128 v[100:103], v152
	ds_read_b128 v[218:221], v152 offset:1024
	ds_read_b128 v[222:225], v152 offset:2048
	ds_read_b128 v[152:155], v152 offset:3072
	s_setprio 1
	s_barrier
	s_waitcnt lgkmcnt(0)
	v_mfma_f32_16x16x32_bf16 v[88:91], v[186:189], v[222:225], v[88:91]
	v_mfma_f32_16x16x32_bf16 v[92:95], v[186:189], v[100:103], v[92:95]
	v_mfma_f32_16x16x32_bf16 v[88:91], v[190:193], v[152:155], v[88:91]
	v_mfma_f32_16x16x32_bf16 v[84:87], v[194:197], v[100:103], v[84:87]
	v_mfma_f32_16x16x32_bf16 v[80:83], v[194:197], v[222:225], v[80:83]
	v_mfma_f32_16x16x32_bf16 v[76:79], v[202:205], v[100:103], v[76:79]
	v_mfma_f32_16x16x32_bf16 v[72:75], v[202:205], v[222:225], v[72:75]
	v_mfma_f32_16x16x32_bf16 v[68:71], v[210:213], v[100:103], v[68:71]
	v_mfma_f32_16x16x32_bf16 v[64:67], v[210:213], v[222:225], v[64:67]
	v_mfma_f32_16x16x32_bf16 v[226:229], v[190:193], v[218:221], v[92:95]
	v_mfma_f32_16x16x32_bf16 v[186:189], v[198:201], v[218:221], v[84:87]
	v_mfma_f32_16x16x32_bf16 v[190:193], v[198:201], v[152:155], v[80:83]
	v_mfma_f32_16x16x32_bf16 v[194:197], v[206:209], v[218:221], v[76:79]
	v_mfma_f32_16x16x32_bf16 v[198:201], v[206:209], v[152:155], v[72:75]
	v_mfma_f32_16x16x32_bf16 v[202:205], v[214:217], v[218:221], v[68:71]
	v_mfma_f32_16x16x32_bf16 v[206:209], v[214:217], v[152:155], v[64:67]
	s_setprio 0
	s_barrier
; #define LDA(dst, b, h)                                                                                    \
;   _Pragma("unroll") for (int m = 0; m < 4; ++m) _Pragma("unroll") for (int k = 0; k < 2; ++k)             \
;       dst[m][k] = *reinterpret_cast<const bf16x8*>((char*)SA(b, h) + lds_byte(wr * 64 + m * 16 + fr, k * 32 + fq * 8))
; #define LDB(dst, b, h)                                                                                    \
;   _Pragma("unroll") for (int n = 0; n < 2; ++n) _Pragma("unroll") for (int k = 0; k < 2; ++k)             \
;       dst[n][k] = *reinterpret_cast<const bf16x8*>((char*)SB(b, h) + lds_byte(wc * 32 + n * 16 + fr, k * 32 + fq * 8))
; #define WAIT_V(n) asm volatile("s_waitcnt vmcnt(" #n ")" ::: "memory")
; #define WAIT_L(n) asm volatile("s_waitcnt lgkmcnt(" #n ")" ::: "memory")
; #define BAR __builtin_amdgcn_s_barrier()
; template <int EPI> ...
;     ...
;     LDA(At, 0, 1); WAIT_V(4); BAR; WAIT_L(0); MMA(1, 0, At, B0); MMA(1, 1, At, B1); BAR;
;   }
;   {
;     LDB(B0, 1, 0); LDA(At, 1, 0); WAIT_V(2); BAR; WAIT_L(0); MMA(0, 0, At, B0); BAR;
	s_nop 0
	ds_read_b128 v[64:67], v135 offset:16384
	ds_read_b128 v[68:71], v135 offset:17408
	ds_read_b128 v[72:75], v156 offset:16384
	ds_read_b128 v[76:79], v156 offset:17408
	ds_read_b128 v[80:83], v157 offset:16384
	ds_read_b128 v[84:87], v157 offset:17408
	ds_read_b128 v[92:95], v158 offset:16384
	ds_read_b128 v[210:213], v158 offset:17408
	s_waitcnt vmcnt(4)
	s_setprio 1
	s_barrier
	s_waitcnt lgkmcnt(0)
	v_mfma_f32_16x16x32_bf16 v[60:63], v[64:67], v[142:145], v[60:63]
	v_mfma_f32_16x16x32_bf16 v[56:59], v[64:67], v[178:181], v[56:59]
	v_mfma_f32_16x16x32_bf16 v[52:55], v[72:75], v[142:145], v[52:55]
	v_mfma_f32_16x16x32_bf16 v[48:51], v[72:75], v[178:181], v[48:51]
	v_mfma_f32_16x16x32_bf16 v[44:47], v[80:83], v[142:145], v[44:47]
	v_mfma_f32_16x16x32_bf16 v[40:43], v[80:83], v[178:181], v[40:43]
	v_mfma_f32_16x16x32_bf16 v[36:39], v[92:95], v[142:145], v[36:39]
	v_mfma_f32_16x16x32_bf16 v[32:35], v[92:95], v[178:181], v[32:35]
	v_mfma_f32_16x16x32_bf16 v[60:63], v[68:71], v[162:165], v[60:63]
	v_mfma_f32_16x16x32_bf16 v[56:59], v[68:71], v[182:185], v[56:59]
	v_mfma_f32_16x16x32_bf16 v[52:55], v[76:79], v[162:165], v[52:55]
	v_mfma_f32_16x16x32_bf16 v[48:51], v[76:79], v[182:185], v[48:51]
	v_mfma_f32_16x16x32_bf16 v[44:47], v[84:87], v[162:165], v[44:47]
	v_mfma_f32_16x16x32_bf16 v[40:43], v[84:87], v[182:185], v[40:43]
	v_mfma_f32_16x16x32_bf16 v[36:39], v[210:213], v[162:165], v[36:39]
	v_mfma_f32_16x16x32_bf16 v[32:35], v[210:213], v[182:185], v[32:35]
	s_setprio 0
	s_setprio 1
	v_mfma_f32_16x16x32_bf16 v[28:31], v[64:67], v[100:103], v[28:31]
	v_mfma_f32_16x16x32_bf16 v[24:27], v[64:67], v[222:225], v[24:27]
	v_mfma_f32_16x16x32_bf16 v[20:23], v[72:75], v[100:103], v[20:23]
	v_mfma_f32_16x16x32_bf16 v[16:19], v[72:75], v[222:225], v[16:19]
	v_mfma_f32_16x16x32_bf16 v[12:15], v[80:83], v[100:103], v[12:15]
	v_mfma_f32_16x16x32_bf16 v[8:11], v[80:83], v[222:225], v[8:11]
	v_mfma_f32_16x16x32_bf16 v[4:7], v[92:95], v[100:103], v[4:7]
	v_mfma_f32_16x16x32_bf16 v[0:3], v[92:95], v[222:225], v[0:3]
	v_mfma_f32_16x16x32_bf16 v[142:145], v[68:71], v[218:221], v[28:31]
	v_mfma_f32_16x16x32_bf16 v[160:163], v[68:71], v[152:155], v[24:27]
	v_mfma_f32_16x16x32_bf16 v[164:167], v[76:79], v[218:221], v[20:23]
	v_mfma_f32_16x16x32_bf16 v[178:181], v[76:79], v[152:155], v[16:19]
	v_mfma_f32_16x16x32_bf16 v[182:185], v[84:87], v[218:221], v[12:15]
	v_mfma_f32_16x16x32_bf16 v[214:217], v[84:87], v[152:155], v[8:11]
	v_mfma_f32_16x16x32_bf16 v[218:221], v[210:213], v[218:221], v[4:7]
	v_mfma_f32_16x16x32_bf16 v[152:155], v[210:213], v[152:155], v[0:3]
	s_setprio 0
	s_barrier
	s_nop 0
	ds_read_b128 v[0:3], v140
	ds_read_b128 v[4:7], v140 offset:1024
	ds_read_b128 v[210:213], v140 offset:2048
	ds_read_b128 v[138:141], v140 offset:3072
	ds_read_b128 v[8:11], v135 offset:32768
	ds_read_b128 v[12:15], v135 offset:33792
	ds_read_b128 v[16:19], v156 offset:32768
	ds_read_b128 v[20:23], v156 offset:33792
	ds_read_b128 v[24:27], v157 offset:32768
	ds_read_b128 v[28:31], v157 offset:33792
	ds_read_b128 v[222:225], v158 offset:32768
	ds_read_b128 v[230:233], v158 offset:33792
	s_waitcnt vmcnt(2)
	s_setprio 1
	s_barrier
	s_waitcnt lgkmcnt(0)
	v_mfma_f32_16x16x32_bf16 v[64:67], v[8:11], v[0:3], v[124:127]
	v_mfma_f32_16x16x32_bf16 v[92:95], v[12:15], v[4:7], v[64:67]
	v_mfma_f32_16x16x32_bf16 v[64:67], v[8:11], v[210:213], v[120:123]
	v_mfma_f32_16x16x32_bf16 v[100:103], v[12:15], v[138:141], v[64:67]
	v_mfma_f32_16x16x32_bf16 v[64:67], v[16:19], v[0:3], v[116:119]
	v_mfma_f32_16x16x32_bf16 v[80:83], v[20:23], v[4:7], v[64:67]
	v_mfma_f32_16x16x32_bf16 v[64:67], v[16:19], v[210:213], v[112:115]
	v_mfma_f32_16x16x32_bf16 v[84:87], v[20:23], v[138:141], v[64:67]
	v_mfma_f32_16x16x32_bf16 v[64:67], v[24:27], v[0:3], v[108:111]
	v_mfma_f32_16x16x32_bf16 v[72:75], v[28:31], v[4:7], v[64:67]
	v_mfma_f32_16x16x32_bf16 v[64:67], v[24:27], v[210:213], v[104:107]
	v_mfma_f32_16x16x32_bf16 v[76:79], v[28:31], v[138:141], v[64:67]
	v_mfma_f32_16x16x32_bf16 v[64:67], v[222:225], v[0:3], v[128:131]
	v_mfma_f32_16x16x32_bf16 v[68:71], v[222:225], v[210:213], v[96:99]
	v_mfma_f32_16x16x32_bf16 v[64:67], v[230:233], v[4:7], v[64:67]
	v_mfma_f32_16x16x32_bf16 v[68:71], v[230:233], v[138:141], v[68:71]
	s_setprio 0
	s_barrier
; #define LDA(dst, b, h)                                                                                    \
;   _Pragma("unroll") for (int m = 0; m < 4; ++m) _Pragma("unroll") for (int k = 0; k < 2; ++k)             \
;       dst[m][k] = *reinterpret_cast<const bf16x8*>((char*)SA(b, h) + lds_byte(wr * 64 + m * 16 + fr, k * 32 + fq * 8))
; #define LDB(dst, b, h)                                                                                    \
;   _Pragma("unroll") for (int n = 0; n < 2; ++n) _Pragma("unroll") for (int k = 0; k < 2; ++k)             \
;       dst[n][k] = *reinterpret_cast<const bf16x8*>((char*)SB(b, h) + lds_byte(wc * 32 + n * 16 + fr, k * 32 + fq * 8))
; #define WAIT_V(n) asm volatile("s_waitcnt vmcnt(" #n ")" ::: "memory")
; #define WAIT_L(n) asm volatile("s_waitcnt lgkmcnt(" #n ")" ::: "memory")
; #define BAR __builtin_amdgcn_s_barrier()
; template <int EPI> ...
;     ...
;     LDB(B1, 1, 1); WAIT_V(0); BAR; WAIT_L(0); MMA(0, 1, At, B1); BAR;
;     LDA(At, 1, 1); BAR; WAIT_L(0); MMA(1, 0, At, B0); MMA(1, 1, At, B1); BAR;
;   }
;   if (wr == 0) BAR;
	ds_read_b128 v[128:131], v137
	ds_read_b128 v[234:237], v137 offset:1024
	ds_read_b128 v[238:241], v137 offset:2048
	ds_read_b128 v[242:245], v137 offset:3072
	s_waitcnt vmcnt(0)
	s_setprio 1
	s_barrier
	s_waitcnt lgkmcnt(0)
	v_mfma_f32_16x16x32_bf16 v[96:99], v[8:11], v[128:131], v[226:229]
	v_mfma_f32_16x16x32_bf16 v[8:11], v[8:11], v[238:241], v[88:91]
	v_mfma_f32_16x16x32_bf16 v[124:127], v[12:15], v[242:245], v[8:11]
	v_mfma_f32_16x16x32_bf16 v[8:11], v[16:19], v[128:131], v[186:189]
	v_mfma_f32_16x16x32_bf16 v[112:115], v[20:23], v[234:237], v[8:11]
	v_mfma_f32_16x16x32_bf16 v[8:11], v[16:19], v[238:241], v[190:193]
	v_mfma_f32_16x16x32_bf16 v[116:119], v[20:23], v[242:245], v[8:11]
	v_mfma_f32_16x16x32_bf16 v[8:11], v[24:27], v[128:131], v[194:197]
	v_mfma_f32_16x16x32_bf16 v[104:107], v[28:31], v[234:237], v[8:11]
	v_mfma_f32_16x16x32_bf16 v[8:11], v[24:27], v[238:241], v[198:201]
	v_mfma_f32_16x16x32_bf16 v[108:111], v[28:31], v[242:245], v[8:11]
	v_mfma_f32_16x16x32_bf16 v[8:11], v[222:225], v[128:131], v[202:205]
	v_mfma_f32_16x16x32_bf16 v[88:91], v[230:233], v[234:237], v[8:11]
	v_mfma_f32_16x16x32_bf16 v[8:11], v[222:225], v[238:241], v[206:209]
	v_mfma_f32_16x16x32_bf16 v[120:123], v[12:15], v[234:237], v[96:99]
	v_mfma_f32_16x16x32_bf16 v[96:99], v[230:233], v[242:245], v[8:11]
	s_setprio 0
	s_barrier
	ds_read_b128 v[186:189], v135 offset:49152
	ds_read_b128 v[134:137], v135 offset:50176
	ds_read_b128 v[190:193], v156 offset:49152
	ds_read_b128 v[194:197], v156 offset:50176
	ds_read_b128 v[198:201], v157 offset:49152
	ds_read_b128 v[202:205], v157 offset:50176
	ds_read_b128 v[206:209], v158 offset:49152
	ds_read_b128 v[156:159], v158 offset:50176
	s_setprio 1
	s_barrier
	s_waitcnt lgkmcnt(0)
	v_mfma_f32_16x16x32_bf16 v[8:11], v[186:189], v[0:3], v[60:63]
	v_mfma_f32_16x16x32_bf16 v[24:27], v[134:137], v[4:7], v[8:11]
	v_mfma_f32_16x16x32_bf16 v[8:11], v[186:189], v[210:213], v[56:59]
	v_mfma_f32_16x16x32_bf16 v[28:31], v[134:137], v[138:141], v[8:11]
	v_mfma_f32_16x16x32_bf16 v[8:11], v[190:193], v[0:3], v[52:55]
	v_mfma_f32_16x16x32_bf16 v[16:19], v[194:197], v[4:7], v[8:11]
	v_mfma_f32_16x16x32_bf16 v[8:11], v[190:193], v[210:213], v[48:51]
	v_mfma_f32_16x16x32_bf16 v[20:23], v[194:197], v[138:141], v[8:11]
	v_mfma_f32_16x16x32_bf16 v[8:11], v[198:201], v[0:3], v[44:47]
	v_mfma_f32_16x16x32_bf16 v[0:3], v[206:209], v[0:3], v[36:39]
	v_mfma_f32_16x16x32_bf16 v[8:11], v[202:205], v[4:7], v[8:11]
	v_mfma_f32_16x16x32_bf16 v[12:15], v[198:201], v[210:213], v[40:43]
	v_mfma_f32_16x16x32_bf16 v[0:3], v[156:159], v[4:7], v[0:3]
	v_mfma_f32_16x16x32_bf16 v[4:7], v[206:209], v[210:213], v[32:35]
	v_mfma_f32_16x16x32_bf16 v[12:15], v[202:205], v[138:141], v[12:15]
	v_mfma_f32_16x16x32_bf16 v[4:7], v[156:159], v[138:141], v[4:7]
	s_setprio 0
	s_setprio 1
	v_mfma_f32_16x16x32_bf16 v[32:35], v[186:189], v[128:131], v[142:145]
	v_mfma_f32_16x16x32_bf16 v[56:59], v[134:137], v[234:237], v[32:35]
	v_mfma_f32_16x16x32_bf16 v[32:35], v[186:189], v[238:241], v[160:163]
	v_mfma_f32_16x16x32_bf16 v[60:63], v[134:137], v[242:245], v[32:35]
	v_mfma_f32_16x16x32_bf16 v[32:35], v[190:193], v[128:131], v[164:167]
	v_mfma_f32_16x16x32_bf16 v[48:51], v[194:197], v[234:237], v[32:35]
	v_mfma_f32_16x16x32_bf16 v[32:35], v[190:193], v[238:241], v[178:181]
	v_mfma_f32_16x16x32_bf16 v[52:55], v[194:197], v[242:245], v[32:35]
	v_mfma_f32_16x16x32_bf16 v[32:35], v[198:201], v[128:131], v[182:185]
	v_mfma_f32_16x16x32_bf16 v[40:43], v[202:205], v[234:237], v[32:35]
	v_mfma_f32_16x16x32_bf16 v[32:35], v[198:201], v[238:241], v[214:217]
	v_mfma_f32_16x16x32_bf16 v[44:47], v[202:205], v[242:245], v[32:35]
	v_mfma_f32_16x16x32_bf16 v[32:35], v[206:209], v[128:131], v[218:221]
	v_mfma_f32_16x16x32_bf16 v[36:39], v[206:209], v[238:241], v[152:155]
	v_mfma_f32_16x16x32_bf16 v[32:35], v[156:159], v[234:237], v[32:35]
	v_mfma_f32_16x16x32_bf16 v[36:39], v[156:159], v[242:245], v[36:39]
	s_setprio 0
	s_cmpk_gt_u32 s62, 0xff
	s_barrier
	s_cbranch_scc1 .LBB0_169
	s_barrier

; #define LDA(dst, b, h)                                                                                    \
;   _Pragma("unroll") for (int m = 0; m < 4; ++m) _Pragma("unroll") for (int k = 0; k < 2; ++k)             \
;       dst[m][k] = *reinterpret_cast<const bf16x8*>((char*)SA(b, h) + lds_byte(wr * 64 + m * 16 + fr, k * 32 + fq * 8))
; #define LDB(dst, b, h)                                                                                    \
;   _Pragma("unroll") for (int n = 0; n < 2; ++n) _Pragma("unroll") for (int k = 0; k < 2; ++k)             \
;       dst[n][k] = *reinterpret_cast<const bf16x8*>((char*)SB(b, h) + lds_byte(wc * 32 + n * 16 + fr, k * 32 + fq * 8))
; #define WAIT_V(n) asm volatile("s_waitcnt vmcnt(" #n ")" ::: "memory")
; #define WAIT_L(n) asm volatile("s_waitcnt lgkmcnt(" #n ")" ::: "memory")
; #define BAR __builtin_amdgcn_s_barrier()
; #define SCHED __builtin_amdgcn_sched_barrier(0)
; template <int EPI> ...
;     ...
;     LDB(B0, 0, 0); SCHED; LDA(At, 0, 0); STAGE(SA(1, 1), A, brow + HALF, t + 1);
;     WAIT_L(8); BAR; WAIT_L(0); MMA(0, 0, At, B0); BAR; SCHED;
;     LDB(B1, 0, 1); STAGE(SB(0, 0), Bt, bcol, t + 2);
;     BAR; WAIT_L(0); MMA(0, 1, At, B1); BAR;
;     LDA(At, 0, 1); STAGE(SA(0, 0), A, brow, t + 2);
;     BAR; WAIT_L(0); MMA(1, 0, At, B0); BAR; SCHED;
;     STAGE(SB(0, 1), Bt, bcol + HALF, t + 2);
;     WAIT_V(6); BAR; MMA(1, 1, At, B1); BAR;
.LBB0_416:
	ds_read_b128 v[162:165], v155
	ds_read_b128 v[178:181], v155 offset:1024
	ds_read_b128 v[182:185], v155 offset:2048
	ds_read_b128 v[186:189], v155 offset:3072
	s_add_u32 s14, s8, s12
	v_add_u32_e32 v156, s64, v154
	v_add_u32_e32 v157, s65, v154
	v_add_u32_e32 v158, s66, v154
	s_addc_u32 s15, s9, s13
	ds_read_b128 v[190:193], v135
	ds_read_b128 v[194:197], v135 offset:1024
	ds_read_b128 v[198:201], v156
	ds_read_b128 v[202:205], v156 offset:1024
	ds_read_b128 v[206:209], v157
	ds_read_b128 v[210:213], v157 offset:1024
	ds_read_b128 v[214:217], v158
	ds_read_b128 v[218:221], v158 offset:1024
	v_add_u32_e32 v159, 0xe000, v129
	v_add_u32_e32 v160, 0xc000, v129
	s_add_u32 m0, s32, 0xc000
	s_add_u32 s98, s14, 0x40080
	s_addc_u32 s99, s15, 0
	global_load_lds_dwordx4 v253, s[98:99]
	s_add_u32 m0, s32, 0xe000
	s_nop 0
	global_load_lds_dwordx4 v252, s[98:99]
	s_waitcnt lgkmcnt(8)
	s_setprio 1
	s_barrier
	s_waitcnt lgkmcnt(0)
	v_mfma_f32_16x16x32_bf16 v[124:127], v[190:193], v[162:165], v[124:127]
	v_mfma_f32_16x16x32_bf16 v[120:123], v[190:193], v[182:185], v[120:123]
	v_mfma_f32_16x16x32_bf16 v[116:119], v[198:201], v[162:165], v[116:119]
	v_mfma_f32_16x16x32_bf16 v[112:115], v[198:201], v[182:185], v[112:115]
	v_mfma_f32_16x16x32_bf16 v[108:111], v[206:209], v[162:165], v[108:111]
	v_mfma_f32_16x16x32_bf16 v[104:107], v[206:209], v[182:185], v[104:107]
	v_mfma_f32_16x16x32_bf16 v[100:103], v[214:217], v[162:165], v[100:103]
	v_mfma_f32_16x16x32_bf16 v[96:99], v[214:217], v[182:185], v[96:99]
	v_mfma_f32_16x16x32_bf16 v[124:127], v[194:197], v[178:181], v[124:127]
	v_mfma_f32_16x16x32_bf16 v[120:123], v[194:197], v[186:189], v[120:123]
	v_mfma_f32_16x16x32_bf16 v[116:119], v[202:205], v[178:181], v[116:119]
	v_mfma_f32_16x16x32_bf16 v[112:115], v[202:205], v[186:189], v[112:115]
	v_mfma_f32_16x16x32_bf16 v[108:111], v[210:213], v[178:181], v[108:111]
	v_mfma_f32_16x16x32_bf16 v[104:107], v[210:213], v[186:189], v[104:107]
	v_mfma_f32_16x16x32_bf16 v[100:103], v[218:221], v[178:181], v[100:103]
	v_mfma_f32_16x16x32_bf16 v[96:99], v[218:221], v[186:189], v[96:99]
	s_setprio 0
	s_barrier
	s_add_u32 s34, s6, s12
	s_addc_u32 s35, s7, s13
	ds_read_b128 v[222:225], v152
	ds_read_b128 v[226:229], v152 offset:1024
	ds_read_b128 v[230:233], v152 offset:2048
	ds_read_b128 v[234:237], v152 offset:3072
	s_add_u32 m0, s32, 0x10000
	s_add_u32 s98, s34, 0x100
	s_addc_u32 s99, s35, 0
	global_load_lds_dwordx4 v253, s[98:99]
	s_add_u32 m0, s32, 0x12000
	s_nop 0
	global_load_lds_dwordx4 v252, s[98:99]
	s_setprio 1
	s_barrier
	s_waitcnt lgkmcnt(0)
	v_mfma_f32_16x16x32_bf16 v[92:95], v[190:193], v[222:225], v[92:95]
	v_mfma_f32_16x16x32_bf16 v[88:91], v[190:193], v[230:233], v[88:91]
	v_mfma_f32_16x16x32_bf16 v[84:87], v[198:201], v[222:225], v[84:87]
	v_mfma_f32_16x16x32_bf16 v[80:83], v[198:201], v[230:233], v[80:83]
	v_mfma_f32_16x16x32_bf16 v[76:79], v[206:209], v[222:225], v[76:79]
	v_mfma_f32_16x16x32_bf16 v[72:75], v[206:209], v[230:233], v[72:75]
	v_mfma_f32_16x16x32_bf16 v[68:71], v[214:217], v[222:225], v[68:71]
	v_mfma_f32_16x16x32_bf16 v[64:67], v[214:217], v[230:233], v[64:67]
	v_mfma_f32_16x16x32_bf16 v[92:95], v[194:197], v[226:229], v[92:95]
	v_mfma_f32_16x16x32_bf16 v[88:91], v[194:197], v[234:237], v[88:91]
	v_mfma_f32_16x16x32_bf16 v[84:87], v[202:205], v[226:229], v[84:87]
	v_mfma_f32_16x16x32_bf16 v[80:83], v[202:205], v[234:237], v[80:83]
	v_mfma_f32_16x16x32_bf16 v[76:79], v[210:213], v[226:229], v[76:79]
	v_mfma_f32_16x16x32_bf16 v[72:75], v[210:213], v[234:237], v[72:75]
	v_mfma_f32_16x16x32_bf16 v[68:71], v[218:221], v[226:229], v[68:71]
	v_mfma_f32_16x16x32_bf16 v[64:67], v[218:221], v[234:237], v[64:67]
	s_setprio 0
	s_barrier
	ds_read_b128 v[190:193], v135 offset:16384
	ds_read_b128 v[194:197], v135 offset:17408
	ds_read_b128 v[198:201], v156 offset:16384
	ds_read_b128 v[202:205], v156 offset:17408
	ds_read_b128 v[206:209], v157 offset:16384
	ds_read_b128 v[210:213], v157 offset:17408
	ds_read_b128 v[214:217], v158 offset:16384
	ds_read_b128 v[218:221], v158 offset:17408
	s_mov_b32 m0, s32
	s_add_u32 s98, s14, 0x100
	s_addc_u32 s99, s15, 0
	global_load_lds_dwordx4 v253, s[98:99]
	s_add_u32 m0, s32, 0x2000
	s_nop 0
	global_load_lds_dwordx4 v252, s[98:99]
	s_setprio 1
	s_barrier
	s_waitcnt lgkmcnt(0)
	v_mfma_f32_16x16x32_bf16 v[60:63], v[190:193], v[162:165], v[60:63]
	v_mfma_f32_16x16x32_bf16 v[56:59], v[190:193], v[182:185], v[56:59]
	v_mfma_f32_16x16x32_bf16 v[52:55], v[198:201], v[162:165], v[52:55]
	v_mfma_f32_16x16x32_bf16 v[48:51], v[198:201], v[182:185], v[48:51]
	v_mfma_f32_16x16x32_bf16 v[44:47], v[206:209], v[162:165], v[44:47]
	v_mfma_f32_16x16x32_bf16 v[40:43], v[206:209], v[182:185], v[40:43]
	v_mfma_f32_16x16x32_bf16 v[36:39], v[214:217], v[162:165], v[36:39]
	v_mfma_f32_16x16x32_bf16 v[32:35], v[214:217], v[182:185], v[32:35]
	v_mfma_f32_16x16x32_bf16 v[60:63], v[194:197], v[178:181], v[60:63]
	v_mfma_f32_16x16x32_bf16 v[56:59], v[194:197], v[186:189], v[56:59]
	v_mfma_f32_16x16x32_bf16 v[52:55], v[202:205], v[178:181], v[52:55]
	v_mfma_f32_16x16x32_bf16 v[48:51], v[202:205], v[186:189], v[48:51]
	v_mfma_f32_16x16x32_bf16 v[44:47], v[210:213], v[178:181], v[44:47]
	v_mfma_f32_16x16x32_bf16 v[40:43], v[210:213], v[186:189], v[40:43]
	v_mfma_f32_16x16x32_bf16 v[36:39], v[218:221], v[178:181], v[36:39]
	v_mfma_f32_16x16x32_bf16 v[32:35], v[218:221], v[186:189], v[32:35]
	s_setprio 0
	s_barrier
	s_add_u32 m0, s32, 0x14000
	s_add_u32 s98, s34, 0x40100
	s_addc_u32 s99, s35, 0
	global_load_lds_dwordx4 v253, s[98:99]
	s_add_u32 m0, s32, 0x16000
	s_nop 0
	global_load_lds_dwordx4 v252, s[98:99]
	s_waitcnt vmcnt(6)
	s_barrier
; #define LDA(dst, b, h)                                                                                    \
;   _Pragma("unroll") for (int m = 0; m < 4; ++m) _Pragma("unroll") for (int k = 0; k < 2; ++k)             \
;       dst[m][k] = *reinterpret_cast<const bf16x8*>((char*)SA(b, h) + lds_byte(wr * 64 + m * 16 + fr, k * 32 + fq * 8))
; #define LDB(dst, b, h)                                                                                    \
;   _Pragma("unroll") for (int n = 0; n < 2; ++n) _Pragma("unroll") for (int k = 0; k < 2; ++k)             \
;       dst[n][k] = *reinterpret_cast<const bf16x8*>((char*)SB(b, h) + lds_byte(wc * 32 + n * 16 + fr, k * 32 + fq * 8))
; #define WAIT_V(n) asm volatile("s_waitcnt vmcnt(" #n ")" ::: "memory")
; #define WAIT_L(n) asm volatile("s_waitcnt lgkmcnt(" #n ")" ::: "memory")
; #define BAR __builtin_amdgcn_s_barrier()
; #define SCHED __builtin_amdgcn_sched_barrier(0)
; template <int EPI> ...
;     ...
;     WAIT_V(6); BAR; MMA(1, 1, At, B1); BAR;
;     LDB(B0, 1, 0); SCHED; LDA(At, 1, 0); STAGE(SA(0, 1), A, brow + HALF, t + 2);
;     WAIT_L(8); BAR; WAIT_L(0); MMA(0, 0, At, B0); BAR; SCHED;
;     LDB(B1, 1, 1); STAGE(SB(1, 0), Bt, bcol, t + 3);
;     BAR; WAIT_L(0); MMA(0, 1, At, B1); BAR;
;     LDA(At, 1, 1); STAGE(SA(1, 0), A, brow, t + 3);
	s_setprio 1
	v_mfma_f32_16x16x32_bf16 v[28:31], v[190:193], v[222:225], v[28:31]
	v_mfma_f32_16x16x32_bf16 v[24:27], v[190:193], v[230:233], v[24:27]
	v_mfma_f32_16x16x32_bf16 v[20:23], v[198:201], v[222:225], v[20:23]
	v_mfma_f32_16x16x32_bf16 v[16:19], v[198:201], v[230:233], v[16:19]
	v_mfma_f32_16x16x32_bf16 v[12:15], v[206:209], v[222:225], v[12:15]
	v_mfma_f32_16x16x32_bf16 v[8:11], v[206:209], v[230:233], v[8:11]
	v_mfma_f32_16x16x32_bf16 v[4:7], v[214:217], v[222:225], v[4:7]
	v_mfma_f32_16x16x32_bf16 v[0:3], v[214:217], v[230:233], v[0:3]
	v_mfma_f32_16x16x32_bf16 v[28:31], v[194:197], v[226:229], v[28:31]
	v_mfma_f32_16x16x32_bf16 v[24:27], v[194:197], v[234:237], v[24:27]
	v_mfma_f32_16x16x32_bf16 v[20:23], v[202:205], v[226:229], v[20:23]
	v_mfma_f32_16x16x32_bf16 v[16:19], v[202:205], v[234:237], v[16:19]
	v_mfma_f32_16x16x32_bf16 v[12:15], v[210:213], v[226:229], v[12:15]
	v_mfma_f32_16x16x32_bf16 v[8:11], v[210:213], v[234:237], v[8:11]
	v_mfma_f32_16x16x32_bf16 v[4:7], v[218:221], v[226:229], v[4:7]
	v_mfma_f32_16x16x32_bf16 v[0:3], v[218:221], v[234:237], v[0:3]
	s_setprio 0
	s_barrier
	ds_read_b128 v[162:165], v140
	ds_read_b128 v[178:181], v140 offset:1024
	ds_read_b128 v[182:185], v140 offset:2048
	ds_read_b128 v[186:189], v140 offset:3072
	ds_read_b128 v[190:193], v135 offset:32768
	ds_read_b128 v[194:197], v135 offset:33792
	ds_read_b128 v[198:201], v156 offset:32768
	ds_read_b128 v[202:205], v156 offset:33792
	ds_read_b128 v[206:209], v157 offset:32768
	ds_read_b128 v[210:213], v157 offset:33792
	ds_read_b128 v[214:217], v158 offset:32768
	ds_read_b128 v[218:221], v158 offset:33792
	s_add_u32 m0, s32, 0x4000
	s_add_u32 s98, s14, 0x40100
	s_addc_u32 s99, s15, 0
	global_load_lds_dwordx4 v253, s[98:99]
	s_add_u32 m0, s32, 0x6000
	s_nop 0
	global_load_lds_dwordx4 v252, s[98:99]
	s_waitcnt lgkmcnt(8)
	s_setprio 1
	s_barrier
	s_waitcnt lgkmcnt(0)
	v_mfma_f32_16x16x32_bf16 v[124:127], v[190:193], v[162:165], v[124:127]
	v_mfma_f32_16x16x32_bf16 v[120:123], v[190:193], v[182:185], v[120:123]
	v_mfma_f32_16x16x32_bf16 v[116:119], v[198:201], v[162:165], v[116:119]
	v_mfma_f32_16x16x32_bf16 v[112:115], v[198:201], v[182:185], v[112:115]
	v_mfma_f32_16x16x32_bf16 v[108:111], v[206:209], v[162:165], v[108:111]
	v_mfma_f32_16x16x32_bf16 v[104:107], v[206:209], v[182:185], v[104:107]
	v_mfma_f32_16x16x32_bf16 v[100:103], v[214:217], v[162:165], v[100:103]
	v_mfma_f32_16x16x32_bf16 v[96:99], v[214:217], v[182:185], v[96:99]
	v_mfma_f32_16x16x32_bf16 v[124:127], v[194:197], v[178:181], v[124:127]
	v_mfma_f32_16x16x32_bf16 v[120:123], v[194:197], v[186:189], v[120:123]
	v_mfma_f32_16x16x32_bf16 v[116:119], v[202:205], v[178:181], v[116:119]
	v_mfma_f32_16x16x32_bf16 v[112:115], v[202:205], v[186:189], v[112:115]
	v_mfma_f32_16x16x32_bf16 v[108:111], v[210:213], v[178:181], v[108:111]
	v_mfma_f32_16x16x32_bf16 v[104:107], v[210:213], v[186:189], v[104:107]
	v_mfma_f32_16x16x32_bf16 v[100:103], v[218:221], v[178:181], v[100:103]
	v_mfma_f32_16x16x32_bf16 v[96:99], v[218:221], v[186:189], v[96:99]
	s_setprio 0
	s_barrier
	ds_read_b128 v[222:225], v137
	ds_read_b128 v[226:229], v137 offset:1024
	ds_read_b128 v[230:233], v137 offset:2048
	ds_read_b128 v[234:237], v137 offset:3072
	s_add_u32 m0, s32, 0x18000
	s_add_u32 s98, s34, 0x180
	s_addc_u32 s99, s35, 0
	global_load_lds_dwordx4 v253, s[98:99]
	s_add_u32 m0, s32, 0x1a000
	s_nop 0
	global_load_lds_dwordx4 v252, s[98:99]
	s_setprio 1
	s_barrier
	s_waitcnt lgkmcnt(0)
	v_mfma_f32_16x16x32_bf16 v[92:95], v[190:193], v[222:225], v[92:95]
	v_mfma_f32_16x16x32_bf16 v[88:91], v[190:193], v[230:233], v[88:91]
	v_mfma_f32_16x16x32_bf16 v[84:87], v[198:201], v[222:225], v[84:87]
	v_mfma_f32_16x16x32_bf16 v[80:83], v[198:201], v[230:233], v[80:83]
	v_mfma_f32_16x16x32_bf16 v[76:79], v[206:209], v[222:225], v[76:79]
	v_mfma_f32_16x16x32_bf16 v[72:75], v[206:209], v[230:233], v[72:75]
	v_mfma_f32_16x16x32_bf16 v[68:71], v[214:217], v[222:225], v[68:71]
	v_mfma_f32_16x16x32_bf16 v[64:67], v[214:217], v[230:233], v[64:67]
	v_mfma_f32_16x16x32_bf16 v[92:95], v[194:197], v[226:229], v[92:95]
	v_mfma_f32_16x16x32_bf16 v[88:91], v[194:197], v[234:237], v[88:91]
	v_mfma_f32_16x16x32_bf16 v[84:87], v[202:205], v[226:229], v[84:87]
	v_mfma_f32_16x16x32_bf16 v[80:83], v[202:205], v[234:237], v[80:83]
	v_mfma_f32_16x16x32_bf16 v[76:79], v[210:213], v[226:229], v[76:79]
	v_mfma_f32_16x16x32_bf16 v[72:75], v[210:213], v[234:237], v[72:75]
	v_mfma_f32_16x16x32_bf16 v[68:71], v[218:221], v[226:229], v[68:71]
	v_mfma_f32_16x16x32_bf16 v[64:67], v[218:221], v[234:237], v[64:67]
	s_setprio 0
	s_barrier
	ds_read_b128 v[190:193], v135 offset:49152
	ds_read_b128 v[194:197], v135 offset:50176
	ds_read_b128 v[198:201], v156 offset:49152
	ds_read_b128 v[202:205], v156 offset:50176
	ds_read_b128 v[206:209], v157 offset:49152
	ds_read_b128 v[210:213], v157 offset:50176
	ds_read_b128 v[214:217], v158 offset:49152
	ds_read_b128 v[218:221], v158 offset:50176
	s_add_u32 m0, s32, 0x8000
	s_add_u32 s98, s14, 0x180
	s_addc_u32 s99, s15, 0
	global_load_lds_dwordx4 v253, s[98:99]
	s_nop 0
	s_add_u32 m0, s32, 0xa000
	s_nop 0
	global_load_lds_dwordx4 v252, s[98:99]
	s_setprio 1
	s_barrier
; #define LDA(dst, b, h)                                                                                    \
;   _Pragma("unroll") for (int m = 0; m < 4; ++m) _Pragma("unroll") for (int k = 0; k < 2; ++k)             \
;       dst[m][k] = *reinterpret_cast<const bf16x8*>((char*)SA(b, h) + lds_byte(wr * 64 + m * 16 + fr, k * 32 + fq * 8))
; #define LDB(dst, b, h)                                                                                    \
;   _Pragma("unroll") for (int n = 0; n < 2; ++n) _Pragma("unroll") for (int k = 0; k < 2; ++k)             \
;       dst[n][k] = *reinterpret_cast<const bf16x8*>((char*)SB(b, h) + lds_byte(wc * 32 + n * 16 + fr, k * 32 + fq * 8))
; #define WAIT_V(n) asm volatile("s_waitcnt vmcnt(" #n ")" ::: "memory")
; #define WAIT_L(n) asm volatile("s_waitcnt lgkmcnt(" #n ")" ::: "memory")
; #define BAR __builtin_amdgcn_s_barrier()
; #define SCHED __builtin_amdgcn_sched_barrier(0)
; template <int EPI> ...
;     ...
;     BAR; WAIT_L(0); MMA(1, 0, At, B0); BAR; SCHED;
;     STAGE(SB(1, 1), Bt, bcol + HALF, t + 3);
;     WAIT_V(6); BAR; MMA(1, 1, At, B1); BAR;
;   }
;   {
;     LDB(B0, 0, 0); LDA(At, 0, 0); STAGE(SA(1, 1), A, brow + HALF, nt - 1);
;     BAR; WAIT_L(0); MMA(0, 0, At, B0); BAR;
;     LDB(B1, 0, 1); BAR; WAIT_L(0); MMA(0, 1, At, B1); BAR;
	s_waitcnt lgkmcnt(0)
	v_mfma_f32_16x16x32_bf16 v[60:63], v[190:193], v[162:165], v[60:63]
	v_mfma_f32_16x16x32_bf16 v[56:59], v[190:193], v[182:185], v[56:59]
	v_mfma_f32_16x16x32_bf16 v[52:55], v[198:201], v[162:165], v[52:55]
	v_mfma_f32_16x16x32_bf16 v[48:51], v[198:201], v[182:185], v[48:51]
	v_mfma_f32_16x16x32_bf16 v[44:47], v[206:209], v[162:165], v[44:47]
	v_mfma_f32_16x16x32_bf16 v[40:43], v[206:209], v[182:185], v[40:43]
	v_mfma_f32_16x16x32_bf16 v[36:39], v[214:217], v[162:165], v[36:39]
	v_mfma_f32_16x16x32_bf16 v[32:35], v[214:217], v[182:185], v[32:35]
	v_mfma_f32_16x16x32_bf16 v[60:63], v[194:197], v[178:181], v[60:63]
	v_mfma_f32_16x16x32_bf16 v[56:59], v[194:197], v[186:189], v[56:59]
	v_mfma_f32_16x16x32_bf16 v[52:55], v[202:205], v[178:181], v[52:55]
	v_mfma_f32_16x16x32_bf16 v[48:51], v[202:205], v[186:189], v[48:51]
	v_mfma_f32_16x16x32_bf16 v[44:47], v[210:213], v[178:181], v[44:47]
	v_mfma_f32_16x16x32_bf16 v[40:43], v[210:213], v[186:189], v[40:43]
	v_mfma_f32_16x16x32_bf16 v[36:39], v[218:221], v[178:181], v[36:39]
	v_mfma_f32_16x16x32_bf16 v[32:35], v[218:221], v[186:189], v[32:35]
	s_setprio 0
	s_barrier
	s_add_u32 m0, s32, 0x1c000
	s_add_u32 s98, s34, 0x40180
	s_addc_u32 s99, s35, 0
	global_load_lds_dwordx4 v253, s[98:99]
	s_add_u32 m0, s32, 0x1e000
	s_nop 0
	global_load_lds_dwordx4 v252, s[98:99]
	s_waitcnt vmcnt(6)
	s_barrier
	s_setprio 1
	v_mfma_f32_16x16x32_bf16 v[28:31], v[190:193], v[222:225], v[28:31]
	v_mfma_f32_16x16x32_bf16 v[24:27], v[190:193], v[230:233], v[24:27]
	v_mfma_f32_16x16x32_bf16 v[20:23], v[198:201], v[222:225], v[20:23]
	v_mfma_f32_16x16x32_bf16 v[16:19], v[198:201], v[230:233], v[16:19]
	v_mfma_f32_16x16x32_bf16 v[12:15], v[206:209], v[222:225], v[12:15]
	v_mfma_f32_16x16x32_bf16 v[8:11], v[206:209], v[230:233], v[8:11]
	v_mfma_f32_16x16x32_bf16 v[4:7], v[214:217], v[222:225], v[4:7]
	v_mfma_f32_16x16x32_bf16 v[0:3], v[214:217], v[230:233], v[0:3]
	v_mfma_f32_16x16x32_bf16 v[28:31], v[194:197], v[226:229], v[28:31]
	v_mfma_f32_16x16x32_bf16 v[24:27], v[194:197], v[234:237], v[24:27]
	v_mfma_f32_16x16x32_bf16 v[20:23], v[202:205], v[226:229], v[20:23]
	v_mfma_f32_16x16x32_bf16 v[16:19], v[202:205], v[234:237], v[16:19]
	v_mfma_f32_16x16x32_bf16 v[12:15], v[210:213], v[226:229], v[12:15]
	v_mfma_f32_16x16x32_bf16 v[8:11], v[210:213], v[234:237], v[8:11]
	v_mfma_f32_16x16x32_bf16 v[4:7], v[218:221], v[226:229], v[4:7]
	v_mfma_f32_16x16x32_bf16 v[0:3], v[218:221], v[234:237], v[0:3]
	s_setprio 0
	s_add_i32 s67, s67, 2
	s_add_u32 s12, s12, 0x100
	s_addc_u32 s13, s13, 0
	s_cmp_lt_u32 s67, 12
	s_barrier
	s_cbranch_scc1 .LBB0_416
	ds_read_b128 v[142:145], v155
	ds_read_b128 v[162:165], v155 offset:1024
	ds_read_b128 v[178:181], v155 offset:2048
	ds_read_b128 v[182:185], v155 offset:3072
	ds_read_b128 v[186:189], v135
	ds_read_b128 v[190:193], v135 offset:1024
	ds_read_b128 v[194:197], v156
	ds_read_b128 v[198:201], v156 offset:1024
	ds_read_b128 v[202:205], v157
	ds_read_b128 v[206:209], v157 offset:1024
	ds_read_b128 v[210:213], v158
	ds_read_b128 v[214:217], v158 offset:1024
	v_mov_b32_e32 v129, v149
	v_lshl_add_u64 v[128:129], v[128:129], 1, s[10:11]
	s_mov_b64 s[8:9], 0x780
	v_readfirstlane_b32 s6, v160
	v_lshl_add_u64 v[128:129], v[128:129], 0, s[8:9]
	s_mov_b32 m0, s6
	v_mov_b32_e32 v131, v149
	global_load_lds_dwordx4 v[128:129], off
	v_readfirstlane_b32 s6, v159
	v_lshl_add_u64 v[128:129], v[130:131], 1, s[10:11]
	v_lshl_add_u64 v[128:129], v[128:129], 0, s[8:9]
	s_mov_b32 m0, s6
	s_nop 0
	global_load_lds_dwordx4 v[128:129], off
	s_setprio 1
	s_barrier
	s_waitcnt lgkmcnt(0)
	v_mfma_f32_16x16x32_bf16 v[124:127], v[186:189], v[142:145], v[124:127]
	v_mfma_f32_16x16x32_bf16 v[120:123], v[186:189], v[178:181], v[120:123]
	v_mfma_f32_16x16x32_bf16 v[116:119], v[194:197], v[142:145], v[116:119]
	v_mfma_f32_16x16x32_bf16 v[112:115], v[194:197], v[178:181], v[112:115]
	v_mfma_f32_16x16x32_bf16 v[108:111], v[202:205], v[142:145], v[108:111]
	v_mfma_f32_16x16x32_bf16 v[104:107], v[202:205], v[178:181], v[104:107]
	v_mfma_f32_16x16x32_bf16 v[96:99], v[210:213], v[178:181], v[96:99]
	v_mfma_f32_16x16x32_bf16 v[124:127], v[190:193], v[162:165], v[124:127]
	v_mfma_f32_16x16x32_bf16 v[120:123], v[190:193], v[182:185], v[120:123]
	v_mfma_f32_16x16x32_bf16 v[116:119], v[198:201], v[162:165], v[116:119]
	v_mfma_f32_16x16x32_bf16 v[112:115], v[198:201], v[182:185], v[112:115]
	v_mfma_f32_16x16x32_bf16 v[108:111], v[206:209], v[162:165], v[108:111]
	v_mfma_f32_16x16x32_bf16 v[104:107], v[206:209], v[182:185], v[104:107]
	v_mfma_f32_16x16x32_bf16 v[100:103], v[210:213], v[142:145], v[100:103]
	v_mfma_f32_16x16x32_bf16 v[96:99], v[214:217], v[182:185], v[96:99]
	v_mfma_f32_16x16x32_bf16 v[128:131], v[214:217], v[162:165], v[100:103]
	s_setprio 0
	s_barrier
	s_nop 3
	ds_read_b128 v[100:103], v152
	ds_read_b128 v[218:221], v152 offset:1024
	ds_read_b128 v[222:225], v152 offset:2048
	ds_read_b128 v[152:155], v152 offset:3072
	s_setprio 1
	s_barrier
	s_waitcnt lgkmcnt(0)
	v_mfma_f32_16x16x32_bf16 v[88:91], v[186:189], v[222:225], v[88:91]
	v_mfma_f32_16x16x32_bf16 v[92:95], v[186:189], v[100:103], v[92:95]
	v_mfma_f32_16x16x32_bf16 v[88:91], v[190:193], v[152:155], v[88:91]
	v_mfma_f32_16x16x32_bf16 v[84:87], v[194:197], v[100:103], v[84:87]
	v_mfma_f32_16x16x32_bf16 v[80:83], v[194:197], v[222:225], v[80:83]
	v_mfma_f32_16x16x32_bf16 v[76:79], v[202:205], v[100:103], v[76:79]
	v_mfma_f32_16x16x32_bf16 v[72:75], v[202:205], v[222:225], v[72:75]
	v_mfma_f32_16x16x32_bf16 v[68:71], v[210:213], v[100:103], v[68:71]
	v_mfma_f32_16x16x32_bf16 v[64:67], v[210:213], v[222:225], v[64:67]
	v_mfma_f32_16x16x32_bf16 v[226:229], v[190:193], v[218:221], v[92:95]
	v_mfma_f32_16x16x32_bf16 v[186:189], v[198:201], v[218:221], v[84:87]
	v_mfma_f32_16x16x32_bf16 v[190:193], v[198:201], v[152:155], v[80:83]
	v_mfma_f32_16x16x32_bf16 v[194:197], v[206:209], v[218:221], v[76:79]
	v_mfma_f32_16x16x32_bf16 v[198:201], v[206:209], v[152:155], v[72:75]
	v_mfma_f32_16x16x32_bf16 v[202:205], v[214:217], v[218:221], v[68:71]
	v_mfma_f32_16x16x32_bf16 v[206:209], v[214:217], v[152:155], v[64:67]
	s_setprio 0
	s_barrier
; #define LDA(dst, b, h)                                                                                    \
;   _Pragma("unroll") for (int m = 0; m < 4; ++m) _Pragma("unroll") for (int k = 0; k < 2; ++k)             \
;       dst[m][k] = *reinterpret_cast<const bf16x8*>((char*)SA(b, h) + lds_byte(wr * 64 + m * 16 + fr, k * 32 + fq * 8))
; #define LDB(dst, b, h)                                                                                    \
;   _Pragma("unroll") for (int n = 0; n < 2; ++n) _Pragma("unroll") for (int k = 0; k < 2; ++k)             \
;       dst[n][k] = *reinterpret_cast<const bf16x8*>((char*)SB(b, h) + lds_byte(wc * 32 + n * 16 + fr, k * 32 + fq * 8))
; #define WAIT_V(n) asm volatile("s_waitcnt vmcnt(" #n ")" ::: "memory")
; #define WAIT_L(n) asm volatile("s_waitcnt lgkmcnt(" #n ")" ::: "memory")
; #define BAR __builtin_amdgcn_s_barrier()
; template <int EPI> ...
;     ...
;     LDA(At, 0, 1); WAIT_V(4); BAR; WAIT_L(0); MMA(1, 0, At, B0); MMA(1, 1, At, B1); BAR;
;   }
;   {
;     LDB(B0, 1, 0); LDA(At, 1, 0); WAIT_V(2); BAR; WAIT_L(0); MMA(0, 0, At, B0); BAR;
	s_nop 0
	ds_read_b128 v[64:67], v135 offset:16384
	ds_read_b128 v[68:71], v135 offset:17408
	ds_read_b128 v[72:75], v156 offset:16384
	ds_read_b128 v[76:79], v156 offset:17408
	ds_read_b128 v[80:83], v157 offset:16384
	ds_read_b128 v[84:87], v157 offset:17408
	ds_read_b128 v[92:95], v158 offset:16384
	ds_read_b128 v[210:213], v158 offset:17408
	s_waitcnt vmcnt(4)
	s_setprio 1
	s_barrier
	s_waitcnt lgkmcnt(0)
	v_mfma_f32_16x16x32_bf16 v[60:63], v[64:67], v[142:145], v[60:63]
	v_mfma_f32_16x16x32_bf16 v[56:59], v[64:67], v[178:181], v[56:59]
	v_mfma_f32_16x16x32_bf16 v[52:55], v[72:75], v[142:145], v[52:55]
	v_mfma_f32_16x16x32_bf16 v[48:51], v[72:75], v[178:181], v[48:51]
	v_mfma_f32_16x16x32_bf16 v[44:47], v[80:83], v[142:145], v[44:47]
	v_mfma_f32_16x16x32_bf16 v[40:43], v[80:83], v[178:181], v[40:43]
	v_mfma_f32_16x16x32_bf16 v[36:39], v[92:95], v[142:145], v[36:39]
	v_mfma_f32_16x16x32_bf16 v[32:35], v[92:95], v[178:181], v[32:35]
	v_mfma_f32_16x16x32_bf16 v[60:63], v[68:71], v[162:165], v[60:63]
	v_mfma_f32_16x16x32_bf16 v[56:59], v[68:71], v[182:185], v[56:59]
	v_mfma_f32_16x16x32_bf16 v[52:55], v[76:79], v[162:165], v[52:55]
	v_mfma_f32_16x16x32_bf16 v[48:51], v[76:79], v[182:185], v[48:51]
	v_mfma_f32_16x16x32_bf16 v[44:47], v[84:87], v[162:165], v[44:47]
	v_mfma_f32_16x16x32_bf16 v[40:43], v[84:87], v[182:185], v[40:43]
	v_mfma_f32_16x16x32_bf16 v[36:39], v[210:213], v[162:165], v[36:39]
	v_mfma_f32_16x16x32_bf16 v[32:35], v[210:213], v[182:185], v[32:35]
	s_setprio 0
	s_setprio 1
	v_mfma_f32_16x16x32_bf16 v[28:31], v[64:67], v[100:103], v[28:31]
	v_mfma_f32_16x16x32_bf16 v[24:27], v[64:67], v[222:225], v[24:27]
	v_mfma_f32_16x16x32_bf16 v[20:23], v[72:75], v[100:103], v[20:23]
	v_mfma_f32_16x16x32_bf16 v[16:19], v[72:75], v[222:225], v[16:19]
	v_mfma_f32_16x16x32_bf16 v[12:15], v[80:83], v[100:103], v[12:15]
	v_mfma_f32_16x16x32_bf16 v[8:11], v[80:83], v[222:225], v[8:11]
	v_mfma_f32_16x16x32_bf16 v[4:7], v[92:95], v[100:103], v[4:7]
	v_mfma_f32_16x16x32_bf16 v[0:3], v[92:95], v[222:225], v[0:3]
	v_mfma_f32_16x16x32_bf16 v[142:145], v[68:71], v[218:221], v[28:31]
	v_mfma_f32_16x16x32_bf16 v[160:163], v[68:71], v[152:155], v[24:27]
	v_mfma_f32_16x16x32_bf16 v[164:167], v[76:79], v[218:221], v[20:23]
	v_mfma_f32_16x16x32_bf16 v[178:181], v[76:79], v[152:155], v[16:19]
	v_mfma_f32_16x16x32_bf16 v[182:185], v[84:87], v[218:221], v[12:15]
	v_mfma_f32_16x16x32_bf16 v[214:217], v[84:87], v[152:155], v[8:11]
	v_mfma_f32_16x16x32_bf16 v[218:221], v[210:213], v[218:221], v[4:7]
	v_mfma_f32_16x16x32_bf16 v[152:155], v[210:213], v[152:155], v[0:3]
	s_setprio 0
	s_barrier
	s_nop 0
	ds_read_b128 v[0:3], v140
	ds_read_b128 v[4:7], v140 offset:1024
	ds_read_b128 v[210:213], v140 offset:2048
	ds_read_b128 v[138:141], v140 offset:3072
	ds_read_b128 v[8:11], v135 offset:32768
	ds_read_b128 v[12:15], v135 offset:33792
	ds_read_b128 v[16:19], v156 offset:32768
	ds_read_b128 v[20:23], v156 offset:33792
	ds_read_b128 v[24:27], v157 offset:32768
	ds_read_b128 v[28:31], v157 offset:33792
	ds_read_b128 v[222:225], v158 offset:32768
	ds_read_b128 v[230:233], v158 offset:33792
	s_waitcnt vmcnt(2)
	s_setprio 1
	s_barrier
	s_waitcnt lgkmcnt(0)
	v_mfma_f32_16x16x32_bf16 v[64:67], v[8:11], v[0:3], v[124:127]
	v_mfma_f32_16x16x32_bf16 v[92:95], v[12:15], v[4:7], v[64:67]
	v_mfma_f32_16x16x32_bf16 v[64:67], v[8:11], v[210:213], v[120:123]
	v_mfma_f32_16x16x32_bf16 v[100:103], v[12:15], v[138:141], v[64:67]
	v_mfma_f32_16x16x32_bf16 v[64:67], v[16:19], v[0:3], v[116:119]
	v_mfma_f32_16x16x32_bf16 v[80:83], v[20:23], v[4:7], v[64:67]
	v_mfma_f32_16x16x32_bf16 v[64:67], v[16:19], v[210:213], v[112:115]
	v_mfma_f32_16x16x32_bf16 v[84:87], v[20:23], v[138:141], v[64:67]
	v_mfma_f32_16x16x32_bf16 v[64:67], v[24:27], v[0:3], v[108:111]
	v_mfma_f32_16x16x32_bf16 v[72:75], v[28:31], v[4:7], v[64:67]
	v_mfma_f32_16x16x32_bf16 v[64:67], v[24:27], v[210:213], v[104:107]
	v_mfma_f32_16x16x32_bf16 v[76:79], v[28:31], v[138:141], v[64:67]
	v_mfma_f32_16x16x32_bf16 v[64:67], v[222:225], v[0:3], v[128:131]
	v_mfma_f32_16x16x32_bf16 v[68:71], v[222:225], v[210:213], v[96:99]
	v_mfma_f32_16x16x32_bf16 v[64:67], v[230:233], v[4:7], v[64:67]
	v_mfma_f32_16x16x32_bf16 v[68:71], v[230:233], v[138:141], v[68:71]
	s_setprio 0
	s_barrier
; #define LDA(dst, b, h)                                                                                    \
;   _Pragma("unroll") for (int m = 0; m < 4; ++m) _Pragma("unroll") for (int k = 0; k < 2; ++k)             \
;       dst[m][k] = *reinterpret_cast<const bf16x8*>((char*)SA(b, h) + lds_byte(wr * 64 + m * 16 + fr, k * 32 + fq * 8))
; #define LDB(dst, b, h)                                                                                    \
;   _Pragma("unroll") for (int n = 0; n < 2; ++n) _Pragma("unroll") for (int k = 0; k < 2; ++k)             \
;       dst[n][k] = *reinterpret_cast<const bf16x8*>((char*)SB(b, h) + lds_byte(wc * 32 + n * 16 + fr, k * 32 + fq * 8))
; #define WAIT_V(n) asm volatile("s_waitcnt vmcnt(" #n ")" ::: "memory")
; #define WAIT_L(n) asm volatile("s_waitcnt lgkmcnt(" #n ")" ::: "memory")
; #define BAR __builtin_amdgcn_s_barrier()
; template <int EPI> ...
;     ...
;     LDB(B1, 1, 1); WAIT_V(0); BAR; WAIT_L(0); MMA(0, 1, At, B1); BAR;
;     LDA(At, 1, 1); BAR; WAIT_L(0); MMA(1, 0, At, B0); MMA(1, 1, At, B1); BAR;
;   }
;   if (wr == 0) BAR;
	ds_read_b128 v[128:131], v137
	ds_read_b128 v[234:237], v137 offset:1024
	ds_read_b128 v[238:241], v137 offset:2048
	ds_read_b128 v[242:245], v137 offset:3072
	s_waitcnt vmcnt(0)
	s_setprio 1
	s_barrier
	s_waitcnt lgkmcnt(0)
	v_mfma_f32_16x16x32_bf16 v[96:99], v[8:11], v[128:131], v[226:229]
	v_mfma_f32_16x16x32_bf16 v[8:11], v[8:11], v[238:241], v[88:91]
	v_mfma_f32_16x16x32_bf16 v[124:127], v[12:15], v[242:245], v[8:11]
	v_mfma_f32_16x16x32_bf16 v[8:11], v[16:19], v[128:131], v[186:189]
	v_mfma_f32_16x16x32_bf16 v[112:115], v[20:23], v[234:237], v[8:11]
	v_mfma_f32_16x16x32_bf16 v[8:11], v[16:19], v[238:241], v[190:193]
	v_mfma_f32_16x16x32_bf16 v[116:119], v[20:23], v[242:245], v[8:11]
	v_mfma_f32_16x16x32_bf16 v[8:11], v[24:27], v[128:131], v[194:197]
	v_mfma_f32_16x16x32_bf16 v[104:107], v[28:31], v[234:237], v[8:11]
	v_mfma_f32_16x16x32_bf16 v[8:11], v[24:27], v[238:241], v[198:201]
	v_mfma_f32_16x16x32_bf16 v[108:111], v[28:31], v[242:245], v[8:11]
	v_mfma_f32_16x16x32_bf16 v[8:11], v[222:225], v[128:131], v[202:205]
	v_mfma_f32_16x16x32_bf16 v[88:91], v[230:233], v[234:237], v[8:11]
	v_mfma_f32_16x16x32_bf16 v[8:11], v[222:225], v[238:241], v[206:209]
	v_mfma_f32_16x16x32_bf16 v[120:123], v[12:15], v[234:237], v[96:99]
	v_mfma_f32_16x16x32_bf16 v[96:99], v[230:233], v[242:245], v[8:11]
	s_setprio 0
	s_barrier
	ds_read_b128 v[186:189], v135 offset:49152
	ds_read_b128 v[134:137], v135 offset:50176
	ds_read_b128 v[190:193], v156 offset:49152
	ds_read_b128 v[194:197], v156 offset:50176
	ds_read_b128 v[198:201], v157 offset:49152
	ds_read_b128 v[202:205], v157 offset:50176
	ds_read_b128 v[206:209], v158 offset:49152
	ds_read_b128 v[156:159], v158 offset:50176
	s_setprio 1
	s_barrier
	s_waitcnt lgkmcnt(0)
	v_mfma_f32_16x16x32_bf16 v[8:11], v[186:189], v[0:3], v[60:63]
	v_mfma_f32_16x16x32_bf16 v[24:27], v[134:137], v[4:7], v[8:11]
	v_mfma_f32_16x16x32_bf16 v[8:11], v[186:189], v[210:213], v[56:59]
	v_mfma_f32_16x16x32_bf16 v[28:31], v[134:137], v[138:141], v[8:11]
	v_mfma_f32_16x16x32_bf16 v[8:11], v[190:193], v[0:3], v[52:55]
	v_mfma_f32_16x16x32_bf16 v[16:19], v[194:197], v[4:7], v[8:11]
	v_mfma_f32_16x16x32_bf16 v[8:11], v[190:193], v[210:213], v[48:51]
	v_mfma_f32_16x16x32_bf16 v[20:23], v[194:197], v[138:141], v[8:11]
	v_mfma_f32_16x16x32_bf16 v[8:11], v[198:201], v[0:3], v[44:47]
	v_mfma_f32_16x16x32_bf16 v[0:3], v[206:209], v[0:3], v[36:39]
	v_mfma_f32_16x16x32_bf16 v[8:11], v[202:205], v[4:7], v[8:11]
	v_mfma_f32_16x16x32_bf16 v[12:15], v[198:201], v[210:213], v[40:43]
	v_mfma_f32_16x16x32_bf16 v[0:3], v[156:159], v[4:7], v[0:3]
	v_mfma_f32_16x16x32_bf16 v[4:7], v[206:209], v[210:213], v[32:35]
	v_mfma_f32_16x16x32_bf16 v[12:15], v[202:205], v[138:141], v[12:15]
	v_mfma_f32_16x16x32_bf16 v[4:7], v[156:159], v[138:141], v[4:7]
	s_setprio 0
	s_setprio 1
	v_mfma_f32_16x16x32_bf16 v[32:35], v[186:189], v[128:131], v[142:145]
	v_mfma_f32_16x16x32_bf16 v[56:59], v[134:137], v[234:237], v[32:35]
	v_mfma_f32_16x16x32_bf16 v[32:35], v[186:189], v[238:241], v[160:163]
	v_mfma_f32_16x16x32_bf16 v[60:63], v[134:137], v[242:245], v[32:35]
	v_mfma_f32_16x16x32_bf16 v[32:35], v[190:193], v[128:131], v[164:167]
	v_mfma_f32_16x16x32_bf16 v[48:51], v[194:197], v[234:237], v[32:35]
	v_mfma_f32_16x16x32_bf16 v[32:35], v[190:193], v[238:241], v[178:181]
	v_mfma_f32_16x16x32_bf16 v[52:55], v[194:197], v[242:245], v[32:35]
	v_mfma_f32_16x16x32_bf16 v[32:35], v[198:201], v[128:131], v[182:185]
	v_mfma_f32_16x16x32_bf16 v[40:43], v[202:205], v[234:237], v[32:35]
	v_mfma_f32_16x16x32_bf16 v[32:35], v[198:201], v[238:241], v[214:217]
	v_mfma_f32_16x16x32_bf16 v[44:47], v[202:205], v[242:245], v[32:35]
	v_mfma_f32_16x16x32_bf16 v[32:35], v[206:209], v[128:131], v[218:221]
	v_mfma_f32_16x16x32_bf16 v[36:39], v[206:209], v[238:241], v[152:155]
	v_mfma_f32_16x16x32_bf16 v[32:35], v[156:159], v[234:237], v[32:35]
	v_mfma_f32_16x16x32_bf16 v[36:39], v[156:159], v[242:245], v[36:39]
	s_setprio 0
	s_cmpk_gt_u32 s62, 0xff
	s_barrier
	s_cbranch_scc1 .LBB0_419
	s_barrier

; DEVI f32x4 ozero() { float z = 0.f; asm volatile("" : "+v"(z)); return f32x4{z, z, z, z}; }
; #define LDA(dst, b, h)                                                                                    \
;   _Pragma("unroll") for (int m = 0; m < 4; ++m) _Pragma("unroll") for (int k = 0; k < 2; ++k)             \
;       dst[m][k] = *reinterpret_cast<const bf16x8*>((char*)SA(b, h) + lds_byte(wr * 64 + m * 16 + fr, k * 32 + fq * 8))
; #define LDB(dst, b, h)                                                                                    \
;   _Pragma("unroll") for (int n = 0; n < 2; ++n) _Pragma("unroll") for (int k = 0; k < 2; ++k)             \
;       dst[n][k] = *reinterpret_cast<const bf16x8*>((char*)SB(b, h) + lds_byte(wc * 32 + n * 16 + fr, k * 32 + fq * 8))
; #define WAIT_V(n) asm volatile("s_waitcnt vmcnt(" #n ")" ::: "memory")
; #define WAIT_L(n) asm volatile("s_waitcnt lgkmcnt(" #n ")" ::: "memory")
; #define BAR __builtin_amdgcn_s_barrier()
; #define SCHED __builtin_amdgcn_sched_barrier(0)
; template <int EPI> ...
;     ...
;   const int brow = m0, bcol = n0;
;   const int wid = __builtin_amdgcn_readfirstlane(tid >> 6), lane = tid & 63, wr = wid >> 2, wc = wid & 3, fr = lane & 15, fq = lane >> 4;
;   f32x4 acc[2][2][4][2];
;   {
;     const f32x4 zq = ozero();
; #pragma unroll
;     for (int a_ = 0; a_ < 2; ++a_)
; #pragma unroll
;       for (int b_ = 0; b_ < 2; ++b_)
; #pragma unroll
;         for (int m = 0; m < 4; ++m) { acc[a_][b_][m][0] = zq; acc[a_][b_][m][1] = zq; }
;   }
;   bf16x8 At[4][2], B0[2][2], B1[2][2];
;   const int nt = K / BK;
;     ...
;   if (first) {
;     WAIT_V(0);
;     ISSUE_PRO(brow, bcol);
;   }
;   if (wr == 1) BAR;
;   WAIT_V(10); BAR;
;   WAIT_V(6); BAR;
;   for (int t = 0; t < nt - 2; t += 2) {
;     LDB(B0, 0, 0); SCHED; LDA(At, 0, 0); STAGE(SA(1, 1), A, brow + HALF, t + 1);
;     WAIT_L(8); BAR; WAIT_L(0); MMA(0, 0, At, B0); BAR; SCHED;
;     LDB(B1, 0, 1); STAGE(SB(0, 0), Bt, bcol, t + 2);
;     BAR; WAIT_L(0); MMA(0, 1, At, B1); BAR;
;     LDA(At, 0, 1); STAGE(SA(0, 0), A, brow, t + 2);
.LBB0_704:
	s_ashr_i32 s30, s23, 6
	s_and_b32 s31, s30, 3
	v_and_b32_e32 v128, 15, v130
	v_and_b32_e32 v9, 48, v130
	v_lshlrev_b32_e32 v131, 2, v130
	s_lshl_b32 s44, s31, 12
	v_lshl_or_b32 v8, v128, 6, v9
	v_and_b32_e32 v12, 32, v131
	v_bitop3_b32 v129, s44, v8, v12 bitop3:0xf6
	v_or_b32_e32 v5, 0x10000, v129
	v_or_b32_e32 v10, 0x10800, v129
	s_waitcnt vmcnt(10)
	s_barrier
	s_waitcnt vmcnt(6)
	s_barrier
	v_or_b32_e32 v7, 0x10400, v129
	ds_read_b128 v[32:35], v5
	ds_read_b128 v[36:39], v7
	v_or_b32_e32 v11, 0x10c00, v129
	ds_read_b128 v[40:43], v10
	ds_read_b128 v[44:47], v11
	v_mov_b32_e32 v1, v0
	v_mov_b32_e32 v2, v0
	v_mov_b32_e32 v3, v0
	v_lshlrev_b32_e32 v13, 6, v130
	s_movk_i32 s64, 0x3c0
	s_lshl_b32 s44, s22, 13
	v_and_or_b32 v9, v13, s64, v9
	v_bitop3_b32 v8, s44, v8, v12 bitop3:0xf6
	v_bitop3_b32 v9, s44, v9, v12 bitop3:0xf6
	v_mov_b32_e32 v148, v4
	ds_read_b128 v[48:51], v8
	ds_read_b128 v[52:55], v8 offset:1024
	ds_read_b128 v[56:59], v9 offset:2048
	ds_read_b128 v[60:63], v9 offset:3072
	ds_read_b128 v[64:67], v9 offset:4096
	ds_read_b128 v[68:71], v9 offset:5120
	ds_read_b128 v[72:75], v9 offset:6144
	ds_read_b128 v[76:79], v9 offset:7168
	s_nop 0
	v_lshl_add_u64 v[12:13], v[148:149], 1, s[0:1]
	v_lshl_add_u64 v[14:15], v[12:13], 0, s[46:47]
	v_add_u32_e32 v12, 0xc000, v18
	v_mov_b32_e32 v148, v6
	v_readfirstlane_b32 s67, v12
	s_mov_b32 m0, s67
	v_add_u32_e32 v13, 0xe000, v18
	global_load_lds_dwordx4 v[14:15], off
	v_readfirstlane_b32 s44, v13
	v_lshl_add_u64 v[14:15], v[148:149], 1, s[0:1]
	v_lshl_add_u64 v[14:15], v[14:15], 0, s[46:47]
	s_mov_b32 m0, s44
	s_nop 0
	global_load_lds_dwordx4 v[14:15], off
	s_waitcnt lgkmcnt(8)
	s_setprio 1
	s_barrier
	s_waitcnt lgkmcnt(0)
	v_mfma_f32_16x16x32_bf16 v[14:17], v[48:51], v[32:35], v[0:3]
	v_mfma_f32_16x16x32_bf16 v[80:83], v[52:55], v[36:39], v[14:17]
	v_mfma_f32_16x16x32_bf16 v[14:17], v[48:51], v[40:43], v[0:3]
	v_mfma_f32_16x16x32_bf16 v[84:87], v[52:55], v[44:47], v[14:17]
	v_mfma_f32_16x16x32_bf16 v[14:17], v[56:59], v[32:35], v[0:3]
	v_mfma_f32_16x16x32_bf16 v[88:91], v[60:63], v[36:39], v[14:17]
	v_mfma_f32_16x16x32_bf16 v[14:17], v[56:59], v[40:43], v[0:3]
	v_mfma_f32_16x16x32_bf16 v[92:95], v[60:63], v[44:47], v[14:17]
	v_mfma_f32_16x16x32_bf16 v[14:17], v[64:67], v[32:35], v[0:3]
	v_mfma_f32_16x16x32_bf16 v[96:99], v[68:71], v[36:39], v[14:17]
	v_mfma_f32_16x16x32_bf16 v[14:17], v[64:67], v[40:43], v[0:3]
	v_mfma_f32_16x16x32_bf16 v[100:103], v[68:71], v[44:47], v[14:17]
	v_mfma_f32_16x16x32_bf16 v[14:17], v[72:75], v[32:35], v[0:3]
	v_mfma_f32_16x16x32_bf16 v[104:107], v[76:79], v[36:39], v[14:17]
	v_mfma_f32_16x16x32_bf16 v[14:17], v[72:75], v[40:43], v[0:3]
	v_mfma_f32_16x16x32_bf16 v[108:111], v[76:79], v[44:47], v[14:17]
	s_setprio 0
	s_barrier
	s_nop 4
	v_or_b32_e32 v14, 0x14000, v129
	v_or_b32_e32 v16, 0x14800, v129
	v_mov_b32_e32 v148, v4
	v_or_b32_e32 v15, 0x14400, v129
	ds_read_b128 v[112:115], v14
	ds_read_b128 v[116:119], v15
	v_or_b32_e32 v17, 0x14c00, v129
	ds_read_b128 v[120:123], v16
	ds_read_b128 v[124:127], v17
	v_readfirstlane_b32 s70, v30
	v_lshl_add_u64 v[132:133], v[148:149], 1, s[14:15]
	v_lshl_add_u64 v[132:133], v[132:133], 0, s[50:51]
	s_mov_b32 m0, s70
	v_mov_b32_e32 v148, v6
	global_load_lds_dwordx4 v[132:133], off
	v_readfirstlane_b32 s64, v31
	v_lshl_add_u64 v[132:133], v[148:149], 1, s[14:15]
	v_lshl_add_u64 v[132:133], v[132:133], 0, s[50:51]
	s_mov_b32 m0, s64
	s_nop 0
	global_load_lds_dwordx4 v[132:133], off
	s_setprio 1
	s_barrier
	s_waitcnt lgkmcnt(0)
	v_mfma_f32_16x16x32_bf16 v[132:135], v[48:51], v[112:115], v[0:3]
	v_mfma_f32_16x16x32_bf16 v[48:51], v[48:51], v[120:123], v[0:3]
	v_mfma_f32_16x16x32_bf16 v[132:135], v[52:55], v[116:119], v[132:135]
	v_mfma_f32_16x16x32_bf16 v[48:51], v[52:55], v[124:127], v[48:51]
	v_mfma_f32_16x16x32_bf16 v[52:55], v[56:59], v[112:115], v[0:3]
	v_mfma_f32_16x16x32_bf16 v[56:59], v[56:59], v[120:123], v[0:3]
	v_mfma_f32_16x16x32_bf16 v[52:55], v[60:63], v[116:119], v[52:55]
	v_mfma_f32_16x16x32_bf16 v[56:59], v[60:63], v[124:127], v[56:59]
	v_mfma_f32_16x16x32_bf16 v[60:63], v[64:67], v[112:115], v[0:3]
	v_mfma_f32_16x16x32_bf16 v[64:67], v[64:67], v[120:123], v[0:3]
	v_mfma_f32_16x16x32_bf16 v[60:63], v[68:71], v[116:119], v[60:63]
	v_mfma_f32_16x16x32_bf16 v[64:67], v[68:71], v[124:127], v[64:67]
	v_mfma_f32_16x16x32_bf16 v[68:71], v[72:75], v[112:115], v[0:3]
	v_mfma_f32_16x16x32_bf16 v[72:75], v[72:75], v[120:123], v[0:3]
	v_mfma_f32_16x16x32_bf16 v[68:71], v[76:79], v[116:119], v[68:71]
	v_mfma_f32_16x16x32_bf16 v[72:75], v[76:79], v[124:127], v[72:75]
	s_setprio 0
	v_mov_b32_e32 v148, v4
	s_barrier
	ds_read_b128 v[76:79], v8 offset:16384
	ds_read_b128 v[136:139], v8 offset:17408
	ds_read_b128 v[140:143], v9 offset:18432
	ds_read_b128 v[144:147], v9 offset:19456
	ds_read_b128 v[152:155], v9 offset:20480
	ds_read_b128 v[156:159], v9 offset:21504
	ds_read_b128 v[160:163], v9 offset:22528
	ds_read_b128 v[164:167], v9 offset:23552
	v_readfirstlane_b32 s73, v18
	v_lshl_add_u64 v[30:31], v[148:149], 1, s[12:13]
	v_lshl_add_u64 v[30:31], v[30:31], 0, s[50:51]
	s_mov_b32 m0, s73
	v_mov_b32_e32 v148, v6
	global_load_lds_dwordx4 v[30:31], off
	v_readfirstlane_b32 s65, v19
	v_lshl_add_u64 v[30:31], v[148:149], 1, s[12:13]
	v_lshl_add_u64 v[30:31], v[30:31], 0, s[50:51]
	s_mov_b32 m0, s65
	s_nop 0
	global_load_lds_dwordx4 v[30:31], off
	s_setprio 1
	s_barrier
; #define LDA(dst, b, h)                                                                                    \
;   _Pragma("unroll") for (int m = 0; m < 4; ++m) _Pragma("unroll") for (int k = 0; k < 2; ++k)             \
;       dst[m][k] = *reinterpret_cast<const bf16x8*>((char*)SA(b, h) + lds_byte(wr * 64 + m * 16 + fr, k * 32 + fq * 8))
; #define LDB(dst, b, h)                                                                                    \
;   _Pragma("unroll") for (int n = 0; n < 2; ++n) _Pragma("unroll") for (int k = 0; k < 2; ++k)             \
;       dst[n][k] = *reinterpret_cast<const bf16x8*>((char*)SB(b, h) + lds_byte(wc * 32 + n * 16 + fr, k * 32 + fq * 8))
; #define WAIT_V(n) asm volatile("s_waitcnt vmcnt(" #n ")" ::: "memory")
; #define WAIT_L(n) asm volatile("s_waitcnt lgkmcnt(" #n ")" ::: "memory")
; #define BAR __builtin_amdgcn_s_barrier()
; #define SCHED __builtin_amdgcn_sched_barrier(0)
; template <int EPI> ...
;     ...
;     BAR; WAIT_L(0); MMA(1, 0, At, B0); BAR; SCHED;
;     STAGE(SB(0, 1), Bt, bcol + HALF, t + 2);
;     WAIT_V(6); BAR; MMA(1, 1, At, B1); BAR;
;     LDB(B0, 1, 0); SCHED; LDA(At, 1, 0); STAGE(SA(0, 1), A, brow + HALF, t + 2);
;     WAIT_L(8); BAR; WAIT_L(0); MMA(0, 0, At, B0); BAR; SCHED;
;     LDB(B1, 1, 1); STAGE(SB(1, 0), Bt, bcol, t + 3);
	s_waitcnt lgkmcnt(0)
	v_mfma_f32_16x16x32_bf16 v[178:181], v[76:79], v[32:35], v[0:3]
	v_mfma_f32_16x16x32_bf16 v[186:189], v[140:143], v[32:35], v[0:3]
	v_mfma_f32_16x16x32_bf16 v[194:197], v[152:155], v[32:35], v[0:3]
	v_mfma_f32_16x16x32_bf16 v[30:33], v[160:163], v[32:35], v[0:3]
	v_mfma_f32_16x16x32_bf16 v[178:181], v[136:139], v[36:39], v[178:181]
	v_mfma_f32_16x16x32_bf16 v[186:189], v[144:147], v[36:39], v[186:189]
	v_mfma_f32_16x16x32_bf16 v[194:197], v[156:159], v[36:39], v[194:197]
	v_mfma_f32_16x16x32_bf16 v[30:33], v[164:167], v[36:39], v[30:33]
	v_mfma_f32_16x16x32_bf16 v[34:37], v[160:163], v[40:43], v[0:3]
	v_mfma_f32_16x16x32_bf16 v[182:185], v[76:79], v[40:43], v[0:3]
	v_mfma_f32_16x16x32_bf16 v[190:193], v[140:143], v[40:43], v[0:3]
	v_mfma_f32_16x16x32_bf16 v[198:201], v[152:155], v[40:43], v[0:3]
	v_mfma_f32_16x16x32_bf16 v[34:37], v[164:167], v[44:47], v[34:37]
	v_mfma_f32_16x16x32_bf16 v[182:185], v[136:139], v[44:47], v[182:185]
	v_mfma_f32_16x16x32_bf16 v[190:193], v[144:147], v[44:47], v[190:193]
	v_mfma_f32_16x16x32_bf16 v[198:201], v[156:159], v[44:47], v[198:201]
	s_setprio 0
	s_barrier
	v_mov_b32_e32 v148, v4
	v_readfirstlane_b32 s69, v28
	v_lshl_add_u64 v[18:19], v[148:149], 1, s[4:5]
	v_lshl_add_u64 v[18:19], v[18:19], 0, s[50:51]
	s_mov_b32 m0, s69
	v_mov_b32_e32 v148, v6
	global_load_lds_dwordx4 v[18:19], off
	v_readfirstlane_b32 s66, v29
	v_lshl_add_u64 v[18:19], v[148:149], 1, s[4:5]
	v_lshl_add_u64 v[18:19], v[18:19], 0, s[50:51]
	s_mov_b32 m0, s66
	s_nop 0
	global_load_lds_dwordx4 v[18:19], off
	s_waitcnt vmcnt(6)
	s_barrier
	s_setprio 1
	v_mfma_f32_16x16x32_bf16 v[38:41], v[76:79], v[112:115], v[0:3]
	v_mfma_f32_16x16x32_bf16 v[42:45], v[76:79], v[120:123], v[0:3]
	v_mfma_f32_16x16x32_bf16 v[38:41], v[136:139], v[116:119], v[38:41]
	v_mfma_f32_16x16x32_bf16 v[42:45], v[136:139], v[124:127], v[42:45]
	v_mfma_f32_16x16x32_bf16 v[76:79], v[140:143], v[112:115], v[0:3]
	v_mfma_f32_16x16x32_bf16 v[136:139], v[140:143], v[120:123], v[0:3]
	v_mfma_f32_16x16x32_bf16 v[76:79], v[144:147], v[116:119], v[76:79]
	v_mfma_f32_16x16x32_bf16 v[136:139], v[144:147], v[124:127], v[136:139]
	v_mfma_f32_16x16x32_bf16 v[140:143], v[152:155], v[112:115], v[0:3]
	v_mfma_f32_16x16x32_bf16 v[144:147], v[152:155], v[120:123], v[0:3]
	v_mfma_f32_16x16x32_bf16 v[112:115], v[160:163], v[112:115], v[0:3]
	v_mfma_f32_16x16x32_bf16 v[0:3], v[160:163], v[120:123], v[0:3]
	v_mfma_f32_16x16x32_bf16 v[140:143], v[156:159], v[116:119], v[140:143]
	v_mfma_f32_16x16x32_bf16 v[112:115], v[164:167], v[116:119], v[112:115]
	v_mfma_f32_16x16x32_bf16 v[116:119], v[164:167], v[124:127], v[0:3]
	v_mfma_f32_16x16x32_bf16 v[144:147], v[156:159], v[124:127], v[144:147]
	s_setprio 0
	s_nop 2
	v_or_b32_e32 v0, 0x18000, v129
	v_or_b32_e32 v2, 0x18800, v129
	s_barrier
	v_or_b32_e32 v1, 0x18400, v129
	ds_read_b128 v[120:123], v0
	ds_read_b128 v[124:127], v1
	v_or_b32_e32 v3, 0x18c00, v129
	ds_read_b128 v[152:155], v2
	ds_read_b128 v[156:159], v3
	v_mov_b32_e32 v148, v4
	ds_read_b128 v[160:163], v8 offset:32768
	ds_read_b128 v[164:167], v8 offset:33792
	ds_read_b128 v[202:205], v9 offset:34816
	ds_read_b128 v[206:209], v9 offset:35840
	ds_read_b128 v[210:213], v9 offset:36864
	ds_read_b128 v[214:217], v9 offset:37888
	ds_read_b128 v[218:221], v9 offset:38912
	ds_read_b128 v[222:225], v9 offset:39936
	v_readfirstlane_b32 s75, v20
	v_lshl_add_u64 v[18:19], v[148:149], 1, s[0:1]
	v_lshl_add_u64 v[18:19], v[18:19], 0, s[50:51]
	s_mov_b32 m0, s75
	v_mov_b32_e32 v148, v6
	global_load_lds_dwordx4 v[18:19], off
	v_readfirstlane_b32 s68, v21
	v_lshl_add_u64 v[18:19], v[148:149], 1, s[0:1]
	v_lshl_add_u64 v[18:19], v[18:19], 0, s[50:51]
	s_mov_b32 m0, s68
	s_nop 0
	global_load_lds_dwordx4 v[18:19], off
	s_waitcnt lgkmcnt(8)
	s_setprio 1
	s_barrier
	s_waitcnt lgkmcnt(0)
	v_mfma_f32_16x16x32_bf16 v[18:21], v[160:163], v[120:123], v[80:83]
	v_mfma_f32_16x16x32_bf16 v[80:83], v[164:167], v[124:127], v[18:21]
	v_mfma_f32_16x16x32_bf16 v[18:21], v[160:163], v[152:155], v[84:87]
	v_mfma_f32_16x16x32_bf16 v[84:87], v[164:167], v[156:159], v[18:21]
	v_mfma_f32_16x16x32_bf16 v[18:21], v[202:205], v[120:123], v[88:91]
	v_mfma_f32_16x16x32_bf16 v[88:91], v[206:209], v[124:127], v[18:21]
	v_mfma_f32_16x16x32_bf16 v[18:21], v[202:205], v[152:155], v[92:95]
	v_mfma_f32_16x16x32_bf16 v[92:95], v[206:209], v[156:159], v[18:21]
	v_mfma_f32_16x16x32_bf16 v[18:21], v[210:213], v[120:123], v[96:99]
	v_mfma_f32_16x16x32_bf16 v[96:99], v[214:217], v[124:127], v[18:21]
	v_mfma_f32_16x16x32_bf16 v[18:21], v[210:213], v[152:155], v[100:103]
	v_mfma_f32_16x16x32_bf16 v[100:103], v[214:217], v[156:159], v[18:21]
	v_mfma_f32_16x16x32_bf16 v[18:21], v[218:221], v[120:123], v[104:107]
	v_mfma_f32_16x16x32_bf16 v[104:107], v[222:225], v[124:127], v[18:21]
	v_mfma_f32_16x16x32_bf16 v[18:21], v[218:221], v[152:155], v[108:111]
	v_mfma_f32_16x16x32_bf16 v[108:111], v[222:225], v[156:159], v[18:21]
	s_setprio 0
	s_barrier
	s_nop 4
	v_or_b32_e32 v18, 0x1c000, v129
	v_or_b32_e32 v20, 0x1c800, v129
	v_mov_b32_e32 v148, v4
	v_or_b32_e32 v19, 0x1c400, v129
	ds_read_b128 v[226:229], v18
	ds_read_b128 v[230:233], v19
	v_or_b32_e32 v21, 0x1cc00, v129
	ds_read_b128 v[234:237], v20
	ds_read_b128 v[238:241], v21
	v_readfirstlane_b32 s77, v26
	v_lshl_add_u64 v[28:29], v[148:149], 1, s[14:15]
	v_lshl_add_u64 v[28:29], v[28:29], 0, s[54:55]
	s_mov_b32 m0, s77
	v_mov_b32_e32 v148, v6
	global_load_lds_dwordx4 v[28:29], off
	v_readfirstlane_b32 s71, v27
	v_lshl_add_u64 v[28:29], v[148:149], 1, s[14:15]
	v_lshl_add_u64 v[28:29], v[28:29], 0, s[54:55]
	s_mov_b32 m0, s71
	s_nop 0
	global_load_lds_dwordx4 v[28:29], off
	s_setprio 1
	s_barrier
; #define LDA(dst, b, h)                                                                                    \
;   _Pragma("unroll") for (int m = 0; m < 4; ++m) _Pragma("unroll") for (int k = 0; k < 2; ++k)             \
;       dst[m][k] = *reinterpret_cast<const bf16x8*>((char*)SA(b, h) + lds_byte(wr * 64 + m * 16 + fr, k * 32 + fq * 8))
; #define LDB(dst, b, h)                                                                                    \
;   _Pragma("unroll") for (int n = 0; n < 2; ++n) _Pragma("unroll") for (int k = 0; k < 2; ++k)             \
;       dst[n][k] = *reinterpret_cast<const bf16x8*>((char*)SB(b, h) + lds_byte(wc * 32 + n * 16 + fr, k * 32 + fq * 8))
; #define WAIT_V(n) asm volatile("s_waitcnt vmcnt(" #n ")" ::: "memory")
; #define WAIT_L(n) asm volatile("s_waitcnt lgkmcnt(" #n ")" ::: "memory")
; #define BAR __builtin_amdgcn_s_barrier()
; #define SCHED __builtin_amdgcn_sched_barrier(0)
; template <int EPI> ...
;     ...
;     LDB(B0, 0, 0); SCHED; LDA(At, 0, 0); STAGE(SA(1, 1), A, brow + HALF, t + 1);
;     WAIT_L(8); BAR; WAIT_L(0); MMA(0, 0, At, B0); BAR; SCHED;
;     LDB(B1, 0, 1); STAGE(SB(0, 0), Bt, bcol, t + 2);
;     BAR; WAIT_L(0); MMA(0, 1, At, B1); BAR;
;     LDA(At, 0, 1); STAGE(SA(0, 0), A, brow, t + 2);
;     BAR; WAIT_L(0); MMA(1, 0, At, B0); BAR; SCHED;
;     STAGE(SB(0, 1), Bt, bcol + HALF, t + 2);
;     WAIT_V(6); BAR; MMA(1, 1, At, B1); BAR;
;     LDB(B0, 1, 0); SCHED; LDA(At, 1, 0); STAGE(SA(0, 1), A, brow + HALF, t + 2);
;     WAIT_L(8); BAR; WAIT_L(0); MMA(0, 0, At, B0); BAR; SCHED;
;     LDB(B1, 1, 1); STAGE(SB(1, 0), Bt, bcol, t + 3);
;     BAR; WAIT_L(0); MMA(0, 1, At, B1); BAR;
;     LDA(At, 1, 1); STAGE(SA(1, 0), A, brow, t + 3);
;     BAR; WAIT_L(0); MMA(1, 0, At, B0); BAR; SCHED;
;     STAGE(SB(1, 1), Bt, bcol + HALF, t + 3);
;     WAIT_V(6); BAR; MMA(1, 1, At, B1); BAR;
	s_waitcnt lgkmcnt(0)
	v_mfma_f32_16x16x32_bf16 v[26:29], v[160:163], v[226:229], v[132:135]
	v_mfma_f32_16x16x32_bf16 v[46:49], v[160:163], v[234:237], v[48:51]
	v_mfma_f32_16x16x32_bf16 v[50:53], v[202:205], v[226:229], v[52:55]
	v_mfma_f32_16x16x32_bf16 v[54:57], v[202:205], v[234:237], v[56:59]
	v_mfma_f32_16x16x32_bf16 v[58:61], v[210:213], v[226:229], v[60:63]
	v_mfma_f32_16x16x32_bf16 v[62:65], v[210:213], v[234:237], v[64:67]
	v_mfma_f32_16x16x32_bf16 v[66:69], v[218:221], v[226:229], v[68:71]
	v_mfma_f32_16x16x32_bf16 v[70:73], v[218:221], v[234:237], v[72:75]
	v_mfma_f32_16x16x32_bf16 v[26:29], v[164:167], v[230:233], v[26:29]
	v_mfma_f32_16x16x32_bf16 v[46:49], v[164:167], v[238:241], v[46:49]
	v_mfma_f32_16x16x32_bf16 v[50:53], v[206:209], v[230:233], v[50:53]
	v_mfma_f32_16x16x32_bf16 v[54:57], v[206:209], v[238:241], v[54:57]
	v_mfma_f32_16x16x32_bf16 v[58:61], v[214:217], v[230:233], v[58:61]
	v_mfma_f32_16x16x32_bf16 v[62:65], v[214:217], v[238:241], v[62:65]
	v_mfma_f32_16x16x32_bf16 v[66:69], v[222:225], v[230:233], v[66:69]
	v_mfma_f32_16x16x32_bf16 v[70:73], v[222:225], v[238:241], v[70:73]
	s_setprio 0
	v_mov_b32_e32 v148, v4
	s_barrier
	ds_read_b128 v[132:135], v8 offset:49152
	ds_read_b128 v[160:163], v8 offset:50176
	ds_read_b128 v[164:167], v9 offset:51200
	ds_read_b128 v[202:205], v9 offset:52224
	ds_read_b128 v[206:209], v9 offset:53248
	ds_read_b128 v[210:213], v9 offset:54272
	ds_read_b128 v[214:217], v9 offset:55296
	ds_read_b128 v[218:221], v9 offset:56320
	v_readfirstlane_b32 s78, v24
	v_lshl_add_u64 v[74:75], v[148:149], 1, s[12:13]
	v_lshl_add_u64 v[74:75], v[74:75], 0, s[54:55]
	s_mov_b32 m0, s78
	v_mov_b32_e32 v148, v6
	global_load_lds_dwordx4 v[74:75], off
	v_readfirstlane_b32 s72, v25
	v_lshl_add_u64 v[74:75], v[148:149], 1, s[12:13]
	v_lshl_add_u64 v[74:75], v[74:75], 0, s[54:55]
	s_mov_b32 m0, s72
	s_nop 0
	global_load_lds_dwordx4 v[74:75], off
	s_setprio 1
	s_barrier
	s_waitcnt lgkmcnt(0)
	v_mfma_f32_16x16x32_bf16 v[30:33], v[214:217], v[120:123], v[30:33]
	v_mfma_f32_16x16x32_bf16 v[34:37], v[214:217], v[152:155], v[34:37]
	v_mfma_f32_16x16x32_bf16 v[178:181], v[132:135], v[120:123], v[178:181]
	v_mfma_f32_16x16x32_bf16 v[182:185], v[132:135], v[152:155], v[182:185]
	v_mfma_f32_16x16x32_bf16 v[186:189], v[164:167], v[120:123], v[186:189]
	v_mfma_f32_16x16x32_bf16 v[190:193], v[164:167], v[152:155], v[190:193]
	v_mfma_f32_16x16x32_bf16 v[194:197], v[206:209], v[120:123], v[194:197]
	v_mfma_f32_16x16x32_bf16 v[198:201], v[206:209], v[152:155], v[198:201]
	v_mfma_f32_16x16x32_bf16 v[30:33], v[218:221], v[124:127], v[30:33]
	v_mfma_f32_16x16x32_bf16 v[34:37], v[218:221], v[156:159], v[34:37]
	v_mfma_f32_16x16x32_bf16 v[178:181], v[160:163], v[124:127], v[178:181]
	v_mfma_f32_16x16x32_bf16 v[182:185], v[160:163], v[156:159], v[182:185]
	v_mfma_f32_16x16x32_bf16 v[186:189], v[202:205], v[124:127], v[186:189]
	v_mfma_f32_16x16x32_bf16 v[190:193], v[202:205], v[156:159], v[190:193]
	v_mfma_f32_16x16x32_bf16 v[194:197], v[210:213], v[124:127], v[194:197]
	v_mfma_f32_16x16x32_bf16 v[198:201], v[210:213], v[156:159], v[198:201]
	s_setprio 0
	s_barrier
	v_mov_b32_e32 v148, v4
	v_readfirstlane_b32 s76, v22
	v_lshl_add_u64 v[24:25], v[148:149], 1, s[4:5]
	v_lshl_add_u64 v[24:25], v[24:25], 0, s[54:55]
	s_mov_b32 m0, s76
	v_mov_b32_e32 v148, v6
	global_load_lds_dwordx4 v[24:25], off
	v_readfirstlane_b32 s74, v23
	v_lshl_add_u64 v[24:25], v[148:149], 1, s[4:5]
	v_lshl_add_u64 v[24:25], v[24:25], 0, s[54:55]
	s_mov_b32 m0, s74
	s_nop 0
	global_load_lds_dwordx4 v[24:25], off
	s_waitcnt vmcnt(6)
	s_barrier
	s_setprio 1
	v_mfma_f32_16x16x32_bf16 v[22:25], v[132:135], v[226:229], v[38:41]
	v_mfma_f32_16x16x32_bf16 v[38:41], v[132:135], v[234:237], v[42:45]
	v_mfma_f32_16x16x32_bf16 v[42:45], v[164:167], v[226:229], v[76:79]
	v_mfma_f32_16x16x32_bf16 v[74:77], v[164:167], v[234:237], v[136:139]
	v_mfma_f32_16x16x32_bf16 v[120:123], v[206:209], v[226:229], v[140:143]
	v_mfma_f32_16x16x32_bf16 v[124:127], v[206:209], v[234:237], v[144:147]
	v_mfma_f32_16x16x32_bf16 v[112:115], v[214:217], v[226:229], v[112:115]
	v_mfma_f32_16x16x32_bf16 v[116:119], v[214:217], v[234:237], v[116:119]
	v_mfma_f32_16x16x32_bf16 v[22:25], v[160:163], v[230:233], v[22:25]
	v_mfma_f32_16x16x32_bf16 v[38:41], v[160:163], v[238:241], v[38:41]
	v_mfma_f32_16x16x32_bf16 v[42:45], v[202:205], v[230:233], v[42:45]
	v_mfma_f32_16x16x32_bf16 v[74:77], v[202:205], v[238:241], v[74:77]
	v_mfma_f32_16x16x32_bf16 v[120:123], v[210:213], v[230:233], v[120:123]
	v_mfma_f32_16x16x32_bf16 v[124:127], v[210:213], v[238:241], v[124:127]
	v_mfma_f32_16x16x32_bf16 v[112:115], v[218:221], v[230:233], v[112:115]
	v_mfma_f32_16x16x32_bf16 v[116:119], v[218:221], v[238:241], v[116:119]
	s_setprio 0
	s_barrier
	ds_read_b128 v[132:135], v5
	ds_read_b128 v[136:139], v7
	ds_read_b128 v[140:143], v10
	ds_read_b128 v[144:147], v11
	v_mov_b32_e32 v148, v4
	ds_read_b128 v[152:155], v8
	ds_read_b128 v[156:159], v8 offset:1024
	ds_read_b128 v[160:163], v9 offset:2048
	ds_read_b128 v[164:167], v9 offset:3072
	ds_read_b128 v[202:205], v9 offset:4096
	ds_read_b128 v[206:209], v9 offset:5120
	ds_read_b128 v[210:213], v9 offset:6144
	ds_read_b128 v[214:217], v9 offset:7168
	s_mov_b32 m0, s67
	v_lshl_add_u64 v[78:79], v[148:149], 1, s[0:1]
	v_lshl_add_u64 v[78:79], v[78:79], 0, s[54:55]
	v_mov_b32_e32 v148, v6
	global_load_lds_dwordx4 v[78:79], off
	s_mov_b32 m0, s44
	v_lshl_add_u64 v[78:79], v[148:149], 1, s[0:1]
	v_lshl_add_u64 v[78:79], v[78:79], 0, s[54:55]
	global_load_lds_dwordx4 v[78:79], off
	s_waitcnt lgkmcnt(8)
	s_setprio 1
	s_barrier
; #define LDA(dst, b, h)                                                                                    \
;   _Pragma("unroll") for (int m = 0; m < 4; ++m) _Pragma("unroll") for (int k = 0; k < 2; ++k)             \
;       dst[m][k] = *reinterpret_cast<const bf16x8*>((char*)SA(b, h) + lds_byte(wr * 64 + m * 16 + fr, k * 32 + fq * 8))
; #define LDB(dst, b, h)                                                                                    \
;   _Pragma("unroll") for (int n = 0; n < 2; ++n) _Pragma("unroll") for (int k = 0; k < 2; ++k)             \
;       dst[n][k] = *reinterpret_cast<const bf16x8*>((char*)SB(b, h) + lds_byte(wc * 32 + n * 16 + fr, k * 32 + fq * 8))
; #define WAIT_V(n) asm volatile("s_waitcnt vmcnt(" #n ")" ::: "memory")
; #define WAIT_L(n) asm volatile("s_waitcnt lgkmcnt(" #n ")" ::: "memory")
; #define BAR __builtin_amdgcn_s_barrier()
; #define SCHED __builtin_amdgcn_sched_barrier(0)
; template <int EPI> ...
;     ...
;     WAIT_L(8); BAR; WAIT_L(0); MMA(0, 0, At, B0); BAR; SCHED;
;     LDB(B1, 0, 1); STAGE(SB(0, 0), Bt, bcol, t + 2);
;     BAR; WAIT_L(0); MMA(0, 1, At, B1); BAR;
;     LDA(At, 0, 1); STAGE(SA(0, 0), A, brow, t + 2);
;     BAR; WAIT_L(0); MMA(1, 0, At, B0); BAR; SCHED;
;     STAGE(SB(0, 1), Bt, bcol + HALF, t + 2);
;     WAIT_V(6); BAR; MMA(1, 1, At, B1); BAR;
	s_waitcnt lgkmcnt(0)
	v_mfma_f32_16x16x32_bf16 v[78:81], v[152:155], v[132:135], v[80:83]
	v_mfma_f32_16x16x32_bf16 v[82:85], v[152:155], v[140:143], v[84:87]
	v_mfma_f32_16x16x32_bf16 v[86:89], v[160:163], v[132:135], v[88:91]
	v_mfma_f32_16x16x32_bf16 v[90:93], v[160:163], v[140:143], v[92:95]
	v_mfma_f32_16x16x32_bf16 v[94:97], v[202:205], v[132:135], v[96:99]
	v_mfma_f32_16x16x32_bf16 v[98:101], v[202:205], v[140:143], v[100:103]
	v_mfma_f32_16x16x32_bf16 v[102:105], v[210:213], v[132:135], v[104:107]
	v_mfma_f32_16x16x32_bf16 v[106:109], v[210:213], v[140:143], v[108:111]
	v_mfma_f32_16x16x32_bf16 v[78:81], v[156:159], v[136:139], v[78:81]
	v_mfma_f32_16x16x32_bf16 v[82:85], v[156:159], v[144:147], v[82:85]
	v_mfma_f32_16x16x32_bf16 v[86:89], v[164:167], v[136:139], v[86:89]
	v_mfma_f32_16x16x32_bf16 v[90:93], v[164:167], v[144:147], v[90:93]
	v_mfma_f32_16x16x32_bf16 v[94:97], v[206:209], v[136:139], v[94:97]
	v_mfma_f32_16x16x32_bf16 v[98:101], v[206:209], v[144:147], v[98:101]
	v_mfma_f32_16x16x32_bf16 v[102:105], v[214:217], v[136:139], v[102:105]
	v_mfma_f32_16x16x32_bf16 v[106:109], v[214:217], v[144:147], v[106:109]
	s_setprio 0
	s_barrier
	v_mov_b32_e32 v148, v4
	ds_read_b128 v[218:221], v14
	ds_read_b128 v[222:225], v15
	ds_read_b128 v[226:229], v16
	ds_read_b128 v[230:233], v17
	s_mov_b64 s[80:81], 0x200
	v_lshl_add_u64 v[110:111], v[148:149], 1, s[14:15]
	s_mov_b32 m0, s70
	v_lshl_add_u64 v[110:111], v[110:111], 0, s[80:81]
	v_mov_b32_e32 v148, v6
	global_load_lds_dwordx4 v[110:111], off
	s_mov_b32 m0, s64
	v_lshl_add_u64 v[110:111], v[148:149], 1, s[14:15]
	v_lshl_add_u64 v[110:111], v[110:111], 0, s[80:81]
	global_load_lds_dwordx4 v[110:111], off
	s_setprio 1
	s_barrier
	s_waitcnt lgkmcnt(0)
	v_mfma_f32_16x16x32_bf16 v[26:29], v[152:155], v[218:221], v[26:29]
	v_mfma_f32_16x16x32_bf16 v[46:49], v[152:155], v[226:229], v[46:49]
	v_mfma_f32_16x16x32_bf16 v[50:53], v[160:163], v[218:221], v[50:53]
	v_mfma_f32_16x16x32_bf16 v[54:57], v[160:163], v[226:229], v[54:57]
	v_mfma_f32_16x16x32_bf16 v[58:61], v[202:205], v[218:221], v[58:61]
	v_mfma_f32_16x16x32_bf16 v[62:65], v[202:205], v[226:229], v[62:65]
	v_mfma_f32_16x16x32_bf16 v[66:69], v[210:213], v[218:221], v[66:69]
	v_mfma_f32_16x16x32_bf16 v[70:73], v[210:213], v[226:229], v[70:73]
	v_mfma_f32_16x16x32_bf16 v[26:29], v[156:159], v[222:225], v[26:29]
	v_mfma_f32_16x16x32_bf16 v[46:49], v[156:159], v[230:233], v[46:49]
	v_mfma_f32_16x16x32_bf16 v[50:53], v[164:167], v[222:225], v[50:53]
	v_mfma_f32_16x16x32_bf16 v[54:57], v[164:167], v[230:233], v[54:57]
	v_mfma_f32_16x16x32_bf16 v[58:61], v[206:209], v[222:225], v[58:61]
	v_mfma_f32_16x16x32_bf16 v[62:65], v[206:209], v[230:233], v[62:65]
	v_mfma_f32_16x16x32_bf16 v[66:69], v[214:217], v[222:225], v[66:69]
	v_mfma_f32_16x16x32_bf16 v[70:73], v[214:217], v[230:233], v[70:73]
	s_setprio 0
	v_mov_b32_e32 v148, v4
	s_barrier
	ds_read_b128 v[152:155], v8 offset:16384
	ds_read_b128 v[156:159], v8 offset:17408
	ds_read_b128 v[160:163], v9 offset:18432
	ds_read_b128 v[164:167], v9 offset:19456
	ds_read_b128 v[202:205], v9 offset:20480
	ds_read_b128 v[206:209], v9 offset:21504
	ds_read_b128 v[210:213], v9 offset:22528
	ds_read_b128 v[214:217], v9 offset:23552
	s_mov_b32 m0, s73
	v_lshl_add_u64 v[110:111], v[148:149], 1, s[12:13]
	v_lshl_add_u64 v[110:111], v[110:111], 0, s[80:81]
	v_mov_b32_e32 v148, v6
	global_load_lds_dwordx4 v[110:111], off
	s_mov_b32 m0, s65
	v_lshl_add_u64 v[110:111], v[148:149], 1, s[12:13]
	v_lshl_add_u64 v[110:111], v[110:111], 0, s[80:81]
	global_load_lds_dwordx4 v[110:111], off
	s_setprio 1
	s_barrier
	s_waitcnt lgkmcnt(0)
	v_mfma_f32_16x16x32_bf16 v[30:33], v[210:213], v[132:135], v[30:33]
	v_mfma_f32_16x16x32_bf16 v[34:37], v[210:213], v[140:143], v[34:37]
	v_mfma_f32_16x16x32_bf16 v[178:181], v[152:155], v[132:135], v[178:181]
	v_mfma_f32_16x16x32_bf16 v[182:185], v[152:155], v[140:143], v[182:185]
	v_mfma_f32_16x16x32_bf16 v[186:189], v[160:163], v[132:135], v[186:189]
	v_mfma_f32_16x16x32_bf16 v[190:193], v[160:163], v[140:143], v[190:193]
	v_mfma_f32_16x16x32_bf16 v[194:197], v[202:205], v[132:135], v[194:197]
	v_mfma_f32_16x16x32_bf16 v[198:201], v[202:205], v[140:143], v[198:201]
	v_mfma_f32_16x16x32_bf16 v[30:33], v[214:217], v[136:139], v[30:33]
	v_mfma_f32_16x16x32_bf16 v[34:37], v[214:217], v[144:147], v[34:37]
	v_mfma_f32_16x16x32_bf16 v[178:181], v[156:159], v[136:139], v[178:181]
	v_mfma_f32_16x16x32_bf16 v[182:185], v[156:159], v[144:147], v[182:185]
	v_mfma_f32_16x16x32_bf16 v[186:189], v[164:167], v[136:139], v[186:189]
	v_mfma_f32_16x16x32_bf16 v[190:193], v[164:167], v[144:147], v[190:193]
	v_mfma_f32_16x16x32_bf16 v[194:197], v[206:209], v[136:139], v[194:197]
	v_mfma_f32_16x16x32_bf16 v[198:201], v[206:209], v[144:147], v[198:201]
	s_setprio 0
	s_barrier
	v_mov_b32_e32 v148, v4
	s_mov_b32 m0, s69
	v_lshl_add_u64 v[110:111], v[148:149], 1, s[4:5]
	v_lshl_add_u64 v[110:111], v[110:111], 0, s[80:81]
	v_mov_b32_e32 v148, v6
	global_load_lds_dwordx4 v[110:111], off
	s_mov_b32 m0, s66
	v_lshl_add_u64 v[110:111], v[148:149], 1, s[4:5]
	v_lshl_add_u64 v[110:111], v[110:111], 0, s[80:81]
	global_load_lds_dwordx4 v[110:111], off
	s_waitcnt vmcnt(6)
	s_barrier
; #define LDA(dst, b, h)                                                                                    \
;   _Pragma("unroll") for (int m = 0; m < 4; ++m) _Pragma("unroll") for (int k = 0; k < 2; ++k)             \
;       dst[m][k] = *reinterpret_cast<const bf16x8*>((char*)SA(b, h) + lds_byte(wr * 64 + m * 16 + fr, k * 32 + fq * 8))
; #define LDB(dst, b, h)                                                                                    \
;   _Pragma("unroll") for (int n = 0; n < 2; ++n) _Pragma("unroll") for (int k = 0; k < 2; ++k)             \
;       dst[n][k] = *reinterpret_cast<const bf16x8*>((char*)SB(b, h) + lds_byte(wc * 32 + n * 16 + fr, k * 32 + fq * 8))
; #define WAIT_V(n) asm volatile("s_waitcnt vmcnt(" #n ")" ::: "memory")
; #define WAIT_L(n) asm volatile("s_waitcnt lgkmcnt(" #n ")" ::: "memory")
; #define BAR __builtin_amdgcn_s_barrier()
; #define SCHED __builtin_amdgcn_sched_barrier(0)
; template <int EPI> ...
;     ...
;     WAIT_V(6); BAR; MMA(1, 1, At, B1); BAR;
;     LDB(B0, 1, 0); SCHED; LDA(At, 1, 0); STAGE(SA(0, 1), A, brow + HALF, t + 2);
;     WAIT_L(8); BAR; WAIT_L(0); MMA(0, 0, At, B0); BAR; SCHED;
;     LDB(B1, 1, 1); STAGE(SB(1, 0), Bt, bcol, t + 3);
;     BAR; WAIT_L(0); MMA(0, 1, At, B1); BAR;
;     LDA(At, 1, 1); STAGE(SA(1, 0), A, brow, t + 3);
	s_setprio 1
	v_mfma_f32_16x16x32_bf16 v[22:25], v[152:155], v[218:221], v[22:25]
	v_mfma_f32_16x16x32_bf16 v[38:41], v[152:155], v[226:229], v[38:41]
	v_mfma_f32_16x16x32_bf16 v[42:45], v[160:163], v[218:221], v[42:45]
	v_mfma_f32_16x16x32_bf16 v[74:77], v[160:163], v[226:229], v[74:77]
	v_mfma_f32_16x16x32_bf16 v[120:123], v[202:205], v[218:221], v[120:123]
	v_mfma_f32_16x16x32_bf16 v[124:127], v[202:205], v[226:229], v[124:127]
	v_mfma_f32_16x16x32_bf16 v[110:113], v[210:213], v[218:221], v[112:115]
	v_mfma_f32_16x16x32_bf16 v[114:117], v[210:213], v[226:229], v[116:119]
	v_mfma_f32_16x16x32_bf16 v[22:25], v[156:159], v[222:225], v[22:25]
	v_mfma_f32_16x16x32_bf16 v[38:41], v[156:159], v[230:233], v[38:41]
	v_mfma_f32_16x16x32_bf16 v[42:45], v[164:167], v[222:225], v[42:45]
	v_mfma_f32_16x16x32_bf16 v[74:77], v[164:167], v[230:233], v[74:77]
	v_mfma_f32_16x16x32_bf16 v[120:123], v[206:209], v[222:225], v[120:123]
	v_mfma_f32_16x16x32_bf16 v[124:127], v[206:209], v[230:233], v[124:127]
	v_mfma_f32_16x16x32_bf16 v[110:113], v[214:217], v[222:225], v[110:113]
	v_mfma_f32_16x16x32_bf16 v[114:117], v[214:217], v[230:233], v[114:117]
	s_setprio 0
	s_barrier
	ds_read_b128 v[132:135], v0
	ds_read_b128 v[136:139], v1
	ds_read_b128 v[140:143], v2
	ds_read_b128 v[144:147], v3
	v_mov_b32_e32 v148, v4
	ds_read_b128 v[152:155], v8 offset:32768
	ds_read_b128 v[156:159], v8 offset:33792
	ds_read_b128 v[160:163], v9 offset:34816
	ds_read_b128 v[164:167], v9 offset:35840
	ds_read_b128 v[202:205], v9 offset:36864
	ds_read_b128 v[206:209], v9 offset:37888
	ds_read_b128 v[210:213], v9 offset:38912
	ds_read_b128 v[214:217], v9 offset:39936
	s_mov_b32 m0, s75
	v_lshl_add_u64 v[118:119], v[148:149], 1, s[0:1]
	v_lshl_add_u64 v[118:119], v[118:119], 0, s[80:81]
	v_mov_b32_e32 v148, v6
	global_load_lds_dwordx4 v[118:119], off
	s_mov_b32 m0, s68
	v_lshl_add_u64 v[118:119], v[148:149], 1, s[0:1]
	v_lshl_add_u64 v[118:119], v[118:119], 0, s[80:81]
	global_load_lds_dwordx4 v[118:119], off
	s_waitcnt lgkmcnt(8)
	s_setprio 1
	s_barrier
	s_waitcnt lgkmcnt(0)
	v_mfma_f32_16x16x32_bf16 v[78:81], v[152:155], v[132:135], v[78:81]
	v_mfma_f32_16x16x32_bf16 v[82:85], v[152:155], v[140:143], v[82:85]
	v_mfma_f32_16x16x32_bf16 v[86:89], v[160:163], v[132:135], v[86:89]
	v_mfma_f32_16x16x32_bf16 v[90:93], v[160:163], v[140:143], v[90:93]
	v_mfma_f32_16x16x32_bf16 v[94:97], v[202:205], v[132:135], v[94:97]
	v_mfma_f32_16x16x32_bf16 v[98:101], v[202:205], v[140:143], v[98:101]
	v_mfma_f32_16x16x32_bf16 v[102:105], v[210:213], v[132:135], v[102:105]
	v_mfma_f32_16x16x32_bf16 v[106:109], v[210:213], v[140:143], v[106:109]
	v_mfma_f32_16x16x32_bf16 v[78:81], v[156:159], v[136:139], v[78:81]
	v_mfma_f32_16x16x32_bf16 v[82:85], v[156:159], v[144:147], v[82:85]
	v_mfma_f32_16x16x32_bf16 v[86:89], v[164:167], v[136:139], v[86:89]
	v_mfma_f32_16x16x32_bf16 v[90:93], v[164:167], v[144:147], v[90:93]
	v_mfma_f32_16x16x32_bf16 v[94:97], v[206:209], v[136:139], v[94:97]
	v_mfma_f32_16x16x32_bf16 v[98:101], v[206:209], v[144:147], v[98:101]
	v_mfma_f32_16x16x32_bf16 v[102:105], v[214:217], v[136:139], v[102:105]
	v_mfma_f32_16x16x32_bf16 v[106:109], v[214:217], v[144:147], v[106:109]
	s_setprio 0
	s_barrier
	v_mov_b32_e32 v148, v4
	ds_read_b128 v[218:221], v18
	ds_read_b128 v[222:225], v19
	ds_read_b128 v[226:229], v20
	ds_read_b128 v[230:233], v21
	s_mov_b64 s[64:65], 0x280
	v_lshl_add_u64 v[118:119], v[148:149], 1, s[14:15]
	s_mov_b32 m0, s77
	v_lshl_add_u64 v[118:119], v[118:119], 0, s[64:65]
	v_mov_b32_e32 v148, v6
	global_load_lds_dwordx4 v[118:119], off
	s_mov_b32 m0, s71
	v_lshl_add_u64 v[118:119], v[148:149], 1, s[14:15]
	v_lshl_add_u64 v[118:119], v[118:119], 0, s[64:65]
	global_load_lds_dwordx4 v[118:119], off
	s_setprio 1
	s_barrier
	s_waitcnt lgkmcnt(0)
	v_mfma_f32_16x16x32_bf16 v[26:29], v[152:155], v[218:221], v[26:29]
	v_mfma_f32_16x16x32_bf16 v[46:49], v[152:155], v[226:229], v[46:49]
	v_mfma_f32_16x16x32_bf16 v[50:53], v[160:163], v[218:221], v[50:53]
	v_mfma_f32_16x16x32_bf16 v[54:57], v[160:163], v[226:229], v[54:57]
	v_mfma_f32_16x16x32_bf16 v[58:61], v[202:205], v[218:221], v[58:61]
	v_mfma_f32_16x16x32_bf16 v[62:65], v[202:205], v[226:229], v[62:65]
	v_mfma_f32_16x16x32_bf16 v[66:69], v[210:213], v[218:221], v[66:69]
	v_mfma_f32_16x16x32_bf16 v[70:73], v[210:213], v[226:229], v[70:73]
	v_mfma_f32_16x16x32_bf16 v[26:29], v[156:159], v[222:225], v[26:29]
	v_mfma_f32_16x16x32_bf16 v[46:49], v[156:159], v[230:233], v[46:49]
	v_mfma_f32_16x16x32_bf16 v[50:53], v[164:167], v[222:225], v[50:53]
	v_mfma_f32_16x16x32_bf16 v[54:57], v[164:167], v[230:233], v[54:57]
	v_mfma_f32_16x16x32_bf16 v[58:61], v[206:209], v[222:225], v[58:61]
	v_mfma_f32_16x16x32_bf16 v[62:65], v[206:209], v[230:233], v[62:65]
	v_mfma_f32_16x16x32_bf16 v[66:69], v[214:217], v[222:225], v[66:69]
	v_mfma_f32_16x16x32_bf16 v[70:73], v[214:217], v[230:233], v[70:73]
	s_setprio 0
	v_mov_b32_e32 v148, v4
	s_barrier
	ds_read_b128 v[152:155], v8 offset:49152
	ds_read_b128 v[156:159], v8 offset:50176
	ds_read_b128 v[160:163], v9 offset:51200
	ds_read_b128 v[164:167], v9 offset:52224
	ds_read_b128 v[202:205], v9 offset:53248
	ds_read_b128 v[206:209], v9 offset:54272
	ds_read_b128 v[210:213], v9 offset:55296
	ds_read_b128 v[214:217], v9 offset:56320
	s_mov_b32 m0, s78
	v_lshl_add_u64 v[118:119], v[148:149], 1, s[12:13]
	v_lshl_add_u64 v[118:119], v[118:119], 0, s[64:65]
	v_mov_b32_e32 v148, v6
	global_load_lds_dwordx4 v[118:119], off
	s_mov_b32 m0, s72
	v_lshl_add_u64 v[118:119], v[148:149], 1, s[12:13]
	v_lshl_add_u64 v[118:119], v[118:119], 0, s[64:65]
	global_load_lds_dwordx4 v[118:119], off
	s_setprio 1
	s_barrier
; #define LDA(dst, b, h)                                                                                    \
;   _Pragma("unroll") for (int m = 0; m < 4; ++m) _Pragma("unroll") for (int k = 0; k < 2; ++k)             \
;       dst[m][k] = *reinterpret_cast<const bf16x8*>((char*)SA(b, h) + lds_byte(wr * 64 + m * 16 + fr, k * 32 + fq * 8))
; #define LDB(dst, b, h)                                                                                    \
;   _Pragma("unroll") for (int n = 0; n < 2; ++n) _Pragma("unroll") for (int k = 0; k < 2; ++k)             \
;       dst[n][k] = *reinterpret_cast<const bf16x8*>((char*)SB(b, h) + lds_byte(wc * 32 + n * 16 + fr, k * 32 + fq * 8))
; #define WAIT_V(n) asm volatile("s_waitcnt vmcnt(" #n ")" ::: "memory")
; #define WAIT_L(n) asm volatile("s_waitcnt lgkmcnt(" #n ")" ::: "memory")
; #define BAR __builtin_amdgcn_s_barrier()
; #define SCHED __builtin_amdgcn_sched_barrier(0)
; template <int EPI> ...
;     ...
;     BAR; WAIT_L(0); MMA(1, 0, At, B0); BAR; SCHED;
;     STAGE(SB(1, 1), Bt, bcol + HALF, t + 3);
;     WAIT_V(6); BAR; MMA(1, 1, At, B1); BAR;
;   }
;   {
;     LDB(B0, 0, 0); LDA(At, 0, 0); STAGE(SA(1, 1), A, brow + HALF, nt - 1);
;     BAR; WAIT_L(0); MMA(0, 0, At, B0); BAR;
;     LDB(B1, 0, 1); BAR; WAIT_L(0); MMA(0, 1, At, B1); BAR;
	s_waitcnt lgkmcnt(0)
	v_mfma_f32_16x16x32_bf16 v[30:33], v[210:213], v[132:135], v[30:33]
	v_mfma_f32_16x16x32_bf16 v[34:37], v[210:213], v[140:143], v[34:37]
	v_mfma_f32_16x16x32_bf16 v[178:181], v[152:155], v[132:135], v[178:181]
	v_mfma_f32_16x16x32_bf16 v[182:185], v[152:155], v[140:143], v[182:185]
	v_mfma_f32_16x16x32_bf16 v[186:189], v[160:163], v[132:135], v[186:189]
	v_mfma_f32_16x16x32_bf16 v[190:193], v[160:163], v[140:143], v[190:193]
	v_mfma_f32_16x16x32_bf16 v[194:197], v[202:205], v[132:135], v[194:197]
	v_mfma_f32_16x16x32_bf16 v[198:201], v[202:205], v[140:143], v[198:201]
	v_mfma_f32_16x16x32_bf16 v[30:33], v[214:217], v[136:139], v[30:33]
	v_mfma_f32_16x16x32_bf16 v[34:37], v[214:217], v[144:147], v[34:37]
	v_mfma_f32_16x16x32_bf16 v[178:181], v[156:159], v[136:139], v[178:181]
	v_mfma_f32_16x16x32_bf16 v[182:185], v[156:159], v[144:147], v[182:185]
	v_mfma_f32_16x16x32_bf16 v[186:189], v[164:167], v[136:139], v[186:189]
	v_mfma_f32_16x16x32_bf16 v[190:193], v[164:167], v[144:147], v[190:193]
	v_mfma_f32_16x16x32_bf16 v[194:197], v[206:209], v[136:139], v[194:197]
	v_mfma_f32_16x16x32_bf16 v[198:201], v[206:209], v[144:147], v[198:201]
	s_setprio 0
	s_barrier
	v_mov_b32_e32 v148, v4
	s_mov_b32 m0, s76
	v_lshl_add_u64 v[118:119], v[148:149], 1, s[4:5]
	v_lshl_add_u64 v[118:119], v[118:119], 0, s[64:65]
	v_mov_b32_e32 v148, v6
	global_load_lds_dwordx4 v[118:119], off
	s_mov_b32 m0, s74
	v_lshl_add_u64 v[118:119], v[148:149], 1, s[4:5]
	v_lshl_add_u64 v[118:119], v[118:119], 0, s[64:65]
	global_load_lds_dwordx4 v[118:119], off
	s_waitcnt vmcnt(6)
	s_barrier
	s_setprio 1
	v_mfma_f32_16x16x32_bf16 v[22:25], v[152:155], v[218:221], v[22:25]
	v_mfma_f32_16x16x32_bf16 v[38:41], v[152:155], v[226:229], v[38:41]
	v_mfma_f32_16x16x32_bf16 v[42:45], v[160:163], v[218:221], v[42:45]
	v_mfma_f32_16x16x32_bf16 v[74:77], v[160:163], v[226:229], v[74:77]
	v_mfma_f32_16x16x32_bf16 v[118:121], v[202:205], v[218:221], v[120:123]
	v_mfma_f32_16x16x32_bf16 v[122:125], v[202:205], v[226:229], v[124:127]
	v_mfma_f32_16x16x32_bf16 v[110:113], v[210:213], v[218:221], v[110:113]
	v_mfma_f32_16x16x32_bf16 v[114:117], v[210:213], v[226:229], v[114:117]
	v_mfma_f32_16x16x32_bf16 v[22:25], v[156:159], v[222:225], v[22:25]
	v_mfma_f32_16x16x32_bf16 v[38:41], v[156:159], v[230:233], v[38:41]
	v_mfma_f32_16x16x32_bf16 v[42:45], v[164:167], v[222:225], v[42:45]
	v_mfma_f32_16x16x32_bf16 v[74:77], v[164:167], v[230:233], v[74:77]
	v_mfma_f32_16x16x32_bf16 v[118:121], v[206:209], v[222:225], v[118:121]
	v_mfma_f32_16x16x32_bf16 v[122:125], v[206:209], v[230:233], v[122:125]
	v_mfma_f32_16x16x32_bf16 v[110:113], v[214:217], v[222:225], v[110:113]
	v_mfma_f32_16x16x32_bf16 v[114:117], v[214:217], v[230:233], v[114:117]
	s_setprio 0
	s_barrier
	ds_read_b128 v[132:135], v5
	ds_read_b128 v[136:139], v7
	ds_read_b128 v[140:143], v10
	ds_read_b128 v[144:147], v11
	ds_read_b128 v[152:155], v8
	ds_read_b128 v[156:159], v8 offset:1024
	ds_read_b128 v[160:163], v9 offset:2048
	ds_read_b128 v[164:167], v9 offset:3072
	ds_read_b128 v[202:205], v9 offset:4096
	ds_read_b128 v[206:209], v9 offset:5120
	ds_read_b128 v[210:213], v9 offset:6144
	ds_read_b128 v[214:217], v9 offset:7168
	v_mov_b32_e32 v5, v149
	v_lshl_add_u64 v[4:5], v[4:5], 1, s[0:1]
	v_readfirstlane_b32 s4, v12
	v_lshl_add_u64 v[4:5], v[4:5], 0, s[64:65]
	s_mov_b32 m0, s4
	v_mov_b32_e32 v7, v149
	global_load_lds_dwordx4 v[4:5], off
	s_nop 0
	v_lshl_add_u64 v[4:5], v[6:7], 1, s[0:1]
	v_readfirstlane_b32 s0, v13
	v_lshl_add_u64 v[4:5], v[4:5], 0, s[64:65]
	s_mov_b32 m0, s0
	s_nop 0
	global_load_lds_dwordx4 v[4:5], off
	s_setprio 1
	s_barrier
	s_waitcnt lgkmcnt(0)
	v_mfma_f32_16x16x32_bf16 v[4:7], v[152:155], v[132:135], v[78:81]
	v_mfma_f32_16x16x32_bf16 v[10:13], v[152:155], v[140:143], v[82:85]
	v_mfma_f32_16x16x32_bf16 v[78:81], v[160:163], v[132:135], v[86:89]
	v_mfma_f32_16x16x32_bf16 v[82:85], v[160:163], v[140:143], v[90:93]
	v_mfma_f32_16x16x32_bf16 v[88:91], v[202:205], v[132:135], v[94:97]
	v_mfma_f32_16x16x32_bf16 v[92:95], v[202:205], v[140:143], v[98:101]
	v_mfma_f32_16x16x32_bf16 v[96:99], v[206:209], v[144:147], v[92:95]
	v_mfma_f32_16x16x32_bf16 v[92:95], v[210:213], v[132:135], v[102:105]
	v_mfma_f32_16x16x32_bf16 v[218:221], v[214:217], v[136:139], v[92:95]
	v_mfma_f32_16x16x32_bf16 v[92:95], v[210:213], v[140:143], v[106:109]
	v_mfma_f32_16x16x32_bf16 v[4:7], v[156:159], v[136:139], v[4:7]
	v_mfma_f32_16x16x32_bf16 v[10:13], v[156:159], v[144:147], v[10:13]
	v_mfma_f32_16x16x32_bf16 v[78:81], v[164:167], v[136:139], v[78:81]
	v_mfma_f32_16x16x32_bf16 v[84:87], v[164:167], v[144:147], v[82:85]
	v_mfma_f32_16x16x32_bf16 v[88:91], v[206:209], v[136:139], v[88:91]
	v_mfma_f32_16x16x32_bf16 v[104:107], v[214:217], v[144:147], v[92:95]
	s_setprio 0
	s_barrier
	s_nop 0
	ds_read_b128 v[92:95], v14
	ds_read_b128 v[100:103], v15
	ds_read_b128 v[222:225], v16
	ds_read_b128 v[14:17], v17
	s_setprio 1
	s_barrier
	s_waitcnt lgkmcnt(0)
	v_mfma_f32_16x16x32_bf16 v[62:65], v[202:205], v[222:225], v[62:65]
	v_mfma_f32_16x16x32_bf16 v[26:29], v[152:155], v[92:95], v[26:29]
	v_mfma_f32_16x16x32_bf16 v[46:49], v[152:155], v[222:225], v[46:49]
	v_mfma_f32_16x16x32_bf16 v[50:53], v[160:163], v[92:95], v[50:53]
	v_mfma_f32_16x16x32_bf16 v[54:57], v[160:163], v[222:225], v[54:57]
	v_mfma_f32_16x16x32_bf16 v[58:61], v[202:205], v[92:95], v[58:61]
	v_mfma_f32_16x16x32_bf16 v[152:155], v[206:209], v[14:17], v[62:65]
	v_mfma_f32_16x16x32_bf16 v[62:65], v[210:213], v[92:95], v[66:69]
	v_mfma_f32_16x16x32_bf16 v[26:29], v[156:159], v[100:103], v[26:29]
	v_mfma_f32_16x16x32_bf16 v[46:49], v[156:159], v[14:17], v[46:49]
	v_mfma_f32_16x16x32_bf16 v[50:53], v[164:167], v[100:103], v[50:53]
	v_mfma_f32_16x16x32_bf16 v[54:57], v[164:167], v[14:17], v[54:57]
	v_mfma_f32_16x16x32_bf16 v[58:61], v[206:209], v[100:103], v[58:61]
	v_mfma_f32_16x16x32_bf16 v[156:159], v[214:217], v[100:103], v[62:65]
	v_mfma_f32_16x16x32_bf16 v[62:65], v[210:213], v[222:225], v[70:73]
	v_mfma_f32_16x16x32_bf16 v[160:163], v[214:217], v[14:17], v[62:65]
	s_setprio 0
	s_barrier
; #define LDA(dst, b, h)                                                                                    \
;   _Pragma("unroll") for (int m = 0; m < 4; ++m) _Pragma("unroll") for (int k = 0; k < 2; ++k)             \
;       dst[m][k] = *reinterpret_cast<const bf16x8*>((char*)SA(b, h) + lds_byte(wr * 64 + m * 16 + fr, k * 32 + fq * 8))
; #define LDB(dst, b, h)                                                                                    \
;   _Pragma("unroll") for (int n = 0; n < 2; ++n) _Pragma("unroll") for (int k = 0; k < 2; ++k)             \
;       dst[n][k] = *reinterpret_cast<const bf16x8*>((char*)SB(b, h) + lds_byte(wc * 32 + n * 16 + fr, k * 32 + fq * 8))
; #define WAIT_V(n) asm volatile("s_waitcnt vmcnt(" #n ")" ::: "memory")
; #define WAIT_L(n) asm volatile("s_waitcnt lgkmcnt(" #n ")" ::: "memory")
; #define BAR __builtin_amdgcn_s_barrier()
; template <int EPI> ...
;     ...
;     LDA(At, 0, 1); WAIT_V(4); BAR; WAIT_L(0); MMA(1, 0, At, B0); MMA(1, 1, At, B1); BAR;
;   }
;   {
;     LDB(B0, 1, 0); LDA(At, 1, 0); WAIT_V(2); BAR; WAIT_L(0); MMA(0, 0, At, B0); BAR;
	s_nop 4
	ds_read_b128 v[62:65], v8 offset:16384
	ds_read_b128 v[66:69], v8 offset:17408
	ds_read_b128 v[70:73], v9 offset:18432
	ds_read_b128 v[164:167], v9 offset:19456
	ds_read_b128 v[202:205], v9 offset:20480
	ds_read_b128 v[206:209], v9 offset:21504
	ds_read_b128 v[210:213], v9 offset:22528
	ds_read_b128 v[214:217], v9 offset:23552
	s_waitcnt vmcnt(4)
	s_setprio 1
	s_barrier
	s_waitcnt lgkmcnt(0)
	v_mfma_f32_16x16x32_bf16 v[30:33], v[210:213], v[132:135], v[30:33]
	v_mfma_f32_16x16x32_bf16 v[178:181], v[62:65], v[132:135], v[178:181]
	v_mfma_f32_16x16x32_bf16 v[186:189], v[70:73], v[132:135], v[186:189]
	v_mfma_f32_16x16x32_bf16 v[194:197], v[202:205], v[132:135], v[194:197]
	v_mfma_f32_16x16x32_bf16 v[132:135], v[214:217], v[136:139], v[30:33]
	v_mfma_f32_16x16x32_bf16 v[30:33], v[210:213], v[140:143], v[34:37]
	v_mfma_f32_16x16x32_bf16 v[182:185], v[62:65], v[140:143], v[182:185]
	v_mfma_f32_16x16x32_bf16 v[190:193], v[70:73], v[140:143], v[190:193]
	v_mfma_f32_16x16x32_bf16 v[198:201], v[202:205], v[140:143], v[198:201]
	v_mfma_f32_16x16x32_bf16 v[32:35], v[214:217], v[144:147], v[30:33]
	v_mfma_f32_16x16x32_bf16 v[178:181], v[66:69], v[136:139], v[178:181]
	v_mfma_f32_16x16x32_bf16 v[182:185], v[66:69], v[144:147], v[182:185]
	v_mfma_f32_16x16x32_bf16 v[186:189], v[164:167], v[136:139], v[186:189]
	v_mfma_f32_16x16x32_bf16 v[190:193], v[164:167], v[144:147], v[190:193]
	v_mfma_f32_16x16x32_bf16 v[194:197], v[206:209], v[136:139], v[194:197]
	v_mfma_f32_16x16x32_bf16 v[198:201], v[206:209], v[144:147], v[198:201]
	s_setprio 0
	s_setprio 1
	v_mfma_f32_16x16x32_bf16 v[22:25], v[62:65], v[92:95], v[22:25]
	v_mfma_f32_16x16x32_bf16 v[136:139], v[66:69], v[100:103], v[22:25]
	v_mfma_f32_16x16x32_bf16 v[22:25], v[62:65], v[222:225], v[38:41]
	v_mfma_f32_16x16x32_bf16 v[36:39], v[66:69], v[14:17], v[22:25]
	v_mfma_f32_16x16x32_bf16 v[22:25], v[70:73], v[92:95], v[42:45]
	v_mfma_f32_16x16x32_bf16 v[40:43], v[164:167], v[100:103], v[22:25]
	v_mfma_f32_16x16x32_bf16 v[22:25], v[70:73], v[222:225], v[74:77]
	v_mfma_f32_16x16x32_bf16 v[140:143], v[164:167], v[14:17], v[22:25]
	v_mfma_f32_16x16x32_bf16 v[22:25], v[202:205], v[92:95], v[118:121]
	v_mfma_f32_16x16x32_bf16 v[144:147], v[206:209], v[100:103], v[22:25]
	v_mfma_f32_16x16x32_bf16 v[22:25], v[202:205], v[222:225], v[122:125]
	v_mfma_f32_16x16x32_bf16 v[164:167], v[206:209], v[14:17], v[22:25]
	v_mfma_f32_16x16x32_bf16 v[22:25], v[210:213], v[92:95], v[110:113]
	v_mfma_f32_16x16x32_bf16 v[202:205], v[214:217], v[100:103], v[22:25]
	v_mfma_f32_16x16x32_bf16 v[22:25], v[210:213], v[222:225], v[114:117]
	v_mfma_f32_16x16x32_bf16 v[206:209], v[214:217], v[14:17], v[22:25]
	s_setprio 0
	s_barrier
	ds_read_b128 v[210:213], v0
	ds_read_b128 v[214:217], v1
	ds_read_b128 v[222:225], v2
	ds_read_b128 v[226:229], v3
	ds_read_b128 v[0:3], v8 offset:32768
	ds_read_b128 v[14:17], v8 offset:33792
	ds_read_b128 v[22:25], v9 offset:34816
	ds_read_b128 v[108:111], v9 offset:35840
	ds_read_b128 v[230:233], v9 offset:36864
	ds_read_b128 v[234:237], v9 offset:37888
	ds_read_b128 v[238:241], v9 offset:38912
	ds_read_b128 v[242:245], v9 offset:39936
	s_waitcnt vmcnt(2)
	s_setprio 1
	s_barrier
	s_waitcnt lgkmcnt(0)
	v_mfma_f32_16x16x32_bf16 v[4:7], v[0:3], v[210:213], v[4:7]
	v_mfma_f32_16x16x32_bf16 v[92:95], v[14:17], v[214:217], v[4:7]
	v_mfma_f32_16x16x32_bf16 v[4:7], v[0:3], v[222:225], v[10:13]
	v_mfma_f32_16x16x32_bf16 v[100:103], v[14:17], v[226:229], v[4:7]
	v_mfma_f32_16x16x32_bf16 v[4:7], v[22:25], v[210:213], v[78:81]
	v_mfma_f32_16x16x32_bf16 v[80:83], v[108:111], v[214:217], v[4:7]
	v_mfma_f32_16x16x32_bf16 v[4:7], v[22:25], v[222:225], v[84:87]
	v_mfma_f32_16x16x32_bf16 v[84:87], v[108:111], v[226:229], v[4:7]
	v_mfma_f32_16x16x32_bf16 v[4:7], v[230:233], v[210:213], v[88:91]
	v_mfma_f32_16x16x32_bf16 v[72:75], v[234:237], v[214:217], v[4:7]
	v_mfma_f32_16x16x32_bf16 v[4:7], v[230:233], v[222:225], v[96:99]
	v_mfma_f32_16x16x32_bf16 v[76:79], v[234:237], v[226:229], v[4:7]
	v_mfma_f32_16x16x32_bf16 v[4:7], v[238:241], v[210:213], v[218:221]
	v_mfma_f32_16x16x32_bf16 v[64:67], v[242:245], v[214:217], v[4:7]
	v_mfma_f32_16x16x32_bf16 v[4:7], v[238:241], v[222:225], v[104:107]
	v_mfma_f32_16x16x32_bf16 v[68:71], v[242:245], v[226:229], v[4:7]
	s_setprio 0
	s_barrier
; #define LDA(dst, b, h)                                                                                    \
;   _Pragma("unroll") for (int m = 0; m < 4; ++m) _Pragma("unroll") for (int k = 0; k < 2; ++k)             \
;       dst[m][k] = *reinterpret_cast<const bf16x8*>((char*)SA(b, h) + lds_byte(wr * 64 + m * 16 + fr, k * 32 + fq * 8))
; #define LDB(dst, b, h)                                                                                    \
;   _Pragma("unroll") for (int n = 0; n < 2; ++n) _Pragma("unroll") for (int k = 0; k < 2; ++k)             \
;       dst[n][k] = *reinterpret_cast<const bf16x8*>((char*)SB(b, h) + lds_byte(wc * 32 + n * 16 + fr, k * 32 + fq * 8))
; #define WAIT_V(n) asm volatile("s_waitcnt vmcnt(" #n ")" ::: "memory")
; #define WAIT_L(n) asm volatile("s_waitcnt lgkmcnt(" #n ")" ::: "memory")
; #define BAR __builtin_amdgcn_s_barrier()
; template <int EPI> ...
;     ...
;     LDB(B1, 1, 1); WAIT_V(0); BAR; WAIT_L(0); MMA(0, 1, At, B1); BAR;
;     LDA(At, 1, 1); BAR; WAIT_L(0); MMA(1, 0, At, B0); MMA(1, 1, At, B1); BAR;
;   }
;   if (wr == 0) BAR;
	ds_read_b128 v[218:221], v18
	ds_read_b128 v[246:249], v19
	ds_read_b128 v[250:253], v20
	ds_read_b128 v[174:177], v21
	s_waitcnt vmcnt(0)
	s_setprio 1
	s_barrier
	s_waitcnt lgkmcnt(0)
	v_mfma_f32_16x16x32_bf16 v[4:7], v[0:3], v[218:221], v[26:29]
	v_mfma_f32_16x16x32_bf16 v[0:3], v[0:3], v[250:253], v[46:49]
	v_mfma_f32_16x16x32_bf16 v[124:127], v[14:17], v[174:177], v[0:3]
	v_mfma_f32_16x16x32_bf16 v[0:3], v[22:25], v[218:221], v[50:53]
	v_mfma_f32_16x16x32_bf16 v[112:115], v[108:111], v[246:249], v[0:3]
	v_mfma_f32_16x16x32_bf16 v[0:3], v[22:25], v[250:253], v[54:57]
	v_mfma_f32_16x16x32_bf16 v[116:119], v[108:111], v[174:177], v[0:3]
	v_mfma_f32_16x16x32_bf16 v[0:3], v[230:233], v[218:221], v[58:61]
	v_mfma_f32_16x16x32_bf16 v[104:107], v[234:237], v[246:249], v[0:3]
	v_mfma_f32_16x16x32_bf16 v[0:3], v[230:233], v[250:253], v[152:155]
	v_mfma_f32_16x16x32_bf16 v[108:111], v[234:237], v[174:177], v[0:3]
	v_mfma_f32_16x16x32_bf16 v[0:3], v[238:241], v[218:221], v[156:159]
	v_mfma_f32_16x16x32_bf16 v[88:91], v[242:245], v[246:249], v[0:3]
	v_mfma_f32_16x16x32_bf16 v[0:3], v[238:241], v[250:253], v[160:163]
	v_mfma_f32_16x16x32_bf16 v[120:123], v[14:17], v[246:249], v[4:7]
	v_mfma_f32_16x16x32_bf16 v[96:99], v[242:245], v[174:177], v[0:3]
	s_setprio 0
	s_barrier
	ds_read_b128 v[44:47], v8 offset:49152
	ds_read_b128 v[48:51], v8 offset:50176
	ds_read_b128 v[52:55], v9 offset:51200
	ds_read_b128 v[152:155], v9 offset:52224
	ds_read_b128 v[156:159], v9 offset:53248
	ds_read_b128 v[160:163], v9 offset:54272
	ds_read_b128 v[230:233], v9 offset:55296
	ds_read_b128 v[234:237], v9 offset:56320
	s_setprio 1
	s_barrier
	s_waitcnt lgkmcnt(0)
	v_mfma_f32_16x16x32_bf16 v[0:3], v[44:47], v[210:213], v[178:181]
	v_mfma_f32_16x16x32_bf16 v[24:27], v[48:51], v[214:217], v[0:3]
	v_mfma_f32_16x16x32_bf16 v[0:3], v[44:47], v[222:225], v[182:185]
	v_mfma_f32_16x16x32_bf16 v[28:31], v[48:51], v[226:229], v[0:3]
	v_mfma_f32_16x16x32_bf16 v[0:3], v[52:55], v[210:213], v[186:189]
	v_mfma_f32_16x16x32_bf16 v[16:19], v[152:155], v[214:217], v[0:3]
	v_mfma_f32_16x16x32_bf16 v[0:3], v[52:55], v[222:225], v[190:193]
	v_mfma_f32_16x16x32_bf16 v[20:23], v[152:155], v[226:229], v[0:3]
	v_mfma_f32_16x16x32_bf16 v[0:3], v[156:159], v[210:213], v[194:197]
	v_mfma_f32_16x16x32_bf16 v[8:11], v[160:163], v[214:217], v[0:3]
	v_mfma_f32_16x16x32_bf16 v[0:3], v[156:159], v[222:225], v[198:201]
	v_mfma_f32_16x16x32_bf16 v[12:15], v[160:163], v[226:229], v[0:3]
	v_mfma_f32_16x16x32_bf16 v[0:3], v[230:233], v[210:213], v[132:135]
	v_mfma_f32_16x16x32_bf16 v[4:7], v[230:233], v[222:225], v[32:35]
	v_mfma_f32_16x16x32_bf16 v[0:3], v[234:237], v[214:217], v[0:3]
	v_mfma_f32_16x16x32_bf16 v[4:7], v[234:237], v[226:229], v[4:7]
	s_setprio 0
	s_setprio 1
	v_mfma_f32_16x16x32_bf16 v[32:35], v[44:47], v[218:221], v[136:139]
	v_mfma_f32_16x16x32_bf16 v[56:59], v[48:51], v[246:249], v[32:35]
	v_mfma_f32_16x16x32_bf16 v[32:35], v[44:47], v[250:253], v[36:39]
	v_mfma_f32_16x16x32_bf16 v[60:63], v[48:51], v[174:177], v[32:35]
	v_mfma_f32_16x16x32_bf16 v[32:35], v[52:55], v[218:221], v[40:43]
	v_mfma_f32_16x16x32_bf16 v[48:51], v[152:155], v[246:249], v[32:35]
	v_mfma_f32_16x16x32_bf16 v[32:35], v[52:55], v[250:253], v[140:143]
	v_mfma_f32_16x16x32_bf16 v[52:55], v[152:155], v[174:177], v[32:35]
	v_mfma_f32_16x16x32_bf16 v[32:35], v[156:159], v[218:221], v[144:147]
	v_mfma_f32_16x16x32_bf16 v[40:43], v[160:163], v[246:249], v[32:35]
	v_mfma_f32_16x16x32_bf16 v[32:35], v[156:159], v[250:253], v[164:167]
	v_mfma_f32_16x16x32_bf16 v[44:47], v[160:163], v[174:177], v[32:35]
	v_mfma_f32_16x16x32_bf16 v[32:35], v[230:233], v[218:221], v[202:205]
	v_mfma_f32_16x16x32_bf16 v[36:39], v[230:233], v[250:253], v[206:209]
	v_mfma_f32_16x16x32_bf16 v[32:35], v[234:237], v[246:249], v[32:35]
	v_mfma_f32_16x16x32_bf16 v[36:39], v[234:237], v[174:177], v[36:39]
	s_setprio 0
	s_cmpk_gt_u32 s23, 0xff
	s_barrier
	s_cbranch_scc1 .LBB0_706
	s_barrier

; DEVI f32x4 ozero() { float z = 0.f; asm volatile("" : "+v"(z)); return f32x4{z, z, z, z}; }
; #define LDA(dst, b, h)                                                                                    \
;   _Pragma("unroll") for (int m = 0; m < 4; ++m) _Pragma("unroll") for (int k = 0; k < 2; ++k)             \
;       dst[m][k] = *reinterpret_cast<const bf16x8*>((char*)SA(b, h) + lds_byte(wr * 64 + m * 16 + fr, k * 32 + fq * 8))
; #define LDB(dst, b, h)                                                                                    \
;   _Pragma("unroll") for (int n = 0; n < 2; ++n) _Pragma("unroll") for (int k = 0; k < 2; ++k)             \
;       dst[n][k] = *reinterpret_cast<const bf16x8*>((char*)SB(b, h) + lds_byte(wc * 32 + n * 16 + fr, k * 32 + fq * 8))
; #define WAIT_V(n) asm volatile("s_waitcnt vmcnt(" #n ")" ::: "memory")
; #define WAIT_L(n) asm volatile("s_waitcnt lgkmcnt(" #n ")" ::: "memory")
; #define BAR __builtin_amdgcn_s_barrier()
; #define SCHED __builtin_amdgcn_sched_barrier(0)
; template <int EPI> ...
;     ...
;   const int brow = m0, bcol = n0;
;   const int wid = __builtin_amdgcn_readfirstlane(tid >> 6), lane = tid & 63, wr = wid >> 2, wc = wid & 3, fr = lane & 15, fq = lane >> 4;
;   f32x4 acc[2][2][4][2];
;   {
;     const f32x4 zq = ozero();
; #pragma unroll
;     for (int a_ = 0; a_ < 2; ++a_)
; #pragma unroll
;       for (int b_ = 0; b_ < 2; ++b_)
; #pragma unroll
;         for (int m = 0; m < 4; ++m) { acc[a_][b_][m][0] = zq; acc[a_][b_][m][1] = zq; }
;   }
;   bf16x8 At[4][2], B0[2][2], B1[2][2];
;   const int nt = K / BK;
;     ...
;   if (first) {
;     WAIT_V(0);
;     ISSUE_PRO(brow, bcol);
;   }
;   if (wr == 1) BAR;
;   WAIT_V(10); BAR;
;   WAIT_V(6); BAR;
;   for (int t = 0; t < nt - 2; t += 2) {
;     LDB(B0, 0, 0); SCHED; LDA(At, 0, 0); STAGE(SA(1, 1), A, brow + HALF, t + 1);
;     WAIT_L(8); BAR; WAIT_L(0); MMA(0, 0, At, B0); BAR; SCHED;
;     LDB(B1, 0, 1); STAGE(SB(0, 0), Bt, bcol, t + 2);
;     BAR; WAIT_L(0); MMA(0, 1, At, B1); BAR;
;     LDA(At, 0, 1); STAGE(SA(0, 0), A, brow, t + 2);
;     BAR; WAIT_L(0); MMA(1, 0, At, B0); BAR; SCHED;
;     STAGE(SB(0, 1), Bt, bcol + HALF, t + 2);
;     WAIT_V(6); BAR; MMA(1, 1, At, B1); BAR;
.LBB0_909:
	s_ashr_i32 s13, s64, 6
	v_and_b32_e32 v130, 15, v128
	s_and_b32 s15, s13, 3
	v_and_b32_e32 v9, 48, v128
	v_lshlrev_b32_e32 v1, 2, v128
	s_lshl_b32 s65, s15, 12
	v_lshl_or_b32 v8, v130, 6, v9
	v_and_b32_e32 v46, 32, v1
	v_bitop3_b32 v126, s65, v8, v46 bitop3:0xf6
	v_or_b32_e32 v127, 0x10000, v126
	v_or_b32_e32 v131, 0x10800, v126
	s_waitcnt vmcnt(10)
	s_barrier
	s_waitcnt vmcnt(6)
	s_barrier
	v_or_b32_e32 v129, 0x10400, v126
	ds_read_b128 v[22:25], v127
	ds_read_b128 v[26:29], v129
	v_or_b32_e32 v222, 0x10c00, v126
	ds_read_b128 v[30:33], v131
	ds_read_b128 v[34:37], v222
	v_mov_b32_e32 v1, v0
	v_mov_b32_e32 v2, v0
	v_mov_b32_e32 v3, v0
	v_lshlrev_b32_e32 v47, 6, v128
	s_movk_i32 s66, 0x3c0
	s_lshl_b32 s65, s63, 13
	v_and_or_b32 v9, v47, s66, v9
	v_bitop3_b32 v8, s65, v8, v46 bitop3:0xf6
	v_bitop3_b32 v9, s65, v9, v46 bitop3:0xf6
	v_mov_b32_e32 v148, v4
	v_add_u32_e32 v72, 0xc000, v12
	ds_read_b128 v[38:41], v8
	ds_read_b128 v[42:45], v8 offset:1024
	ds_read_b128 v[46:49], v9 offset:2048
	ds_read_b128 v[50:53], v9 offset:3072
	ds_read_b128 v[54:57], v9 offset:4096
	ds_read_b128 v[58:61], v9 offset:5120
	ds_read_b128 v[62:65], v9 offset:6144
	ds_read_b128 v[66:69], v9 offset:7168
	v_readfirstlane_b32 s66, v72
	v_lshl_add_u64 v[70:71], v[148:149], 1, s[2:3]
	v_lshl_add_u64 v[70:71], v[70:71], 0, s[46:47]
	s_mov_b32 m0, s66
	v_mov_b32_e32 v148, v6
	v_add_u32_e32 v72, 0xe000, v12
	global_load_lds_dwordx4 v[70:71], off
	v_readfirstlane_b32 s65, v72
	v_lshl_add_u64 v[70:71], v[148:149], 1, s[2:3]
	v_lshl_add_u64 v[70:71], v[70:71], 0, s[46:47]
	s_mov_b32 m0, s65
	s_nop 0
	global_load_lds_dwordx4 v[70:71], off
	s_waitcnt lgkmcnt(8)
	s_setprio 1
	s_barrier
	s_waitcnt lgkmcnt(0)
	v_mfma_f32_16x16x32_bf16 v[70:73], v[38:41], v[22:25], v[0:3]
	v_mfma_f32_16x16x32_bf16 v[74:77], v[38:41], v[30:33], v[0:3]
	v_mfma_f32_16x16x32_bf16 v[78:81], v[46:49], v[22:25], v[0:3]
	v_mfma_f32_16x16x32_bf16 v[82:85], v[46:49], v[30:33], v[0:3]
	v_mfma_f32_16x16x32_bf16 v[86:89], v[54:57], v[22:25], v[0:3]
	v_mfma_f32_16x16x32_bf16 v[90:93], v[54:57], v[30:33], v[0:3]
	v_mfma_f32_16x16x32_bf16 v[94:97], v[62:65], v[22:25], v[0:3]
	v_mfma_f32_16x16x32_bf16 v[98:101], v[62:65], v[30:33], v[0:3]
	v_mfma_f32_16x16x32_bf16 v[70:73], v[42:45], v[26:29], v[70:73]
	v_mfma_f32_16x16x32_bf16 v[74:77], v[42:45], v[34:37], v[74:77]
	v_mfma_f32_16x16x32_bf16 v[78:81], v[50:53], v[26:29], v[78:81]
	v_mfma_f32_16x16x32_bf16 v[82:85], v[50:53], v[34:37], v[82:85]
	v_mfma_f32_16x16x32_bf16 v[86:89], v[58:61], v[26:29], v[86:89]
	v_mfma_f32_16x16x32_bf16 v[90:93], v[58:61], v[34:37], v[90:93]
	v_mfma_f32_16x16x32_bf16 v[94:97], v[66:69], v[26:29], v[94:97]
	v_mfma_f32_16x16x32_bf16 v[98:101], v[66:69], v[34:37], v[98:101]
	s_setprio 0
	s_barrier
	v_or_b32_e32 v223, 0x14000, v126
	v_or_b32_e32 v225, 0x14800, v126
	v_mov_b32_e32 v148, v4
	v_or_b32_e32 v224, 0x14400, v126
	ds_read_b128 v[102:105], v223
	ds_read_b128 v[106:109], v224
	v_or_b32_e32 v226, 0x14c00, v126
	ds_read_b128 v[110:113], v225
	ds_read_b128 v[114:117], v226
	v_readfirstlane_b32 s67, v20
	v_lshl_add_u64 v[118:119], v[148:149], 1, s[22:23]
	v_lshl_add_u64 v[118:119], v[118:119], 0, s[50:51]
	s_mov_b32 m0, s67
	v_mov_b32_e32 v148, v6
	global_load_lds_dwordx4 v[118:119], off
	v_readfirstlane_b32 s67, v21
	v_lshl_add_u64 v[118:119], v[148:149], 1, s[22:23]
	v_lshl_add_u64 v[118:119], v[118:119], 0, s[50:51]
	s_mov_b32 m0, s67
	s_nop 0
	global_load_lds_dwordx4 v[118:119], off
	s_setprio 1
	s_barrier
	s_waitcnt lgkmcnt(0)
	v_mfma_f32_16x16x32_bf16 v[118:121], v[38:41], v[102:105], v[0:3]
	v_mfma_f32_16x16x32_bf16 v[38:41], v[38:41], v[110:113], v[0:3]
	v_mfma_f32_16x16x32_bf16 v[118:121], v[42:45], v[106:109], v[118:121]
	v_mfma_f32_16x16x32_bf16 v[38:41], v[42:45], v[114:117], v[38:41]
	v_mfma_f32_16x16x32_bf16 v[42:45], v[46:49], v[102:105], v[0:3]
	v_mfma_f32_16x16x32_bf16 v[46:49], v[46:49], v[110:113], v[0:3]
	v_mfma_f32_16x16x32_bf16 v[42:45], v[50:53], v[106:109], v[42:45]
	v_mfma_f32_16x16x32_bf16 v[46:49], v[50:53], v[114:117], v[46:49]
	v_mfma_f32_16x16x32_bf16 v[50:53], v[54:57], v[102:105], v[0:3]
	v_mfma_f32_16x16x32_bf16 v[54:57], v[54:57], v[110:113], v[0:3]
	v_mfma_f32_16x16x32_bf16 v[50:53], v[58:61], v[106:109], v[50:53]
	v_mfma_f32_16x16x32_bf16 v[54:57], v[58:61], v[114:117], v[54:57]
	v_mfma_f32_16x16x32_bf16 v[58:61], v[62:65], v[102:105], v[0:3]
	v_mfma_f32_16x16x32_bf16 v[62:65], v[62:65], v[110:113], v[0:3]
	v_mfma_f32_16x16x32_bf16 v[58:61], v[66:69], v[106:109], v[58:61]
	v_mfma_f32_16x16x32_bf16 v[62:65], v[66:69], v[114:117], v[62:65]
	s_setprio 0
	v_mov_b32_e32 v148, v4
	s_barrier
	ds_read_b128 v[66:69], v8 offset:16384
	ds_read_b128 v[122:125], v8 offset:17408
	ds_read_b128 v[132:135], v9 offset:18432
	ds_read_b128 v[136:139], v9 offset:19456
	ds_read_b128 v[140:143], v9 offset:20480
	ds_read_b128 v[144:147], v9 offset:21504
	ds_read_b128 v[152:155], v9 offset:22528
	ds_read_b128 v[156:159], v9 offset:23552
	v_readfirstlane_b32 s67, v12
	v_lshl_add_u64 v[20:21], v[148:149], 1, s[20:21]
	v_lshl_add_u64 v[20:21], v[20:21], 0, s[50:51]
	s_mov_b32 m0, s67
	v_mov_b32_e32 v148, v6
	global_load_lds_dwordx4 v[20:21], off
	v_readfirstlane_b32 s67, v15
	v_lshl_add_u64 v[20:21], v[148:149], 1, s[20:21]
	v_lshl_add_u64 v[20:21], v[20:21], 0, s[50:51]
	s_mov_b32 m0, s67
	s_nop 0
	global_load_lds_dwordx4 v[20:21], off
	s_setprio 1
	s_barrier
; #define LDA(dst, b, h)                                                                                    \
;   _Pragma("unroll") for (int m = 0; m < 4; ++m) _Pragma("unroll") for (int k = 0; k < 2; ++k)             \
;       dst[m][k] = *reinterpret_cast<const bf16x8*>((char*)SA(b, h) + lds_byte(wr * 64 + m * 16 + fr, k * 32 + fq * 8))
; #define LDB(dst, b, h)                                                                                    \
;   _Pragma("unroll") for (int n = 0; n < 2; ++n) _Pragma("unroll") for (int k = 0; k < 2; ++k)             \
;       dst[n][k] = *reinterpret_cast<const bf16x8*>((char*)SB(b, h) + lds_byte(wc * 32 + n * 16 + fr, k * 32 + fq * 8))
; #define WAIT_V(n) asm volatile("s_waitcnt vmcnt(" #n ")" ::: "memory")
; #define WAIT_L(n) asm volatile("s_waitcnt lgkmcnt(" #n ")" ::: "memory")
; #define BAR __builtin_amdgcn_s_barrier()
; #define SCHED __builtin_amdgcn_sched_barrier(0)
; template <int EPI> ...
;     ...
;     BAR; WAIT_L(0); MMA(1, 0, At, B0); BAR; SCHED;
;     STAGE(SB(0, 1), Bt, bcol + HALF, t + 2);
;     WAIT_V(6); BAR; MMA(1, 1, At, B1); BAR;
;     LDB(B0, 1, 0); SCHED; LDA(At, 1, 0); STAGE(SA(0, 1), A, brow + HALF, t + 2);
;     WAIT_L(8); BAR; WAIT_L(0); MMA(0, 0, At, B0); BAR; SCHED;
;     LDB(B1, 1, 1); STAGE(SB(1, 0), Bt, bcol, t + 3);
	s_waitcnt lgkmcnt(0)
	v_mfma_f32_16x16x32_bf16 v[160:163], v[66:69], v[22:25], v[0:3]
	v_mfma_f32_16x16x32_bf16 v[174:177], v[132:135], v[22:25], v[0:3]
	v_mfma_f32_16x16x32_bf16 v[182:185], v[140:143], v[22:25], v[0:3]
	v_mfma_f32_16x16x32_bf16 v[20:23], v[152:155], v[22:25], v[0:3]
	v_mfma_f32_16x16x32_bf16 v[160:163], v[122:125], v[26:29], v[160:163]
	v_mfma_f32_16x16x32_bf16 v[174:177], v[136:139], v[26:29], v[174:177]
	v_mfma_f32_16x16x32_bf16 v[182:185], v[144:147], v[26:29], v[182:185]
	v_mfma_f32_16x16x32_bf16 v[20:23], v[156:159], v[26:29], v[20:23]
	v_mfma_f32_16x16x32_bf16 v[24:27], v[152:155], v[30:33], v[0:3]
	v_mfma_f32_16x16x32_bf16 v[164:167], v[66:69], v[30:33], v[0:3]
	v_mfma_f32_16x16x32_bf16 v[178:181], v[132:135], v[30:33], v[0:3]
	v_mfma_f32_16x16x32_bf16 v[186:189], v[140:143], v[30:33], v[0:3]
	v_mfma_f32_16x16x32_bf16 v[24:27], v[156:159], v[34:37], v[24:27]
	v_mfma_f32_16x16x32_bf16 v[164:167], v[122:125], v[34:37], v[164:167]
	v_mfma_f32_16x16x32_bf16 v[178:181], v[136:139], v[34:37], v[178:181]
	v_mfma_f32_16x16x32_bf16 v[186:189], v[144:147], v[34:37], v[186:189]
	s_setprio 0
	s_barrier
	v_mov_b32_e32 v148, v4
	v_readfirstlane_b32 s67, v18
	v_lshl_add_u64 v[28:29], v[148:149], 1, s[18:19]
	v_lshl_add_u64 v[28:29], v[28:29], 0, s[50:51]
	s_mov_b32 m0, s67
	v_mov_b32_e32 v148, v6
	global_load_lds_dwordx4 v[28:29], off
	v_readfirstlane_b32 s67, v19
	v_lshl_add_u64 v[28:29], v[148:149], 1, s[18:19]
	v_lshl_add_u64 v[28:29], v[28:29], 0, s[50:51]
	s_mov_b32 m0, s67
	s_nop 0
	global_load_lds_dwordx4 v[28:29], off
	s_waitcnt vmcnt(6)
	s_barrier
	s_setprio 1
	v_mfma_f32_16x16x32_bf16 v[28:31], v[66:69], v[102:105], v[0:3]
	v_mfma_f32_16x16x32_bf16 v[32:35], v[66:69], v[110:113], v[0:3]
	v_mfma_f32_16x16x32_bf16 v[28:31], v[122:125], v[106:109], v[28:31]
	v_mfma_f32_16x16x32_bf16 v[32:35], v[122:125], v[114:117], v[32:35]
	v_mfma_f32_16x16x32_bf16 v[66:69], v[132:135], v[102:105], v[0:3]
	v_mfma_f32_16x16x32_bf16 v[122:125], v[132:135], v[110:113], v[0:3]
	v_mfma_f32_16x16x32_bf16 v[66:69], v[136:139], v[106:109], v[66:69]
	v_mfma_f32_16x16x32_bf16 v[122:125], v[136:139], v[114:117], v[122:125]
	v_mfma_f32_16x16x32_bf16 v[132:135], v[140:143], v[102:105], v[0:3]
	v_mfma_f32_16x16x32_bf16 v[136:139], v[140:143], v[110:113], v[0:3]
	v_mfma_f32_16x16x32_bf16 v[102:105], v[152:155], v[102:105], v[0:3]
	v_mfma_f32_16x16x32_bf16 v[0:3], v[152:155], v[110:113], v[0:3]
	v_mfma_f32_16x16x32_bf16 v[102:105], v[156:159], v[106:109], v[102:105]
	v_mfma_f32_16x16x32_bf16 v[0:3], v[156:159], v[114:117], v[0:3]
	v_mfma_f32_16x16x32_bf16 v[132:135], v[144:147], v[106:109], v[132:135]
	v_mfma_f32_16x16x32_bf16 v[136:139], v[144:147], v[114:117], v[136:139]
	s_setprio 0
	v_or_b32_e32 v227, 0x18000, v126
	v_or_b32_e32 v229, 0x18800, v126
	s_barrier
	v_or_b32_e32 v228, 0x18400, v126
	ds_read_b128 v[106:109], v227
	ds_read_b128 v[110:113], v228
	v_or_b32_e32 v230, 0x18c00, v126
	ds_read_b128 v[114:117], v229
	ds_read_b128 v[140:143], v230
	v_mov_b32_e32 v148, v4
	ds_read_b128 v[144:147], v8 offset:32768
	ds_read_b128 v[152:155], v8 offset:33792
	ds_read_b128 v[156:159], v9 offset:34816
	ds_read_b128 v[190:193], v9 offset:35840
	ds_read_b128 v[194:197], v9 offset:36864
	ds_read_b128 v[198:201], v9 offset:37888
	ds_read_b128 v[202:205], v9 offset:38912
	ds_read_b128 v[206:209], v9 offset:39936
	v_readfirstlane_b32 s67, v16
	v_lshl_add_u64 v[18:19], v[148:149], 1, s[2:3]
	v_lshl_add_u64 v[18:19], v[18:19], 0, s[50:51]
	s_mov_b32 m0, s67
	v_mov_b32_e32 v148, v6
	global_load_lds_dwordx4 v[18:19], off
	v_readfirstlane_b32 s67, v17
	v_lshl_add_u64 v[18:19], v[148:149], 1, s[2:3]
	v_lshl_add_u64 v[18:19], v[18:19], 0, s[50:51]
	s_mov_b32 m0, s67
	s_nop 0
	global_load_lds_dwordx4 v[18:19], off
	s_waitcnt lgkmcnt(8)
	s_setprio 1
	s_barrier
	s_waitcnt lgkmcnt(0)
	v_mfma_f32_16x16x32_bf16 v[16:19], v[144:147], v[106:109], v[70:73]
	v_mfma_f32_16x16x32_bf16 v[70:73], v[144:147], v[114:117], v[74:77]
	v_mfma_f32_16x16x32_bf16 v[74:77], v[156:159], v[106:109], v[78:81]
	v_mfma_f32_16x16x32_bf16 v[78:81], v[156:159], v[114:117], v[82:85]
	v_mfma_f32_16x16x32_bf16 v[82:85], v[194:197], v[106:109], v[86:89]
	v_mfma_f32_16x16x32_bf16 v[86:89], v[194:197], v[114:117], v[90:93]
	v_mfma_f32_16x16x32_bf16 v[90:93], v[202:205], v[106:109], v[94:97]
	v_mfma_f32_16x16x32_bf16 v[94:97], v[202:205], v[114:117], v[98:101]
	v_mfma_f32_16x16x32_bf16 v[16:19], v[152:155], v[110:113], v[16:19]
	v_mfma_f32_16x16x32_bf16 v[70:73], v[152:155], v[140:143], v[70:73]
	v_mfma_f32_16x16x32_bf16 v[74:77], v[190:193], v[110:113], v[74:77]
	v_mfma_f32_16x16x32_bf16 v[78:81], v[190:193], v[140:143], v[78:81]
	v_mfma_f32_16x16x32_bf16 v[82:85], v[198:201], v[110:113], v[82:85]
	v_mfma_f32_16x16x32_bf16 v[86:89], v[198:201], v[140:143], v[86:89]
	v_mfma_f32_16x16x32_bf16 v[90:93], v[206:209], v[110:113], v[90:93]
	v_mfma_f32_16x16x32_bf16 v[94:97], v[206:209], v[140:143], v[94:97]
	s_setprio 0
	s_barrier
	v_or_b32_e32 v234, 0x1c000, v126
	v_or_b32_e32 v236, 0x1c800, v126
	v_mov_b32_e32 v148, v4
	v_or_b32_e32 v235, 0x1c400, v126
	ds_read_b128 v[98:101], v234
	ds_read_b128 v[210:213], v235
	v_or_b32_e32 v126, 0x1cc00, v126
	ds_read_b128 v[214:217], v236
	ds_read_b128 v[218:221], v126
	v_readfirstlane_b32 s67, v13
	v_lshl_add_u64 v[36:37], v[148:149], 1, s[22:23]
	v_lshl_add_u64 v[36:37], v[36:37], 0, s[54:55]
	s_mov_b32 m0, s67
	v_mov_b32_e32 v148, v6
	global_load_lds_dwordx4 v[36:37], off
	s_nop 0
	v_lshl_add_u64 v[12:13], v[148:149], 1, s[22:23]
	v_readfirstlane_b32 s22, v14
	v_lshl_add_u64 v[12:13], v[12:13], 0, s[54:55]
	s_mov_b32 m0, s22
	s_nop 0
	global_load_lds_dwordx4 v[12:13], off
	s_setprio 1
	s_barrier
; #define LDA(dst, b, h)                                                                                    \
;   _Pragma("unroll") for (int m = 0; m < 4; ++m) _Pragma("unroll") for (int k = 0; k < 2; ++k)             \
;       dst[m][k] = *reinterpret_cast<const bf16x8*>((char*)SA(b, h) + lds_byte(wr * 64 + m * 16 + fr, k * 32 + fq * 8))
; #define LDB(dst, b, h)                                                                                    \
;   _Pragma("unroll") for (int n = 0; n < 2; ++n) _Pragma("unroll") for (int k = 0; k < 2; ++k)             \
;       dst[n][k] = *reinterpret_cast<const bf16x8*>((char*)SB(b, h) + lds_byte(wc * 32 + n * 16 + fr, k * 32 + fq * 8))
; #define WAIT_V(n) asm volatile("s_waitcnt vmcnt(" #n ")" ::: "memory")
; #define WAIT_L(n) asm volatile("s_waitcnt lgkmcnt(" #n ")" ::: "memory")
; #define BAR __builtin_amdgcn_s_barrier()
; #define SCHED __builtin_amdgcn_sched_barrier(0)
; template <int EPI> ...
;     ...
;     LDB(B1, 1, 1); STAGE(SB(1, 0), Bt, bcol, t + 3);
;     BAR; WAIT_L(0); MMA(0, 1, At, B1); BAR;
;     LDA(At, 1, 1); STAGE(SA(1, 0), A, brow, t + 3);
;     BAR; WAIT_L(0); MMA(1, 0, At, B0); BAR; SCHED;
;     STAGE(SB(1, 1), Bt, bcol + HALF, t + 3);
;     WAIT_V(6); BAR; MMA(1, 1, At, B1); BAR;
;   }
;   {
;     LDB(B0, 0, 0); LDA(At, 0, 0); STAGE(SA(1, 1), A, brow + HALF, nt - 1);
	s_waitcnt lgkmcnt(0)
	v_mfma_f32_16x16x32_bf16 v[12:15], v[144:147], v[98:101], v[118:121]
	v_mfma_f32_16x16x32_bf16 v[36:39], v[144:147], v[214:217], v[38:41]
	v_mfma_f32_16x16x32_bf16 v[40:43], v[156:159], v[98:101], v[42:45]
	v_mfma_f32_16x16x32_bf16 v[44:47], v[156:159], v[214:217], v[46:49]
	v_mfma_f32_16x16x32_bf16 v[48:51], v[194:197], v[98:101], v[50:53]
	v_mfma_f32_16x16x32_bf16 v[52:55], v[194:197], v[214:217], v[54:57]
	v_mfma_f32_16x16x32_bf16 v[56:59], v[202:205], v[98:101], v[58:61]
	v_mfma_f32_16x16x32_bf16 v[60:63], v[202:205], v[214:217], v[62:65]
	v_mfma_f32_16x16x32_bf16 v[12:15], v[152:155], v[210:213], v[12:15]
	v_mfma_f32_16x16x32_bf16 v[36:39], v[152:155], v[218:221], v[36:39]
	v_mfma_f32_16x16x32_bf16 v[40:43], v[190:193], v[210:213], v[40:43]
	v_mfma_f32_16x16x32_bf16 v[44:47], v[190:193], v[218:221], v[44:47]
	v_mfma_f32_16x16x32_bf16 v[48:51], v[198:201], v[210:213], v[48:51]
	v_mfma_f32_16x16x32_bf16 v[52:55], v[198:201], v[218:221], v[52:55]
	v_mfma_f32_16x16x32_bf16 v[56:59], v[206:209], v[210:213], v[56:59]
	v_mfma_f32_16x16x32_bf16 v[60:63], v[206:209], v[218:221], v[60:63]
	s_setprio 0
	v_mov_b32_e32 v148, v4
	s_barrier
	ds_read_b128 v[118:121], v8 offset:49152
	ds_read_b128 v[144:147], v8 offset:50176
	ds_read_b128 v[152:155], v9 offset:51200
	ds_read_b128 v[156:159], v9 offset:52224
	ds_read_b128 v[190:193], v9 offset:53248
	ds_read_b128 v[194:197], v9 offset:54272
	ds_read_b128 v[198:201], v9 offset:55296
	ds_read_b128 v[202:205], v9 offset:56320
	v_readfirstlane_b32 s22, v10
	v_lshl_add_u64 v[64:65], v[148:149], 1, s[20:21]
	v_lshl_add_u64 v[64:65], v[64:65], 0, s[54:55]
	s_mov_b32 m0, s22
	v_mov_b32_e32 v148, v6
	global_load_lds_dwordx4 v[64:65], off
	s_nop 0
	v_lshl_add_u64 v[64:65], v[148:149], 1, s[20:21]
	v_readfirstlane_b32 s20, v11
	v_lshl_add_u64 v[64:65], v[64:65], 0, s[54:55]
	s_mov_b32 m0, s20
	s_nop 0
	global_load_lds_dwordx4 v[64:65], off
	s_setprio 1
	s_barrier
	s_waitcnt lgkmcnt(0)
	v_mfma_f32_16x16x32_bf16 v[20:23], v[198:201], v[106:109], v[20:23]
	v_mfma_f32_16x16x32_bf16 v[24:27], v[198:201], v[114:117], v[24:27]
	v_mfma_f32_16x16x32_bf16 v[160:163], v[118:121], v[106:109], v[160:163]
	v_mfma_f32_16x16x32_bf16 v[164:167], v[118:121], v[114:117], v[164:167]
	v_mfma_f32_16x16x32_bf16 v[174:177], v[152:155], v[106:109], v[174:177]
	v_mfma_f32_16x16x32_bf16 v[178:181], v[152:155], v[114:117], v[178:181]
	v_mfma_f32_16x16x32_bf16 v[182:185], v[190:193], v[106:109], v[182:185]
	v_mfma_f32_16x16x32_bf16 v[186:189], v[190:193], v[114:117], v[186:189]
	v_mfma_f32_16x16x32_bf16 v[20:23], v[202:205], v[110:113], v[20:23]
	v_mfma_f32_16x16x32_bf16 v[24:27], v[202:205], v[140:143], v[24:27]
	v_mfma_f32_16x16x32_bf16 v[160:163], v[144:147], v[110:113], v[160:163]
	v_mfma_f32_16x16x32_bf16 v[164:167], v[144:147], v[140:143], v[164:167]
	v_mfma_f32_16x16x32_bf16 v[174:177], v[156:159], v[110:113], v[174:177]
	v_mfma_f32_16x16x32_bf16 v[178:181], v[156:159], v[140:143], v[178:181]
	v_mfma_f32_16x16x32_bf16 v[182:185], v[194:197], v[110:113], v[182:185]
	v_mfma_f32_16x16x32_bf16 v[186:189], v[194:197], v[140:143], v[186:189]
	s_setprio 0
	s_barrier
	v_mov_b32_e32 v148, v4
	v_readfirstlane_b32 s20, v5
	v_lshl_add_u64 v[10:11], v[148:149], 1, s[18:19]
	v_lshl_add_u64 v[10:11], v[10:11], 0, s[54:55]
	s_mov_b32 m0, s20
	v_mov_b32_e32 v148, v6
	global_load_lds_dwordx4 v[10:11], off
	s_nop 0
	v_lshl_add_u64 v[10:11], v[148:149], 1, s[18:19]
	v_readfirstlane_b32 s18, v7
	v_lshl_add_u64 v[10:11], v[10:11], 0, s[54:55]
	s_mov_b32 m0, s18
	s_nop 0
	global_load_lds_dwordx4 v[10:11], off
	s_waitcnt vmcnt(6)
	s_barrier
	s_setprio 1
	v_mfma_f32_16x16x32_bf16 v[28:31], v[118:121], v[98:101], v[28:31]
	v_mfma_f32_16x16x32_bf16 v[32:35], v[118:121], v[214:217], v[32:35]
	v_mfma_f32_16x16x32_bf16 v[64:67], v[152:155], v[98:101], v[66:69]
	v_mfma_f32_16x16x32_bf16 v[106:109], v[152:155], v[214:217], v[122:125]
	v_mfma_f32_16x16x32_bf16 v[110:113], v[190:193], v[98:101], v[132:135]
	v_mfma_f32_16x16x32_bf16 v[114:117], v[190:193], v[214:217], v[136:139]
	v_mfma_f32_16x16x32_bf16 v[98:101], v[198:201], v[98:101], v[102:105]
	v_mfma_f32_16x16x32_bf16 v[0:3], v[198:201], v[214:217], v[0:3]
	v_mfma_f32_16x16x32_bf16 v[28:31], v[144:147], v[210:213], v[28:31]
	v_mfma_f32_16x16x32_bf16 v[32:35], v[144:147], v[218:221], v[32:35]
	v_mfma_f32_16x16x32_bf16 v[64:67], v[156:159], v[210:213], v[64:67]
	v_mfma_f32_16x16x32_bf16 v[106:109], v[156:159], v[218:221], v[106:109]
	v_mfma_f32_16x16x32_bf16 v[110:113], v[194:197], v[210:213], v[110:113]
	v_mfma_f32_16x16x32_bf16 v[114:117], v[194:197], v[218:221], v[114:117]
	v_mfma_f32_16x16x32_bf16 v[98:101], v[202:205], v[210:213], v[98:101]
	v_mfma_f32_16x16x32_bf16 v[0:3], v[202:205], v[218:221], v[0:3]
	s_setprio 0
	s_barrier
	ds_read_b128 v[102:105], v127
	ds_read_b128 v[118:121], v129
	ds_read_b128 v[122:125], v131
	ds_read_b128 v[132:135], v222
	ds_read_b128 v[136:139], v8
	ds_read_b128 v[140:143], v8 offset:1024
	ds_read_b128 v[144:147], v9 offset:2048
	ds_read_b128 v[152:155], v9 offset:3072
	ds_read_b128 v[156:159], v9 offset:4096
	ds_read_b128 v[190:193], v9 offset:5120
	ds_read_b128 v[194:197], v9 offset:6144
	ds_read_b128 v[198:201], v9 offset:7168
	v_mov_b32_e32 v5, v149
	v_lshl_add_u64 v[4:5], v[4:5], 1, s[2:3]
	s_mov_b32 m0, s66
	v_lshl_add_u64 v[4:5], v[4:5], 0, s[54:55]
	v_mov_b32_e32 v7, v149
	global_load_lds_dwordx4 v[4:5], off
	s_mov_b32 m0, s65
	v_lshl_add_u64 v[4:5], v[6:7], 1, s[2:3]
	v_lshl_add_u64 v[4:5], v[4:5], 0, s[54:55]
	global_load_lds_dwordx4 v[4:5], off
	s_setprio 1
	s_barrier
; #define LDA(dst, b, h)                                                                                    \
;   _Pragma("unroll") for (int m = 0; m < 4; ++m) _Pragma("unroll") for (int k = 0; k < 2; ++k)             \
;       dst[m][k] = *reinterpret_cast<const bf16x8*>((char*)SA(b, h) + lds_byte(wr * 64 + m * 16 + fr, k * 32 + fq * 8))
; #define LDB(dst, b, h)                                                                                    \
;   _Pragma("unroll") for (int n = 0; n < 2; ++n) _Pragma("unroll") for (int k = 0; k < 2; ++k)             \
;       dst[n][k] = *reinterpret_cast<const bf16x8*>((char*)SB(b, h) + lds_byte(wc * 32 + n * 16 + fr, k * 32 + fq * 8))
; #define WAIT_V(n) asm volatile("s_waitcnt vmcnt(" #n ")" ::: "memory")
; #define WAIT_L(n) asm volatile("s_waitcnt lgkmcnt(" #n ")" ::: "memory")
; #define BAR __builtin_amdgcn_s_barrier()
; template <int EPI> ...
;     ...
;     LDB(B0, 0, 0); LDA(At, 0, 0); STAGE(SA(1, 1), A, brow + HALF, nt - 1);
;     BAR; WAIT_L(0); MMA(0, 0, At, B0); BAR;
;     LDB(B1, 0, 1); BAR; WAIT_L(0); MMA(0, 1, At, B1); BAR;
;     LDA(At, 0, 1); WAIT_V(4); BAR; WAIT_L(0); MMA(1, 0, At, B0); MMA(1, 1, At, B1); BAR;
	s_waitcnt lgkmcnt(0)
	v_mfma_f32_16x16x32_bf16 v[4:7], v[136:139], v[102:105], v[16:19]
	v_mfma_f32_16x16x32_bf16 v[16:19], v[136:139], v[122:125], v[70:73]
	v_mfma_f32_16x16x32_bf16 v[68:71], v[144:147], v[102:105], v[74:77]
	v_mfma_f32_16x16x32_bf16 v[72:75], v[144:147], v[122:125], v[78:81]
	v_mfma_f32_16x16x32_bf16 v[76:79], v[156:159], v[102:105], v[82:85]
	v_mfma_f32_16x16x32_bf16 v[80:83], v[156:159], v[122:125], v[86:89]
	v_mfma_f32_16x16x32_bf16 v[202:205], v[190:193], v[132:135], v[80:83]
	v_mfma_f32_16x16x32_bf16 v[80:83], v[194:197], v[102:105], v[90:93]
	v_mfma_f32_16x16x32_bf16 v[206:209], v[198:201], v[118:121], v[80:83]
	v_mfma_f32_16x16x32_bf16 v[80:83], v[194:197], v[122:125], v[94:97]
	v_mfma_f32_16x16x32_bf16 v[4:7], v[140:143], v[118:121], v[4:7]
	v_mfma_f32_16x16x32_bf16 v[16:19], v[140:143], v[132:135], v[16:19]
	v_mfma_f32_16x16x32_bf16 v[68:71], v[152:155], v[118:121], v[68:71]
	v_mfma_f32_16x16x32_bf16 v[72:75], v[152:155], v[132:135], v[72:75]
	v_mfma_f32_16x16x32_bf16 v[76:79], v[190:193], v[118:121], v[76:79]
	v_mfma_f32_16x16x32_bf16 v[92:95], v[198:201], v[132:135], v[80:83]
	s_setprio 0
	s_barrier
	s_nop 0
	ds_read_b128 v[80:83], v223
	ds_read_b128 v[84:87], v224
	ds_read_b128 v[88:91], v225
	ds_read_b128 v[210:213], v226
	s_setprio 1
	s_barrier
	s_waitcnt lgkmcnt(0)
	v_mfma_f32_16x16x32_bf16 v[10:13], v[136:139], v[80:83], v[12:15]
	v_mfma_f32_16x16x32_bf16 v[36:39], v[136:139], v[88:91], v[36:39]
	v_mfma_f32_16x16x32_bf16 v[40:43], v[144:147], v[80:83], v[40:43]
	v_mfma_f32_16x16x32_bf16 v[44:47], v[144:147], v[88:91], v[44:47]
	v_mfma_f32_16x16x32_bf16 v[48:51], v[156:159], v[80:83], v[48:51]
	v_mfma_f32_16x16x32_bf16 v[52:55], v[156:159], v[88:91], v[52:55]
	v_mfma_f32_16x16x32_bf16 v[56:59], v[194:197], v[80:83], v[56:59]
	v_mfma_f32_16x16x32_bf16 v[60:63], v[194:197], v[88:91], v[60:63]
	v_mfma_f32_16x16x32_bf16 v[10:13], v[140:143], v[84:87], v[10:13]
	v_mfma_f32_16x16x32_bf16 v[36:39], v[140:143], v[210:213], v[36:39]
	v_mfma_f32_16x16x32_bf16 v[40:43], v[152:155], v[84:87], v[40:43]
	v_mfma_f32_16x16x32_bf16 v[44:47], v[152:155], v[210:213], v[44:47]
	v_mfma_f32_16x16x32_bf16 v[48:51], v[190:193], v[84:87], v[48:51]
	v_mfma_f32_16x16x32_bf16 v[52:55], v[190:193], v[210:213], v[52:55]
	v_mfma_f32_16x16x32_bf16 v[56:59], v[198:201], v[84:87], v[56:59]
	v_mfma_f32_16x16x32_bf16 v[60:63], v[198:201], v[210:213], v[60:63]
	s_setprio 0
	s_barrier
	ds_read_b128 v[136:139], v8 offset:16384
	ds_read_b128 v[140:143], v8 offset:17408
	ds_read_b128 v[144:147], v9 offset:18432
	ds_read_b128 v[152:155], v9 offset:19456
	ds_read_b128 v[156:159], v9 offset:20480
	ds_read_b128 v[190:193], v9 offset:21504
	ds_read_b128 v[194:197], v9 offset:22528
	ds_read_b128 v[198:201], v9 offset:23552
	s_waitcnt vmcnt(4)
	s_setprio 1
	s_barrier
	s_waitcnt lgkmcnt(0)
	v_mfma_f32_16x16x32_bf16 v[20:23], v[194:197], v[102:105], v[20:23]
	v_mfma_f32_16x16x32_bf16 v[160:163], v[136:139], v[102:105], v[160:163]
	v_mfma_f32_16x16x32_bf16 v[164:167], v[136:139], v[122:125], v[164:167]
	v_mfma_f32_16x16x32_bf16 v[174:177], v[144:147], v[102:105], v[174:177]
	v_mfma_f32_16x16x32_bf16 v[178:181], v[144:147], v[122:125], v[178:181]
	v_mfma_f32_16x16x32_bf16 v[182:185], v[156:159], v[102:105], v[182:185]
	v_mfma_f32_16x16x32_bf16 v[186:189], v[156:159], v[122:125], v[186:189]
	v_mfma_f32_16x16x32_bf16 v[214:217], v[198:201], v[118:121], v[20:23]
	v_mfma_f32_16x16x32_bf16 v[20:23], v[194:197], v[122:125], v[24:27]
	v_mfma_f32_16x16x32_bf16 v[160:163], v[140:143], v[118:121], v[160:163]
	v_mfma_f32_16x16x32_bf16 v[164:167], v[140:143], v[132:135], v[164:167]
	v_mfma_f32_16x16x32_bf16 v[174:177], v[152:155], v[118:121], v[174:177]
	v_mfma_f32_16x16x32_bf16 v[178:181], v[152:155], v[132:135], v[178:181]
	v_mfma_f32_16x16x32_bf16 v[182:185], v[190:193], v[118:121], v[182:185]
	v_mfma_f32_16x16x32_bf16 v[186:189], v[190:193], v[132:135], v[186:189]
	v_mfma_f32_16x16x32_bf16 v[132:135], v[198:201], v[132:135], v[20:23]
	s_setprio 0
	s_setprio 1
	v_mfma_f32_16x16x32_bf16 v[20:23], v[136:139], v[80:83], v[28:31]
	v_mfma_f32_16x16x32_bf16 v[218:221], v[140:143], v[84:87], v[20:23]
	v_mfma_f32_16x16x32_bf16 v[20:23], v[136:139], v[88:91], v[32:35]
	v_mfma_f32_16x16x32_bf16 v[32:35], v[140:143], v[210:213], v[20:23]
	v_mfma_f32_16x16x32_bf16 v[20:23], v[144:147], v[80:83], v[64:67]
	v_mfma_f32_16x16x32_bf16 v[136:139], v[152:155], v[84:87], v[20:23]
	v_mfma_f32_16x16x32_bf16 v[20:23], v[144:147], v[88:91], v[106:109]
	v_mfma_f32_16x16x32_bf16 v[140:143], v[152:155], v[210:213], v[20:23]
	v_mfma_f32_16x16x32_bf16 v[20:23], v[156:159], v[80:83], v[110:113]
	v_mfma_f32_16x16x32_bf16 v[144:147], v[190:193], v[84:87], v[20:23]
	v_mfma_f32_16x16x32_bf16 v[20:23], v[156:159], v[88:91], v[114:117]
	v_mfma_f32_16x16x32_bf16 v[152:155], v[190:193], v[210:213], v[20:23]
	v_mfma_f32_16x16x32_bf16 v[20:23], v[194:197], v[80:83], v[98:101]
	v_mfma_f32_16x16x32_bf16 v[0:3], v[194:197], v[88:91], v[0:3]
	v_mfma_f32_16x16x32_bf16 v[156:159], v[198:201], v[84:87], v[20:23]
	v_mfma_f32_16x16x32_bf16 v[190:193], v[198:201], v[210:213], v[0:3]
	s_setprio 0
	s_barrier
; #define LDA(dst, b, h)                                                                                    \
;   _Pragma("unroll") for (int m = 0; m < 4; ++m) _Pragma("unroll") for (int k = 0; k < 2; ++k)             \
;       dst[m][k] = *reinterpret_cast<const bf16x8*>((char*)SA(b, h) + lds_byte(wr * 64 + m * 16 + fr, k * 32 + fq * 8))
; #define LDB(dst, b, h)                                                                                    \
;   _Pragma("unroll") for (int n = 0; n < 2; ++n) _Pragma("unroll") for (int k = 0; k < 2; ++k)             \
;       dst[n][k] = *reinterpret_cast<const bf16x8*>((char*)SB(b, h) + lds_byte(wc * 32 + n * 16 + fr, k * 32 + fq * 8))
; #define WAIT_V(n) asm volatile("s_waitcnt vmcnt(" #n ")" ::: "memory")
; #define WAIT_L(n) asm volatile("s_waitcnt lgkmcnt(" #n ")" ::: "memory")
; #define BAR __builtin_amdgcn_s_barrier()
; template <int EPI> ...
;     ...
;     LDB(B0, 1, 0); LDA(At, 1, 0); WAIT_V(2); BAR; WAIT_L(0); MMA(0, 0, At, B0); BAR;
;     LDB(B1, 1, 1); WAIT_V(0); BAR; WAIT_L(0); MMA(0, 1, At, B1); BAR;
;     LDA(At, 1, 1); BAR; WAIT_L(0); MMA(1, 0, At, B0); MMA(1, 1, At, B1); BAR;
;   }
;   if (wr == 0) BAR;
	s_nop 3
	ds_read_b128 v[0:3], v227
	ds_read_b128 v[194:197], v228
	ds_read_b128 v[198:201], v229
	ds_read_b128 v[210:213], v230
	ds_read_b128 v[20:23], v8 offset:32768
	ds_read_b128 v[24:27], v8 offset:33792
	ds_read_b128 v[28:31], v9 offset:34816
	ds_read_b128 v[100:103], v9 offset:35840
	ds_read_b128 v[108:111], v9 offset:36864
	ds_read_b128 v[222:225], v9 offset:37888
	ds_read_b128 v[226:229], v9 offset:38912
	ds_read_b128 v[230:233], v9 offset:39936
	s_waitcnt vmcnt(2)
	s_setprio 1
	s_barrier
	s_waitcnt lgkmcnt(0)
	v_mfma_f32_16x16x32_bf16 v[4:7], v[20:23], v[0:3], v[4:7]
	v_mfma_f32_16x16x32_bf16 v[88:91], v[24:27], v[194:197], v[4:7]
	v_mfma_f32_16x16x32_bf16 v[4:7], v[20:23], v[198:201], v[16:19]
	v_mfma_f32_16x16x32_bf16 v[96:99], v[24:27], v[210:213], v[4:7]
	v_mfma_f32_16x16x32_bf16 v[4:7], v[28:31], v[0:3], v[68:71]
	v_mfma_f32_16x16x32_bf16 v[80:83], v[100:103], v[194:197], v[4:7]
	v_mfma_f32_16x16x32_bf16 v[4:7], v[28:31], v[198:201], v[72:75]
	v_mfma_f32_16x16x32_bf16 v[84:87], v[100:103], v[210:213], v[4:7]
	v_mfma_f32_16x16x32_bf16 v[4:7], v[108:111], v[0:3], v[76:79]
	v_mfma_f32_16x16x32_bf16 v[72:75], v[222:225], v[194:197], v[4:7]
	v_mfma_f32_16x16x32_bf16 v[4:7], v[108:111], v[198:201], v[202:205]
	v_mfma_f32_16x16x32_bf16 v[76:79], v[222:225], v[210:213], v[4:7]
	v_mfma_f32_16x16x32_bf16 v[4:7], v[226:229], v[0:3], v[206:209]
	v_mfma_f32_16x16x32_bf16 v[64:67], v[230:233], v[194:197], v[4:7]
	v_mfma_f32_16x16x32_bf16 v[4:7], v[226:229], v[198:201], v[92:95]
	v_mfma_f32_16x16x32_bf16 v[68:71], v[230:233], v[210:213], v[4:7]
	s_setprio 0
	s_barrier
	ds_read_b128 v[202:205], v234
	ds_read_b128 v[206:209], v235
	ds_read_b128 v[234:237], v236
	ds_read_b128 v[238:241], v126
	s_waitcnt vmcnt(0)
	s_setprio 1
	s_barrier
	s_waitcnt lgkmcnt(0)
	v_mfma_f32_16x16x32_bf16 v[4:7], v[20:23], v[202:205], v[10:13]
	v_mfma_f32_16x16x32_bf16 v[120:123], v[24:27], v[206:209], v[4:7]
	v_mfma_f32_16x16x32_bf16 v[4:7], v[20:23], v[234:237], v[36:39]
	v_mfma_f32_16x16x32_bf16 v[124:127], v[24:27], v[238:241], v[4:7]
	v_mfma_f32_16x16x32_bf16 v[4:7], v[28:31], v[202:205], v[40:43]
	v_mfma_f32_16x16x32_bf16 v[112:115], v[100:103], v[206:209], v[4:7]
	v_mfma_f32_16x16x32_bf16 v[4:7], v[28:31], v[234:237], v[44:47]
	v_mfma_f32_16x16x32_bf16 v[116:119], v[100:103], v[238:241], v[4:7]
	v_mfma_f32_16x16x32_bf16 v[4:7], v[108:111], v[202:205], v[48:51]
	v_mfma_f32_16x16x32_bf16 v[104:107], v[222:225], v[206:209], v[4:7]
	v_mfma_f32_16x16x32_bf16 v[4:7], v[108:111], v[234:237], v[52:55]
	v_mfma_f32_16x16x32_bf16 v[108:111], v[222:225], v[238:241], v[4:7]
	v_mfma_f32_16x16x32_bf16 v[4:7], v[226:229], v[202:205], v[56:59]
	v_mfma_f32_16x16x32_bf16 v[92:95], v[230:233], v[206:209], v[4:7]
	v_mfma_f32_16x16x32_bf16 v[4:7], v[226:229], v[234:237], v[60:63]
	v_mfma_f32_16x16x32_bf16 v[100:103], v[230:233], v[238:241], v[4:7]
	s_setprio 0
	s_barrier
	ds_read_b128 v[36:39], v8 offset:49152
	ds_read_b128 v[40:43], v8 offset:50176
	ds_read_b128 v[44:47], v9 offset:51200
	ds_read_b128 v[52:55], v9 offset:52224
	ds_read_b128 v[222:225], v9 offset:53248
	ds_read_b128 v[226:229], v9 offset:54272
	ds_read_b128 v[230:233], v9 offset:55296
	ds_read_b128 v[242:245], v9 offset:56320
	s_setprio 1
	s_barrier
	s_waitcnt lgkmcnt(0)
	v_mfma_f32_16x16x32_bf16 v[4:7], v[36:39], v[0:3], v[160:163]
	v_mfma_f32_16x16x32_bf16 v[24:27], v[40:43], v[194:197], v[4:7]
	v_mfma_f32_16x16x32_bf16 v[4:7], v[36:39], v[198:201], v[164:167]
	v_mfma_f32_16x16x32_bf16 v[28:31], v[40:43], v[210:213], v[4:7]
	v_mfma_f32_16x16x32_bf16 v[4:7], v[44:47], v[0:3], v[174:177]
	v_mfma_f32_16x16x32_bf16 v[16:19], v[52:55], v[194:197], v[4:7]
	v_mfma_f32_16x16x32_bf16 v[4:7], v[44:47], v[198:201], v[178:181]
	v_mfma_f32_16x16x32_bf16 v[20:23], v[52:55], v[210:213], v[4:7]
	v_mfma_f32_16x16x32_bf16 v[4:7], v[222:225], v[0:3], v[182:185]
	v_mfma_f32_16x16x32_bf16 v[8:11], v[226:229], v[194:197], v[4:7]
	v_mfma_f32_16x16x32_bf16 v[4:7], v[222:225], v[198:201], v[186:189]
	v_mfma_f32_16x16x32_bf16 v[12:15], v[226:229], v[210:213], v[4:7]
	v_mfma_f32_16x16x32_bf16 v[0:3], v[230:233], v[0:3], v[214:217]
	v_mfma_f32_16x16x32_bf16 v[4:7], v[230:233], v[198:201], v[132:135]
	v_mfma_f32_16x16x32_bf16 v[0:3], v[242:245], v[194:197], v[0:3]
	v_mfma_f32_16x16x32_bf16 v[4:7], v[242:245], v[210:213], v[4:7]
	s_setprio 0
	s_setprio 1
	v_mfma_f32_16x16x32_bf16 v[32:35], v[36:39], v[234:237], v[32:35]
	v_mfma_f32_16x16x32_bf16 v[48:51], v[36:39], v[202:205], v[218:221]
	v_mfma_f32_16x16x32_bf16 v[60:63], v[40:43], v[238:241], v[32:35]
	v_mfma_f32_16x16x32_bf16 v[32:35], v[44:47], v[202:205], v[136:139]
	v_mfma_f32_16x16x32_bf16 v[56:59], v[40:43], v[206:209], v[48:51]
	v_mfma_f32_16x16x32_bf16 v[48:51], v[52:55], v[206:209], v[32:35]
	v_mfma_f32_16x16x32_bf16 v[32:35], v[44:47], v[234:237], v[140:143]
	v_mfma_f32_16x16x32_bf16 v[52:55], v[52:55], v[238:241], v[32:35]
	v_mfma_f32_16x16x32_bf16 v[32:35], v[222:225], v[202:205], v[144:147]
	v_mfma_f32_16x16x32_bf16 v[40:43], v[226:229], v[206:209], v[32:35]
	v_mfma_f32_16x16x32_bf16 v[32:35], v[222:225], v[234:237], v[152:155]
	v_mfma_f32_16x16x32_bf16 v[44:47], v[226:229], v[238:241], v[32:35]
	v_mfma_f32_16x16x32_bf16 v[32:35], v[230:233], v[202:205], v[156:159]
	v_mfma_f32_16x16x32_bf16 v[36:39], v[230:233], v[234:237], v[190:193]
	v_mfma_f32_16x16x32_bf16 v[32:35], v[242:245], v[206:209], v[32:35]
	v_mfma_f32_16x16x32_bf16 v[36:39], v[242:245], v[238:241], v[36:39]
	s_setprio 0
	s_cmpk_gt_u32 s64, 0xff
	s_barrier
	s_cbranch_scc1 .LBB0_911
	s_barrier

; #define LDA(dst, b, h)                                                                                    \
;   _Pragma("unroll") for (int m = 0; m < 4; ++m) _Pragma("unroll") for (int k = 0; k < 2; ++k)             \
;       dst[m][k] = *reinterpret_cast<const bf16x8*>((char*)SA(b, h) + lds_byte(wr * 64 + m * 16 + fr, k * 32 + fq * 8))
; #define LDB(dst, b, h)                                                                                    \
;   _Pragma("unroll") for (int n = 0; n < 2; ++n) _Pragma("unroll") for (int k = 0; k < 2; ++k)             \
;       dst[n][k] = *reinterpret_cast<const bf16x8*>((char*)SB(b, h) + lds_byte(wc * 32 + n * 16 + fr, k * 32 + fq * 8))
; #define WAIT_V(n) asm volatile("s_waitcnt vmcnt(" #n ")" ::: "memory")
; #define WAIT_L(n) asm volatile("s_waitcnt lgkmcnt(" #n ")" ::: "memory")
; #define BAR __builtin_amdgcn_s_barrier()
; #define SCHED __builtin_amdgcn_sched_barrier(0)
; template <int EPI> ...
;     ...
;     LDB(B0, 0, 0); SCHED; LDA(At, 0, 0); STAGE(SA(1, 1), A, brow + HALF, t + 1);
;     WAIT_L(8); BAR; WAIT_L(0); MMA(0, 0, At, B0); BAR; SCHED;
;     LDB(B1, 0, 1); STAGE(SB(0, 0), Bt, bcol, t + 2);
;     BAR; WAIT_L(0); MMA(0, 1, At, B1); BAR;
;     LDA(At, 0, 1); STAGE(SA(0, 0), A, brow, t + 2);
;     BAR; WAIT_L(0); MMA(1, 0, At, B0); BAR; SCHED;
;     STAGE(SB(0, 1), Bt, bcol + HALF, t + 2);
;     WAIT_V(6); BAR; MMA(1, 1, At, B1); BAR;
.LBB0_1016:
	ds_read_b128 v[162:165], v155
	ds_read_b128 v[174:177], v155 offset:1024
	ds_read_b128 v[178:181], v155 offset:2048
	ds_read_b128 v[182:185], v155 offset:3072
	s_add_u32 s22, s14, s20
	v_add_u32_e32 v156, s63, v154
	v_add_u32_e32 v157, s69, v154
	v_add_u32_e32 v158, s70, v154
	s_addc_u32 s23, s15, s21
	ds_read_b128 v[186:189], v135
	ds_read_b128 v[190:193], v135 offset:1024
	ds_read_b128 v[194:197], v156
	ds_read_b128 v[198:201], v156 offset:1024
	ds_read_b128 v[202:205], v157
	ds_read_b128 v[206:209], v157 offset:1024
	ds_read_b128 v[210:213], v158
	ds_read_b128 v[214:217], v158 offset:1024
	v_add_u32_e32 v159, 0xe000, v129
	v_add_u32_e32 v160, 0xc000, v129
	s_add_u32 m0, s32, 0xc000
	s_add_u32 s98, s22, 0x40080
	s_addc_u32 s99, s23, 0
	global_load_lds_dwordx4 v253, s[98:99]
	s_add_u32 m0, s32, 0xe000
	s_nop 0
	global_load_lds_dwordx4 v252, s[98:99]
	s_waitcnt lgkmcnt(8)
	s_setprio 1
	s_barrier
	s_waitcnt lgkmcnt(0)
	v_mfma_f32_16x16x32_bf16 v[124:127], v[186:189], v[162:165], v[124:127]
	v_mfma_f32_16x16x32_bf16 v[120:123], v[186:189], v[178:181], v[120:123]
	v_mfma_f32_16x16x32_bf16 v[116:119], v[194:197], v[162:165], v[116:119]
	v_mfma_f32_16x16x32_bf16 v[112:115], v[194:197], v[178:181], v[112:115]
	v_mfma_f32_16x16x32_bf16 v[108:111], v[202:205], v[162:165], v[108:111]
	v_mfma_f32_16x16x32_bf16 v[104:107], v[202:205], v[178:181], v[104:107]
	v_mfma_f32_16x16x32_bf16 v[100:103], v[210:213], v[162:165], v[100:103]
	v_mfma_f32_16x16x32_bf16 v[96:99], v[210:213], v[178:181], v[96:99]
	v_mfma_f32_16x16x32_bf16 v[124:127], v[190:193], v[174:177], v[124:127]
	v_mfma_f32_16x16x32_bf16 v[120:123], v[190:193], v[182:185], v[120:123]
	v_mfma_f32_16x16x32_bf16 v[116:119], v[198:201], v[174:177], v[116:119]
	v_mfma_f32_16x16x32_bf16 v[112:115], v[198:201], v[182:185], v[112:115]
	v_mfma_f32_16x16x32_bf16 v[108:111], v[206:209], v[174:177], v[108:111]
	v_mfma_f32_16x16x32_bf16 v[104:107], v[206:209], v[182:185], v[104:107]
	v_mfma_f32_16x16x32_bf16 v[100:103], v[214:217], v[174:177], v[100:103]
	v_mfma_f32_16x16x32_bf16 v[96:99], v[214:217], v[182:185], v[96:99]
	s_setprio 0
	s_barrier
	s_add_u32 s30, s12, s20
	s_addc_u32 s31, s13, s21
	ds_read_b128 v[218:221], v152
	ds_read_b128 v[222:225], v152 offset:1024
	ds_read_b128 v[226:229], v152 offset:2048
	ds_read_b128 v[230:233], v152 offset:3072
	s_add_u32 m0, s32, 0x10000
	s_add_u32 s98, s30, 0x100
	s_addc_u32 s99, s31, 0
	global_load_lds_dwordx4 v253, s[98:99]
	s_add_u32 m0, s32, 0x12000
	s_nop 0
	global_load_lds_dwordx4 v252, s[98:99]
	s_setprio 1
	s_barrier
	s_waitcnt lgkmcnt(0)
	v_mfma_f32_16x16x32_bf16 v[92:95], v[186:189], v[218:221], v[92:95]
	v_mfma_f32_16x16x32_bf16 v[88:91], v[186:189], v[226:229], v[88:91]
	v_mfma_f32_16x16x32_bf16 v[84:87], v[194:197], v[218:221], v[84:87]
	v_mfma_f32_16x16x32_bf16 v[80:83], v[194:197], v[226:229], v[80:83]
	v_mfma_f32_16x16x32_bf16 v[76:79], v[202:205], v[218:221], v[76:79]
	v_mfma_f32_16x16x32_bf16 v[72:75], v[202:205], v[226:229], v[72:75]
	v_mfma_f32_16x16x32_bf16 v[68:71], v[210:213], v[218:221], v[68:71]
	v_mfma_f32_16x16x32_bf16 v[64:67], v[210:213], v[226:229], v[64:67]
	v_mfma_f32_16x16x32_bf16 v[92:95], v[190:193], v[222:225], v[92:95]
	v_mfma_f32_16x16x32_bf16 v[88:91], v[190:193], v[230:233], v[88:91]
	v_mfma_f32_16x16x32_bf16 v[84:87], v[198:201], v[222:225], v[84:87]
	v_mfma_f32_16x16x32_bf16 v[80:83], v[198:201], v[230:233], v[80:83]
	v_mfma_f32_16x16x32_bf16 v[76:79], v[206:209], v[222:225], v[76:79]
	v_mfma_f32_16x16x32_bf16 v[72:75], v[206:209], v[230:233], v[72:75]
	v_mfma_f32_16x16x32_bf16 v[68:71], v[214:217], v[222:225], v[68:71]
	v_mfma_f32_16x16x32_bf16 v[64:67], v[214:217], v[230:233], v[64:67]
	s_setprio 0
	s_barrier
	ds_read_b128 v[186:189], v135 offset:16384
	ds_read_b128 v[190:193], v135 offset:17408
	ds_read_b128 v[194:197], v156 offset:16384
	ds_read_b128 v[198:201], v156 offset:17408
	ds_read_b128 v[202:205], v157 offset:16384
	ds_read_b128 v[206:209], v157 offset:17408
	ds_read_b128 v[210:213], v158 offset:16384
	ds_read_b128 v[214:217], v158 offset:17408
	s_mov_b32 m0, s32
	s_add_u32 s98, s22, 0x100
	s_addc_u32 s99, s23, 0
	global_load_lds_dwordx4 v253, s[98:99]
	s_add_u32 m0, s32, 0x2000
	s_nop 0
	global_load_lds_dwordx4 v252, s[98:99]
	s_setprio 1
	s_barrier
	s_waitcnt lgkmcnt(0)
	v_mfma_f32_16x16x32_bf16 v[60:63], v[186:189], v[162:165], v[60:63]
	v_mfma_f32_16x16x32_bf16 v[56:59], v[186:189], v[178:181], v[56:59]
	v_mfma_f32_16x16x32_bf16 v[52:55], v[194:197], v[162:165], v[52:55]
	v_mfma_f32_16x16x32_bf16 v[48:51], v[194:197], v[178:181], v[48:51]
	v_mfma_f32_16x16x32_bf16 v[44:47], v[202:205], v[162:165], v[44:47]
	v_mfma_f32_16x16x32_bf16 v[40:43], v[202:205], v[178:181], v[40:43]
	v_mfma_f32_16x16x32_bf16 v[36:39], v[210:213], v[162:165], v[36:39]
	v_mfma_f32_16x16x32_bf16 v[32:35], v[210:213], v[178:181], v[32:35]
	v_mfma_f32_16x16x32_bf16 v[60:63], v[190:193], v[174:177], v[60:63]
	v_mfma_f32_16x16x32_bf16 v[56:59], v[190:193], v[182:185], v[56:59]
	v_mfma_f32_16x16x32_bf16 v[52:55], v[198:201], v[174:177], v[52:55]
	v_mfma_f32_16x16x32_bf16 v[48:51], v[198:201], v[182:185], v[48:51]
	v_mfma_f32_16x16x32_bf16 v[44:47], v[206:209], v[174:177], v[44:47]
	v_mfma_f32_16x16x32_bf16 v[40:43], v[206:209], v[182:185], v[40:43]
	v_mfma_f32_16x16x32_bf16 v[36:39], v[214:217], v[174:177], v[36:39]
	v_mfma_f32_16x16x32_bf16 v[32:35], v[214:217], v[182:185], v[32:35]
	s_setprio 0
	s_barrier
	s_add_u32 m0, s32, 0x14000
	s_add_u32 s98, s30, 0x40100
	s_addc_u32 s99, s31, 0
	global_load_lds_dwordx4 v253, s[98:99]
	s_add_u32 m0, s32, 0x16000
	s_nop 0
	global_load_lds_dwordx4 v252, s[98:99]
	s_waitcnt vmcnt(6)
	s_barrier
; #define LDA(dst, b, h)                                                                                    \
;   _Pragma("unroll") for (int m = 0; m < 4; ++m) _Pragma("unroll") for (int k = 0; k < 2; ++k)             \
;       dst[m][k] = *reinterpret_cast<const bf16x8*>((char*)SA(b, h) + lds_byte(wr * 64 + m * 16 + fr, k * 32 + fq * 8))
; #define LDB(dst, b, h)                                                                                    \
;   _Pragma("unroll") for (int n = 0; n < 2; ++n) _Pragma("unroll") for (int k = 0; k < 2; ++k)             \
;       dst[n][k] = *reinterpret_cast<const bf16x8*>((char*)SB(b, h) + lds_byte(wc * 32 + n * 16 + fr, k * 32 + fq * 8))
; #define WAIT_V(n) asm volatile("s_waitcnt vmcnt(" #n ")" ::: "memory")
; #define WAIT_L(n) asm volatile("s_waitcnt lgkmcnt(" #n ")" ::: "memory")
; #define BAR __builtin_amdgcn_s_barrier()
; #define SCHED __builtin_amdgcn_sched_barrier(0)
; template <int EPI> ...
;     ...
;     WAIT_V(6); BAR; MMA(1, 1, At, B1); BAR;
;     LDB(B0, 1, 0); SCHED; LDA(At, 1, 0); STAGE(SA(0, 1), A, brow + HALF, t + 2);
;     WAIT_L(8); BAR; WAIT_L(0); MMA(0, 0, At, B0); BAR; SCHED;
;     LDB(B1, 1, 1); STAGE(SB(1, 0), Bt, bcol, t + 3);
;     BAR; WAIT_L(0); MMA(0, 1, At, B1); BAR;
;     LDA(At, 1, 1); STAGE(SA(1, 0), A, brow, t + 3);
	s_setprio 1
	v_mfma_f32_16x16x32_bf16 v[28:31], v[186:189], v[218:221], v[28:31]
	v_mfma_f32_16x16x32_bf16 v[24:27], v[186:189], v[226:229], v[24:27]
	v_mfma_f32_16x16x32_bf16 v[20:23], v[194:197], v[218:221], v[20:23]
	v_mfma_f32_16x16x32_bf16 v[16:19], v[194:197], v[226:229], v[16:19]
	v_mfma_f32_16x16x32_bf16 v[12:15], v[202:205], v[218:221], v[12:15]
	v_mfma_f32_16x16x32_bf16 v[8:11], v[202:205], v[226:229], v[8:11]
	v_mfma_f32_16x16x32_bf16 v[4:7], v[210:213], v[218:221], v[4:7]
	v_mfma_f32_16x16x32_bf16 v[0:3], v[210:213], v[226:229], v[0:3]
	v_mfma_f32_16x16x32_bf16 v[28:31], v[190:193], v[222:225], v[28:31]
	v_mfma_f32_16x16x32_bf16 v[24:27], v[190:193], v[230:233], v[24:27]
	v_mfma_f32_16x16x32_bf16 v[20:23], v[198:201], v[222:225], v[20:23]
	v_mfma_f32_16x16x32_bf16 v[16:19], v[198:201], v[230:233], v[16:19]
	v_mfma_f32_16x16x32_bf16 v[12:15], v[206:209], v[222:225], v[12:15]
	v_mfma_f32_16x16x32_bf16 v[8:11], v[206:209], v[230:233], v[8:11]
	v_mfma_f32_16x16x32_bf16 v[4:7], v[214:217], v[222:225], v[4:7]
	v_mfma_f32_16x16x32_bf16 v[0:3], v[214:217], v[230:233], v[0:3]
	s_setprio 0
	s_barrier
	ds_read_b128 v[162:165], v140
	ds_read_b128 v[174:177], v140 offset:1024
	ds_read_b128 v[178:181], v140 offset:2048
	ds_read_b128 v[182:185], v140 offset:3072
	ds_read_b128 v[186:189], v135 offset:32768
	ds_read_b128 v[190:193], v135 offset:33792
	ds_read_b128 v[194:197], v156 offset:32768
	ds_read_b128 v[198:201], v156 offset:33792
	ds_read_b128 v[202:205], v157 offset:32768
	ds_read_b128 v[206:209], v157 offset:33792
	ds_read_b128 v[210:213], v158 offset:32768
	ds_read_b128 v[214:217], v158 offset:33792
	s_add_u32 m0, s32, 0x4000
	s_add_u32 s98, s22, 0x40100
	s_addc_u32 s99, s23, 0
	global_load_lds_dwordx4 v253, s[98:99]
	s_add_u32 m0, s32, 0x6000
	s_nop 0
	global_load_lds_dwordx4 v252, s[98:99]
	s_waitcnt lgkmcnt(8)
	s_setprio 1
	s_barrier
	s_waitcnt lgkmcnt(0)
	v_mfma_f32_16x16x32_bf16 v[124:127], v[186:189], v[162:165], v[124:127]
	v_mfma_f32_16x16x32_bf16 v[120:123], v[186:189], v[178:181], v[120:123]
	v_mfma_f32_16x16x32_bf16 v[116:119], v[194:197], v[162:165], v[116:119]
	v_mfma_f32_16x16x32_bf16 v[112:115], v[194:197], v[178:181], v[112:115]
	v_mfma_f32_16x16x32_bf16 v[108:111], v[202:205], v[162:165], v[108:111]
	v_mfma_f32_16x16x32_bf16 v[104:107], v[202:205], v[178:181], v[104:107]
	v_mfma_f32_16x16x32_bf16 v[100:103], v[210:213], v[162:165], v[100:103]
	v_mfma_f32_16x16x32_bf16 v[96:99], v[210:213], v[178:181], v[96:99]
	v_mfma_f32_16x16x32_bf16 v[124:127], v[190:193], v[174:177], v[124:127]
	v_mfma_f32_16x16x32_bf16 v[120:123], v[190:193], v[182:185], v[120:123]
	v_mfma_f32_16x16x32_bf16 v[116:119], v[198:201], v[174:177], v[116:119]
	v_mfma_f32_16x16x32_bf16 v[112:115], v[198:201], v[182:185], v[112:115]
	v_mfma_f32_16x16x32_bf16 v[108:111], v[206:209], v[174:177], v[108:111]
	v_mfma_f32_16x16x32_bf16 v[104:107], v[206:209], v[182:185], v[104:107]
	v_mfma_f32_16x16x32_bf16 v[100:103], v[214:217], v[174:177], v[100:103]
	v_mfma_f32_16x16x32_bf16 v[96:99], v[214:217], v[182:185], v[96:99]
	s_setprio 0
	s_barrier
	ds_read_b128 v[218:221], v137
	ds_read_b128 v[222:225], v137 offset:1024
	ds_read_b128 v[226:229], v137 offset:2048
	ds_read_b128 v[230:233], v137 offset:3072
	s_add_u32 m0, s32, 0x18000
	s_add_u32 s98, s30, 0x180
	s_addc_u32 s99, s31, 0
	global_load_lds_dwordx4 v253, s[98:99]
	s_add_u32 m0, s32, 0x1a000
	s_nop 0
	global_load_lds_dwordx4 v252, s[98:99]
	s_setprio 1
	s_barrier
	s_waitcnt lgkmcnt(0)
	v_mfma_f32_16x16x32_bf16 v[92:95], v[186:189], v[218:221], v[92:95]
	v_mfma_f32_16x16x32_bf16 v[88:91], v[186:189], v[226:229], v[88:91]
	v_mfma_f32_16x16x32_bf16 v[84:87], v[194:197], v[218:221], v[84:87]
	v_mfma_f32_16x16x32_bf16 v[80:83], v[194:197], v[226:229], v[80:83]
	v_mfma_f32_16x16x32_bf16 v[76:79], v[202:205], v[218:221], v[76:79]
	v_mfma_f32_16x16x32_bf16 v[72:75], v[202:205], v[226:229], v[72:75]
	v_mfma_f32_16x16x32_bf16 v[68:71], v[210:213], v[218:221], v[68:71]
	v_mfma_f32_16x16x32_bf16 v[64:67], v[210:213], v[226:229], v[64:67]
	v_mfma_f32_16x16x32_bf16 v[92:95], v[190:193], v[222:225], v[92:95]
	v_mfma_f32_16x16x32_bf16 v[88:91], v[190:193], v[230:233], v[88:91]
	v_mfma_f32_16x16x32_bf16 v[84:87], v[198:201], v[222:225], v[84:87]
	v_mfma_f32_16x16x32_bf16 v[80:83], v[198:201], v[230:233], v[80:83]
	v_mfma_f32_16x16x32_bf16 v[76:79], v[206:209], v[222:225], v[76:79]
	v_mfma_f32_16x16x32_bf16 v[72:75], v[206:209], v[230:233], v[72:75]
	v_mfma_f32_16x16x32_bf16 v[68:71], v[214:217], v[222:225], v[68:71]
	v_mfma_f32_16x16x32_bf16 v[64:67], v[214:217], v[230:233], v[64:67]
	s_setprio 0
	s_barrier
	ds_read_b128 v[186:189], v135 offset:49152
	ds_read_b128 v[190:193], v135 offset:50176
	ds_read_b128 v[194:197], v156 offset:49152
	ds_read_b128 v[198:201], v156 offset:50176
	ds_read_b128 v[202:205], v157 offset:49152
	ds_read_b128 v[206:209], v157 offset:50176
	ds_read_b128 v[210:213], v158 offset:49152
	ds_read_b128 v[214:217], v158 offset:50176
	s_add_u32 m0, s32, 0x8000
	s_add_u32 s98, s22, 0x180
	s_addc_u32 s99, s23, 0
	global_load_lds_dwordx4 v253, s[98:99]
	s_nop 0
	s_add_u32 m0, s32, 0xa000
	s_nop 0
	global_load_lds_dwordx4 v252, s[98:99]
	s_setprio 1
	s_barrier
; #define LDA(dst, b, h)                                                                                    \
;   _Pragma("unroll") for (int m = 0; m < 4; ++m) _Pragma("unroll") for (int k = 0; k < 2; ++k)             \
;       dst[m][k] = *reinterpret_cast<const bf16x8*>((char*)SA(b, h) + lds_byte(wr * 64 + m * 16 + fr, k * 32 + fq * 8))
; #define LDB(dst, b, h)                                                                                    \
;   _Pragma("unroll") for (int n = 0; n < 2; ++n) _Pragma("unroll") for (int k = 0; k < 2; ++k)             \
;       dst[n][k] = *reinterpret_cast<const bf16x8*>((char*)SB(b, h) + lds_byte(wc * 32 + n * 16 + fr, k * 32 + fq * 8))
; #define WAIT_V(n) asm volatile("s_waitcnt vmcnt(" #n ")" ::: "memory")
; #define WAIT_L(n) asm volatile("s_waitcnt lgkmcnt(" #n ")" ::: "memory")
; #define BAR __builtin_amdgcn_s_barrier()
; #define SCHED __builtin_amdgcn_sched_barrier(0)
; template <int EPI> ...
;     ...
;     BAR; WAIT_L(0); MMA(1, 0, At, B0); BAR; SCHED;
;     STAGE(SB(1, 1), Bt, bcol + HALF, t + 3);
;     WAIT_V(6); BAR; MMA(1, 1, At, B1); BAR;
;   }
;   {
;     LDB(B0, 0, 0); LDA(At, 0, 0); STAGE(SA(1, 1), A, brow + HALF, nt - 1);
;     BAR; WAIT_L(0); MMA(0, 0, At, B0); BAR;
;     LDB(B1, 0, 1); BAR; WAIT_L(0); MMA(0, 1, At, B1); BAR;
	s_waitcnt lgkmcnt(0)
	v_mfma_f32_16x16x32_bf16 v[60:63], v[186:189], v[162:165], v[60:63]
	v_mfma_f32_16x16x32_bf16 v[56:59], v[186:189], v[178:181], v[56:59]
	v_mfma_f32_16x16x32_bf16 v[52:55], v[194:197], v[162:165], v[52:55]
	v_mfma_f32_16x16x32_bf16 v[48:51], v[194:197], v[178:181], v[48:51]
	v_mfma_f32_16x16x32_bf16 v[44:47], v[202:205], v[162:165], v[44:47]
	v_mfma_f32_16x16x32_bf16 v[40:43], v[202:205], v[178:181], v[40:43]
	v_mfma_f32_16x16x32_bf16 v[36:39], v[210:213], v[162:165], v[36:39]
	v_mfma_f32_16x16x32_bf16 v[32:35], v[210:213], v[178:181], v[32:35]
	v_mfma_f32_16x16x32_bf16 v[60:63], v[190:193], v[174:177], v[60:63]
	v_mfma_f32_16x16x32_bf16 v[56:59], v[190:193], v[182:185], v[56:59]
	v_mfma_f32_16x16x32_bf16 v[52:55], v[198:201], v[174:177], v[52:55]
	v_mfma_f32_16x16x32_bf16 v[48:51], v[198:201], v[182:185], v[48:51]
	v_mfma_f32_16x16x32_bf16 v[44:47], v[206:209], v[174:177], v[44:47]
	v_mfma_f32_16x16x32_bf16 v[40:43], v[206:209], v[182:185], v[40:43]
	v_mfma_f32_16x16x32_bf16 v[36:39], v[214:217], v[174:177], v[36:39]
	v_mfma_f32_16x16x32_bf16 v[32:35], v[214:217], v[182:185], v[32:35]
	s_setprio 0
	s_barrier
	s_add_u32 m0, s32, 0x1c000
	s_add_u32 s98, s30, 0x40180
	s_addc_u32 s99, s31, 0
	global_load_lds_dwordx4 v253, s[98:99]
	s_add_u32 m0, s32, 0x1e000
	s_nop 0
	global_load_lds_dwordx4 v252, s[98:99]
	s_waitcnt vmcnt(6)
	s_barrier
	s_setprio 1
	v_mfma_f32_16x16x32_bf16 v[28:31], v[186:189], v[218:221], v[28:31]
	v_mfma_f32_16x16x32_bf16 v[24:27], v[186:189], v[226:229], v[24:27]
	v_mfma_f32_16x16x32_bf16 v[20:23], v[194:197], v[218:221], v[20:23]
	v_mfma_f32_16x16x32_bf16 v[16:19], v[194:197], v[226:229], v[16:19]
	v_mfma_f32_16x16x32_bf16 v[12:15], v[202:205], v[218:221], v[12:15]
	v_mfma_f32_16x16x32_bf16 v[8:11], v[202:205], v[226:229], v[8:11]
	v_mfma_f32_16x16x32_bf16 v[4:7], v[210:213], v[218:221], v[4:7]
	v_mfma_f32_16x16x32_bf16 v[0:3], v[210:213], v[226:229], v[0:3]
	v_mfma_f32_16x16x32_bf16 v[28:31], v[190:193], v[222:225], v[28:31]
	v_mfma_f32_16x16x32_bf16 v[24:27], v[190:193], v[230:233], v[24:27]
	v_mfma_f32_16x16x32_bf16 v[20:23], v[198:201], v[222:225], v[20:23]
	v_mfma_f32_16x16x32_bf16 v[16:19], v[198:201], v[230:233], v[16:19]
	v_mfma_f32_16x16x32_bf16 v[12:15], v[206:209], v[222:225], v[12:15]
	v_mfma_f32_16x16x32_bf16 v[8:11], v[206:209], v[230:233], v[8:11]
	v_mfma_f32_16x16x32_bf16 v[4:7], v[214:217], v[222:225], v[4:7]
	v_mfma_f32_16x16x32_bf16 v[0:3], v[214:217], v[230:233], v[0:3]
	s_setprio 0
	s_add_i32 s71, s71, 2
	s_add_u32 s20, s20, 0x100
	s_addc_u32 s21, s21, 0
	s_cmp_lt_u32 s71, 12
	s_barrier
	s_cbranch_scc1 .LBB0_1016
	ds_read_b128 v[142:145], v155
	ds_read_b128 v[162:165], v155 offset:1024
	ds_read_b128 v[174:177], v155 offset:2048
	ds_read_b128 v[178:181], v155 offset:3072
	ds_read_b128 v[182:185], v135
	ds_read_b128 v[186:189], v135 offset:1024
	ds_read_b128 v[190:193], v156
	ds_read_b128 v[194:197], v156 offset:1024
	ds_read_b128 v[198:201], v157
	ds_read_b128 v[202:205], v157 offset:1024
	ds_read_b128 v[206:209], v158
	ds_read_b128 v[210:213], v158 offset:1024
	v_mov_b32_e32 v129, v149
	v_lshl_add_u64 v[128:129], v[128:129], 1, s[18:19]
	s_mov_b64 s[14:15], 0x780
	v_readfirstlane_b32 s12, v160
	v_lshl_add_u64 v[128:129], v[128:129], 0, s[14:15]
	s_mov_b32 m0, s12
	v_mov_b32_e32 v131, v149
	global_load_lds_dwordx4 v[128:129], off
	v_readfirstlane_b32 s12, v159
	v_lshl_add_u64 v[128:129], v[130:131], 1, s[18:19]
	v_lshl_add_u64 v[128:129], v[128:129], 0, s[14:15]
	s_mov_b32 m0, s12
	s_nop 0
	global_load_lds_dwordx4 v[128:129], off
	s_setprio 1
	s_barrier
	s_waitcnt lgkmcnt(0)
	v_mfma_f32_16x16x32_bf16 v[124:127], v[182:185], v[142:145], v[124:127]
	v_mfma_f32_16x16x32_bf16 v[120:123], v[182:185], v[174:177], v[120:123]
	v_mfma_f32_16x16x32_bf16 v[116:119], v[190:193], v[142:145], v[116:119]
	v_mfma_f32_16x16x32_bf16 v[112:115], v[190:193], v[174:177], v[112:115]
	v_mfma_f32_16x16x32_bf16 v[108:111], v[198:201], v[142:145], v[108:111]
	v_mfma_f32_16x16x32_bf16 v[104:107], v[198:201], v[174:177], v[104:107]
	v_mfma_f32_16x16x32_bf16 v[96:99], v[206:209], v[174:177], v[96:99]
	v_mfma_f32_16x16x32_bf16 v[124:127], v[186:189], v[162:165], v[124:127]
	v_mfma_f32_16x16x32_bf16 v[120:123], v[186:189], v[178:181], v[120:123]
	v_mfma_f32_16x16x32_bf16 v[116:119], v[194:197], v[162:165], v[116:119]
	v_mfma_f32_16x16x32_bf16 v[112:115], v[194:197], v[178:181], v[112:115]
	v_mfma_f32_16x16x32_bf16 v[108:111], v[202:205], v[162:165], v[108:111]
	v_mfma_f32_16x16x32_bf16 v[104:107], v[202:205], v[178:181], v[104:107]
	v_mfma_f32_16x16x32_bf16 v[100:103], v[206:209], v[142:145], v[100:103]
	v_mfma_f32_16x16x32_bf16 v[96:99], v[210:213], v[178:181], v[96:99]
	v_mfma_f32_16x16x32_bf16 v[128:131], v[210:213], v[162:165], v[100:103]
	s_setprio 0
	s_barrier
	s_nop 3
	ds_read_b128 v[100:103], v152
	ds_read_b128 v[214:217], v152 offset:1024
	ds_read_b128 v[218:221], v152 offset:2048
	ds_read_b128 v[152:155], v152 offset:3072
	s_setprio 1
	s_barrier
	s_waitcnt lgkmcnt(0)
	v_mfma_f32_16x16x32_bf16 v[88:91], v[182:185], v[218:221], v[88:91]
	v_mfma_f32_16x16x32_bf16 v[92:95], v[182:185], v[100:103], v[92:95]
	v_mfma_f32_16x16x32_bf16 v[88:91], v[186:189], v[152:155], v[88:91]
	v_mfma_f32_16x16x32_bf16 v[84:87], v[190:193], v[100:103], v[84:87]
	v_mfma_f32_16x16x32_bf16 v[80:83], v[190:193], v[218:221], v[80:83]
	v_mfma_f32_16x16x32_bf16 v[76:79], v[198:201], v[100:103], v[76:79]
	v_mfma_f32_16x16x32_bf16 v[72:75], v[198:201], v[218:221], v[72:75]
	v_mfma_f32_16x16x32_bf16 v[68:71], v[206:209], v[100:103], v[68:71]
	v_mfma_f32_16x16x32_bf16 v[64:67], v[206:209], v[218:221], v[64:67]
	v_mfma_f32_16x16x32_bf16 v[222:225], v[186:189], v[214:217], v[92:95]
	v_mfma_f32_16x16x32_bf16 v[182:185], v[194:197], v[214:217], v[84:87]
	v_mfma_f32_16x16x32_bf16 v[186:189], v[194:197], v[152:155], v[80:83]
	v_mfma_f32_16x16x32_bf16 v[190:193], v[202:205], v[214:217], v[76:79]
	v_mfma_f32_16x16x32_bf16 v[194:197], v[202:205], v[152:155], v[72:75]
	v_mfma_f32_16x16x32_bf16 v[198:201], v[210:213], v[214:217], v[68:71]
	v_mfma_f32_16x16x32_bf16 v[202:205], v[210:213], v[152:155], v[64:67]
	s_setprio 0
	s_barrier
; #define LDA(dst, b, h)                                                                                    \
;   _Pragma("unroll") for (int m = 0; m < 4; ++m) _Pragma("unroll") for (int k = 0; k < 2; ++k)             \
;       dst[m][k] = *reinterpret_cast<const bf16x8*>((char*)SA(b, h) + lds_byte(wr * 64 + m * 16 + fr, k * 32 + fq * 8))
; #define LDB(dst, b, h)                                                                                    \
;   _Pragma("unroll") for (int n = 0; n < 2; ++n) _Pragma("unroll") for (int k = 0; k < 2; ++k)             \
;       dst[n][k] = *reinterpret_cast<const bf16x8*>((char*)SB(b, h) + lds_byte(wc * 32 + n * 16 + fr, k * 32 + fq * 8))
; #define WAIT_V(n) asm volatile("s_waitcnt vmcnt(" #n ")" ::: "memory")
; #define WAIT_L(n) asm volatile("s_waitcnt lgkmcnt(" #n ")" ::: "memory")
; #define BAR __builtin_amdgcn_s_barrier()
; template <int EPI> ...
;     ...
;     LDA(At, 0, 1); WAIT_V(4); BAR; WAIT_L(0); MMA(1, 0, At, B0); MMA(1, 1, At, B1); BAR;
;   }
;   {
;     LDB(B0, 1, 0); LDA(At, 1, 0); WAIT_V(2); BAR; WAIT_L(0); MMA(0, 0, At, B0); BAR;
	s_nop 0
	ds_read_b128 v[64:67], v135 offset:16384
	ds_read_b128 v[68:71], v135 offset:17408
	ds_read_b128 v[72:75], v156 offset:16384
	ds_read_b128 v[76:79], v156 offset:17408
	ds_read_b128 v[80:83], v157 offset:16384
	ds_read_b128 v[84:87], v157 offset:17408
	ds_read_b128 v[92:95], v158 offset:16384
	ds_read_b128 v[206:209], v158 offset:17408
	s_waitcnt vmcnt(4)
	s_setprio 1
	s_barrier
	s_waitcnt lgkmcnt(0)
	v_mfma_f32_16x16x32_bf16 v[60:63], v[64:67], v[142:145], v[60:63]
	v_mfma_f32_16x16x32_bf16 v[56:59], v[64:67], v[174:177], v[56:59]
	v_mfma_f32_16x16x32_bf16 v[52:55], v[72:75], v[142:145], v[52:55]
	v_mfma_f32_16x16x32_bf16 v[48:51], v[72:75], v[174:177], v[48:51]
	v_mfma_f32_16x16x32_bf16 v[44:47], v[80:83], v[142:145], v[44:47]
	v_mfma_f32_16x16x32_bf16 v[40:43], v[80:83], v[174:177], v[40:43]
	v_mfma_f32_16x16x32_bf16 v[36:39], v[92:95], v[142:145], v[36:39]
	v_mfma_f32_16x16x32_bf16 v[32:35], v[92:95], v[174:177], v[32:35]
	v_mfma_f32_16x16x32_bf16 v[60:63], v[68:71], v[162:165], v[60:63]
	v_mfma_f32_16x16x32_bf16 v[56:59], v[68:71], v[178:181], v[56:59]
	v_mfma_f32_16x16x32_bf16 v[52:55], v[76:79], v[162:165], v[52:55]
	v_mfma_f32_16x16x32_bf16 v[48:51], v[76:79], v[178:181], v[48:51]
	v_mfma_f32_16x16x32_bf16 v[44:47], v[84:87], v[162:165], v[44:47]
	v_mfma_f32_16x16x32_bf16 v[40:43], v[84:87], v[178:181], v[40:43]
	v_mfma_f32_16x16x32_bf16 v[36:39], v[206:209], v[162:165], v[36:39]
	v_mfma_f32_16x16x32_bf16 v[32:35], v[206:209], v[178:181], v[32:35]
	s_setprio 0
	s_setprio 1
	v_mfma_f32_16x16x32_bf16 v[28:31], v[64:67], v[100:103], v[28:31]
	v_mfma_f32_16x16x32_bf16 v[24:27], v[64:67], v[218:221], v[24:27]
	v_mfma_f32_16x16x32_bf16 v[20:23], v[72:75], v[100:103], v[20:23]
	v_mfma_f32_16x16x32_bf16 v[16:19], v[72:75], v[218:221], v[16:19]
	v_mfma_f32_16x16x32_bf16 v[12:15], v[80:83], v[100:103], v[12:15]
	v_mfma_f32_16x16x32_bf16 v[8:11], v[80:83], v[218:221], v[8:11]
	v_mfma_f32_16x16x32_bf16 v[4:7], v[92:95], v[100:103], v[4:7]
	v_mfma_f32_16x16x32_bf16 v[0:3], v[92:95], v[218:221], v[0:3]
	v_mfma_f32_16x16x32_bf16 v[142:145], v[68:71], v[214:217], v[28:31]
	v_mfma_f32_16x16x32_bf16 v[160:163], v[68:71], v[152:155], v[24:27]
	v_mfma_f32_16x16x32_bf16 v[164:167], v[76:79], v[214:217], v[20:23]
	v_mfma_f32_16x16x32_bf16 v[174:177], v[76:79], v[152:155], v[16:19]
	v_mfma_f32_16x16x32_bf16 v[178:181], v[84:87], v[214:217], v[12:15]
	v_mfma_f32_16x16x32_bf16 v[210:213], v[84:87], v[152:155], v[8:11]
	v_mfma_f32_16x16x32_bf16 v[214:217], v[206:209], v[214:217], v[4:7]
	v_mfma_f32_16x16x32_bf16 v[152:155], v[206:209], v[152:155], v[0:3]
	s_setprio 0
	s_barrier
	s_nop 0
	ds_read_b128 v[0:3], v140
	ds_read_b128 v[4:7], v140 offset:1024
	ds_read_b128 v[206:209], v140 offset:2048
	ds_read_b128 v[138:141], v140 offset:3072
	ds_read_b128 v[8:11], v135 offset:32768
	ds_read_b128 v[12:15], v135 offset:33792
	ds_read_b128 v[16:19], v156 offset:32768
	ds_read_b128 v[20:23], v156 offset:33792
	ds_read_b128 v[24:27], v157 offset:32768
	ds_read_b128 v[28:31], v157 offset:33792
	ds_read_b128 v[218:221], v158 offset:32768
	ds_read_b128 v[226:229], v158 offset:33792
	s_waitcnt vmcnt(2)
	s_setprio 1
	s_barrier
	s_waitcnt lgkmcnt(0)
	v_mfma_f32_16x16x32_bf16 v[64:67], v[8:11], v[0:3], v[124:127]
	v_mfma_f32_16x16x32_bf16 v[92:95], v[12:15], v[4:7], v[64:67]
	v_mfma_f32_16x16x32_bf16 v[64:67], v[8:11], v[206:209], v[120:123]
	v_mfma_f32_16x16x32_bf16 v[100:103], v[12:15], v[138:141], v[64:67]
	v_mfma_f32_16x16x32_bf16 v[64:67], v[16:19], v[0:3], v[116:119]
	v_mfma_f32_16x16x32_bf16 v[80:83], v[20:23], v[4:7], v[64:67]
	v_mfma_f32_16x16x32_bf16 v[64:67], v[16:19], v[206:209], v[112:115]
	v_mfma_f32_16x16x32_bf16 v[84:87], v[20:23], v[138:141], v[64:67]
	v_mfma_f32_16x16x32_bf16 v[64:67], v[24:27], v[0:3], v[108:111]
	v_mfma_f32_16x16x32_bf16 v[72:75], v[28:31], v[4:7], v[64:67]
	v_mfma_f32_16x16x32_bf16 v[64:67], v[24:27], v[206:209], v[104:107]
	v_mfma_f32_16x16x32_bf16 v[76:79], v[28:31], v[138:141], v[64:67]
	v_mfma_f32_16x16x32_bf16 v[64:67], v[218:221], v[0:3], v[128:131]
	v_mfma_f32_16x16x32_bf16 v[68:71], v[218:221], v[206:209], v[96:99]
	v_mfma_f32_16x16x32_bf16 v[64:67], v[226:229], v[4:7], v[64:67]
	v_mfma_f32_16x16x32_bf16 v[68:71], v[226:229], v[138:141], v[68:71]
	s_setprio 0
	s_barrier
; #define LDA(dst, b, h)                                                                                    \
;   _Pragma("unroll") for (int m = 0; m < 4; ++m) _Pragma("unroll") for (int k = 0; k < 2; ++k)             \
;       dst[m][k] = *reinterpret_cast<const bf16x8*>((char*)SA(b, h) + lds_byte(wr * 64 + m * 16 + fr, k * 32 + fq * 8))
; #define LDB(dst, b, h)                                                                                    \
;   _Pragma("unroll") for (int n = 0; n < 2; ++n) _Pragma("unroll") for (int k = 0; k < 2; ++k)             \
;       dst[n][k] = *reinterpret_cast<const bf16x8*>((char*)SB(b, h) + lds_byte(wc * 32 + n * 16 + fr, k * 32 + fq * 8))
; #define WAIT_V(n) asm volatile("s_waitcnt vmcnt(" #n ")" ::: "memory")
; #define WAIT_L(n) asm volatile("s_waitcnt lgkmcnt(" #n ")" ::: "memory")
; #define BAR __builtin_amdgcn_s_barrier()
; template <int EPI> ...
;     ...
;     LDB(B1, 1, 1); WAIT_V(0); BAR; WAIT_L(0); MMA(0, 1, At, B1); BAR;
;     LDA(At, 1, 1); BAR; WAIT_L(0); MMA(1, 0, At, B0); MMA(1, 1, At, B1); BAR;
;   }
;   if (wr == 0) BAR;
	ds_read_b128 v[128:131], v137
	ds_read_b128 v[230:233], v137 offset:1024
	ds_read_b128 v[234:237], v137 offset:2048
	ds_read_b128 v[238:241], v137 offset:3072
	s_waitcnt vmcnt(0)
	s_setprio 1
	s_barrier
	s_waitcnt lgkmcnt(0)
	v_mfma_f32_16x16x32_bf16 v[96:99], v[8:11], v[128:131], v[222:225]
	v_mfma_f32_16x16x32_bf16 v[8:11], v[8:11], v[234:237], v[88:91]
	v_mfma_f32_16x16x32_bf16 v[124:127], v[12:15], v[238:241], v[8:11]
	v_mfma_f32_16x16x32_bf16 v[8:11], v[16:19], v[128:131], v[182:185]
	v_mfma_f32_16x16x32_bf16 v[112:115], v[20:23], v[230:233], v[8:11]
	v_mfma_f32_16x16x32_bf16 v[8:11], v[16:19], v[234:237], v[186:189]
	v_mfma_f32_16x16x32_bf16 v[116:119], v[20:23], v[238:241], v[8:11]
	v_mfma_f32_16x16x32_bf16 v[8:11], v[24:27], v[128:131], v[190:193]
	v_mfma_f32_16x16x32_bf16 v[104:107], v[28:31], v[230:233], v[8:11]
	v_mfma_f32_16x16x32_bf16 v[8:11], v[24:27], v[234:237], v[194:197]
	v_mfma_f32_16x16x32_bf16 v[108:111], v[28:31], v[238:241], v[8:11]
	v_mfma_f32_16x16x32_bf16 v[8:11], v[218:221], v[128:131], v[198:201]
	v_mfma_f32_16x16x32_bf16 v[88:91], v[226:229], v[230:233], v[8:11]
	v_mfma_f32_16x16x32_bf16 v[8:11], v[218:221], v[234:237], v[202:205]
	v_mfma_f32_16x16x32_bf16 v[120:123], v[12:15], v[230:233], v[96:99]
	v_mfma_f32_16x16x32_bf16 v[96:99], v[226:229], v[238:241], v[8:11]
	s_setprio 0
	s_barrier
	ds_read_b128 v[182:185], v135 offset:49152
	ds_read_b128 v[134:137], v135 offset:50176
	ds_read_b128 v[186:189], v156 offset:49152
	ds_read_b128 v[190:193], v156 offset:50176
	ds_read_b128 v[194:197], v157 offset:49152
	ds_read_b128 v[198:201], v157 offset:50176
	ds_read_b128 v[202:205], v158 offset:49152
	ds_read_b128 v[156:159], v158 offset:50176
	s_setprio 1
	s_barrier
	s_waitcnt lgkmcnt(0)
	v_mfma_f32_16x16x32_bf16 v[8:11], v[182:185], v[0:3], v[60:63]
	v_mfma_f32_16x16x32_bf16 v[24:27], v[134:137], v[4:7], v[8:11]
	v_mfma_f32_16x16x32_bf16 v[8:11], v[182:185], v[206:209], v[56:59]
	v_mfma_f32_16x16x32_bf16 v[28:31], v[134:137], v[138:141], v[8:11]
	v_mfma_f32_16x16x32_bf16 v[8:11], v[186:189], v[0:3], v[52:55]
	v_mfma_f32_16x16x32_bf16 v[16:19], v[190:193], v[4:7], v[8:11]
	v_mfma_f32_16x16x32_bf16 v[8:11], v[186:189], v[206:209], v[48:51]
	v_mfma_f32_16x16x32_bf16 v[20:23], v[190:193], v[138:141], v[8:11]
	v_mfma_f32_16x16x32_bf16 v[8:11], v[194:197], v[0:3], v[44:47]
	v_mfma_f32_16x16x32_bf16 v[0:3], v[202:205], v[0:3], v[36:39]
	v_mfma_f32_16x16x32_bf16 v[8:11], v[198:201], v[4:7], v[8:11]
	v_mfma_f32_16x16x32_bf16 v[12:15], v[194:197], v[206:209], v[40:43]
	v_mfma_f32_16x16x32_bf16 v[0:3], v[156:159], v[4:7], v[0:3]
	v_mfma_f32_16x16x32_bf16 v[4:7], v[202:205], v[206:209], v[32:35]
	v_mfma_f32_16x16x32_bf16 v[12:15], v[198:201], v[138:141], v[12:15]
	v_mfma_f32_16x16x32_bf16 v[4:7], v[156:159], v[138:141], v[4:7]
	s_setprio 0
	s_setprio 1
	v_mfma_f32_16x16x32_bf16 v[32:35], v[182:185], v[128:131], v[142:145]
	v_mfma_f32_16x16x32_bf16 v[56:59], v[134:137], v[230:233], v[32:35]
	v_mfma_f32_16x16x32_bf16 v[32:35], v[182:185], v[234:237], v[160:163]
	v_mfma_f32_16x16x32_bf16 v[60:63], v[134:137], v[238:241], v[32:35]
	v_mfma_f32_16x16x32_bf16 v[32:35], v[186:189], v[128:131], v[164:167]
	v_mfma_f32_16x16x32_bf16 v[48:51], v[190:193], v[230:233], v[32:35]
	v_mfma_f32_16x16x32_bf16 v[32:35], v[186:189], v[234:237], v[174:177]
	v_mfma_f32_16x16x32_bf16 v[52:55], v[190:193], v[238:241], v[32:35]
	v_mfma_f32_16x16x32_bf16 v[32:35], v[194:197], v[128:131], v[178:181]
	v_mfma_f32_16x16x32_bf16 v[40:43], v[198:201], v[230:233], v[32:35]
	v_mfma_f32_16x16x32_bf16 v[32:35], v[194:197], v[234:237], v[210:213]
	v_mfma_f32_16x16x32_bf16 v[44:47], v[198:201], v[238:241], v[32:35]
	v_mfma_f32_16x16x32_bf16 v[32:35], v[202:205], v[128:131], v[214:217]
	v_mfma_f32_16x16x32_bf16 v[36:39], v[202:205], v[234:237], v[152:155]
	v_mfma_f32_16x16x32_bf16 v[32:35], v[156:159], v[230:233], v[32:35]
	v_mfma_f32_16x16x32_bf16 v[36:39], v[156:159], v[238:241], v[36:39]
	s_setprio 0
	s_cmpk_gt_u32 s34, 0xff
	s_barrier
	s_cbranch_scc1 .LBB0_1019
	s_barrier

; #define LDA(dst, b, h)                                                                                    \
;   _Pragma("unroll") for (int m = 0; m < 4; ++m) _Pragma("unroll") for (int k = 0; k < 2; ++k)             \
;       dst[m][k] = *reinterpret_cast<const bf16x8*>((char*)SA(b, h) + lds_byte(wr * 64 + m * 16 + fr, k * 32 + fq * 8))
; #define LDB(dst, b, h)                                                                                    \
;   _Pragma("unroll") for (int n = 0; n < 2; ++n) _Pragma("unroll") for (int k = 0; k < 2; ++k)             \
;       dst[n][k] = *reinterpret_cast<const bf16x8*>((char*)SB(b, h) + lds_byte(wc * 32 + n * 16 + fr, k * 32 + fq * 8))
; #define WAIT_L(n) asm volatile("s_waitcnt lgkmcnt(" #n ")" ::: "memory")
; #define BAR __builtin_amdgcn_s_barrier()
; #define SCHED __builtin_amdgcn_sched_barrier(0)
; template <int EPI> ...
;     ...
;     LDB(B0, 0, 0); SCHED; LDA(At, 0, 0); STAGE(SA(1, 1), A, brow + HALF, t + 1);
;     WAIT_L(8); BAR; WAIT_L(0); MMA(0, 0, At, B0); BAR; SCHED;
;     LDB(B1, 0, 1); STAGE(SB(0, 0), Bt, bcol, t + 2);
;     BAR; WAIT_L(0); MMA(0, 1, At, B1); BAR;
;     LDA(At, 0, 1); STAGE(SA(0, 0), A, brow, t + 2);
;     BAR; WAIT_L(0); MMA(1, 0, At, B0); BAR; SCHED;
.LBB0_1117:
	ds_read_b128 v[162:165], v155
	ds_read_b128 v[178:181], v155 offset:1024
	ds_read_b128 v[182:185], v155 offset:2048
	ds_read_b128 v[186:189], v155 offset:3072
	s_add_u32 s22, s4, s8
	v_add_u32_e32 v156, s66, v154
	v_add_u32_e32 v157, s67, v154
	v_add_u32_e32 v158, s68, v154
	v_mov_b32_e32 v148, v128
	s_addc_u32 s23, s5, s9
	ds_read_b128 v[190:193], v134
	ds_read_b128 v[194:197], v134 offset:1024
	ds_read_b128 v[198:201], v156
	ds_read_b128 v[202:205], v156 offset:1024
	ds_read_b128 v[206:209], v157
	ds_read_b128 v[210:213], v157 offset:1024
	ds_read_b128 v[214:217], v158
	ds_read_b128 v[218:221], v158 offset:1024
	v_add_u32_e32 v159, 0xe000, v129
	v_lshl_add_u64 v[160:161], v[148:149], 1, s[22:23]
	v_lshl_add_u64 v[166:167], v[160:161], 0, s[48:49]
	v_add_u32_e32 v160, 0xc000, v129
	v_mov_b32_e32 v148, v130
	v_readfirstlane_b32 s30, v160
	s_mov_b32 m0, s30
	v_readfirstlane_b32 s30, v159
	global_load_lds_dwordx4 v[166:167], off
	s_mov_b32 m0, s30
	v_lshl_add_u64 v[166:167], v[148:149], 1, s[22:23]
	v_lshl_add_u64 v[166:167], v[166:167], 0, s[48:49]
	global_load_lds_dwordx4 v[166:167], off
	s_waitcnt lgkmcnt(8)
	s_setprio 1
	s_barrier
	s_waitcnt lgkmcnt(0)
	v_mfma_f32_16x16x32_bf16 v[124:127], v[190:193], v[162:165], v[124:127]
	v_mfma_f32_16x16x32_bf16 v[120:123], v[190:193], v[182:185], v[120:123]
	v_mfma_f32_16x16x32_bf16 v[116:119], v[198:201], v[162:165], v[116:119]
	v_mfma_f32_16x16x32_bf16 v[112:115], v[198:201], v[182:185], v[112:115]
	v_mfma_f32_16x16x32_bf16 v[108:111], v[206:209], v[162:165], v[108:111]
	v_mfma_f32_16x16x32_bf16 v[104:107], v[206:209], v[182:185], v[104:107]
	v_mfma_f32_16x16x32_bf16 v[100:103], v[214:217], v[162:165], v[100:103]
	v_mfma_f32_16x16x32_bf16 v[96:99], v[214:217], v[182:185], v[96:99]
	v_mfma_f32_16x16x32_bf16 v[124:127], v[194:197], v[178:181], v[124:127]
	v_mfma_f32_16x16x32_bf16 v[120:123], v[194:197], v[186:189], v[120:123]
	v_mfma_f32_16x16x32_bf16 v[116:119], v[202:205], v[178:181], v[116:119]
	v_mfma_f32_16x16x32_bf16 v[112:115], v[202:205], v[186:189], v[112:115]
	v_mfma_f32_16x16x32_bf16 v[108:111], v[210:213], v[178:181], v[108:111]
	v_mfma_f32_16x16x32_bf16 v[104:107], v[210:213], v[186:189], v[104:107]
	v_mfma_f32_16x16x32_bf16 v[100:103], v[218:221], v[178:181], v[100:103]
	v_mfma_f32_16x16x32_bf16 v[96:99], v[218:221], v[186:189], v[96:99]
	s_setprio 0
	s_barrier
	s_add_u32 s30, s0, s8
	v_mov_b32_e32 v148, v128
	s_addc_u32 s31, s1, s9
	ds_read_b128 v[222:225], v152
	ds_read_b128 v[226:229], v152 offset:1024
	ds_read_b128 v[230:233], v152 offset:2048
	ds_read_b128 v[234:237], v152 offset:3072
	v_readfirstlane_b32 s70, v133
	v_lshl_add_u64 v[166:167], v[148:149], 1, s[30:31]
	v_lshl_add_u64 v[166:167], v[166:167], 0, s[50:51]
	s_mov_b32 m0, s70
	v_mov_b32_e32 v148, v130
	global_load_lds_dwordx4 v[166:167], off
	v_readfirstlane_b32 s70, v135
	v_lshl_add_u64 v[166:167], v[148:149], 1, s[30:31]
	v_lshl_add_u64 v[166:167], v[166:167], 0, s[50:51]
	s_mov_b32 m0, s70
	s_nop 0
	global_load_lds_dwordx4 v[166:167], off
	s_setprio 1
	s_barrier
	s_waitcnt lgkmcnt(0)
	v_mfma_f32_16x16x32_bf16 v[92:95], v[190:193], v[222:225], v[92:95]
	v_mfma_f32_16x16x32_bf16 v[88:91], v[190:193], v[230:233], v[88:91]
	v_mfma_f32_16x16x32_bf16 v[84:87], v[198:201], v[222:225], v[84:87]
	v_mfma_f32_16x16x32_bf16 v[80:83], v[198:201], v[230:233], v[80:83]
	v_mfma_f32_16x16x32_bf16 v[76:79], v[206:209], v[222:225], v[76:79]
	v_mfma_f32_16x16x32_bf16 v[72:75], v[206:209], v[230:233], v[72:75]
	v_mfma_f32_16x16x32_bf16 v[68:71], v[214:217], v[222:225], v[68:71]
	v_mfma_f32_16x16x32_bf16 v[64:67], v[214:217], v[230:233], v[64:67]
	v_mfma_f32_16x16x32_bf16 v[92:95], v[194:197], v[226:229], v[92:95]
	v_mfma_f32_16x16x32_bf16 v[88:91], v[194:197], v[234:237], v[88:91]
	v_mfma_f32_16x16x32_bf16 v[84:87], v[202:205], v[226:229], v[84:87]
	v_mfma_f32_16x16x32_bf16 v[80:83], v[202:205], v[234:237], v[80:83]
	v_mfma_f32_16x16x32_bf16 v[76:79], v[210:213], v[226:229], v[76:79]
	v_mfma_f32_16x16x32_bf16 v[72:75], v[210:213], v[234:237], v[72:75]
	v_mfma_f32_16x16x32_bf16 v[68:71], v[218:221], v[226:229], v[68:71]
	v_mfma_f32_16x16x32_bf16 v[64:67], v[218:221], v[234:237], v[64:67]
	s_setprio 0
	v_mov_b32_e32 v148, v128
	s_barrier
	ds_read_b128 v[190:193], v134 offset:16384
	ds_read_b128 v[194:197], v134 offset:17408
	ds_read_b128 v[198:201], v156 offset:16384
	ds_read_b128 v[202:205], v156 offset:17408
	ds_read_b128 v[206:209], v157 offset:16384
	ds_read_b128 v[210:213], v157 offset:17408
	ds_read_b128 v[214:217], v158 offset:16384
	ds_read_b128 v[218:221], v158 offset:17408
	v_readfirstlane_b32 s70, v129
	v_lshl_add_u64 v[166:167], v[148:149], 1, s[22:23]
	v_lshl_add_u64 v[166:167], v[166:167], 0, s[50:51]
	s_mov_b32 m0, s70
	v_mov_b32_e32 v148, v130
	global_load_lds_dwordx4 v[166:167], off
	v_readfirstlane_b32 s70, v131
	v_lshl_add_u64 v[166:167], v[148:149], 1, s[22:23]
	v_lshl_add_u64 v[166:167], v[166:167], 0, s[50:51]
	s_mov_b32 m0, s70
	s_nop 0
	global_load_lds_dwordx4 v[166:167], off
	s_setprio 1
	s_barrier
	s_waitcnt lgkmcnt(0)
	v_mfma_f32_16x16x32_bf16 v[60:63], v[190:193], v[162:165], v[60:63]
	v_mfma_f32_16x16x32_bf16 v[56:59], v[190:193], v[182:185], v[56:59]
	v_mfma_f32_16x16x32_bf16 v[52:55], v[198:201], v[162:165], v[52:55]
	v_mfma_f32_16x16x32_bf16 v[48:51], v[198:201], v[182:185], v[48:51]
	v_mfma_f32_16x16x32_bf16 v[44:47], v[206:209], v[162:165], v[44:47]
	v_mfma_f32_16x16x32_bf16 v[40:43], v[206:209], v[182:185], v[40:43]
	v_mfma_f32_16x16x32_bf16 v[36:39], v[214:217], v[162:165], v[36:39]
	v_mfma_f32_16x16x32_bf16 v[32:35], v[214:217], v[182:185], v[32:35]
	v_mfma_f32_16x16x32_bf16 v[60:63], v[194:197], v[178:181], v[60:63]
	v_mfma_f32_16x16x32_bf16 v[56:59], v[194:197], v[186:189], v[56:59]
	v_mfma_f32_16x16x32_bf16 v[52:55], v[202:205], v[178:181], v[52:55]
	v_mfma_f32_16x16x32_bf16 v[48:51], v[202:205], v[186:189], v[48:51]
	v_mfma_f32_16x16x32_bf16 v[44:47], v[210:213], v[178:181], v[44:47]
	v_mfma_f32_16x16x32_bf16 v[40:43], v[210:213], v[186:189], v[40:43]
	v_mfma_f32_16x16x32_bf16 v[36:39], v[218:221], v[178:181], v[36:39]
	v_mfma_f32_16x16x32_bf16 v[32:35], v[218:221], v[186:189], v[32:35]
	s_setprio 0
	s_barrier
; #define LDA(dst, b, h)                                                                                    \
;   _Pragma("unroll") for (int m = 0; m < 4; ++m) _Pragma("unroll") for (int k = 0; k < 2; ++k)             \
;       dst[m][k] = *reinterpret_cast<const bf16x8*>((char*)SA(b, h) + lds_byte(wr * 64 + m * 16 + fr, k * 32 + fq * 8))
; #define LDB(dst, b, h)                                                                                    \
;   _Pragma("unroll") for (int n = 0; n < 2; ++n) _Pragma("unroll") for (int k = 0; k < 2; ++k)             \
;       dst[n][k] = *reinterpret_cast<const bf16x8*>((char*)SB(b, h) + lds_byte(wc * 32 + n * 16 + fr, k * 32 + fq * 8))
; #define WAIT_V(n) asm volatile("s_waitcnt vmcnt(" #n ")" ::: "memory")
; #define WAIT_L(n) asm volatile("s_waitcnt lgkmcnt(" #n ")" ::: "memory")
; #define BAR __builtin_amdgcn_s_barrier()
; #define SCHED __builtin_amdgcn_sched_barrier(0)
; template <int EPI> ...
;     ...
;     STAGE(SB(0, 1), Bt, bcol + HALF, t + 2);
;     WAIT_V(6); BAR; MMA(1, 1, At, B1); BAR;
;     LDB(B0, 1, 0); SCHED; LDA(At, 1, 0); STAGE(SA(0, 1), A, brow + HALF, t + 2);
;     WAIT_L(8); BAR; WAIT_L(0); MMA(0, 0, At, B0); BAR; SCHED;
;     LDB(B1, 1, 1); STAGE(SB(1, 0), Bt, bcol, t + 3);
;     BAR; WAIT_L(0); MMA(0, 1, At, B1); BAR;
	v_mov_b32_e32 v148, v128
	v_readfirstlane_b32 s70, v138
	v_lshl_add_u64 v[162:163], v[148:149], 1, s[30:31]
	v_lshl_add_u64 v[162:163], v[162:163], 0, s[52:53]
	s_mov_b32 m0, s70
	v_mov_b32_e32 v148, v130
	global_load_lds_dwordx4 v[162:163], off
	v_readfirstlane_b32 s70, v139
	v_lshl_add_u64 v[162:163], v[148:149], 1, s[30:31]
	v_lshl_add_u64 v[162:163], v[162:163], 0, s[52:53]
	s_mov_b32 m0, s70
	s_nop 0
	global_load_lds_dwordx4 v[162:163], off
	s_waitcnt vmcnt(6)
	s_barrier
	s_setprio 1
	v_mfma_f32_16x16x32_bf16 v[28:31], v[190:193], v[222:225], v[28:31]
	v_mfma_f32_16x16x32_bf16 v[24:27], v[190:193], v[230:233], v[24:27]
	v_mfma_f32_16x16x32_bf16 v[20:23], v[198:201], v[222:225], v[20:23]
	v_mfma_f32_16x16x32_bf16 v[16:19], v[198:201], v[230:233], v[16:19]
	v_mfma_f32_16x16x32_bf16 v[12:15], v[206:209], v[222:225], v[12:15]
	v_mfma_f32_16x16x32_bf16 v[8:11], v[206:209], v[230:233], v[8:11]
	v_mfma_f32_16x16x32_bf16 v[4:7], v[214:217], v[222:225], v[4:7]
	v_mfma_f32_16x16x32_bf16 v[0:3], v[214:217], v[230:233], v[0:3]
	v_mfma_f32_16x16x32_bf16 v[28:31], v[194:197], v[226:229], v[28:31]
	v_mfma_f32_16x16x32_bf16 v[24:27], v[194:197], v[234:237], v[24:27]
	v_mfma_f32_16x16x32_bf16 v[20:23], v[202:205], v[226:229], v[20:23]
	v_mfma_f32_16x16x32_bf16 v[16:19], v[202:205], v[234:237], v[16:19]
	v_mfma_f32_16x16x32_bf16 v[12:15], v[210:213], v[226:229], v[12:15]
	v_mfma_f32_16x16x32_bf16 v[8:11], v[210:213], v[234:237], v[8:11]
	v_mfma_f32_16x16x32_bf16 v[4:7], v[218:221], v[226:229], v[4:7]
	v_mfma_f32_16x16x32_bf16 v[0:3], v[218:221], v[234:237], v[0:3]
	s_setprio 0
	s_barrier
	ds_read_b128 v[162:165], v140
	ds_read_b128 v[178:181], v140 offset:1024
	ds_read_b128 v[182:185], v140 offset:2048
	ds_read_b128 v[186:189], v140 offset:3072
	v_mov_b32_e32 v148, v128
	ds_read_b128 v[190:193], v134 offset:32768
	ds_read_b128 v[194:197], v134 offset:33792
	ds_read_b128 v[198:201], v156 offset:32768
	ds_read_b128 v[202:205], v156 offset:33792
	ds_read_b128 v[206:209], v157 offset:32768
	ds_read_b128 v[210:213], v157 offset:33792
	ds_read_b128 v[214:217], v158 offset:32768
	ds_read_b128 v[218:221], v158 offset:33792
	v_readfirstlane_b32 s70, v141
	v_lshl_add_u64 v[166:167], v[148:149], 1, s[22:23]
	v_lshl_add_u64 v[166:167], v[166:167], 0, s[52:53]
	s_mov_b32 m0, s70
	v_mov_b32_e32 v148, v130
	global_load_lds_dwordx4 v[166:167], off
	v_readfirstlane_b32 s70, v142
	v_lshl_add_u64 v[166:167], v[148:149], 1, s[22:23]
	v_lshl_add_u64 v[166:167], v[166:167], 0, s[52:53]
	s_mov_b32 m0, s70
	s_nop 0
	global_load_lds_dwordx4 v[166:167], off
	s_waitcnt lgkmcnt(8)
	s_setprio 1
	s_barrier
	s_waitcnt lgkmcnt(0)
	v_mfma_f32_16x16x32_bf16 v[124:127], v[190:193], v[162:165], v[124:127]
	v_mfma_f32_16x16x32_bf16 v[120:123], v[190:193], v[182:185], v[120:123]
	v_mfma_f32_16x16x32_bf16 v[116:119], v[198:201], v[162:165], v[116:119]
	v_mfma_f32_16x16x32_bf16 v[112:115], v[198:201], v[182:185], v[112:115]
	v_mfma_f32_16x16x32_bf16 v[108:111], v[206:209], v[162:165], v[108:111]
	v_mfma_f32_16x16x32_bf16 v[104:107], v[206:209], v[182:185], v[104:107]
	v_mfma_f32_16x16x32_bf16 v[100:103], v[214:217], v[162:165], v[100:103]
	v_mfma_f32_16x16x32_bf16 v[96:99], v[214:217], v[182:185], v[96:99]
	v_mfma_f32_16x16x32_bf16 v[124:127], v[194:197], v[178:181], v[124:127]
	v_mfma_f32_16x16x32_bf16 v[120:123], v[194:197], v[186:189], v[120:123]
	v_mfma_f32_16x16x32_bf16 v[116:119], v[202:205], v[178:181], v[116:119]
	v_mfma_f32_16x16x32_bf16 v[112:115], v[202:205], v[186:189], v[112:115]
	v_mfma_f32_16x16x32_bf16 v[108:111], v[210:213], v[178:181], v[108:111]
	v_mfma_f32_16x16x32_bf16 v[104:107], v[210:213], v[186:189], v[104:107]
	v_mfma_f32_16x16x32_bf16 v[100:103], v[218:221], v[178:181], v[100:103]
	v_mfma_f32_16x16x32_bf16 v[96:99], v[218:221], v[186:189], v[96:99]
	s_setprio 0
	s_barrier
	v_mov_b32_e32 v148, v128
	ds_read_b128 v[222:225], v137
	ds_read_b128 v[226:229], v137 offset:1024
	ds_read_b128 v[230:233], v137 offset:2048
	ds_read_b128 v[234:237], v137 offset:3072
	v_readfirstlane_b32 s70, v143
	v_lshl_add_u64 v[166:167], v[148:149], 1, s[30:31]
	v_lshl_add_u64 v[166:167], v[166:167], 0, s[54:55]
	s_mov_b32 m0, s70
	v_mov_b32_e32 v148, v130
	global_load_lds_dwordx4 v[166:167], off
	v_readfirstlane_b32 s70, v144
	v_lshl_add_u64 v[166:167], v[148:149], 1, s[30:31]
	v_lshl_add_u64 v[166:167], v[166:167], 0, s[54:55]
	s_mov_b32 m0, s70
	s_nop 0
	global_load_lds_dwordx4 v[166:167], off
	s_setprio 1
	s_barrier
	s_waitcnt lgkmcnt(0)
	v_mfma_f32_16x16x32_bf16 v[92:95], v[190:193], v[222:225], v[92:95]
	v_mfma_f32_16x16x32_bf16 v[88:91], v[190:193], v[230:233], v[88:91]
	v_mfma_f32_16x16x32_bf16 v[84:87], v[198:201], v[222:225], v[84:87]
	v_mfma_f32_16x16x32_bf16 v[80:83], v[198:201], v[230:233], v[80:83]
	v_mfma_f32_16x16x32_bf16 v[76:79], v[206:209], v[222:225], v[76:79]
	v_mfma_f32_16x16x32_bf16 v[72:75], v[206:209], v[230:233], v[72:75]
	v_mfma_f32_16x16x32_bf16 v[68:71], v[214:217], v[222:225], v[68:71]
	v_mfma_f32_16x16x32_bf16 v[64:67], v[214:217], v[230:233], v[64:67]
	v_mfma_f32_16x16x32_bf16 v[92:95], v[194:197], v[226:229], v[92:95]
	v_mfma_f32_16x16x32_bf16 v[88:91], v[194:197], v[234:237], v[88:91]
	v_mfma_f32_16x16x32_bf16 v[84:87], v[202:205], v[226:229], v[84:87]
	v_mfma_f32_16x16x32_bf16 v[80:83], v[202:205], v[234:237], v[80:83]
	v_mfma_f32_16x16x32_bf16 v[76:79], v[210:213], v[226:229], v[76:79]
	v_mfma_f32_16x16x32_bf16 v[72:75], v[210:213], v[234:237], v[72:75]
	v_mfma_f32_16x16x32_bf16 v[68:71], v[218:221], v[226:229], v[68:71]
	v_mfma_f32_16x16x32_bf16 v[64:67], v[218:221], v[234:237], v[64:67]
	s_setprio 0
	v_mov_b32_e32 v148, v128
	s_barrier
; #define LDA(dst, b, h)                                                                                    \
;   _Pragma("unroll") for (int m = 0; m < 4; ++m) _Pragma("unroll") for (int k = 0; k < 2; ++k)             \
;       dst[m][k] = *reinterpret_cast<const bf16x8*>((char*)SA(b, h) + lds_byte(wr * 64 + m * 16 + fr, k * 32 + fq * 8))
; #define LDB(dst, b, h)                                                                                    \
;   _Pragma("unroll") for (int n = 0; n < 2; ++n) _Pragma("unroll") for (int k = 0; k < 2; ++k)             \
;       dst[n][k] = *reinterpret_cast<const bf16x8*>((char*)SB(b, h) + lds_byte(wc * 32 + n * 16 + fr, k * 32 + fq * 8))
; #define WAIT_V(n) asm volatile("s_waitcnt vmcnt(" #n ")" ::: "memory")
; #define WAIT_L(n) asm volatile("s_waitcnt lgkmcnt(" #n ")" ::: "memory")
; #define BAR __builtin_amdgcn_s_barrier()
; #define SCHED __builtin_amdgcn_sched_barrier(0)
; template <int EPI> ...
;     ...
;     LDA(At, 1, 1); STAGE(SA(1, 0), A, brow, t + 3);
;     BAR; WAIT_L(0); MMA(1, 0, At, B0); BAR; SCHED;
;     STAGE(SB(1, 1), Bt, bcol + HALF, t + 3);
;     WAIT_V(6); BAR; MMA(1, 1, At, B1); BAR;
;   }
;   {
;     LDB(B0, 0, 0); LDA(At, 0, 0); STAGE(SA(1, 1), A, brow + HALF, nt - 1);
;     BAR; WAIT_L(0); MMA(0, 0, At, B0); BAR;
	ds_read_b128 v[190:193], v134 offset:49152
	ds_read_b128 v[194:197], v134 offset:50176
	ds_read_b128 v[198:201], v156 offset:49152
	ds_read_b128 v[202:205], v156 offset:50176
	ds_read_b128 v[206:209], v157 offset:49152
	ds_read_b128 v[210:213], v157 offset:50176
	ds_read_b128 v[214:217], v158 offset:49152
	ds_read_b128 v[218:221], v158 offset:50176
	v_readfirstlane_b32 s70, v145
	v_lshl_add_u64 v[166:167], v[148:149], 1, s[22:23]
	v_lshl_add_u64 v[166:167], v[166:167], 0, s[54:55]
	s_mov_b32 m0, s70
	v_mov_b32_e32 v148, v130
	global_load_lds_dwordx4 v[166:167], off
	s_nop 0
	v_lshl_add_u64 v[166:167], v[148:149], 1, s[22:23]
	v_readfirstlane_b32 s22, v146
	v_lshl_add_u64 v[166:167], v[166:167], 0, s[54:55]
	s_mov_b32 m0, s22
	s_nop 0
	global_load_lds_dwordx4 v[166:167], off
	s_setprio 1
	s_barrier
	s_waitcnt lgkmcnt(0)
	v_mfma_f32_16x16x32_bf16 v[60:63], v[190:193], v[162:165], v[60:63]
	v_mfma_f32_16x16x32_bf16 v[56:59], v[190:193], v[182:185], v[56:59]
	v_mfma_f32_16x16x32_bf16 v[52:55], v[198:201], v[162:165], v[52:55]
	v_mfma_f32_16x16x32_bf16 v[48:51], v[198:201], v[182:185], v[48:51]
	v_mfma_f32_16x16x32_bf16 v[44:47], v[206:209], v[162:165], v[44:47]
	v_mfma_f32_16x16x32_bf16 v[40:43], v[206:209], v[182:185], v[40:43]
	v_mfma_f32_16x16x32_bf16 v[36:39], v[214:217], v[162:165], v[36:39]
	v_mfma_f32_16x16x32_bf16 v[32:35], v[214:217], v[182:185], v[32:35]
	v_mfma_f32_16x16x32_bf16 v[60:63], v[194:197], v[178:181], v[60:63]
	v_mfma_f32_16x16x32_bf16 v[56:59], v[194:197], v[186:189], v[56:59]
	v_mfma_f32_16x16x32_bf16 v[52:55], v[202:205], v[178:181], v[52:55]
	v_mfma_f32_16x16x32_bf16 v[48:51], v[202:205], v[186:189], v[48:51]
	v_mfma_f32_16x16x32_bf16 v[44:47], v[210:213], v[178:181], v[44:47]
	v_mfma_f32_16x16x32_bf16 v[40:43], v[210:213], v[186:189], v[40:43]
	v_mfma_f32_16x16x32_bf16 v[36:39], v[218:221], v[178:181], v[36:39]
	v_mfma_f32_16x16x32_bf16 v[32:35], v[218:221], v[186:189], v[32:35]
	s_setprio 0
	s_barrier
	v_mov_b32_e32 v148, v128
	v_readfirstlane_b32 s22, v147
	v_lshl_add_u64 v[162:163], v[148:149], 1, s[30:31]
	v_lshl_add_u64 v[162:163], v[162:163], 0, s[56:57]
	s_mov_b32 m0, s22
	v_mov_b32_e32 v148, v130
	global_load_lds_dwordx4 v[162:163], off
	v_readfirstlane_b32 s22, v153
	v_lshl_add_u64 v[162:163], v[148:149], 1, s[30:31]
	v_lshl_add_u64 v[162:163], v[162:163], 0, s[56:57]
	s_mov_b32 m0, s22
	s_nop 0
	global_load_lds_dwordx4 v[162:163], off
	s_waitcnt vmcnt(6)
	s_barrier
	s_setprio 1
	v_mfma_f32_16x16x32_bf16 v[28:31], v[190:193], v[222:225], v[28:31]
	v_mfma_f32_16x16x32_bf16 v[24:27], v[190:193], v[230:233], v[24:27]
	v_mfma_f32_16x16x32_bf16 v[20:23], v[198:201], v[222:225], v[20:23]
	v_mfma_f32_16x16x32_bf16 v[16:19], v[198:201], v[230:233], v[16:19]
	v_mfma_f32_16x16x32_bf16 v[12:15], v[206:209], v[222:225], v[12:15]
	v_mfma_f32_16x16x32_bf16 v[8:11], v[206:209], v[230:233], v[8:11]
	v_mfma_f32_16x16x32_bf16 v[4:7], v[214:217], v[222:225], v[4:7]
	v_mfma_f32_16x16x32_bf16 v[0:3], v[214:217], v[230:233], v[0:3]
	v_mfma_f32_16x16x32_bf16 v[28:31], v[194:197], v[226:229], v[28:31]
	v_mfma_f32_16x16x32_bf16 v[24:27], v[194:197], v[234:237], v[24:27]
	v_mfma_f32_16x16x32_bf16 v[20:23], v[202:205], v[226:229], v[20:23]
	v_mfma_f32_16x16x32_bf16 v[16:19], v[202:205], v[234:237], v[16:19]
	v_mfma_f32_16x16x32_bf16 v[12:15], v[210:213], v[226:229], v[12:15]
	v_mfma_f32_16x16x32_bf16 v[8:11], v[210:213], v[234:237], v[8:11]
	v_mfma_f32_16x16x32_bf16 v[4:7], v[218:221], v[226:229], v[4:7]
	v_mfma_f32_16x16x32_bf16 v[0:3], v[218:221], v[234:237], v[0:3]
	s_setprio 0
	s_add_i32 s69, s69, 2
	s_add_u32 s8, s8, 0x100
	s_addc_u32 s9, s9, 0
	s_cmp_lt_u32 s69, 12
	s_barrier
	s_cbranch_scc1 .LBB0_1117
	ds_read_b128 v[142:145], v155
	ds_read_b128 v[162:165], v155 offset:1024
	ds_read_b128 v[178:181], v155 offset:2048
	ds_read_b128 v[182:185], v155 offset:3072
	ds_read_b128 v[186:189], v134
	ds_read_b128 v[190:193], v134 offset:1024
	ds_read_b128 v[194:197], v156
	ds_read_b128 v[198:201], v156 offset:1024
	ds_read_b128 v[202:205], v157
	ds_read_b128 v[206:209], v157 offset:1024
	ds_read_b128 v[210:213], v158
	ds_read_b128 v[214:217], v158 offset:1024
	v_mov_b32_e32 v129, v149
	v_lshl_add_u64 v[128:129], v[128:129], 1, s[6:7]
	s_mov_b64 s[4:5], 0x780
	v_readfirstlane_b32 s0, v160
	v_lshl_add_u64 v[128:129], v[128:129], 0, s[4:5]
	s_mov_b32 m0, s0
	v_mov_b32_e32 v131, v149
	global_load_lds_dwordx4 v[128:129], off
	v_readfirstlane_b32 s0, v159
	v_lshl_add_u64 v[128:129], v[130:131], 1, s[6:7]
	v_lshl_add_u64 v[128:129], v[128:129], 0, s[4:5]
	s_mov_b32 m0, s0
	s_nop 0
	global_load_lds_dwordx4 v[128:129], off
	s_setprio 1
	s_barrier
	s_waitcnt lgkmcnt(0)
	v_mfma_f32_16x16x32_bf16 v[124:127], v[186:189], v[142:145], v[124:127]
	v_mfma_f32_16x16x32_bf16 v[120:123], v[186:189], v[178:181], v[120:123]
	v_mfma_f32_16x16x32_bf16 v[116:119], v[194:197], v[142:145], v[116:119]
	v_mfma_f32_16x16x32_bf16 v[112:115], v[194:197], v[178:181], v[112:115]
	v_mfma_f32_16x16x32_bf16 v[108:111], v[202:205], v[142:145], v[108:111]
	v_mfma_f32_16x16x32_bf16 v[104:107], v[202:205], v[178:181], v[104:107]
	v_mfma_f32_16x16x32_bf16 v[100:103], v[210:213], v[142:145], v[100:103]
	v_mfma_f32_16x16x32_bf16 v[124:127], v[190:193], v[162:165], v[124:127]
	v_mfma_f32_16x16x32_bf16 v[120:123], v[190:193], v[182:185], v[120:123]
	v_mfma_f32_16x16x32_bf16 v[116:119], v[198:201], v[162:165], v[116:119]
	v_mfma_f32_16x16x32_bf16 v[112:115], v[198:201], v[182:185], v[112:115]
	v_mfma_f32_16x16x32_bf16 v[108:111], v[206:209], v[162:165], v[108:111]
	v_mfma_f32_16x16x32_bf16 v[104:107], v[206:209], v[182:185], v[104:107]
	v_mfma_f32_16x16x32_bf16 v[100:103], v[214:217], v[162:165], v[100:103]
	v_mfma_f32_16x16x32_bf16 v[96:99], v[210:213], v[178:181], v[96:99]
	v_mfma_f32_16x16x32_bf16 v[128:131], v[214:217], v[182:185], v[96:99]
	s_setprio 0
	s_barrier
; #define LDA(dst, b, h)                                                                                    \
;   _Pragma("unroll") for (int m = 0; m < 4; ++m) _Pragma("unroll") for (int k = 0; k < 2; ++k)             \
;       dst[m][k] = *reinterpret_cast<const bf16x8*>((char*)SA(b, h) + lds_byte(wr * 64 + m * 16 + fr, k * 32 + fq * 8))
; #define LDB(dst, b, h)                                                                                    \
;   _Pragma("unroll") for (int n = 0; n < 2; ++n) _Pragma("unroll") for (int k = 0; k < 2; ++k)             \
;       dst[n][k] = *reinterpret_cast<const bf16x8*>((char*)SB(b, h) + lds_byte(wc * 32 + n * 16 + fr, k * 32 + fq * 8))
; #define WAIT_V(n) asm volatile("s_waitcnt vmcnt(" #n ")" ::: "memory")
; #define WAIT_L(n) asm volatile("s_waitcnt lgkmcnt(" #n ")" ::: "memory")
; #define BAR __builtin_amdgcn_s_barrier()
; template <int EPI> ...
;     ...
;     LDB(B1, 0, 1); BAR; WAIT_L(0); MMA(0, 1, At, B1); BAR;
;     LDA(At, 0, 1); WAIT_V(4); BAR; WAIT_L(0); MMA(1, 0, At, B0); MMA(1, 1, At, B1); BAR;
;   }
;   {
;     LDB(B0, 1, 0); LDA(At, 1, 0); WAIT_V(2); BAR; WAIT_L(0); MMA(0, 0, At, B0); BAR;
	s_nop 4
	ds_read_b128 v[96:99], v152
	ds_read_b128 v[218:221], v152 offset:1024
	ds_read_b128 v[222:225], v152 offset:2048
	ds_read_b128 v[152:155], v152 offset:3072
	s_setprio 1
	s_barrier
	s_waitcnt lgkmcnt(0)
	v_mfma_f32_16x16x32_bf16 v[92:95], v[186:189], v[96:99], v[92:95]
	v_mfma_f32_16x16x32_bf16 v[92:95], v[190:193], v[218:221], v[92:95]
	v_mfma_f32_16x16x32_bf16 v[88:91], v[186:189], v[222:225], v[88:91]
	v_mfma_f32_16x16x32_bf16 v[84:87], v[194:197], v[96:99], v[84:87]
	v_mfma_f32_16x16x32_bf16 v[80:83], v[194:197], v[222:225], v[80:83]
	v_mfma_f32_16x16x32_bf16 v[76:79], v[202:205], v[96:99], v[76:79]
	v_mfma_f32_16x16x32_bf16 v[72:75], v[202:205], v[222:225], v[72:75]
	v_mfma_f32_16x16x32_bf16 v[68:71], v[210:213], v[96:99], v[68:71]
	v_mfma_f32_16x16x32_bf16 v[64:67], v[210:213], v[222:225], v[64:67]
	v_mfma_f32_16x16x32_bf16 v[186:189], v[190:193], v[152:155], v[88:91]
	v_mfma_f32_16x16x32_bf16 v[190:193], v[198:201], v[218:221], v[84:87]
	v_mfma_f32_16x16x32_bf16 v[194:197], v[198:201], v[152:155], v[80:83]
	v_mfma_f32_16x16x32_bf16 v[198:201], v[206:209], v[218:221], v[76:79]
	v_mfma_f32_16x16x32_bf16 v[202:205], v[206:209], v[152:155], v[72:75]
	v_mfma_f32_16x16x32_bf16 v[206:209], v[214:217], v[218:221], v[68:71]
	v_mfma_f32_16x16x32_bf16 v[210:213], v[214:217], v[152:155], v[64:67]
	s_setprio 0
	s_barrier
	s_nop 0
	ds_read_b128 v[64:67], v134 offset:16384
	ds_read_b128 v[68:71], v134 offset:17408
	ds_read_b128 v[72:75], v156 offset:16384
	ds_read_b128 v[76:79], v156 offset:17408
	ds_read_b128 v[80:83], v157 offset:16384
	ds_read_b128 v[84:87], v157 offset:17408
	ds_read_b128 v[88:91], v158 offset:16384
	ds_read_b128 v[214:217], v158 offset:17408
	s_waitcnt vmcnt(4)
	s_setprio 1
	s_barrier
	s_waitcnt lgkmcnt(0)
	v_mfma_f32_16x16x32_bf16 v[60:63], v[64:67], v[142:145], v[60:63]
	v_mfma_f32_16x16x32_bf16 v[56:59], v[64:67], v[178:181], v[56:59]
	v_mfma_f32_16x16x32_bf16 v[52:55], v[72:75], v[142:145], v[52:55]
	v_mfma_f32_16x16x32_bf16 v[48:51], v[72:75], v[178:181], v[48:51]
	v_mfma_f32_16x16x32_bf16 v[44:47], v[80:83], v[142:145], v[44:47]
	v_mfma_f32_16x16x32_bf16 v[40:43], v[80:83], v[178:181], v[40:43]
	v_mfma_f32_16x16x32_bf16 v[36:39], v[88:91], v[142:145], v[36:39]
	v_mfma_f32_16x16x32_bf16 v[32:35], v[88:91], v[178:181], v[32:35]
	v_mfma_f32_16x16x32_bf16 v[60:63], v[68:71], v[162:165], v[60:63]
	v_mfma_f32_16x16x32_bf16 v[56:59], v[68:71], v[182:185], v[56:59]
	v_mfma_f32_16x16x32_bf16 v[52:55], v[76:79], v[162:165], v[52:55]
	v_mfma_f32_16x16x32_bf16 v[48:51], v[76:79], v[182:185], v[48:51]
	v_mfma_f32_16x16x32_bf16 v[44:47], v[84:87], v[162:165], v[44:47]
	v_mfma_f32_16x16x32_bf16 v[40:43], v[84:87], v[182:185], v[40:43]
	v_mfma_f32_16x16x32_bf16 v[36:39], v[214:217], v[162:165], v[36:39]
	v_mfma_f32_16x16x32_bf16 v[32:35], v[214:217], v[182:185], v[32:35]
	s_setprio 0
	s_setprio 1
	v_mfma_f32_16x16x32_bf16 v[28:31], v[64:67], v[96:99], v[28:31]
	v_mfma_f32_16x16x32_bf16 v[24:27], v[64:67], v[222:225], v[24:27]
	v_mfma_f32_16x16x32_bf16 v[20:23], v[72:75], v[96:99], v[20:23]
	v_mfma_f32_16x16x32_bf16 v[16:19], v[72:75], v[222:225], v[16:19]
	v_mfma_f32_16x16x32_bf16 v[12:15], v[80:83], v[96:99], v[12:15]
	v_mfma_f32_16x16x32_bf16 v[8:11], v[80:83], v[222:225], v[8:11]
	v_mfma_f32_16x16x32_bf16 v[4:7], v[88:91], v[96:99], v[4:7]
	v_mfma_f32_16x16x32_bf16 v[0:3], v[88:91], v[222:225], v[0:3]
	v_mfma_f32_16x16x32_bf16 v[142:145], v[68:71], v[218:221], v[28:31]
	v_mfma_f32_16x16x32_bf16 v[160:163], v[68:71], v[152:155], v[24:27]
	v_mfma_f32_16x16x32_bf16 v[164:167], v[76:79], v[218:221], v[20:23]
	v_mfma_f32_16x16x32_bf16 v[178:181], v[76:79], v[152:155], v[16:19]
	v_mfma_f32_16x16x32_bf16 v[182:185], v[84:87], v[218:221], v[12:15]
	v_mfma_f32_16x16x32_bf16 v[226:229], v[84:87], v[152:155], v[8:11]
	v_mfma_f32_16x16x32_bf16 v[218:221], v[214:217], v[218:221], v[4:7]
	v_mfma_f32_16x16x32_bf16 v[152:155], v[214:217], v[152:155], v[0:3]
	s_setprio 0
	s_barrier
	s_nop 0
	ds_read_b128 v[0:3], v140
	ds_read_b128 v[4:7], v140 offset:1024
	ds_read_b128 v[214:217], v140 offset:2048
	ds_read_b128 v[138:141], v140 offset:3072
	ds_read_b128 v[8:11], v134 offset:32768
	ds_read_b128 v[12:15], v134 offset:33792
	ds_read_b128 v[16:19], v156 offset:32768
	ds_read_b128 v[20:23], v156 offset:33792
	ds_read_b128 v[24:27], v157 offset:32768
	ds_read_b128 v[28:31], v157 offset:33792
	ds_read_b128 v[222:225], v158 offset:32768
	ds_read_b128 v[230:233], v158 offset:33792
	s_waitcnt vmcnt(2)
	s_setprio 1
	s_barrier
; #define LDA(dst, b, h)                                                                                    \
;   _Pragma("unroll") for (int m = 0; m < 4; ++m) _Pragma("unroll") for (int k = 0; k < 2; ++k)             \
;       dst[m][k] = *reinterpret_cast<const bf16x8*>((char*)SA(b, h) + lds_byte(wr * 64 + m * 16 + fr, k * 32 + fq * 8))
; #define LDB(dst, b, h)                                                                                    \
;   _Pragma("unroll") for (int n = 0; n < 2; ++n) _Pragma("unroll") for (int k = 0; k < 2; ++k)             \
;       dst[n][k] = *reinterpret_cast<const bf16x8*>((char*)SB(b, h) + lds_byte(wc * 32 + n * 16 + fr, k * 32 + fq * 8))
; #define WAIT_V(n) asm volatile("s_waitcnt vmcnt(" #n ")" ::: "memory")
; #define WAIT_L(n) asm volatile("s_waitcnt lgkmcnt(" #n ")" ::: "memory")
; #define BAR __builtin_amdgcn_s_barrier()
; template <int EPI> ...
;     ...
;     LDB(B0, 1, 0); LDA(At, 1, 0); WAIT_V(2); BAR; WAIT_L(0); MMA(0, 0, At, B0); BAR;
;     LDB(B1, 1, 1); WAIT_V(0); BAR; WAIT_L(0); MMA(0, 1, At, B1); BAR;
;     LDA(At, 1, 1); BAR; WAIT_L(0); MMA(1, 0, At, B0); MMA(1, 1, At, B1); BAR;
;   }
;   if (wr == 0) BAR;
	s_waitcnt lgkmcnt(0)
	v_mfma_f32_16x16x32_bf16 v[64:67], v[8:11], v[0:3], v[124:127]
	v_mfma_f32_16x16x32_bf16 v[88:91], v[12:15], v[4:7], v[64:67]
	v_mfma_f32_16x16x32_bf16 v[64:67], v[8:11], v[214:217], v[120:123]
	v_mfma_f32_16x16x32_bf16 v[96:99], v[12:15], v[138:141], v[64:67]
	v_mfma_f32_16x16x32_bf16 v[64:67], v[16:19], v[0:3], v[116:119]
	v_mfma_f32_16x16x32_bf16 v[80:83], v[20:23], v[4:7], v[64:67]
	v_mfma_f32_16x16x32_bf16 v[64:67], v[16:19], v[214:217], v[112:115]
	v_mfma_f32_16x16x32_bf16 v[84:87], v[20:23], v[138:141], v[64:67]
	v_mfma_f32_16x16x32_bf16 v[64:67], v[24:27], v[0:3], v[108:111]
	v_mfma_f32_16x16x32_bf16 v[72:75], v[28:31], v[4:7], v[64:67]
	v_mfma_f32_16x16x32_bf16 v[64:67], v[24:27], v[214:217], v[104:107]
	v_mfma_f32_16x16x32_bf16 v[76:79], v[28:31], v[138:141], v[64:67]
	v_mfma_f32_16x16x32_bf16 v[64:67], v[222:225], v[0:3], v[100:103]
	v_mfma_f32_16x16x32_bf16 v[68:71], v[222:225], v[214:217], v[128:131]
	v_mfma_f32_16x16x32_bf16 v[64:67], v[230:233], v[4:7], v[64:67]
	v_mfma_f32_16x16x32_bf16 v[68:71], v[230:233], v[138:141], v[68:71]
	s_setprio 0
	s_barrier
	ds_read_b128 v[128:131], v137
	ds_read_b128 v[234:237], v137 offset:1024
	ds_read_b128 v[238:241], v137 offset:2048
	ds_read_b128 v[242:245], v137 offset:3072
	s_waitcnt vmcnt(0)
	s_setprio 1
	s_barrier
	s_waitcnt lgkmcnt(0)
	v_mfma_f32_16x16x32_bf16 v[92:95], v[8:11], v[128:131], v[92:95]
	v_mfma_f32_16x16x32_bf16 v[8:11], v[8:11], v[238:241], v[186:189]
	v_mfma_f32_16x16x32_bf16 v[124:127], v[12:15], v[242:245], v[8:11]
	v_mfma_f32_16x16x32_bf16 v[8:11], v[16:19], v[128:131], v[190:193]
	v_mfma_f32_16x16x32_bf16 v[112:115], v[20:23], v[234:237], v[8:11]
	v_mfma_f32_16x16x32_bf16 v[8:11], v[16:19], v[238:241], v[194:197]
	v_mfma_f32_16x16x32_bf16 v[116:119], v[20:23], v[242:245], v[8:11]
	v_mfma_f32_16x16x32_bf16 v[8:11], v[24:27], v[128:131], v[198:201]
	v_mfma_f32_16x16x32_bf16 v[104:107], v[28:31], v[234:237], v[8:11]
	v_mfma_f32_16x16x32_bf16 v[8:11], v[24:27], v[238:241], v[202:205]
	v_mfma_f32_16x16x32_bf16 v[108:111], v[28:31], v[242:245], v[8:11]
	v_mfma_f32_16x16x32_bf16 v[8:11], v[222:225], v[128:131], v[206:209]
	v_mfma_f32_16x16x32_bf16 v[120:123], v[12:15], v[234:237], v[92:95]
	v_mfma_f32_16x16x32_bf16 v[92:95], v[230:233], v[234:237], v[8:11]
	v_mfma_f32_16x16x32_bf16 v[8:11], v[222:225], v[238:241], v[210:213]
	v_mfma_f32_16x16x32_bf16 v[100:103], v[230:233], v[242:245], v[8:11]
	s_setprio 0
	s_barrier
	ds_read_b128 v[186:189], v134 offset:49152
	ds_read_b128 v[190:193], v134 offset:50176
	ds_read_b128 v[194:197], v156 offset:49152
	ds_read_b128 v[198:201], v156 offset:50176
	ds_read_b128 v[202:205], v157 offset:49152
	ds_read_b128 v[206:209], v157 offset:50176
	ds_read_b128 v[210:213], v158 offset:49152
	ds_read_b128 v[156:159], v158 offset:50176
	s_setprio 1
	s_barrier
	s_waitcnt lgkmcnt(0)
	v_mfma_f32_16x16x32_bf16 v[8:11], v[186:189], v[0:3], v[60:63]
	v_mfma_f32_16x16x32_bf16 v[24:27], v[190:193], v[4:7], v[8:11]
	v_mfma_f32_16x16x32_bf16 v[8:11], v[186:189], v[214:217], v[56:59]
	v_mfma_f32_16x16x32_bf16 v[28:31], v[190:193], v[138:141], v[8:11]
	v_mfma_f32_16x16x32_bf16 v[8:11], v[194:197], v[0:3], v[52:55]
	v_mfma_f32_16x16x32_bf16 v[16:19], v[198:201], v[4:7], v[8:11]
	v_mfma_f32_16x16x32_bf16 v[8:11], v[194:197], v[214:217], v[48:51]
	v_mfma_f32_16x16x32_bf16 v[20:23], v[198:201], v[138:141], v[8:11]
	v_mfma_f32_16x16x32_bf16 v[8:11], v[202:205], v[0:3], v[44:47]
	v_mfma_f32_16x16x32_bf16 v[0:3], v[210:213], v[0:3], v[36:39]
	v_mfma_f32_16x16x32_bf16 v[8:11], v[206:209], v[4:7], v[8:11]
	v_mfma_f32_16x16x32_bf16 v[12:15], v[202:205], v[214:217], v[40:43]
	v_mfma_f32_16x16x32_bf16 v[0:3], v[156:159], v[4:7], v[0:3]
	v_mfma_f32_16x16x32_bf16 v[4:7], v[210:213], v[214:217], v[32:35]
	v_mfma_f32_16x16x32_bf16 v[12:15], v[206:209], v[138:141], v[12:15]
	v_mfma_f32_16x16x32_bf16 v[4:7], v[156:159], v[138:141], v[4:7]
	s_setprio 0
	s_setprio 1
	v_mfma_f32_16x16x32_bf16 v[32:35], v[186:189], v[128:131], v[142:145]
	v_mfma_f32_16x16x32_bf16 v[56:59], v[190:193], v[234:237], v[32:35]
	v_mfma_f32_16x16x32_bf16 v[32:35], v[186:189], v[238:241], v[160:163]
	v_mfma_f32_16x16x32_bf16 v[60:63], v[190:193], v[242:245], v[32:35]
	v_mfma_f32_16x16x32_bf16 v[32:35], v[194:197], v[128:131], v[164:167]
	v_mfma_f32_16x16x32_bf16 v[48:51], v[198:201], v[234:237], v[32:35]
	v_mfma_f32_16x16x32_bf16 v[32:35], v[194:197], v[238:241], v[178:181]
	v_mfma_f32_16x16x32_bf16 v[52:55], v[198:201], v[242:245], v[32:35]
	v_mfma_f32_16x16x32_bf16 v[32:35], v[202:205], v[128:131], v[182:185]
	v_mfma_f32_16x16x32_bf16 v[40:43], v[206:209], v[234:237], v[32:35]
	v_mfma_f32_16x16x32_bf16 v[32:35], v[202:205], v[238:241], v[226:229]
	v_mfma_f32_16x16x32_bf16 v[44:47], v[206:209], v[242:245], v[32:35]
	v_mfma_f32_16x16x32_bf16 v[32:35], v[210:213], v[128:131], v[218:221]
	v_mfma_f32_16x16x32_bf16 v[36:39], v[210:213], v[238:241], v[152:155]
	v_mfma_f32_16x16x32_bf16 v[32:35], v[156:159], v[234:237], v[32:35]
	v_mfma_f32_16x16x32_bf16 v[36:39], v[156:159], v[242:245], v[36:39]
	s_setprio 0
	s_cmpk_gt_u32 s35, 0xff
	s_barrier
	s_cbranch_scc1 .LBB0_1120
	s_barrier

; #define LDA(dst, b, h)                                                                                    \
;   _Pragma("unroll") for (int m = 0; m < 4; ++m) _Pragma("unroll") for (int k = 0; k < 2; ++k)             \
;       dst[m][k] = *reinterpret_cast<const bf16x8*>((char*)SA(b, h) + lds_byte(wr * 64 + m * 16 + fr, k * 32 + fq * 8))
; #define LDB(dst, b, h)                                                                                    \
;   _Pragma("unroll") for (int n = 0; n < 2; ++n) _Pragma("unroll") for (int k = 0; k < 2; ++k)             \
;       dst[n][k] = *reinterpret_cast<const bf16x8*>((char*)SB(b, h) + lds_byte(wc * 32 + n * 16 + fr, k * 32 + fq * 8))
; #define WAIT_V(n) asm volatile("s_waitcnt vmcnt(" #n ")" ::: "memory")
; #define WAIT_L(n) asm volatile("s_waitcnt lgkmcnt(" #n ")" ::: "memory")
; #define BAR __builtin_amdgcn_s_barrier()
; #define SCHED __builtin_amdgcn_sched_barrier(0)
; template <int EPI> ...
;     ...
;     LDB(B0, 0, 0); SCHED; LDA(At, 0, 0); STAGE(SA(1, 1), A, brow + HALF, t + 1);
;     WAIT_L(8); BAR; WAIT_L(0); MMA(0, 0, At, B0); BAR; SCHED;
;     LDB(B1, 0, 1); STAGE(SB(0, 0), Bt, bcol, t + 2);
;     BAR; WAIT_L(0); MMA(0, 1, At, B1); BAR;
;     LDA(At, 0, 1); STAGE(SA(0, 0), A, brow, t + 2);
;     BAR; WAIT_L(0); MMA(1, 0, At, B0); BAR; SCHED;
;     STAGE(SB(0, 1), Bt, bcol + HALF, t + 2);
;     WAIT_V(6); BAR; MMA(1, 1, At, B1); BAR;
.LBB0_1666:
	ds_read_b128 v[162:165], v155
	ds_read_b128 v[178:181], v155 offset:1024
	ds_read_b128 v[182:185], v155 offset:2048
	ds_read_b128 v[186:189], v155 offset:3072
	s_add_u32 s20, s14, s18
	v_add_u32_e32 v156, s35, v154
	v_add_u32_e32 v157, s67, v154
	v_add_u32_e32 v158, s68, v154
	s_addc_u32 s21, s15, s19
	ds_read_b128 v[190:193], v135
	ds_read_b128 v[194:197], v135 offset:1024
	ds_read_b128 v[198:201], v156
	ds_read_b128 v[202:205], v156 offset:1024
	ds_read_b128 v[206:209], v157
	ds_read_b128 v[210:213], v157 offset:1024
	ds_read_b128 v[214:217], v158
	ds_read_b128 v[218:221], v158 offset:1024
	v_add_u32_e32 v159, 0xe000, v129
	v_add_u32_e32 v160, 0xc000, v129
	s_add_u32 m0, s32, 0xc000
	s_add_u32 s98, s20, 0x40080
	s_addc_u32 s99, s21, 0
	global_load_lds_dwordx4 v253, s[98:99]
	s_add_u32 m0, s32, 0xe000
	s_nop 0
	global_load_lds_dwordx4 v252, s[98:99]
	s_waitcnt lgkmcnt(8)
	s_setprio 1
	s_barrier
	s_waitcnt lgkmcnt(0)
	v_mfma_f32_16x16x32_bf16 v[124:127], v[190:193], v[162:165], v[124:127]
	v_mfma_f32_16x16x32_bf16 v[120:123], v[190:193], v[182:185], v[120:123]
	v_mfma_f32_16x16x32_bf16 v[116:119], v[198:201], v[162:165], v[116:119]
	v_mfma_f32_16x16x32_bf16 v[112:115], v[198:201], v[182:185], v[112:115]
	v_mfma_f32_16x16x32_bf16 v[108:111], v[206:209], v[162:165], v[108:111]
	v_mfma_f32_16x16x32_bf16 v[104:107], v[206:209], v[182:185], v[104:107]
	v_mfma_f32_16x16x32_bf16 v[100:103], v[214:217], v[162:165], v[100:103]
	v_mfma_f32_16x16x32_bf16 v[96:99], v[214:217], v[182:185], v[96:99]
	v_mfma_f32_16x16x32_bf16 v[124:127], v[194:197], v[178:181], v[124:127]
	v_mfma_f32_16x16x32_bf16 v[120:123], v[194:197], v[186:189], v[120:123]
	v_mfma_f32_16x16x32_bf16 v[116:119], v[202:205], v[178:181], v[116:119]
	v_mfma_f32_16x16x32_bf16 v[112:115], v[202:205], v[186:189], v[112:115]
	v_mfma_f32_16x16x32_bf16 v[108:111], v[210:213], v[178:181], v[108:111]
	v_mfma_f32_16x16x32_bf16 v[104:107], v[210:213], v[186:189], v[104:107]
	v_mfma_f32_16x16x32_bf16 v[100:103], v[218:221], v[178:181], v[100:103]
	v_mfma_f32_16x16x32_bf16 v[96:99], v[218:221], v[186:189], v[96:99]
	s_setprio 0
	s_barrier
	s_add_u32 s22, s12, s18
	s_addc_u32 s23, s13, s19
	ds_read_b128 v[222:225], v152
	ds_read_b128 v[226:229], v152 offset:1024
	ds_read_b128 v[230:233], v152 offset:2048
	ds_read_b128 v[234:237], v152 offset:3072
	s_add_u32 m0, s32, 0x10000
	s_add_u32 s98, s22, 0x100
	s_addc_u32 s99, s23, 0
	global_load_lds_dwordx4 v253, s[98:99]
	s_add_u32 m0, s32, 0x12000
	s_nop 0
	global_load_lds_dwordx4 v252, s[98:99]
	s_setprio 1
	s_barrier
	s_waitcnt lgkmcnt(0)
	v_mfma_f32_16x16x32_bf16 v[92:95], v[190:193], v[222:225], v[92:95]
	v_mfma_f32_16x16x32_bf16 v[88:91], v[190:193], v[230:233], v[88:91]
	v_mfma_f32_16x16x32_bf16 v[84:87], v[198:201], v[222:225], v[84:87]
	v_mfma_f32_16x16x32_bf16 v[80:83], v[198:201], v[230:233], v[80:83]
	v_mfma_f32_16x16x32_bf16 v[76:79], v[206:209], v[222:225], v[76:79]
	v_mfma_f32_16x16x32_bf16 v[72:75], v[206:209], v[230:233], v[72:75]
	v_mfma_f32_16x16x32_bf16 v[68:71], v[214:217], v[222:225], v[68:71]
	v_mfma_f32_16x16x32_bf16 v[64:67], v[214:217], v[230:233], v[64:67]
	v_mfma_f32_16x16x32_bf16 v[92:95], v[194:197], v[226:229], v[92:95]
	v_mfma_f32_16x16x32_bf16 v[88:91], v[194:197], v[234:237], v[88:91]
	v_mfma_f32_16x16x32_bf16 v[84:87], v[202:205], v[226:229], v[84:87]
	v_mfma_f32_16x16x32_bf16 v[80:83], v[202:205], v[234:237], v[80:83]
	v_mfma_f32_16x16x32_bf16 v[76:79], v[210:213], v[226:229], v[76:79]
	v_mfma_f32_16x16x32_bf16 v[72:75], v[210:213], v[234:237], v[72:75]
	v_mfma_f32_16x16x32_bf16 v[68:71], v[218:221], v[226:229], v[68:71]
	v_mfma_f32_16x16x32_bf16 v[64:67], v[218:221], v[234:237], v[64:67]
	s_setprio 0
	s_barrier
	ds_read_b128 v[190:193], v135 offset:16384
	ds_read_b128 v[194:197], v135 offset:17408
	ds_read_b128 v[198:201], v156 offset:16384
	ds_read_b128 v[202:205], v156 offset:17408
	ds_read_b128 v[206:209], v157 offset:16384
	ds_read_b128 v[210:213], v157 offset:17408
	ds_read_b128 v[214:217], v158 offset:16384
	ds_read_b128 v[218:221], v158 offset:17408
	s_mov_b32 m0, s32
	s_add_u32 s98, s20, 0x100
	s_addc_u32 s99, s21, 0
	global_load_lds_dwordx4 v253, s[98:99]
	s_add_u32 m0, s32, 0x2000
	s_nop 0
	global_load_lds_dwordx4 v252, s[98:99]
	s_setprio 1
	s_barrier
	s_waitcnt lgkmcnt(0)
	v_mfma_f32_16x16x32_bf16 v[60:63], v[190:193], v[162:165], v[60:63]
	v_mfma_f32_16x16x32_bf16 v[56:59], v[190:193], v[182:185], v[56:59]
	v_mfma_f32_16x16x32_bf16 v[52:55], v[198:201], v[162:165], v[52:55]
	v_mfma_f32_16x16x32_bf16 v[48:51], v[198:201], v[182:185], v[48:51]
	v_mfma_f32_16x16x32_bf16 v[44:47], v[206:209], v[162:165], v[44:47]
	v_mfma_f32_16x16x32_bf16 v[40:43], v[206:209], v[182:185], v[40:43]
	v_mfma_f32_16x16x32_bf16 v[36:39], v[214:217], v[162:165], v[36:39]
	v_mfma_f32_16x16x32_bf16 v[32:35], v[214:217], v[182:185], v[32:35]
	v_mfma_f32_16x16x32_bf16 v[60:63], v[194:197], v[178:181], v[60:63]
	v_mfma_f32_16x16x32_bf16 v[56:59], v[194:197], v[186:189], v[56:59]
	v_mfma_f32_16x16x32_bf16 v[52:55], v[202:205], v[178:181], v[52:55]
	v_mfma_f32_16x16x32_bf16 v[48:51], v[202:205], v[186:189], v[48:51]
	v_mfma_f32_16x16x32_bf16 v[44:47], v[210:213], v[178:181], v[44:47]
	v_mfma_f32_16x16x32_bf16 v[40:43], v[210:213], v[186:189], v[40:43]
	v_mfma_f32_16x16x32_bf16 v[36:39], v[218:221], v[178:181], v[36:39]
	v_mfma_f32_16x16x32_bf16 v[32:35], v[218:221], v[186:189], v[32:35]
	s_setprio 0
	s_barrier
	s_add_u32 m0, s32, 0x14000
	s_add_u32 s98, s22, 0x40100
	s_addc_u32 s99, s23, 0
	global_load_lds_dwordx4 v253, s[98:99]
	s_add_u32 m0, s32, 0x16000
	s_nop 0
	global_load_lds_dwordx4 v252, s[98:99]
	s_waitcnt vmcnt(6)
	s_barrier
; #define LDA(dst, b, h)                                                                                    \
;   _Pragma("unroll") for (int m = 0; m < 4; ++m) _Pragma("unroll") for (int k = 0; k < 2; ++k)             \
;       dst[m][k] = *reinterpret_cast<const bf16x8*>((char*)SA(b, h) + lds_byte(wr * 64 + m * 16 + fr, k * 32 + fq * 8))
; #define LDB(dst, b, h)                                                                                    \
;   _Pragma("unroll") for (int n = 0; n < 2; ++n) _Pragma("unroll") for (int k = 0; k < 2; ++k)             \
;       dst[n][k] = *reinterpret_cast<const bf16x8*>((char*)SB(b, h) + lds_byte(wc * 32 + n * 16 + fr, k * 32 + fq * 8))
; #define WAIT_V(n) asm volatile("s_waitcnt vmcnt(" #n ")" ::: "memory")
; #define WAIT_L(n) asm volatile("s_waitcnt lgkmcnt(" #n ")" ::: "memory")
; #define BAR __builtin_amdgcn_s_barrier()
; #define SCHED __builtin_amdgcn_sched_barrier(0)
; template <int EPI> ...
;     ...
;     WAIT_V(6); BAR; MMA(1, 1, At, B1); BAR;
;     LDB(B0, 1, 0); SCHED; LDA(At, 1, 0); STAGE(SA(0, 1), A, brow + HALF, t + 2);
;     WAIT_L(8); BAR; WAIT_L(0); MMA(0, 0, At, B0); BAR; SCHED;
;     LDB(B1, 1, 1); STAGE(SB(1, 0), Bt, bcol, t + 3);
;     BAR; WAIT_L(0); MMA(0, 1, At, B1); BAR;
;     LDA(At, 1, 1); STAGE(SA(1, 0), A, brow, t + 3);
	s_setprio 1
	v_mfma_f32_16x16x32_bf16 v[28:31], v[190:193], v[222:225], v[28:31]
	v_mfma_f32_16x16x32_bf16 v[24:27], v[190:193], v[230:233], v[24:27]
	v_mfma_f32_16x16x32_bf16 v[20:23], v[198:201], v[222:225], v[20:23]
	v_mfma_f32_16x16x32_bf16 v[16:19], v[198:201], v[230:233], v[16:19]
	v_mfma_f32_16x16x32_bf16 v[12:15], v[206:209], v[222:225], v[12:15]
	v_mfma_f32_16x16x32_bf16 v[8:11], v[206:209], v[230:233], v[8:11]
	v_mfma_f32_16x16x32_bf16 v[4:7], v[214:217], v[222:225], v[4:7]
	v_mfma_f32_16x16x32_bf16 v[0:3], v[214:217], v[230:233], v[0:3]
	v_mfma_f32_16x16x32_bf16 v[28:31], v[194:197], v[226:229], v[28:31]
	v_mfma_f32_16x16x32_bf16 v[24:27], v[194:197], v[234:237], v[24:27]
	v_mfma_f32_16x16x32_bf16 v[20:23], v[202:205], v[226:229], v[20:23]
	v_mfma_f32_16x16x32_bf16 v[16:19], v[202:205], v[234:237], v[16:19]
	v_mfma_f32_16x16x32_bf16 v[12:15], v[210:213], v[226:229], v[12:15]
	v_mfma_f32_16x16x32_bf16 v[8:11], v[210:213], v[234:237], v[8:11]
	v_mfma_f32_16x16x32_bf16 v[4:7], v[218:221], v[226:229], v[4:7]
	v_mfma_f32_16x16x32_bf16 v[0:3], v[218:221], v[234:237], v[0:3]
	s_setprio 0
	s_barrier
	ds_read_b128 v[162:165], v140
	ds_read_b128 v[178:181], v140 offset:1024
	ds_read_b128 v[182:185], v140 offset:2048
	ds_read_b128 v[186:189], v140 offset:3072
	ds_read_b128 v[190:193], v135 offset:32768
	ds_read_b128 v[194:197], v135 offset:33792
	ds_read_b128 v[198:201], v156 offset:32768
	ds_read_b128 v[202:205], v156 offset:33792
	ds_read_b128 v[206:209], v157 offset:32768
	ds_read_b128 v[210:213], v157 offset:33792
	ds_read_b128 v[214:217], v158 offset:32768
	ds_read_b128 v[218:221], v158 offset:33792
	s_add_u32 m0, s32, 0x4000
	s_add_u32 s98, s20, 0x40100
	s_addc_u32 s99, s21, 0
	global_load_lds_dwordx4 v253, s[98:99]
	s_add_u32 m0, s32, 0x6000
	s_nop 0
	global_load_lds_dwordx4 v252, s[98:99]
	s_waitcnt lgkmcnt(8)
	s_setprio 1
	s_barrier
	s_waitcnt lgkmcnt(0)
	v_mfma_f32_16x16x32_bf16 v[124:127], v[190:193], v[162:165], v[124:127]
	v_mfma_f32_16x16x32_bf16 v[120:123], v[190:193], v[182:185], v[120:123]
	v_mfma_f32_16x16x32_bf16 v[116:119], v[198:201], v[162:165], v[116:119]
	v_mfma_f32_16x16x32_bf16 v[112:115], v[198:201], v[182:185], v[112:115]
	v_mfma_f32_16x16x32_bf16 v[108:111], v[206:209], v[162:165], v[108:111]
	v_mfma_f32_16x16x32_bf16 v[104:107], v[206:209], v[182:185], v[104:107]
	v_mfma_f32_16x16x32_bf16 v[100:103], v[214:217], v[162:165], v[100:103]
	v_mfma_f32_16x16x32_bf16 v[96:99], v[214:217], v[182:185], v[96:99]
	v_mfma_f32_16x16x32_bf16 v[124:127], v[194:197], v[178:181], v[124:127]
	v_mfma_f32_16x16x32_bf16 v[120:123], v[194:197], v[186:189], v[120:123]
	v_mfma_f32_16x16x32_bf16 v[116:119], v[202:205], v[178:181], v[116:119]
	v_mfma_f32_16x16x32_bf16 v[112:115], v[202:205], v[186:189], v[112:115]
	v_mfma_f32_16x16x32_bf16 v[108:111], v[210:213], v[178:181], v[108:111]
	v_mfma_f32_16x16x32_bf16 v[104:107], v[210:213], v[186:189], v[104:107]
	v_mfma_f32_16x16x32_bf16 v[100:103], v[218:221], v[178:181], v[100:103]
	v_mfma_f32_16x16x32_bf16 v[96:99], v[218:221], v[186:189], v[96:99]
	s_setprio 0
	s_barrier
	ds_read_b128 v[222:225], v137
	ds_read_b128 v[226:229], v137 offset:1024
	ds_read_b128 v[230:233], v137 offset:2048
	ds_read_b128 v[234:237], v137 offset:3072
	s_add_u32 m0, s32, 0x18000
	s_add_u32 s98, s22, 0x180
	s_addc_u32 s99, s23, 0
	global_load_lds_dwordx4 v253, s[98:99]
	s_add_u32 m0, s32, 0x1a000
	s_nop 0
	global_load_lds_dwordx4 v252, s[98:99]
	s_setprio 1
	s_barrier
	s_waitcnt lgkmcnt(0)
	v_mfma_f32_16x16x32_bf16 v[92:95], v[190:193], v[222:225], v[92:95]
	v_mfma_f32_16x16x32_bf16 v[88:91], v[190:193], v[230:233], v[88:91]
	v_mfma_f32_16x16x32_bf16 v[84:87], v[198:201], v[222:225], v[84:87]
	v_mfma_f32_16x16x32_bf16 v[80:83], v[198:201], v[230:233], v[80:83]
	v_mfma_f32_16x16x32_bf16 v[76:79], v[206:209], v[222:225], v[76:79]
	v_mfma_f32_16x16x32_bf16 v[72:75], v[206:209], v[230:233], v[72:75]
	v_mfma_f32_16x16x32_bf16 v[68:71], v[214:217], v[222:225], v[68:71]
	v_mfma_f32_16x16x32_bf16 v[64:67], v[214:217], v[230:233], v[64:67]
	v_mfma_f32_16x16x32_bf16 v[92:95], v[194:197], v[226:229], v[92:95]
	v_mfma_f32_16x16x32_bf16 v[88:91], v[194:197], v[234:237], v[88:91]
	v_mfma_f32_16x16x32_bf16 v[84:87], v[202:205], v[226:229], v[84:87]
	v_mfma_f32_16x16x32_bf16 v[80:83], v[202:205], v[234:237], v[80:83]
	v_mfma_f32_16x16x32_bf16 v[76:79], v[210:213], v[226:229], v[76:79]
	v_mfma_f32_16x16x32_bf16 v[72:75], v[210:213], v[234:237], v[72:75]
	v_mfma_f32_16x16x32_bf16 v[68:71], v[218:221], v[226:229], v[68:71]
	v_mfma_f32_16x16x32_bf16 v[64:67], v[218:221], v[234:237], v[64:67]
	s_setprio 0
	s_barrier
	ds_read_b128 v[190:193], v135 offset:49152
	ds_read_b128 v[194:197], v135 offset:50176
	ds_read_b128 v[198:201], v156 offset:49152
	ds_read_b128 v[202:205], v156 offset:50176
	ds_read_b128 v[206:209], v157 offset:49152
	ds_read_b128 v[210:213], v157 offset:50176
	ds_read_b128 v[214:217], v158 offset:49152
	ds_read_b128 v[218:221], v158 offset:50176
	s_add_u32 m0, s32, 0x8000
	s_add_u32 s98, s20, 0x180
	s_addc_u32 s99, s21, 0
	global_load_lds_dwordx4 v253, s[98:99]
	s_nop 0
	s_add_u32 m0, s32, 0xa000
	s_nop 0
	global_load_lds_dwordx4 v252, s[98:99]
	s_setprio 1
	s_barrier
; #define LDA(dst, b, h)                                                                                    \
;   _Pragma("unroll") for (int m = 0; m < 4; ++m) _Pragma("unroll") for (int k = 0; k < 2; ++k)             \
;       dst[m][k] = *reinterpret_cast<const bf16x8*>((char*)SA(b, h) + lds_byte(wr * 64 + m * 16 + fr, k * 32 + fq * 8))
; #define LDB(dst, b, h)                                                                                    \
;   _Pragma("unroll") for (int n = 0; n < 2; ++n) _Pragma("unroll") for (int k = 0; k < 2; ++k)             \
;       dst[n][k] = *reinterpret_cast<const bf16x8*>((char*)SB(b, h) + lds_byte(wc * 32 + n * 16 + fr, k * 32 + fq * 8))
; #define WAIT_V(n) asm volatile("s_waitcnt vmcnt(" #n ")" ::: "memory")
; #define WAIT_L(n) asm volatile("s_waitcnt lgkmcnt(" #n ")" ::: "memory")
; #define BAR __builtin_amdgcn_s_barrier()
; #define SCHED __builtin_amdgcn_sched_barrier(0)
; template <int EPI> ...
;     ...
;     LDA(At, 1, 1); STAGE(SA(1, 0), A, brow, t + 3);
;     BAR; WAIT_L(0); MMA(1, 0, At, B0); BAR; SCHED;
;     STAGE(SB(1, 1), Bt, bcol + HALF, t + 3);
;     WAIT_V(6); BAR; MMA(1, 1, At, B1); BAR;
;   }
;   {
;     LDB(B0, 0, 0); LDA(At, 0, 0); STAGE(SA(1, 1), A, brow + HALF, nt - 1);
;     BAR; WAIT_L(0); MMA(0, 0, At, B0); BAR;
;     LDB(B1, 0, 1); BAR; WAIT_L(0); MMA(0, 1, At, B1); BAR;
;     LDA(At, 0, 1); WAIT_V(4); BAR; WAIT_L(0); MMA(1, 0, At, B0); MMA(1, 1, At, B1); BAR;
	s_waitcnt lgkmcnt(0)
	v_mfma_f32_16x16x32_bf16 v[60:63], v[190:193], v[162:165], v[60:63]
	v_mfma_f32_16x16x32_bf16 v[56:59], v[190:193], v[182:185], v[56:59]
	v_mfma_f32_16x16x32_bf16 v[52:55], v[198:201], v[162:165], v[52:55]
	v_mfma_f32_16x16x32_bf16 v[48:51], v[198:201], v[182:185], v[48:51]
	v_mfma_f32_16x16x32_bf16 v[44:47], v[206:209], v[162:165], v[44:47]
	v_mfma_f32_16x16x32_bf16 v[40:43], v[206:209], v[182:185], v[40:43]
	v_mfma_f32_16x16x32_bf16 v[36:39], v[214:217], v[162:165], v[36:39]
	v_mfma_f32_16x16x32_bf16 v[32:35], v[214:217], v[182:185], v[32:35]
	v_mfma_f32_16x16x32_bf16 v[60:63], v[194:197], v[178:181], v[60:63]
	v_mfma_f32_16x16x32_bf16 v[56:59], v[194:197], v[186:189], v[56:59]
	v_mfma_f32_16x16x32_bf16 v[52:55], v[202:205], v[178:181], v[52:55]
	v_mfma_f32_16x16x32_bf16 v[48:51], v[202:205], v[186:189], v[48:51]
	v_mfma_f32_16x16x32_bf16 v[44:47], v[210:213], v[178:181], v[44:47]
	v_mfma_f32_16x16x32_bf16 v[40:43], v[210:213], v[186:189], v[40:43]
	v_mfma_f32_16x16x32_bf16 v[36:39], v[218:221], v[178:181], v[36:39]
	v_mfma_f32_16x16x32_bf16 v[32:35], v[218:221], v[186:189], v[32:35]
	s_setprio 0
	s_barrier
	s_add_u32 m0, s32, 0x1c000
	s_add_u32 s98, s22, 0x40180
	s_addc_u32 s99, s23, 0
	global_load_lds_dwordx4 v253, s[98:99]
	s_add_u32 m0, s32, 0x1e000
	s_nop 0
	global_load_lds_dwordx4 v252, s[98:99]
	s_waitcnt vmcnt(6)
	s_barrier
	s_setprio 1
	v_mfma_f32_16x16x32_bf16 v[28:31], v[190:193], v[222:225], v[28:31]
	v_mfma_f32_16x16x32_bf16 v[24:27], v[190:193], v[230:233], v[24:27]
	v_mfma_f32_16x16x32_bf16 v[20:23], v[198:201], v[222:225], v[20:23]
	v_mfma_f32_16x16x32_bf16 v[16:19], v[198:201], v[230:233], v[16:19]
	v_mfma_f32_16x16x32_bf16 v[12:15], v[206:209], v[222:225], v[12:15]
	v_mfma_f32_16x16x32_bf16 v[8:11], v[206:209], v[230:233], v[8:11]
	v_mfma_f32_16x16x32_bf16 v[4:7], v[214:217], v[222:225], v[4:7]
	v_mfma_f32_16x16x32_bf16 v[0:3], v[214:217], v[230:233], v[0:3]
	v_mfma_f32_16x16x32_bf16 v[28:31], v[194:197], v[226:229], v[28:31]
	v_mfma_f32_16x16x32_bf16 v[24:27], v[194:197], v[234:237], v[24:27]
	v_mfma_f32_16x16x32_bf16 v[20:23], v[202:205], v[226:229], v[20:23]
	v_mfma_f32_16x16x32_bf16 v[16:19], v[202:205], v[234:237], v[16:19]
	v_mfma_f32_16x16x32_bf16 v[12:15], v[210:213], v[226:229], v[12:15]
	v_mfma_f32_16x16x32_bf16 v[8:11], v[210:213], v[234:237], v[8:11]
	v_mfma_f32_16x16x32_bf16 v[4:7], v[218:221], v[226:229], v[4:7]
	v_mfma_f32_16x16x32_bf16 v[0:3], v[218:221], v[234:237], v[0:3]
	s_setprio 0
	s_add_i32 s69, s69, 2
	s_add_u32 s18, s18, 0x100
	s_addc_u32 s19, s19, 0
	s_cmp_lt_u32 s69, 12
	s_barrier
	s_cbranch_scc1 .LBB0_1666
	ds_read_b128 v[142:145], v155
	ds_read_b128 v[162:165], v155 offset:1024
	ds_read_b128 v[178:181], v155 offset:2048
	ds_read_b128 v[182:185], v155 offset:3072
	ds_read_b128 v[186:189], v135
	ds_read_b128 v[190:193], v135 offset:1024
	ds_read_b128 v[194:197], v156
	ds_read_b128 v[198:201], v156 offset:1024
	ds_read_b128 v[202:205], v157
	ds_read_b128 v[206:209], v157 offset:1024
	ds_read_b128 v[210:213], v158
	ds_read_b128 v[214:217], v158 offset:1024
	v_mov_b32_e32 v129, v149
	v_lshl_add_u64 v[128:129], v[128:129], 1, s[16:17]
	s_mov_b64 s[14:15], 0x780
	v_readfirstlane_b32 s12, v160
	v_lshl_add_u64 v[128:129], v[128:129], 0, s[14:15]
	s_mov_b32 m0, s12
	v_mov_b32_e32 v131, v149
	global_load_lds_dwordx4 v[128:129], off
	v_readfirstlane_b32 s12, v159
	v_lshl_add_u64 v[128:129], v[130:131], 1, s[16:17]
	v_lshl_add_u64 v[128:129], v[128:129], 0, s[14:15]
	s_mov_b32 m0, s12
	s_nop 0
	global_load_lds_dwordx4 v[128:129], off
	s_setprio 1
	s_barrier
	s_waitcnt lgkmcnt(0)
	v_mfma_f32_16x16x32_bf16 v[124:127], v[186:189], v[142:145], v[124:127]
	v_mfma_f32_16x16x32_bf16 v[120:123], v[186:189], v[178:181], v[120:123]
	v_mfma_f32_16x16x32_bf16 v[116:119], v[194:197], v[142:145], v[116:119]
	v_mfma_f32_16x16x32_bf16 v[112:115], v[194:197], v[178:181], v[112:115]
	v_mfma_f32_16x16x32_bf16 v[108:111], v[202:205], v[142:145], v[108:111]
	v_mfma_f32_16x16x32_bf16 v[104:107], v[202:205], v[178:181], v[104:107]
	v_mfma_f32_16x16x32_bf16 v[96:99], v[210:213], v[178:181], v[96:99]
	v_mfma_f32_16x16x32_bf16 v[124:127], v[190:193], v[162:165], v[124:127]
	v_mfma_f32_16x16x32_bf16 v[120:123], v[190:193], v[182:185], v[120:123]
	v_mfma_f32_16x16x32_bf16 v[116:119], v[198:201], v[162:165], v[116:119]
	v_mfma_f32_16x16x32_bf16 v[112:115], v[198:201], v[182:185], v[112:115]
	v_mfma_f32_16x16x32_bf16 v[108:111], v[206:209], v[162:165], v[108:111]
	v_mfma_f32_16x16x32_bf16 v[104:107], v[206:209], v[182:185], v[104:107]
	v_mfma_f32_16x16x32_bf16 v[100:103], v[210:213], v[142:145], v[100:103]
	v_mfma_f32_16x16x32_bf16 v[96:99], v[214:217], v[182:185], v[96:99]
	v_mfma_f32_16x16x32_bf16 v[128:131], v[214:217], v[162:165], v[100:103]
	s_setprio 0
	s_barrier
	s_nop 3
	ds_read_b128 v[100:103], v152
	ds_read_b128 v[218:221], v152 offset:1024
	ds_read_b128 v[222:225], v152 offset:2048
	ds_read_b128 v[152:155], v152 offset:3072
	s_setprio 1
	s_barrier
	s_waitcnt lgkmcnt(0)
	v_mfma_f32_16x16x32_bf16 v[88:91], v[186:189], v[222:225], v[88:91]
	v_mfma_f32_16x16x32_bf16 v[92:95], v[186:189], v[100:103], v[92:95]
	v_mfma_f32_16x16x32_bf16 v[88:91], v[190:193], v[152:155], v[88:91]
	v_mfma_f32_16x16x32_bf16 v[84:87], v[194:197], v[100:103], v[84:87]
	v_mfma_f32_16x16x32_bf16 v[80:83], v[194:197], v[222:225], v[80:83]
	v_mfma_f32_16x16x32_bf16 v[76:79], v[202:205], v[100:103], v[76:79]
	v_mfma_f32_16x16x32_bf16 v[72:75], v[202:205], v[222:225], v[72:75]
	v_mfma_f32_16x16x32_bf16 v[68:71], v[210:213], v[100:103], v[68:71]
	v_mfma_f32_16x16x32_bf16 v[64:67], v[210:213], v[222:225], v[64:67]
	v_mfma_f32_16x16x32_bf16 v[226:229], v[190:193], v[218:221], v[92:95]
	v_mfma_f32_16x16x32_bf16 v[186:189], v[198:201], v[218:221], v[84:87]
	v_mfma_f32_16x16x32_bf16 v[190:193], v[198:201], v[152:155], v[80:83]
	v_mfma_f32_16x16x32_bf16 v[194:197], v[206:209], v[218:221], v[76:79]
	v_mfma_f32_16x16x32_bf16 v[198:201], v[206:209], v[152:155], v[72:75]
	v_mfma_f32_16x16x32_bf16 v[202:205], v[214:217], v[218:221], v[68:71]
	v_mfma_f32_16x16x32_bf16 v[206:209], v[214:217], v[152:155], v[64:67]
	s_setprio 0
	s_barrier
; #define LDA(dst, b, h)                                                                                    \
;   _Pragma("unroll") for (int m = 0; m < 4; ++m) _Pragma("unroll") for (int k = 0; k < 2; ++k)             \
;       dst[m][k] = *reinterpret_cast<const bf16x8*>((char*)SA(b, h) + lds_byte(wr * 64 + m * 16 + fr, k * 32 + fq * 8))
; #define LDB(dst, b, h)                                                                                    \
;   _Pragma("unroll") for (int n = 0; n < 2; ++n) _Pragma("unroll") for (int k = 0; k < 2; ++k)             \
;       dst[n][k] = *reinterpret_cast<const bf16x8*>((char*)SB(b, h) + lds_byte(wc * 32 + n * 16 + fr, k * 32 + fq * 8))
; #define WAIT_V(n) asm volatile("s_waitcnt vmcnt(" #n ")" ::: "memory")
; #define WAIT_L(n) asm volatile("s_waitcnt lgkmcnt(" #n ")" ::: "memory")
; #define BAR __builtin_amdgcn_s_barrier()
; template <int EPI> ...
;     ...
;     LDB(B1, 0, 1); BAR; WAIT_L(0); MMA(0, 1, At, B1); BAR;
;     LDA(At, 0, 1); WAIT_V(4); BAR; WAIT_L(0); MMA(1, 0, At, B0); MMA(1, 1, At, B1); BAR;
;   }
;   {
;     LDB(B0, 1, 0); LDA(At, 1, 0); WAIT_V(2); BAR; WAIT_L(0); MMA(0, 0, At, B0); BAR;
	s_nop 0
	ds_read_b128 v[64:67], v135 offset:16384
	ds_read_b128 v[68:71], v135 offset:17408
	ds_read_b128 v[72:75], v156 offset:16384
	ds_read_b128 v[76:79], v156 offset:17408
	ds_read_b128 v[80:83], v157 offset:16384
	ds_read_b128 v[84:87], v157 offset:17408
	ds_read_b128 v[92:95], v158 offset:16384
	ds_read_b128 v[210:213], v158 offset:17408
	s_waitcnt vmcnt(4)
	s_setprio 1
	s_barrier
	s_waitcnt lgkmcnt(0)
	v_mfma_f32_16x16x32_bf16 v[60:63], v[64:67], v[142:145], v[60:63]
	v_mfma_f32_16x16x32_bf16 v[56:59], v[64:67], v[178:181], v[56:59]
	v_mfma_f32_16x16x32_bf16 v[52:55], v[72:75], v[142:145], v[52:55]
	v_mfma_f32_16x16x32_bf16 v[48:51], v[72:75], v[178:181], v[48:51]
	v_mfma_f32_16x16x32_bf16 v[44:47], v[80:83], v[142:145], v[44:47]
	v_mfma_f32_16x16x32_bf16 v[40:43], v[80:83], v[178:181], v[40:43]
	v_mfma_f32_16x16x32_bf16 v[36:39], v[92:95], v[142:145], v[36:39]
	v_mfma_f32_16x16x32_bf16 v[32:35], v[92:95], v[178:181], v[32:35]
	v_mfma_f32_16x16x32_bf16 v[60:63], v[68:71], v[162:165], v[60:63]
	v_mfma_f32_16x16x32_bf16 v[56:59], v[68:71], v[182:185], v[56:59]
	v_mfma_f32_16x16x32_bf16 v[52:55], v[76:79], v[162:165], v[52:55]
	v_mfma_f32_16x16x32_bf16 v[48:51], v[76:79], v[182:185], v[48:51]
	v_mfma_f32_16x16x32_bf16 v[44:47], v[84:87], v[162:165], v[44:47]
	v_mfma_f32_16x16x32_bf16 v[40:43], v[84:87], v[182:185], v[40:43]
	v_mfma_f32_16x16x32_bf16 v[36:39], v[210:213], v[162:165], v[36:39]
	v_mfma_f32_16x16x32_bf16 v[32:35], v[210:213], v[182:185], v[32:35]
	s_setprio 0
	s_setprio 1
	v_mfma_f32_16x16x32_bf16 v[28:31], v[64:67], v[100:103], v[28:31]
	v_mfma_f32_16x16x32_bf16 v[24:27], v[64:67], v[222:225], v[24:27]
	v_mfma_f32_16x16x32_bf16 v[20:23], v[72:75], v[100:103], v[20:23]
	v_mfma_f32_16x16x32_bf16 v[16:19], v[72:75], v[222:225], v[16:19]
	v_mfma_f32_16x16x32_bf16 v[12:15], v[80:83], v[100:103], v[12:15]
	v_mfma_f32_16x16x32_bf16 v[8:11], v[80:83], v[222:225], v[8:11]
	v_mfma_f32_16x16x32_bf16 v[4:7], v[92:95], v[100:103], v[4:7]
	v_mfma_f32_16x16x32_bf16 v[0:3], v[92:95], v[222:225], v[0:3]
	v_mfma_f32_16x16x32_bf16 v[142:145], v[68:71], v[218:221], v[28:31]
	v_mfma_f32_16x16x32_bf16 v[160:163], v[68:71], v[152:155], v[24:27]
	v_mfma_f32_16x16x32_bf16 v[164:167], v[76:79], v[218:221], v[20:23]
	v_mfma_f32_16x16x32_bf16 v[178:181], v[76:79], v[152:155], v[16:19]
	v_mfma_f32_16x16x32_bf16 v[182:185], v[84:87], v[218:221], v[12:15]
	v_mfma_f32_16x16x32_bf16 v[214:217], v[84:87], v[152:155], v[8:11]
	v_mfma_f32_16x16x32_bf16 v[218:221], v[210:213], v[218:221], v[4:7]
	v_mfma_f32_16x16x32_bf16 v[152:155], v[210:213], v[152:155], v[0:3]
	s_setprio 0
	s_barrier
	s_nop 0
	ds_read_b128 v[0:3], v140
	ds_read_b128 v[4:7], v140 offset:1024
	ds_read_b128 v[210:213], v140 offset:2048
	ds_read_b128 v[138:141], v140 offset:3072
	ds_read_b128 v[8:11], v135 offset:32768
	ds_read_b128 v[12:15], v135 offset:33792
	ds_read_b128 v[16:19], v156 offset:32768
	ds_read_b128 v[20:23], v156 offset:33792
	ds_read_b128 v[24:27], v157 offset:32768
	ds_read_b128 v[28:31], v157 offset:33792
	ds_read_b128 v[222:225], v158 offset:32768
	ds_read_b128 v[230:233], v158 offset:33792
	s_waitcnt vmcnt(2)
	s_setprio 1
	s_barrier
	s_waitcnt lgkmcnt(0)
	v_mfma_f32_16x16x32_bf16 v[64:67], v[8:11], v[0:3], v[124:127]
	v_mfma_f32_16x16x32_bf16 v[92:95], v[12:15], v[4:7], v[64:67]
	v_mfma_f32_16x16x32_bf16 v[64:67], v[8:11], v[210:213], v[120:123]
	v_mfma_f32_16x16x32_bf16 v[100:103], v[12:15], v[138:141], v[64:67]
	v_mfma_f32_16x16x32_bf16 v[64:67], v[16:19], v[0:3], v[116:119]
	v_mfma_f32_16x16x32_bf16 v[80:83], v[20:23], v[4:7], v[64:67]
	v_mfma_f32_16x16x32_bf16 v[64:67], v[16:19], v[210:213], v[112:115]
	v_mfma_f32_16x16x32_bf16 v[84:87], v[20:23], v[138:141], v[64:67]
	v_mfma_f32_16x16x32_bf16 v[64:67], v[24:27], v[0:3], v[108:111]
	v_mfma_f32_16x16x32_bf16 v[72:75], v[28:31], v[4:7], v[64:67]
	v_mfma_f32_16x16x32_bf16 v[64:67], v[24:27], v[210:213], v[104:107]
	v_mfma_f32_16x16x32_bf16 v[76:79], v[28:31], v[138:141], v[64:67]
	v_mfma_f32_16x16x32_bf16 v[64:67], v[222:225], v[0:3], v[128:131]
	v_mfma_f32_16x16x32_bf16 v[68:71], v[222:225], v[210:213], v[96:99]
	v_mfma_f32_16x16x32_bf16 v[64:67], v[230:233], v[4:7], v[64:67]
	v_mfma_f32_16x16x32_bf16 v[68:71], v[230:233], v[138:141], v[68:71]
	s_setprio 0
	s_barrier
; #define LDA(dst, b, h)                                                                                    \
;   _Pragma("unroll") for (int m = 0; m < 4; ++m) _Pragma("unroll") for (int k = 0; k < 2; ++k)             \
;       dst[m][k] = *reinterpret_cast<const bf16x8*>((char*)SA(b, h) + lds_byte(wr * 64 + m * 16 + fr, k * 32 + fq * 8))
; #define LDB(dst, b, h)                                                                                    \
;   _Pragma("unroll") for (int n = 0; n < 2; ++n) _Pragma("unroll") for (int k = 0; k < 2; ++k)             \
;       dst[n][k] = *reinterpret_cast<const bf16x8*>((char*)SB(b, h) + lds_byte(wc * 32 + n * 16 + fr, k * 32 + fq * 8))
; #define WAIT_V(n) asm volatile("s_waitcnt vmcnt(" #n ")" ::: "memory")
; #define WAIT_L(n) asm volatile("s_waitcnt lgkmcnt(" #n ")" ::: "memory")
; #define BAR __builtin_amdgcn_s_barrier()
; template <int EPI> ...
;     ...
;     LDB(B0, 1, 0); LDA(At, 1, 0); WAIT_V(2); BAR; WAIT_L(0); MMA(0, 0, At, B0); BAR;
;     LDB(B1, 1, 1); WAIT_V(0); BAR; WAIT_L(0); MMA(0, 1, At, B1); BAR;
;     LDA(At, 1, 1); BAR; WAIT_L(0); MMA(1, 0, At, B0); MMA(1, 1, At, B1); BAR;
;   }
;   if (wr == 0) BAR;
	ds_read_b128 v[128:131], v137
	ds_read_b128 v[234:237], v137 offset:1024
	ds_read_b128 v[238:241], v137 offset:2048
	ds_read_b128 v[242:245], v137 offset:3072
	s_waitcnt vmcnt(0)
	s_setprio 1
	s_barrier
	s_waitcnt lgkmcnt(0)
	v_mfma_f32_16x16x32_bf16 v[96:99], v[8:11], v[128:131], v[226:229]
	v_mfma_f32_16x16x32_bf16 v[8:11], v[8:11], v[238:241], v[88:91]
	v_mfma_f32_16x16x32_bf16 v[124:127], v[12:15], v[242:245], v[8:11]
	v_mfma_f32_16x16x32_bf16 v[8:11], v[16:19], v[128:131], v[186:189]
	v_mfma_f32_16x16x32_bf16 v[112:115], v[20:23], v[234:237], v[8:11]
	v_mfma_f32_16x16x32_bf16 v[8:11], v[16:19], v[238:241], v[190:193]
	v_mfma_f32_16x16x32_bf16 v[116:119], v[20:23], v[242:245], v[8:11]
	v_mfma_f32_16x16x32_bf16 v[8:11], v[24:27], v[128:131], v[194:197]
	v_mfma_f32_16x16x32_bf16 v[104:107], v[28:31], v[234:237], v[8:11]
	v_mfma_f32_16x16x32_bf16 v[8:11], v[24:27], v[238:241], v[198:201]
	v_mfma_f32_16x16x32_bf16 v[108:111], v[28:31], v[242:245], v[8:11]
	v_mfma_f32_16x16x32_bf16 v[8:11], v[222:225], v[128:131], v[202:205]
	v_mfma_f32_16x16x32_bf16 v[88:91], v[230:233], v[234:237], v[8:11]
	v_mfma_f32_16x16x32_bf16 v[8:11], v[222:225], v[238:241], v[206:209]
	v_mfma_f32_16x16x32_bf16 v[120:123], v[12:15], v[234:237], v[96:99]
	v_mfma_f32_16x16x32_bf16 v[96:99], v[230:233], v[242:245], v[8:11]
	s_setprio 0
	s_barrier
	ds_read_b128 v[186:189], v135 offset:49152
	ds_read_b128 v[134:137], v135 offset:50176
	ds_read_b128 v[190:193], v156 offset:49152
	ds_read_b128 v[194:197], v156 offset:50176
	ds_read_b128 v[198:201], v157 offset:49152
	ds_read_b128 v[202:205], v157 offset:50176
	ds_read_b128 v[206:209], v158 offset:49152
	ds_read_b128 v[156:159], v158 offset:50176
	s_setprio 1
	s_barrier
	s_waitcnt lgkmcnt(0)
	v_mfma_f32_16x16x32_bf16 v[8:11], v[186:189], v[0:3], v[60:63]
	v_mfma_f32_16x16x32_bf16 v[24:27], v[134:137], v[4:7], v[8:11]
	v_mfma_f32_16x16x32_bf16 v[8:11], v[186:189], v[210:213], v[56:59]
	v_mfma_f32_16x16x32_bf16 v[28:31], v[134:137], v[138:141], v[8:11]
	v_mfma_f32_16x16x32_bf16 v[8:11], v[190:193], v[0:3], v[52:55]
	v_mfma_f32_16x16x32_bf16 v[16:19], v[194:197], v[4:7], v[8:11]
	v_mfma_f32_16x16x32_bf16 v[8:11], v[190:193], v[210:213], v[48:51]
	v_mfma_f32_16x16x32_bf16 v[20:23], v[194:197], v[138:141], v[8:11]
	v_mfma_f32_16x16x32_bf16 v[8:11], v[198:201], v[0:3], v[44:47]
	v_mfma_f32_16x16x32_bf16 v[0:3], v[206:209], v[0:3], v[36:39]
	v_mfma_f32_16x16x32_bf16 v[8:11], v[202:205], v[4:7], v[8:11]
	v_mfma_f32_16x16x32_bf16 v[12:15], v[198:201], v[210:213], v[40:43]
	v_mfma_f32_16x16x32_bf16 v[0:3], v[156:159], v[4:7], v[0:3]
	v_mfma_f32_16x16x32_bf16 v[4:7], v[206:209], v[210:213], v[32:35]
	v_mfma_f32_16x16x32_bf16 v[12:15], v[202:205], v[138:141], v[12:15]
	v_mfma_f32_16x16x32_bf16 v[4:7], v[156:159], v[138:141], v[4:7]
	s_setprio 0
	s_setprio 1
	v_mfma_f32_16x16x32_bf16 v[32:35], v[186:189], v[128:131], v[142:145]
	v_mfma_f32_16x16x32_bf16 v[56:59], v[134:137], v[234:237], v[32:35]
	v_mfma_f32_16x16x32_bf16 v[32:35], v[186:189], v[238:241], v[160:163]
	v_mfma_f32_16x16x32_bf16 v[60:63], v[134:137], v[242:245], v[32:35]
	v_mfma_f32_16x16x32_bf16 v[32:35], v[190:193], v[128:131], v[164:167]
	v_mfma_f32_16x16x32_bf16 v[48:51], v[194:197], v[234:237], v[32:35]
	v_mfma_f32_16x16x32_bf16 v[32:35], v[190:193], v[238:241], v[178:181]
	v_mfma_f32_16x16x32_bf16 v[52:55], v[194:197], v[242:245], v[32:35]
	v_mfma_f32_16x16x32_bf16 v[32:35], v[198:201], v[128:131], v[182:185]
	v_mfma_f32_16x16x32_bf16 v[40:43], v[202:205], v[234:237], v[32:35]
	v_mfma_f32_16x16x32_bf16 v[32:35], v[198:201], v[238:241], v[214:217]
	v_mfma_f32_16x16x32_bf16 v[44:47], v[202:205], v[242:245], v[32:35]
	v_mfma_f32_16x16x32_bf16 v[32:35], v[206:209], v[128:131], v[218:221]
	v_mfma_f32_16x16x32_bf16 v[36:39], v[206:209], v[238:241], v[152:155]
	v_mfma_f32_16x16x32_bf16 v[32:35], v[156:159], v[234:237], v[32:35]
	v_mfma_f32_16x16x32_bf16 v[36:39], v[156:159], v[242:245], v[36:39]
	s_setprio 0
	s_cmpk_gt_u32 s30, 0xff
	s_barrier
	s_cbranch_scc1 .LBB0_1669
	s_barrier

; #define LDA(dst, b, h)                                                                                    \
;   _Pragma("unroll") for (int m = 0; m < 4; ++m) _Pragma("unroll") for (int k = 0; k < 2; ++k)             \
;       dst[m][k] = *reinterpret_cast<const bf16x8*>((char*)SA(b, h) + lds_byte(wr * 64 + m * 16 + fr, k * 32 + fq * 8))
; #define LDB(dst, b, h)                                                                                    \
;   _Pragma("unroll") for (int n = 0; n < 2; ++n) _Pragma("unroll") for (int k = 0; k < 2; ++k)             \
;       dst[n][k] = *reinterpret_cast<const bf16x8*>((char*)SB(b, h) + lds_byte(wc * 32 + n * 16 + fr, k * 32 + fq * 8))
; #define WAIT_V(n) asm volatile("s_waitcnt vmcnt(" #n ")" ::: "memory")
; #define WAIT_L(n) asm volatile("s_waitcnt lgkmcnt(" #n ")" ::: "memory")
; #define BAR __builtin_amdgcn_s_barrier()
; #define SCHED __builtin_amdgcn_sched_barrier(0)
; template <int EPI> ...
;     ...
;     LDB(B0, 0, 0); SCHED; LDA(At, 0, 0); STAGE(SA(1, 1), A, brow + HALF, t + 1);
;     WAIT_L(8); BAR; WAIT_L(0); MMA(0, 0, At, B0); BAR; SCHED;
;     LDB(B1, 0, 1); STAGE(SB(0, 0), Bt, bcol, t + 2);
;     BAR; WAIT_L(0); MMA(0, 1, At, B1); BAR;
;     LDA(At, 0, 1); STAGE(SA(0, 0), A, brow, t + 2);
;     BAR; WAIT_L(0); MMA(1, 0, At, B0); BAR; SCHED;
;     STAGE(SB(0, 1), Bt, bcol + HALF, t + 2);
;     WAIT_V(6); BAR; MMA(1, 1, At, B1); BAR;
.LBB0_1754:
	ds_read_b128 v[162:165], v155
	ds_read_b128 v[174:177], v155 offset:1024
	ds_read_b128 v[178:181], v155 offset:2048
	ds_read_b128 v[182:185], v155 offset:3072
	s_add_u32 s18, s12, s16
	v_add_u32_e32 v156, s65, v154
	v_add_u32_e32 v157, s66, v154
	v_add_u32_e32 v158, s67, v154
	s_addc_u32 s19, s13, s17
	ds_read_b128 v[186:189], v135
	ds_read_b128 v[190:193], v135 offset:1024
	ds_read_b128 v[194:197], v156
	ds_read_b128 v[198:201], v156 offset:1024
	ds_read_b128 v[202:205], v157
	ds_read_b128 v[206:209], v157 offset:1024
	ds_read_b128 v[210:213], v158
	ds_read_b128 v[214:217], v158 offset:1024
	v_add_u32_e32 v159, 0xe000, v133
	v_add_u32_e32 v160, 0xc000, v133
	s_add_u32 m0, s32, 0xc000
	s_add_u32 s98, s18, 0x40080
	s_addc_u32 s99, s19, 0
	global_load_lds_dwordx4 v253, s[98:99]
	s_add_u32 m0, s32, 0xe000
	s_nop 0
	global_load_lds_dwordx4 v252, s[98:99]
	s_waitcnt lgkmcnt(8)
	s_setprio 1
	s_barrier
	s_waitcnt lgkmcnt(0)
	v_mfma_f32_16x16x32_bf16 v[124:127], v[186:189], v[162:165], v[124:127]
	v_mfma_f32_16x16x32_bf16 v[120:123], v[186:189], v[178:181], v[120:123]
	v_mfma_f32_16x16x32_bf16 v[116:119], v[194:197], v[162:165], v[116:119]
	v_mfma_f32_16x16x32_bf16 v[112:115], v[194:197], v[178:181], v[112:115]
	v_mfma_f32_16x16x32_bf16 v[108:111], v[202:205], v[162:165], v[108:111]
	v_mfma_f32_16x16x32_bf16 v[104:107], v[202:205], v[178:181], v[104:107]
	v_mfma_f32_16x16x32_bf16 v[100:103], v[210:213], v[162:165], v[100:103]
	v_mfma_f32_16x16x32_bf16 v[96:99], v[210:213], v[178:181], v[96:99]
	v_mfma_f32_16x16x32_bf16 v[124:127], v[190:193], v[174:177], v[124:127]
	v_mfma_f32_16x16x32_bf16 v[120:123], v[190:193], v[182:185], v[120:123]
	v_mfma_f32_16x16x32_bf16 v[116:119], v[198:201], v[174:177], v[116:119]
	v_mfma_f32_16x16x32_bf16 v[112:115], v[198:201], v[182:185], v[112:115]
	v_mfma_f32_16x16x32_bf16 v[108:111], v[206:209], v[174:177], v[108:111]
	v_mfma_f32_16x16x32_bf16 v[104:107], v[206:209], v[182:185], v[104:107]
	v_mfma_f32_16x16x32_bf16 v[100:103], v[214:217], v[174:177], v[100:103]
	v_mfma_f32_16x16x32_bf16 v[96:99], v[214:217], v[182:185], v[96:99]
	s_setprio 0
	s_barrier
	s_add_u32 s20, s10, s16
	s_addc_u32 s21, s11, s17
	ds_read_b128 v[218:221], v152
	ds_read_b128 v[222:225], v152 offset:1024
	ds_read_b128 v[226:229], v152 offset:2048
	ds_read_b128 v[230:233], v152 offset:3072
	s_add_u32 m0, s32, 0x10000
	s_add_u32 s98, s20, 0x100
	s_addc_u32 s99, s21, 0
	global_load_lds_dwordx4 v253, s[98:99]
	s_add_u32 m0, s32, 0x12000
	s_nop 0
	global_load_lds_dwordx4 v252, s[98:99]
	s_setprio 1
	s_barrier
	s_waitcnt lgkmcnt(0)
	v_mfma_f32_16x16x32_bf16 v[92:95], v[186:189], v[218:221], v[92:95]
	v_mfma_f32_16x16x32_bf16 v[88:91], v[186:189], v[226:229], v[88:91]
	v_mfma_f32_16x16x32_bf16 v[84:87], v[194:197], v[218:221], v[84:87]
	v_mfma_f32_16x16x32_bf16 v[80:83], v[194:197], v[226:229], v[80:83]
	v_mfma_f32_16x16x32_bf16 v[76:79], v[202:205], v[218:221], v[76:79]
	v_mfma_f32_16x16x32_bf16 v[72:75], v[202:205], v[226:229], v[72:75]
	v_mfma_f32_16x16x32_bf16 v[68:71], v[210:213], v[218:221], v[68:71]
	v_mfma_f32_16x16x32_bf16 v[64:67], v[210:213], v[226:229], v[64:67]
	v_mfma_f32_16x16x32_bf16 v[92:95], v[190:193], v[222:225], v[92:95]
	v_mfma_f32_16x16x32_bf16 v[88:91], v[190:193], v[230:233], v[88:91]
	v_mfma_f32_16x16x32_bf16 v[84:87], v[198:201], v[222:225], v[84:87]
	v_mfma_f32_16x16x32_bf16 v[80:83], v[198:201], v[230:233], v[80:83]
	v_mfma_f32_16x16x32_bf16 v[76:79], v[206:209], v[222:225], v[76:79]
	v_mfma_f32_16x16x32_bf16 v[72:75], v[206:209], v[230:233], v[72:75]
	v_mfma_f32_16x16x32_bf16 v[68:71], v[214:217], v[222:225], v[68:71]
	v_mfma_f32_16x16x32_bf16 v[64:67], v[214:217], v[230:233], v[64:67]
	s_setprio 0
	s_barrier
	ds_read_b128 v[186:189], v135 offset:16384
	ds_read_b128 v[190:193], v135 offset:17408
	ds_read_b128 v[194:197], v156 offset:16384
	ds_read_b128 v[198:201], v156 offset:17408
	ds_read_b128 v[202:205], v157 offset:16384
	ds_read_b128 v[206:209], v157 offset:17408
	ds_read_b128 v[210:213], v158 offset:16384
	ds_read_b128 v[214:217], v158 offset:17408
	s_mov_b32 m0, s32
	s_add_u32 s98, s18, 0x100
	s_addc_u32 s99, s19, 0
	global_load_lds_dwordx4 v253, s[98:99]
	s_add_u32 m0, s32, 0x2000
	s_nop 0
	global_load_lds_dwordx4 v252, s[98:99]
	s_setprio 1
	s_barrier
	s_waitcnt lgkmcnt(0)
	v_mfma_f32_16x16x32_bf16 v[60:63], v[186:189], v[162:165], v[60:63]
	v_mfma_f32_16x16x32_bf16 v[56:59], v[186:189], v[178:181], v[56:59]
	v_mfma_f32_16x16x32_bf16 v[52:55], v[194:197], v[162:165], v[52:55]
	v_mfma_f32_16x16x32_bf16 v[48:51], v[194:197], v[178:181], v[48:51]
	v_mfma_f32_16x16x32_bf16 v[44:47], v[202:205], v[162:165], v[44:47]
	v_mfma_f32_16x16x32_bf16 v[40:43], v[202:205], v[178:181], v[40:43]
	v_mfma_f32_16x16x32_bf16 v[36:39], v[210:213], v[162:165], v[36:39]
	v_mfma_f32_16x16x32_bf16 v[32:35], v[210:213], v[178:181], v[32:35]
	v_mfma_f32_16x16x32_bf16 v[60:63], v[190:193], v[174:177], v[60:63]
	v_mfma_f32_16x16x32_bf16 v[56:59], v[190:193], v[182:185], v[56:59]
	v_mfma_f32_16x16x32_bf16 v[52:55], v[198:201], v[174:177], v[52:55]
	v_mfma_f32_16x16x32_bf16 v[48:51], v[198:201], v[182:185], v[48:51]
	v_mfma_f32_16x16x32_bf16 v[44:47], v[206:209], v[174:177], v[44:47]
	v_mfma_f32_16x16x32_bf16 v[40:43], v[206:209], v[182:185], v[40:43]
	v_mfma_f32_16x16x32_bf16 v[36:39], v[214:217], v[174:177], v[36:39]
	v_mfma_f32_16x16x32_bf16 v[32:35], v[214:217], v[182:185], v[32:35]
	s_setprio 0
	s_barrier
	s_add_u32 m0, s32, 0x14000
	s_add_u32 s98, s20, 0x40100
	s_addc_u32 s99, s21, 0
	global_load_lds_dwordx4 v253, s[98:99]
	s_add_u32 m0, s32, 0x16000
	s_nop 0
	global_load_lds_dwordx4 v252, s[98:99]
	s_waitcnt vmcnt(6)
	s_barrier
; #define LDA(dst, b, h)                                                                                    \
;   _Pragma("unroll") for (int m = 0; m < 4; ++m) _Pragma("unroll") for (int k = 0; k < 2; ++k)             \
;       dst[m][k] = *reinterpret_cast<const bf16x8*>((char*)SA(b, h) + lds_byte(wr * 64 + m * 16 + fr, k * 32 + fq * 8))
; #define LDB(dst, b, h)                                                                                    \
;   _Pragma("unroll") for (int n = 0; n < 2; ++n) _Pragma("unroll") for (int k = 0; k < 2; ++k)             \
;       dst[n][k] = *reinterpret_cast<const bf16x8*>((char*)SB(b, h) + lds_byte(wc * 32 + n * 16 + fr, k * 32 + fq * 8))
; #define WAIT_V(n) asm volatile("s_waitcnt vmcnt(" #n ")" ::: "memory")
; #define WAIT_L(n) asm volatile("s_waitcnt lgkmcnt(" #n ")" ::: "memory")
; #define BAR __builtin_amdgcn_s_barrier()
; #define SCHED __builtin_amdgcn_sched_barrier(0)
; template <int EPI> ...
;     ...
;     WAIT_V(6); BAR; MMA(1, 1, At, B1); BAR;
;     LDB(B0, 1, 0); SCHED; LDA(At, 1, 0); STAGE(SA(0, 1), A, brow + HALF, t + 2);
;     WAIT_L(8); BAR; WAIT_L(0); MMA(0, 0, At, B0); BAR; SCHED;
;     LDB(B1, 1, 1); STAGE(SB(1, 0), Bt, bcol, t + 3);
;     BAR; WAIT_L(0); MMA(0, 1, At, B1); BAR;
;     LDA(At, 1, 1); STAGE(SA(1, 0), A, brow, t + 3);
	s_setprio 1
	v_mfma_f32_16x16x32_bf16 v[28:31], v[186:189], v[218:221], v[28:31]
	v_mfma_f32_16x16x32_bf16 v[24:27], v[186:189], v[226:229], v[24:27]
	v_mfma_f32_16x16x32_bf16 v[20:23], v[194:197], v[218:221], v[20:23]
	v_mfma_f32_16x16x32_bf16 v[16:19], v[194:197], v[226:229], v[16:19]
	v_mfma_f32_16x16x32_bf16 v[12:15], v[202:205], v[218:221], v[12:15]
	v_mfma_f32_16x16x32_bf16 v[8:11], v[202:205], v[226:229], v[8:11]
	v_mfma_f32_16x16x32_bf16 v[4:7], v[210:213], v[218:221], v[4:7]
	v_mfma_f32_16x16x32_bf16 v[0:3], v[210:213], v[226:229], v[0:3]
	v_mfma_f32_16x16x32_bf16 v[28:31], v[190:193], v[222:225], v[28:31]
	v_mfma_f32_16x16x32_bf16 v[24:27], v[190:193], v[230:233], v[24:27]
	v_mfma_f32_16x16x32_bf16 v[20:23], v[198:201], v[222:225], v[20:23]
	v_mfma_f32_16x16x32_bf16 v[16:19], v[198:201], v[230:233], v[16:19]
	v_mfma_f32_16x16x32_bf16 v[12:15], v[206:209], v[222:225], v[12:15]
	v_mfma_f32_16x16x32_bf16 v[8:11], v[206:209], v[230:233], v[8:11]
	v_mfma_f32_16x16x32_bf16 v[4:7], v[214:217], v[222:225], v[4:7]
	v_mfma_f32_16x16x32_bf16 v[0:3], v[214:217], v[230:233], v[0:3]
	s_setprio 0
	s_barrier
	ds_read_b128 v[162:165], v140
	ds_read_b128 v[174:177], v140 offset:1024
	ds_read_b128 v[178:181], v140 offset:2048
	ds_read_b128 v[182:185], v140 offset:3072
	ds_read_b128 v[186:189], v135 offset:32768
	ds_read_b128 v[190:193], v135 offset:33792
	ds_read_b128 v[194:197], v156 offset:32768
	ds_read_b128 v[198:201], v156 offset:33792
	ds_read_b128 v[202:205], v157 offset:32768
	ds_read_b128 v[206:209], v157 offset:33792
	ds_read_b128 v[210:213], v158 offset:32768
	ds_read_b128 v[214:217], v158 offset:33792
	s_add_u32 m0, s32, 0x4000
	s_add_u32 s98, s18, 0x40100
	s_addc_u32 s99, s19, 0
	global_load_lds_dwordx4 v253, s[98:99]
	s_add_u32 m0, s32, 0x6000
	s_nop 0
	global_load_lds_dwordx4 v252, s[98:99]
	s_waitcnt lgkmcnt(8)
	s_setprio 1
	s_barrier
	s_waitcnt lgkmcnt(0)
	v_mfma_f32_16x16x32_bf16 v[124:127], v[186:189], v[162:165], v[124:127]
	v_mfma_f32_16x16x32_bf16 v[120:123], v[186:189], v[178:181], v[120:123]
	v_mfma_f32_16x16x32_bf16 v[116:119], v[194:197], v[162:165], v[116:119]
	v_mfma_f32_16x16x32_bf16 v[112:115], v[194:197], v[178:181], v[112:115]
	v_mfma_f32_16x16x32_bf16 v[108:111], v[202:205], v[162:165], v[108:111]
	v_mfma_f32_16x16x32_bf16 v[104:107], v[202:205], v[178:181], v[104:107]
	v_mfma_f32_16x16x32_bf16 v[100:103], v[210:213], v[162:165], v[100:103]
	v_mfma_f32_16x16x32_bf16 v[96:99], v[210:213], v[178:181], v[96:99]
	v_mfma_f32_16x16x32_bf16 v[124:127], v[190:193], v[174:177], v[124:127]
	v_mfma_f32_16x16x32_bf16 v[120:123], v[190:193], v[182:185], v[120:123]
	v_mfma_f32_16x16x32_bf16 v[116:119], v[198:201], v[174:177], v[116:119]
	v_mfma_f32_16x16x32_bf16 v[112:115], v[198:201], v[182:185], v[112:115]
	v_mfma_f32_16x16x32_bf16 v[108:111], v[206:209], v[174:177], v[108:111]
	v_mfma_f32_16x16x32_bf16 v[104:107], v[206:209], v[182:185], v[104:107]
	v_mfma_f32_16x16x32_bf16 v[100:103], v[214:217], v[174:177], v[100:103]
	v_mfma_f32_16x16x32_bf16 v[96:99], v[214:217], v[182:185], v[96:99]
	s_setprio 0
	s_barrier
	ds_read_b128 v[218:221], v137
	ds_read_b128 v[222:225], v137 offset:1024
	ds_read_b128 v[226:229], v137 offset:2048
	ds_read_b128 v[230:233], v137 offset:3072
	s_add_u32 m0, s32, 0x18000
	s_add_u32 s98, s20, 0x180
	s_addc_u32 s99, s21, 0
	global_load_lds_dwordx4 v253, s[98:99]
	s_add_u32 m0, s32, 0x1a000
	s_nop 0
	global_load_lds_dwordx4 v252, s[98:99]
	s_setprio 1
	s_barrier
	s_waitcnt lgkmcnt(0)
	v_mfma_f32_16x16x32_bf16 v[92:95], v[186:189], v[218:221], v[92:95]
	v_mfma_f32_16x16x32_bf16 v[88:91], v[186:189], v[226:229], v[88:91]
	v_mfma_f32_16x16x32_bf16 v[84:87], v[194:197], v[218:221], v[84:87]
	v_mfma_f32_16x16x32_bf16 v[80:83], v[194:197], v[226:229], v[80:83]
	v_mfma_f32_16x16x32_bf16 v[76:79], v[202:205], v[218:221], v[76:79]
	v_mfma_f32_16x16x32_bf16 v[72:75], v[202:205], v[226:229], v[72:75]
	v_mfma_f32_16x16x32_bf16 v[68:71], v[210:213], v[218:221], v[68:71]
	v_mfma_f32_16x16x32_bf16 v[64:67], v[210:213], v[226:229], v[64:67]
	v_mfma_f32_16x16x32_bf16 v[92:95], v[190:193], v[222:225], v[92:95]
	v_mfma_f32_16x16x32_bf16 v[88:91], v[190:193], v[230:233], v[88:91]
	v_mfma_f32_16x16x32_bf16 v[84:87], v[198:201], v[222:225], v[84:87]
	v_mfma_f32_16x16x32_bf16 v[80:83], v[198:201], v[230:233], v[80:83]
	v_mfma_f32_16x16x32_bf16 v[76:79], v[206:209], v[222:225], v[76:79]
	v_mfma_f32_16x16x32_bf16 v[72:75], v[206:209], v[230:233], v[72:75]
	v_mfma_f32_16x16x32_bf16 v[68:71], v[214:217], v[222:225], v[68:71]
	v_mfma_f32_16x16x32_bf16 v[64:67], v[214:217], v[230:233], v[64:67]
	s_setprio 0
	s_barrier
	ds_read_b128 v[186:189], v135 offset:49152
	ds_read_b128 v[190:193], v135 offset:50176
	ds_read_b128 v[194:197], v156 offset:49152
	ds_read_b128 v[198:201], v156 offset:50176
	ds_read_b128 v[202:205], v157 offset:49152
	ds_read_b128 v[206:209], v157 offset:50176
	ds_read_b128 v[210:213], v158 offset:49152
	ds_read_b128 v[214:217], v158 offset:50176
	s_add_u32 m0, s32, 0x8000
	s_add_u32 s98, s18, 0x180
	s_addc_u32 s99, s19, 0
	global_load_lds_dwordx4 v253, s[98:99]
	s_nop 0
	s_add_u32 m0, s32, 0xa000
	s_nop 0
	global_load_lds_dwordx4 v252, s[98:99]
	s_setprio 1
	s_barrier
; #define LDA(dst, b, h)                                                                                    \
;   _Pragma("unroll") for (int m = 0; m < 4; ++m) _Pragma("unroll") for (int k = 0; k < 2; ++k)             \
;       dst[m][k] = *reinterpret_cast<const bf16x8*>((char*)SA(b, h) + lds_byte(wr * 64 + m * 16 + fr, k * 32 + fq * 8))
; #define LDB(dst, b, h)                                                                                    \
;   _Pragma("unroll") for (int n = 0; n < 2; ++n) _Pragma("unroll") for (int k = 0; k < 2; ++k)             \
;       dst[n][k] = *reinterpret_cast<const bf16x8*>((char*)SB(b, h) + lds_byte(wc * 32 + n * 16 + fr, k * 32 + fq * 8))
; #define WAIT_V(n) asm volatile("s_waitcnt vmcnt(" #n ")" ::: "memory")
; #define WAIT_L(n) asm volatile("s_waitcnt lgkmcnt(" #n ")" ::: "memory")
; #define BAR __builtin_amdgcn_s_barrier()
; #define SCHED __builtin_amdgcn_sched_barrier(0)
; template <int EPI> ...
;     ...
;     LDA(At, 1, 1); STAGE(SA(1, 0), A, brow, t + 3);
;     BAR; WAIT_L(0); MMA(1, 0, At, B0); BAR; SCHED;
;     STAGE(SB(1, 1), Bt, bcol + HALF, t + 3);
;     WAIT_V(6); BAR; MMA(1, 1, At, B1); BAR;
;   }
;   {
;     LDB(B0, 0, 0); LDA(At, 0, 0); STAGE(SA(1, 1), A, brow + HALF, nt - 1);
;     BAR; WAIT_L(0); MMA(0, 0, At, B0); BAR;
;     LDB(B1, 0, 1); BAR; WAIT_L(0); MMA(0, 1, At, B1); BAR;
;     LDA(At, 0, 1); WAIT_V(4); BAR; WAIT_L(0); MMA(1, 0, At, B0); MMA(1, 1, At, B1); BAR;
	s_waitcnt lgkmcnt(0)
	v_mfma_f32_16x16x32_bf16 v[60:63], v[186:189], v[162:165], v[60:63]
	v_mfma_f32_16x16x32_bf16 v[56:59], v[186:189], v[178:181], v[56:59]
	v_mfma_f32_16x16x32_bf16 v[52:55], v[194:197], v[162:165], v[52:55]
	v_mfma_f32_16x16x32_bf16 v[48:51], v[194:197], v[178:181], v[48:51]
	v_mfma_f32_16x16x32_bf16 v[44:47], v[202:205], v[162:165], v[44:47]
	v_mfma_f32_16x16x32_bf16 v[40:43], v[202:205], v[178:181], v[40:43]
	v_mfma_f32_16x16x32_bf16 v[36:39], v[210:213], v[162:165], v[36:39]
	v_mfma_f32_16x16x32_bf16 v[32:35], v[210:213], v[178:181], v[32:35]
	v_mfma_f32_16x16x32_bf16 v[60:63], v[190:193], v[174:177], v[60:63]
	v_mfma_f32_16x16x32_bf16 v[56:59], v[190:193], v[182:185], v[56:59]
	v_mfma_f32_16x16x32_bf16 v[52:55], v[198:201], v[174:177], v[52:55]
	v_mfma_f32_16x16x32_bf16 v[48:51], v[198:201], v[182:185], v[48:51]
	v_mfma_f32_16x16x32_bf16 v[44:47], v[206:209], v[174:177], v[44:47]
	v_mfma_f32_16x16x32_bf16 v[40:43], v[206:209], v[182:185], v[40:43]
	v_mfma_f32_16x16x32_bf16 v[36:39], v[214:217], v[174:177], v[36:39]
	v_mfma_f32_16x16x32_bf16 v[32:35], v[214:217], v[182:185], v[32:35]
	s_setprio 0
	s_barrier
	s_add_u32 m0, s32, 0x1c000
	s_add_u32 s98, s20, 0x40180
	s_addc_u32 s99, s21, 0
	global_load_lds_dwordx4 v253, s[98:99]
	s_add_u32 m0, s32, 0x1e000
	s_nop 0
	global_load_lds_dwordx4 v252, s[98:99]
	s_waitcnt vmcnt(6)
	s_barrier
	s_setprio 1
	v_mfma_f32_16x16x32_bf16 v[28:31], v[186:189], v[218:221], v[28:31]
	v_mfma_f32_16x16x32_bf16 v[24:27], v[186:189], v[226:229], v[24:27]
	v_mfma_f32_16x16x32_bf16 v[20:23], v[194:197], v[218:221], v[20:23]
	v_mfma_f32_16x16x32_bf16 v[16:19], v[194:197], v[226:229], v[16:19]
	v_mfma_f32_16x16x32_bf16 v[12:15], v[202:205], v[218:221], v[12:15]
	v_mfma_f32_16x16x32_bf16 v[8:11], v[202:205], v[226:229], v[8:11]
	v_mfma_f32_16x16x32_bf16 v[4:7], v[210:213], v[218:221], v[4:7]
	v_mfma_f32_16x16x32_bf16 v[0:3], v[210:213], v[226:229], v[0:3]
	v_mfma_f32_16x16x32_bf16 v[28:31], v[190:193], v[222:225], v[28:31]
	v_mfma_f32_16x16x32_bf16 v[24:27], v[190:193], v[230:233], v[24:27]
	v_mfma_f32_16x16x32_bf16 v[20:23], v[198:201], v[222:225], v[20:23]
	v_mfma_f32_16x16x32_bf16 v[16:19], v[198:201], v[230:233], v[16:19]
	v_mfma_f32_16x16x32_bf16 v[12:15], v[206:209], v[222:225], v[12:15]
	v_mfma_f32_16x16x32_bf16 v[8:11], v[206:209], v[230:233], v[8:11]
	v_mfma_f32_16x16x32_bf16 v[4:7], v[214:217], v[222:225], v[4:7]
	v_mfma_f32_16x16x32_bf16 v[0:3], v[214:217], v[230:233], v[0:3]
	s_setprio 0
	s_add_i32 s68, s68, 2
	s_add_u32 s16, s16, 0x100
	s_addc_u32 s17, s17, 0
	s_cmp_lt_u32 s68, 12
	s_barrier
	s_cbranch_scc1 .LBB0_1754
	ds_read_b128 v[142:145], v155
	ds_read_b128 v[162:165], v155 offset:1024
	ds_read_b128 v[174:177], v155 offset:2048
	ds_read_b128 v[178:181], v155 offset:3072
	ds_read_b128 v[182:185], v135
	ds_read_b128 v[186:189], v135 offset:1024
	ds_read_b128 v[190:193], v156
	ds_read_b128 v[194:197], v156 offset:1024
	ds_read_b128 v[198:201], v157
	ds_read_b128 v[202:205], v157 offset:1024
	ds_read_b128 v[206:209], v158
	ds_read_b128 v[210:213], v158 offset:1024
	v_mov_b32_e32 v129, v149
	v_lshl_add_u64 v[128:129], v[128:129], 1, s[14:15]
	s_mov_b64 s[12:13], 0x780
	v_readfirstlane_b32 s10, v160
	v_lshl_add_u64 v[128:129], v[128:129], 0, s[12:13]
	s_mov_b32 m0, s10
	v_mov_b32_e32 v131, v149
	global_load_lds_dwordx4 v[128:129], off
	v_readfirstlane_b32 s10, v159
	v_lshl_add_u64 v[128:129], v[130:131], 1, s[14:15]
	v_lshl_add_u64 v[128:129], v[128:129], 0, s[12:13]
	s_mov_b32 m0, s10
	s_nop 0
	global_load_lds_dwordx4 v[128:129], off
	s_setprio 1
	s_barrier
	s_waitcnt lgkmcnt(0)
	v_mfma_f32_16x16x32_bf16 v[124:127], v[182:185], v[142:145], v[124:127]
	v_mfma_f32_16x16x32_bf16 v[120:123], v[182:185], v[174:177], v[120:123]
	v_mfma_f32_16x16x32_bf16 v[116:119], v[190:193], v[142:145], v[116:119]
	v_mfma_f32_16x16x32_bf16 v[112:115], v[190:193], v[174:177], v[112:115]
	v_mfma_f32_16x16x32_bf16 v[108:111], v[198:201], v[142:145], v[108:111]
	v_mfma_f32_16x16x32_bf16 v[104:107], v[198:201], v[174:177], v[104:107]
	v_mfma_f32_16x16x32_bf16 v[96:99], v[206:209], v[174:177], v[96:99]
	v_mfma_f32_16x16x32_bf16 v[124:127], v[186:189], v[162:165], v[124:127]
	v_mfma_f32_16x16x32_bf16 v[120:123], v[186:189], v[178:181], v[120:123]
	v_mfma_f32_16x16x32_bf16 v[116:119], v[194:197], v[162:165], v[116:119]
	v_mfma_f32_16x16x32_bf16 v[112:115], v[194:197], v[178:181], v[112:115]
	v_mfma_f32_16x16x32_bf16 v[108:111], v[202:205], v[162:165], v[108:111]
	v_mfma_f32_16x16x32_bf16 v[104:107], v[202:205], v[178:181], v[104:107]
	v_mfma_f32_16x16x32_bf16 v[100:103], v[206:209], v[142:145], v[100:103]
	v_mfma_f32_16x16x32_bf16 v[96:99], v[210:213], v[178:181], v[96:99]
	v_mfma_f32_16x16x32_bf16 v[128:131], v[210:213], v[162:165], v[100:103]
	s_setprio 0
	s_barrier
	s_nop 3
	ds_read_b128 v[100:103], v152
	ds_read_b128 v[214:217], v152 offset:1024
	ds_read_b128 v[218:221], v152 offset:2048
	ds_read_b128 v[152:155], v152 offset:3072
	s_setprio 1
	s_barrier
	s_waitcnt lgkmcnt(0)
	v_mfma_f32_16x16x32_bf16 v[88:91], v[182:185], v[218:221], v[88:91]
	v_mfma_f32_16x16x32_bf16 v[92:95], v[182:185], v[100:103], v[92:95]
	v_mfma_f32_16x16x32_bf16 v[88:91], v[186:189], v[152:155], v[88:91]
	v_mfma_f32_16x16x32_bf16 v[84:87], v[190:193], v[100:103], v[84:87]
	v_mfma_f32_16x16x32_bf16 v[80:83], v[190:193], v[218:221], v[80:83]
	v_mfma_f32_16x16x32_bf16 v[76:79], v[198:201], v[100:103], v[76:79]
	v_mfma_f32_16x16x32_bf16 v[72:75], v[198:201], v[218:221], v[72:75]
	v_mfma_f32_16x16x32_bf16 v[68:71], v[206:209], v[100:103], v[68:71]
	v_mfma_f32_16x16x32_bf16 v[64:67], v[206:209], v[218:221], v[64:67]
	v_mfma_f32_16x16x32_bf16 v[222:225], v[186:189], v[214:217], v[92:95]
	v_mfma_f32_16x16x32_bf16 v[182:185], v[194:197], v[214:217], v[84:87]
	v_mfma_f32_16x16x32_bf16 v[186:189], v[194:197], v[152:155], v[80:83]
	v_mfma_f32_16x16x32_bf16 v[190:193], v[202:205], v[214:217], v[76:79]
	v_mfma_f32_16x16x32_bf16 v[194:197], v[202:205], v[152:155], v[72:75]
	v_mfma_f32_16x16x32_bf16 v[198:201], v[210:213], v[214:217], v[68:71]
	v_mfma_f32_16x16x32_bf16 v[202:205], v[210:213], v[152:155], v[64:67]
	s_setprio 0
	s_barrier
; #define LDA(dst, b, h)                                                                                    \
;   _Pragma("unroll") for (int m = 0; m < 4; ++m) _Pragma("unroll") for (int k = 0; k < 2; ++k)             \
;       dst[m][k] = *reinterpret_cast<const bf16x8*>((char*)SA(b, h) + lds_byte(wr * 64 + m * 16 + fr, k * 32 + fq * 8))
; #define LDB(dst, b, h)                                                                                    \
;   _Pragma("unroll") for (int n = 0; n < 2; ++n) _Pragma("unroll") for (int k = 0; k < 2; ++k)             \
;       dst[n][k] = *reinterpret_cast<const bf16x8*>((char*)SB(b, h) + lds_byte(wc * 32 + n * 16 + fr, k * 32 + fq * 8))
; #define WAIT_V(n) asm volatile("s_waitcnt vmcnt(" #n ")" ::: "memory")
; #define WAIT_L(n) asm volatile("s_waitcnt lgkmcnt(" #n ")" ::: "memory")
; #define BAR __builtin_amdgcn_s_barrier()
; template <int EPI> ...
;     ...
;     LDB(B1, 0, 1); BAR; WAIT_L(0); MMA(0, 1, At, B1); BAR;
;     LDA(At, 0, 1); WAIT_V(4); BAR; WAIT_L(0); MMA(1, 0, At, B0); MMA(1, 1, At, B1); BAR;
;   }
;   {
;     LDB(B0, 1, 0); LDA(At, 1, 0); WAIT_V(2); BAR; WAIT_L(0); MMA(0, 0, At, B0); BAR;
	s_nop 0
	ds_read_b128 v[64:67], v135 offset:16384
	ds_read_b128 v[68:71], v135 offset:17408
	ds_read_b128 v[72:75], v156 offset:16384
	ds_read_b128 v[76:79], v156 offset:17408
	ds_read_b128 v[80:83], v157 offset:16384
	ds_read_b128 v[84:87], v157 offset:17408
	ds_read_b128 v[92:95], v158 offset:16384
	ds_read_b128 v[206:209], v158 offset:17408
	s_waitcnt vmcnt(4)
	s_setprio 1
	s_barrier
	s_waitcnt lgkmcnt(0)
	v_mfma_f32_16x16x32_bf16 v[60:63], v[64:67], v[142:145], v[60:63]
	v_mfma_f32_16x16x32_bf16 v[56:59], v[64:67], v[174:177], v[56:59]
	v_mfma_f32_16x16x32_bf16 v[52:55], v[72:75], v[142:145], v[52:55]
	v_mfma_f32_16x16x32_bf16 v[48:51], v[72:75], v[174:177], v[48:51]
	v_mfma_f32_16x16x32_bf16 v[44:47], v[80:83], v[142:145], v[44:47]
	v_mfma_f32_16x16x32_bf16 v[40:43], v[80:83], v[174:177], v[40:43]
	v_mfma_f32_16x16x32_bf16 v[36:39], v[92:95], v[142:145], v[36:39]
	v_mfma_f32_16x16x32_bf16 v[32:35], v[92:95], v[174:177], v[32:35]
	v_mfma_f32_16x16x32_bf16 v[60:63], v[68:71], v[162:165], v[60:63]
	v_mfma_f32_16x16x32_bf16 v[56:59], v[68:71], v[178:181], v[56:59]
	v_mfma_f32_16x16x32_bf16 v[52:55], v[76:79], v[162:165], v[52:55]
	v_mfma_f32_16x16x32_bf16 v[48:51], v[76:79], v[178:181], v[48:51]
	v_mfma_f32_16x16x32_bf16 v[44:47], v[84:87], v[162:165], v[44:47]
	v_mfma_f32_16x16x32_bf16 v[40:43], v[84:87], v[178:181], v[40:43]
	v_mfma_f32_16x16x32_bf16 v[36:39], v[206:209], v[162:165], v[36:39]
	v_mfma_f32_16x16x32_bf16 v[32:35], v[206:209], v[178:181], v[32:35]
	s_setprio 0
	s_setprio 1
	v_mfma_f32_16x16x32_bf16 v[28:31], v[64:67], v[100:103], v[28:31]
	v_mfma_f32_16x16x32_bf16 v[24:27], v[64:67], v[218:221], v[24:27]
	v_mfma_f32_16x16x32_bf16 v[20:23], v[72:75], v[100:103], v[20:23]
	v_mfma_f32_16x16x32_bf16 v[16:19], v[72:75], v[218:221], v[16:19]
	v_mfma_f32_16x16x32_bf16 v[12:15], v[80:83], v[100:103], v[12:15]
	v_mfma_f32_16x16x32_bf16 v[8:11], v[80:83], v[218:221], v[8:11]
	v_mfma_f32_16x16x32_bf16 v[4:7], v[92:95], v[100:103], v[4:7]
	v_mfma_f32_16x16x32_bf16 v[0:3], v[92:95], v[218:221], v[0:3]
	v_mfma_f32_16x16x32_bf16 v[142:145], v[68:71], v[214:217], v[28:31]
	v_mfma_f32_16x16x32_bf16 v[160:163], v[68:71], v[152:155], v[24:27]
	v_mfma_f32_16x16x32_bf16 v[164:167], v[76:79], v[214:217], v[20:23]
	v_mfma_f32_16x16x32_bf16 v[174:177], v[76:79], v[152:155], v[16:19]
	v_mfma_f32_16x16x32_bf16 v[178:181], v[84:87], v[214:217], v[12:15]
	v_mfma_f32_16x16x32_bf16 v[210:213], v[84:87], v[152:155], v[8:11]
	v_mfma_f32_16x16x32_bf16 v[214:217], v[206:209], v[214:217], v[4:7]
	v_mfma_f32_16x16x32_bf16 v[152:155], v[206:209], v[152:155], v[0:3]
	s_setprio 0
	s_barrier
	s_nop 0
	ds_read_b128 v[0:3], v140
	ds_read_b128 v[4:7], v140 offset:1024
	ds_read_b128 v[206:209], v140 offset:2048
	ds_read_b128 v[138:141], v140 offset:3072
	ds_read_b128 v[8:11], v135 offset:32768
	ds_read_b128 v[12:15], v135 offset:33792
	ds_read_b128 v[16:19], v156 offset:32768
	ds_read_b128 v[20:23], v156 offset:33792
	ds_read_b128 v[24:27], v157 offset:32768
	ds_read_b128 v[28:31], v157 offset:33792
	ds_read_b128 v[218:221], v158 offset:32768
	ds_read_b128 v[226:229], v158 offset:33792
	s_waitcnt vmcnt(2)
	s_setprio 1
	s_barrier
	s_waitcnt lgkmcnt(0)
	v_mfma_f32_16x16x32_bf16 v[64:67], v[8:11], v[0:3], v[124:127]
	v_mfma_f32_16x16x32_bf16 v[92:95], v[12:15], v[4:7], v[64:67]
	v_mfma_f32_16x16x32_bf16 v[64:67], v[8:11], v[206:209], v[120:123]
	v_mfma_f32_16x16x32_bf16 v[100:103], v[12:15], v[138:141], v[64:67]
	v_mfma_f32_16x16x32_bf16 v[64:67], v[16:19], v[0:3], v[116:119]
	v_mfma_f32_16x16x32_bf16 v[80:83], v[20:23], v[4:7], v[64:67]
	v_mfma_f32_16x16x32_bf16 v[64:67], v[16:19], v[206:209], v[112:115]
	v_mfma_f32_16x16x32_bf16 v[84:87], v[20:23], v[138:141], v[64:67]
	v_mfma_f32_16x16x32_bf16 v[64:67], v[24:27], v[0:3], v[108:111]
	v_mfma_f32_16x16x32_bf16 v[72:75], v[28:31], v[4:7], v[64:67]
	v_mfma_f32_16x16x32_bf16 v[64:67], v[24:27], v[206:209], v[104:107]
	v_mfma_f32_16x16x32_bf16 v[76:79], v[28:31], v[138:141], v[64:67]
	v_mfma_f32_16x16x32_bf16 v[64:67], v[218:221], v[0:3], v[128:131]
	v_mfma_f32_16x16x32_bf16 v[68:71], v[218:221], v[206:209], v[96:99]
	v_mfma_f32_16x16x32_bf16 v[64:67], v[226:229], v[4:7], v[64:67]
	v_mfma_f32_16x16x32_bf16 v[68:71], v[226:229], v[138:141], v[68:71]
	s_setprio 0
	s_barrier
; #define LDA(dst, b, h)                                                                                    \
;   _Pragma("unroll") for (int m = 0; m < 4; ++m) _Pragma("unroll") for (int k = 0; k < 2; ++k)             \
;       dst[m][k] = *reinterpret_cast<const bf16x8*>((char*)SA(b, h) + lds_byte(wr * 64 + m * 16 + fr, k * 32 + fq * 8))
; #define LDB(dst, b, h)                                                                                    \
;   _Pragma("unroll") for (int n = 0; n < 2; ++n) _Pragma("unroll") for (int k = 0; k < 2; ++k)             \
;       dst[n][k] = *reinterpret_cast<const bf16x8*>((char*)SB(b, h) + lds_byte(wc * 32 + n * 16 + fr, k * 32 + fq * 8))
; #define WAIT_V(n) asm volatile("s_waitcnt vmcnt(" #n ")" ::: "memory")
; #define WAIT_L(n) asm volatile("s_waitcnt lgkmcnt(" #n ")" ::: "memory")
; #define BAR __builtin_amdgcn_s_barrier()
; template <int EPI> ...
;     ...
;     LDB(B0, 1, 0); LDA(At, 1, 0); WAIT_V(2); BAR; WAIT_L(0); MMA(0, 0, At, B0); BAR;
;     LDB(B1, 1, 1); WAIT_V(0); BAR; WAIT_L(0); MMA(0, 1, At, B1); BAR;
;     LDA(At, 1, 1); BAR; WAIT_L(0); MMA(1, 0, At, B0); MMA(1, 1, At, B1); BAR;
;   }
;   if (wr == 0) BAR;
	ds_read_b128 v[128:131], v137
	ds_read_b128 v[230:233], v137 offset:1024
	ds_read_b128 v[234:237], v137 offset:2048
	ds_read_b128 v[238:241], v137 offset:3072
	s_waitcnt vmcnt(0)
	s_setprio 1
	s_barrier
	s_waitcnt lgkmcnt(0)
	v_mfma_f32_16x16x32_bf16 v[96:99], v[8:11], v[128:131], v[222:225]
	v_mfma_f32_16x16x32_bf16 v[8:11], v[8:11], v[234:237], v[88:91]
	v_mfma_f32_16x16x32_bf16 v[124:127], v[12:15], v[238:241], v[8:11]
	v_mfma_f32_16x16x32_bf16 v[8:11], v[16:19], v[128:131], v[182:185]
	v_mfma_f32_16x16x32_bf16 v[112:115], v[20:23], v[230:233], v[8:11]
	v_mfma_f32_16x16x32_bf16 v[8:11], v[16:19], v[234:237], v[186:189]
	v_mfma_f32_16x16x32_bf16 v[116:119], v[20:23], v[238:241], v[8:11]
	v_mfma_f32_16x16x32_bf16 v[8:11], v[24:27], v[128:131], v[190:193]
	v_mfma_f32_16x16x32_bf16 v[104:107], v[28:31], v[230:233], v[8:11]
	v_mfma_f32_16x16x32_bf16 v[8:11], v[24:27], v[234:237], v[194:197]
	v_mfma_f32_16x16x32_bf16 v[108:111], v[28:31], v[238:241], v[8:11]
	v_mfma_f32_16x16x32_bf16 v[8:11], v[218:221], v[128:131], v[198:201]
	v_mfma_f32_16x16x32_bf16 v[88:91], v[226:229], v[230:233], v[8:11]
	v_mfma_f32_16x16x32_bf16 v[8:11], v[218:221], v[234:237], v[202:205]
	v_mfma_f32_16x16x32_bf16 v[120:123], v[12:15], v[230:233], v[96:99]
	v_mfma_f32_16x16x32_bf16 v[96:99], v[226:229], v[238:241], v[8:11]
	s_setprio 0
	s_barrier
	ds_read_b128 v[182:185], v135 offset:49152
	ds_read_b128 v[186:189], v135 offset:50176
	ds_read_b128 v[190:193], v156 offset:49152
	ds_read_b128 v[194:197], v156 offset:50176
	ds_read_b128 v[198:201], v157 offset:49152
	ds_read_b128 v[202:205], v157 offset:50176
	ds_read_b128 v[218:221], v158 offset:49152
	ds_read_b128 v[156:159], v158 offset:50176
	s_setprio 1
	s_barrier
	s_waitcnt lgkmcnt(0)
	v_mfma_f32_16x16x32_bf16 v[8:11], v[182:185], v[0:3], v[60:63]
	v_mfma_f32_16x16x32_bf16 v[24:27], v[186:189], v[4:7], v[8:11]
	v_mfma_f32_16x16x32_bf16 v[8:11], v[182:185], v[206:209], v[56:59]
	v_mfma_f32_16x16x32_bf16 v[28:31], v[186:189], v[138:141], v[8:11]
	v_mfma_f32_16x16x32_bf16 v[8:11], v[190:193], v[0:3], v[52:55]
	v_mfma_f32_16x16x32_bf16 v[16:19], v[194:197], v[4:7], v[8:11]
	v_mfma_f32_16x16x32_bf16 v[8:11], v[190:193], v[206:209], v[48:51]
	v_mfma_f32_16x16x32_bf16 v[20:23], v[194:197], v[138:141], v[8:11]
	v_mfma_f32_16x16x32_bf16 v[8:11], v[198:201], v[0:3], v[44:47]
	v_mfma_f32_16x16x32_bf16 v[0:3], v[218:221], v[0:3], v[36:39]
	v_mfma_f32_16x16x32_bf16 v[8:11], v[202:205], v[4:7], v[8:11]
	v_mfma_f32_16x16x32_bf16 v[12:15], v[198:201], v[206:209], v[40:43]
	v_mfma_f32_16x16x32_bf16 v[0:3], v[156:159], v[4:7], v[0:3]
	v_mfma_f32_16x16x32_bf16 v[4:7], v[218:221], v[206:209], v[32:35]
	v_mfma_f32_16x16x32_bf16 v[12:15], v[202:205], v[138:141], v[12:15]
	v_mfma_f32_16x16x32_bf16 v[4:7], v[156:159], v[138:141], v[4:7]
	s_setprio 0
	s_setprio 1
	v_mfma_f32_16x16x32_bf16 v[32:35], v[182:185], v[128:131], v[142:145]
	v_mfma_f32_16x16x32_bf16 v[56:59], v[186:189], v[230:233], v[32:35]
	v_mfma_f32_16x16x32_bf16 v[32:35], v[182:185], v[234:237], v[160:163]
	v_mfma_f32_16x16x32_bf16 v[60:63], v[186:189], v[238:241], v[32:35]
	v_mfma_f32_16x16x32_bf16 v[32:35], v[190:193], v[128:131], v[164:167]
	v_mfma_f32_16x16x32_bf16 v[48:51], v[194:197], v[230:233], v[32:35]
	v_mfma_f32_16x16x32_bf16 v[32:35], v[190:193], v[234:237], v[174:177]
	v_mfma_f32_16x16x32_bf16 v[52:55], v[194:197], v[238:241], v[32:35]
	v_mfma_f32_16x16x32_bf16 v[32:35], v[198:201], v[128:131], v[178:181]
	v_mfma_f32_16x16x32_bf16 v[40:43], v[202:205], v[230:233], v[32:35]
	v_mfma_f32_16x16x32_bf16 v[32:35], v[198:201], v[234:237], v[210:213]
	v_mfma_f32_16x16x32_bf16 v[44:47], v[202:205], v[238:241], v[32:35]
	v_mfma_f32_16x16x32_bf16 v[32:35], v[218:221], v[128:131], v[214:217]
	v_mfma_f32_16x16x32_bf16 v[36:39], v[218:221], v[234:237], v[152:155]
	v_mfma_f32_16x16x32_bf16 v[32:35], v[156:159], v[230:233], v[32:35]
	v_mfma_f32_16x16x32_bf16 v[36:39], v[156:159], v[238:241], v[36:39]
	s_setprio 0
	s_cmpk_gt_u32 s62, 0xff
	s_barrier
	s_cbranch_scc1 .LBB0_1748
	s_barrier
	s_branch .LBB0_1748

; #define LDA(dst, b, h)                                                                                    \
;   _Pragma("unroll") for (int m = 0; m < 4; ++m) _Pragma("unroll") for (int k = 0; k < 2; ++k)             \
;       dst[m][k] = *reinterpret_cast<const bf16x8*>((char*)SA(b, h) + lds_byte(wr * 64 + m * 16 + fr, k * 32 + fq * 8))
; #define LDB(dst, b, h)                                                                                    \
;   _Pragma("unroll") for (int n = 0; n < 2; ++n) _Pragma("unroll") for (int k = 0; k < 2; ++k)             \
;       dst[n][k] = *reinterpret_cast<const bf16x8*>((char*)SB(b, h) + lds_byte(wc * 32 + n * 16 + fr, k * 32 + fq * 8))
; #define WAIT_V(n) asm volatile("s_waitcnt vmcnt(" #n ")" ::: "memory")
; #define WAIT_L(n) asm volatile("s_waitcnt lgkmcnt(" #n ")" ::: "memory")
; #define BAR __builtin_amdgcn_s_barrier()
; #define SCHED __builtin_amdgcn_sched_barrier(0)
; template <int EPI> ...
;     ...
;     LDB(B0, 0, 0); SCHED; LDA(At, 0, 0); STAGE(SA(1, 1), A, brow + HALF, t + 1);
;     WAIT_L(8); BAR; WAIT_L(0); MMA(0, 0, At, B0); BAR; SCHED;
;     LDB(B1, 0, 1); STAGE(SB(0, 0), Bt, bcol, t + 2);
;     BAR; WAIT_L(0); MMA(0, 1, At, B1); BAR;
;     LDA(At, 0, 1); STAGE(SA(0, 0), A, brow, t + 2);
;     BAR; WAIT_L(0); MMA(1, 0, At, B0); BAR; SCHED;
;     STAGE(SB(0, 1), Bt, bcol + HALF, t + 2);
;     WAIT_V(6); BAR; MMA(1, 1, At, B1); BAR;
.LBB0_1779:
	ds_read_b128 v[162:165], v155
	ds_read_b128 v[174:177], v155 offset:1024
	ds_read_b128 v[178:181], v155 offset:2048
	ds_read_b128 v[182:185], v155 offset:3072
	s_add_u32 s18, s12, s16
	v_add_u32_e32 v156, s63, v154
	v_add_u32_e32 v157, s68, v154
	v_add_u32_e32 v158, s69, v154
	s_addc_u32 s19, s13, s17
	v_add_u32_e32 v159, 0xc000, v129
	ds_read_b128 v[186:189], v135
	ds_read_b128 v[190:193], v135 offset:1024
	ds_read_b128 v[194:197], v156
	ds_read_b128 v[198:201], v156 offset:1024
	ds_read_b128 v[202:205], v157
	ds_read_b128 v[206:209], v157 offset:1024
	ds_read_b128 v[210:213], v158
	ds_read_b128 v[214:217], v158 offset:1024
	s_add_u32 m0, s32, 0xc000
	s_add_u32 s98, s18, 0xb0080
	s_addc_u32 s99, s19, 0
	global_load_lds_dwordx4 v253, s[98:99]
	s_nop 0
	v_add_u32_e32 v160, 0xe000, v129
	s_nop 0
	s_add_u32 m0, s32, 0xe000
	s_nop 0
	global_load_lds_dwordx4 v252, s[98:99]
	s_waitcnt lgkmcnt(8)
	s_setprio 1
	s_barrier
	s_waitcnt lgkmcnt(0)
	v_mfma_f32_16x16x32_bf16 v[124:127], v[186:189], v[162:165], v[124:127]
	v_mfma_f32_16x16x32_bf16 v[120:123], v[186:189], v[178:181], v[120:123]
	v_mfma_f32_16x16x32_bf16 v[116:119], v[194:197], v[162:165], v[116:119]
	v_mfma_f32_16x16x32_bf16 v[112:115], v[194:197], v[178:181], v[112:115]
	v_mfma_f32_16x16x32_bf16 v[108:111], v[202:205], v[162:165], v[108:111]
	v_mfma_f32_16x16x32_bf16 v[104:107], v[202:205], v[178:181], v[104:107]
	v_mfma_f32_16x16x32_bf16 v[100:103], v[210:213], v[162:165], v[100:103]
	v_mfma_f32_16x16x32_bf16 v[96:99], v[210:213], v[178:181], v[96:99]
	v_mfma_f32_16x16x32_bf16 v[124:127], v[190:193], v[174:177], v[124:127]
	v_mfma_f32_16x16x32_bf16 v[120:123], v[190:193], v[182:185], v[120:123]
	v_mfma_f32_16x16x32_bf16 v[116:119], v[198:201], v[174:177], v[116:119]
	v_mfma_f32_16x16x32_bf16 v[112:115], v[198:201], v[182:185], v[112:115]
	v_mfma_f32_16x16x32_bf16 v[108:111], v[206:209], v[174:177], v[108:111]
	v_mfma_f32_16x16x32_bf16 v[104:107], v[206:209], v[182:185], v[104:107]
	v_mfma_f32_16x16x32_bf16 v[100:103], v[214:217], v[174:177], v[100:103]
	v_mfma_f32_16x16x32_bf16 v[96:99], v[214:217], v[182:185], v[96:99]
	s_setprio 0
	s_barrier
	s_add_u32 s20, s10, s16
	s_addc_u32 s21, s11, s17
	ds_read_b128 v[218:221], v152
	ds_read_b128 v[222:225], v152 offset:1024
	ds_read_b128 v[226:229], v152 offset:2048
	ds_read_b128 v[230:233], v152 offset:3072
	s_add_u32 m0, s32, 0x10000
	s_add_u32 s98, s20, 0x100
	s_addc_u32 s99, s21, 0
	global_load_lds_dwordx4 v253, s[98:99]
	s_add_u32 m0, s32, 0x12000
	s_nop 0
	global_load_lds_dwordx4 v252, s[98:99]
	s_setprio 1
	s_barrier
	s_waitcnt lgkmcnt(0)
	v_mfma_f32_16x16x32_bf16 v[92:95], v[186:189], v[218:221], v[92:95]
	v_mfma_f32_16x16x32_bf16 v[88:91], v[186:189], v[226:229], v[88:91]
	v_mfma_f32_16x16x32_bf16 v[84:87], v[194:197], v[218:221], v[84:87]
	v_mfma_f32_16x16x32_bf16 v[80:83], v[194:197], v[226:229], v[80:83]
	v_mfma_f32_16x16x32_bf16 v[76:79], v[202:205], v[218:221], v[76:79]
	v_mfma_f32_16x16x32_bf16 v[72:75], v[202:205], v[226:229], v[72:75]
	v_mfma_f32_16x16x32_bf16 v[68:71], v[210:213], v[218:221], v[68:71]
	v_mfma_f32_16x16x32_bf16 v[64:67], v[210:213], v[226:229], v[64:67]
	v_mfma_f32_16x16x32_bf16 v[92:95], v[190:193], v[222:225], v[92:95]
	v_mfma_f32_16x16x32_bf16 v[88:91], v[190:193], v[230:233], v[88:91]
	v_mfma_f32_16x16x32_bf16 v[84:87], v[198:201], v[222:225], v[84:87]
	v_mfma_f32_16x16x32_bf16 v[80:83], v[198:201], v[230:233], v[80:83]
	v_mfma_f32_16x16x32_bf16 v[76:79], v[206:209], v[222:225], v[76:79]
	v_mfma_f32_16x16x32_bf16 v[72:75], v[206:209], v[230:233], v[72:75]
	v_mfma_f32_16x16x32_bf16 v[68:71], v[214:217], v[222:225], v[68:71]
	v_mfma_f32_16x16x32_bf16 v[64:67], v[214:217], v[230:233], v[64:67]
	s_setprio 0
	s_barrier
	ds_read_b128 v[186:189], v135 offset:16384
	ds_read_b128 v[190:193], v135 offset:17408
	ds_read_b128 v[194:197], v156 offset:16384
	ds_read_b128 v[198:201], v156 offset:17408
	ds_read_b128 v[202:205], v157 offset:16384
	ds_read_b128 v[206:209], v157 offset:17408
	ds_read_b128 v[210:213], v158 offset:16384
	ds_read_b128 v[214:217], v158 offset:17408
	s_mov_b32 m0, s32
	s_add_u32 s98, s18, 0x100
	s_addc_u32 s99, s19, 0
	global_load_lds_dwordx4 v253, s[98:99]
	s_add_u32 m0, s32, 0x2000
	s_nop 0
	global_load_lds_dwordx4 v252, s[98:99]
	s_setprio 1
	s_barrier
	s_waitcnt lgkmcnt(0)
	v_mfma_f32_16x16x32_bf16 v[60:63], v[186:189], v[162:165], v[60:63]
	v_mfma_f32_16x16x32_bf16 v[56:59], v[186:189], v[178:181], v[56:59]
	v_mfma_f32_16x16x32_bf16 v[52:55], v[194:197], v[162:165], v[52:55]
	v_mfma_f32_16x16x32_bf16 v[48:51], v[194:197], v[178:181], v[48:51]
	v_mfma_f32_16x16x32_bf16 v[44:47], v[202:205], v[162:165], v[44:47]
	v_mfma_f32_16x16x32_bf16 v[40:43], v[202:205], v[178:181], v[40:43]
	v_mfma_f32_16x16x32_bf16 v[36:39], v[210:213], v[162:165], v[36:39]
	v_mfma_f32_16x16x32_bf16 v[32:35], v[210:213], v[178:181], v[32:35]
	v_mfma_f32_16x16x32_bf16 v[60:63], v[190:193], v[174:177], v[60:63]
	v_mfma_f32_16x16x32_bf16 v[56:59], v[190:193], v[182:185], v[56:59]
	v_mfma_f32_16x16x32_bf16 v[52:55], v[198:201], v[174:177], v[52:55]
	v_mfma_f32_16x16x32_bf16 v[48:51], v[198:201], v[182:185], v[48:51]
	v_mfma_f32_16x16x32_bf16 v[44:47], v[206:209], v[174:177], v[44:47]
	v_mfma_f32_16x16x32_bf16 v[40:43], v[206:209], v[182:185], v[40:43]
	v_mfma_f32_16x16x32_bf16 v[36:39], v[214:217], v[174:177], v[36:39]
	v_mfma_f32_16x16x32_bf16 v[32:35], v[214:217], v[182:185], v[32:35]
	s_setprio 0
	s_barrier
	s_add_u32 m0, s32, 0x14000
	s_add_u32 s98, s20, 0xb0100
	s_addc_u32 s99, s21, 0
	global_load_lds_dwordx4 v253, s[98:99]
	s_add_u32 m0, s32, 0x16000
	s_nop 0
	global_load_lds_dwordx4 v252, s[98:99]
	s_waitcnt vmcnt(6)
	s_barrier
; #define LDA(dst, b, h)                                                                                    \
;   _Pragma("unroll") for (int m = 0; m < 4; ++m) _Pragma("unroll") for (int k = 0; k < 2; ++k)             \
;       dst[m][k] = *reinterpret_cast<const bf16x8*>((char*)SA(b, h) + lds_byte(wr * 64 + m * 16 + fr, k * 32 + fq * 8))
; #define LDB(dst, b, h)                                                                                    \
;   _Pragma("unroll") for (int n = 0; n < 2; ++n) _Pragma("unroll") for (int k = 0; k < 2; ++k)             \
;       dst[n][k] = *reinterpret_cast<const bf16x8*>((char*)SB(b, h) + lds_byte(wc * 32 + n * 16 + fr, k * 32 + fq * 8))
; #define WAIT_V(n) asm volatile("s_waitcnt vmcnt(" #n ")" ::: "memory")
; #define WAIT_L(n) asm volatile("s_waitcnt lgkmcnt(" #n ")" ::: "memory")
; #define BAR __builtin_amdgcn_s_barrier()
; #define SCHED __builtin_amdgcn_sched_barrier(0)
; template <int EPI> ...
;     ...
;     WAIT_V(6); BAR; MMA(1, 1, At, B1); BAR;
;     LDB(B0, 1, 0); SCHED; LDA(At, 1, 0); STAGE(SA(0, 1), A, brow + HALF, t + 2);
;     WAIT_L(8); BAR; WAIT_L(0); MMA(0, 0, At, B0); BAR; SCHED;
;     LDB(B1, 1, 1); STAGE(SB(1, 0), Bt, bcol, t + 3);
;     BAR; WAIT_L(0); MMA(0, 1, At, B1); BAR;
;     LDA(At, 1, 1); STAGE(SA(1, 0), A, brow, t + 3);
	s_setprio 1
	v_mfma_f32_16x16x32_bf16 v[28:31], v[186:189], v[218:221], v[28:31]
	v_mfma_f32_16x16x32_bf16 v[24:27], v[186:189], v[226:229], v[24:27]
	v_mfma_f32_16x16x32_bf16 v[20:23], v[194:197], v[218:221], v[20:23]
	v_mfma_f32_16x16x32_bf16 v[16:19], v[194:197], v[226:229], v[16:19]
	v_mfma_f32_16x16x32_bf16 v[12:15], v[202:205], v[218:221], v[12:15]
	v_mfma_f32_16x16x32_bf16 v[8:11], v[202:205], v[226:229], v[8:11]
	v_mfma_f32_16x16x32_bf16 v[4:7], v[210:213], v[218:221], v[4:7]
	v_mfma_f32_16x16x32_bf16 v[0:3], v[210:213], v[226:229], v[0:3]
	v_mfma_f32_16x16x32_bf16 v[28:31], v[190:193], v[222:225], v[28:31]
	v_mfma_f32_16x16x32_bf16 v[24:27], v[190:193], v[230:233], v[24:27]
	v_mfma_f32_16x16x32_bf16 v[20:23], v[198:201], v[222:225], v[20:23]
	v_mfma_f32_16x16x32_bf16 v[16:19], v[198:201], v[230:233], v[16:19]
	v_mfma_f32_16x16x32_bf16 v[12:15], v[206:209], v[222:225], v[12:15]
	v_mfma_f32_16x16x32_bf16 v[8:11], v[206:209], v[230:233], v[8:11]
	v_mfma_f32_16x16x32_bf16 v[4:7], v[214:217], v[222:225], v[4:7]
	v_mfma_f32_16x16x32_bf16 v[0:3], v[214:217], v[230:233], v[0:3]
	s_setprio 0
	s_barrier
	ds_read_b128 v[162:165], v140
	ds_read_b128 v[174:177], v140 offset:1024
	ds_read_b128 v[178:181], v140 offset:2048
	ds_read_b128 v[182:185], v140 offset:3072
	ds_read_b128 v[186:189], v135 offset:32768
	ds_read_b128 v[190:193], v135 offset:33792
	ds_read_b128 v[194:197], v156 offset:32768
	ds_read_b128 v[198:201], v156 offset:33792
	ds_read_b128 v[202:205], v157 offset:32768
	ds_read_b128 v[206:209], v157 offset:33792
	ds_read_b128 v[210:213], v158 offset:32768
	ds_read_b128 v[214:217], v158 offset:33792
	s_add_u32 m0, s32, 0x4000
	s_add_u32 s98, s18, 0xb0100
	s_addc_u32 s99, s19, 0
	global_load_lds_dwordx4 v253, s[98:99]
	s_add_u32 m0, s32, 0x6000
	s_nop 0
	global_load_lds_dwordx4 v252, s[98:99]
	s_waitcnt lgkmcnt(8)
	s_setprio 1
	s_barrier
	s_waitcnt lgkmcnt(0)
	v_mfma_f32_16x16x32_bf16 v[124:127], v[186:189], v[162:165], v[124:127]
	v_mfma_f32_16x16x32_bf16 v[120:123], v[186:189], v[178:181], v[120:123]
	v_mfma_f32_16x16x32_bf16 v[116:119], v[194:197], v[162:165], v[116:119]
	v_mfma_f32_16x16x32_bf16 v[112:115], v[194:197], v[178:181], v[112:115]
	v_mfma_f32_16x16x32_bf16 v[108:111], v[202:205], v[162:165], v[108:111]
	v_mfma_f32_16x16x32_bf16 v[104:107], v[202:205], v[178:181], v[104:107]
	v_mfma_f32_16x16x32_bf16 v[100:103], v[210:213], v[162:165], v[100:103]
	v_mfma_f32_16x16x32_bf16 v[96:99], v[210:213], v[178:181], v[96:99]
	v_mfma_f32_16x16x32_bf16 v[124:127], v[190:193], v[174:177], v[124:127]
	v_mfma_f32_16x16x32_bf16 v[120:123], v[190:193], v[182:185], v[120:123]
	v_mfma_f32_16x16x32_bf16 v[116:119], v[198:201], v[174:177], v[116:119]
	v_mfma_f32_16x16x32_bf16 v[112:115], v[198:201], v[182:185], v[112:115]
	v_mfma_f32_16x16x32_bf16 v[108:111], v[206:209], v[174:177], v[108:111]
	v_mfma_f32_16x16x32_bf16 v[104:107], v[206:209], v[182:185], v[104:107]
	v_mfma_f32_16x16x32_bf16 v[100:103], v[214:217], v[174:177], v[100:103]
	v_mfma_f32_16x16x32_bf16 v[96:99], v[214:217], v[182:185], v[96:99]
	s_setprio 0
	s_barrier
	ds_read_b128 v[218:221], v137
	ds_read_b128 v[222:225], v137 offset:1024
	ds_read_b128 v[226:229], v137 offset:2048
	ds_read_b128 v[230:233], v137 offset:3072
	s_add_u32 m0, s32, 0x18000
	s_add_u32 s98, s20, 0x180
	s_addc_u32 s99, s21, 0
	global_load_lds_dwordx4 v253, s[98:99]
	s_add_u32 m0, s32, 0x1a000
	s_nop 0
	global_load_lds_dwordx4 v252, s[98:99]
	s_setprio 1
	s_barrier
	s_waitcnt lgkmcnt(0)
	v_mfma_f32_16x16x32_bf16 v[92:95], v[186:189], v[218:221], v[92:95]
	v_mfma_f32_16x16x32_bf16 v[88:91], v[186:189], v[226:229], v[88:91]
	v_mfma_f32_16x16x32_bf16 v[84:87], v[194:197], v[218:221], v[84:87]
	v_mfma_f32_16x16x32_bf16 v[80:83], v[194:197], v[226:229], v[80:83]
	v_mfma_f32_16x16x32_bf16 v[76:79], v[202:205], v[218:221], v[76:79]
	v_mfma_f32_16x16x32_bf16 v[72:75], v[202:205], v[226:229], v[72:75]
	v_mfma_f32_16x16x32_bf16 v[68:71], v[210:213], v[218:221], v[68:71]
	v_mfma_f32_16x16x32_bf16 v[64:67], v[210:213], v[226:229], v[64:67]
	v_mfma_f32_16x16x32_bf16 v[92:95], v[190:193], v[222:225], v[92:95]
	v_mfma_f32_16x16x32_bf16 v[88:91], v[190:193], v[230:233], v[88:91]
	v_mfma_f32_16x16x32_bf16 v[84:87], v[198:201], v[222:225], v[84:87]
	v_mfma_f32_16x16x32_bf16 v[80:83], v[198:201], v[230:233], v[80:83]
	v_mfma_f32_16x16x32_bf16 v[76:79], v[206:209], v[222:225], v[76:79]
	v_mfma_f32_16x16x32_bf16 v[72:75], v[206:209], v[230:233], v[72:75]
	v_mfma_f32_16x16x32_bf16 v[68:71], v[214:217], v[222:225], v[68:71]
	v_mfma_f32_16x16x32_bf16 v[64:67], v[214:217], v[230:233], v[64:67]
	s_setprio 0
	s_barrier
	ds_read_b128 v[186:189], v135 offset:49152
	ds_read_b128 v[190:193], v135 offset:50176
	ds_read_b128 v[194:197], v156 offset:49152
	ds_read_b128 v[198:201], v156 offset:50176
	ds_read_b128 v[202:205], v157 offset:49152
	ds_read_b128 v[206:209], v157 offset:50176
	ds_read_b128 v[210:213], v158 offset:49152
	ds_read_b128 v[214:217], v158 offset:50176
	s_add_u32 m0, s32, 0x8000
	s_add_u32 s98, s18, 0x180
	s_addc_u32 s99, s19, 0
	global_load_lds_dwordx4 v253, s[98:99]
	s_nop 0
	s_add_u32 m0, s32, 0xa000
	s_nop 0
	global_load_lds_dwordx4 v252, s[98:99]
	s_setprio 1
	s_barrier
; #define LDA(dst, b, h)                                                                                    \
;   _Pragma("unroll") for (int m = 0; m < 4; ++m) _Pragma("unroll") for (int k = 0; k < 2; ++k)             \
;       dst[m][k] = *reinterpret_cast<const bf16x8*>((char*)SA(b, h) + lds_byte(wr * 64 + m * 16 + fr, k * 32 + fq * 8))
; #define LDB(dst, b, h)                                                                                    \
;   _Pragma("unroll") for (int n = 0; n < 2; ++n) _Pragma("unroll") for (int k = 0; k < 2; ++k)             \
;       dst[n][k] = *reinterpret_cast<const bf16x8*>((char*)SB(b, h) + lds_byte(wc * 32 + n * 16 + fr, k * 32 + fq * 8))
; #define WAIT_V(n) asm volatile("s_waitcnt vmcnt(" #n ")" ::: "memory")
; #define WAIT_L(n) asm volatile("s_waitcnt lgkmcnt(" #n ")" ::: "memory")
; #define BAR __builtin_amdgcn_s_barrier()
; #define SCHED __builtin_amdgcn_sched_barrier(0)
; template <int EPI> ...
;     ...
;     LDA(At, 1, 1); STAGE(SA(1, 0), A, brow, t + 3);
;     BAR; WAIT_L(0); MMA(1, 0, At, B0); BAR; SCHED;
;     STAGE(SB(1, 1), Bt, bcol + HALF, t + 3);
;     WAIT_V(6); BAR; MMA(1, 1, At, B1); BAR;
;   }
;   {
;     LDB(B0, 0, 0); LDA(At, 0, 0); STAGE(SA(1, 1), A, brow + HALF, nt - 1);
;     BAR; WAIT_L(0); MMA(0, 0, At, B0); BAR;
;     LDB(B1, 0, 1); BAR; WAIT_L(0); MMA(0, 1, At, B1); BAR;
;     LDA(At, 0, 1); WAIT_V(4); BAR; WAIT_L(0); MMA(1, 0, At, B0); MMA(1, 1, At, B1); BAR;
	s_waitcnt lgkmcnt(0)
	v_mfma_f32_16x16x32_bf16 v[60:63], v[186:189], v[162:165], v[60:63]
	v_mfma_f32_16x16x32_bf16 v[56:59], v[186:189], v[178:181], v[56:59]
	v_mfma_f32_16x16x32_bf16 v[52:55], v[194:197], v[162:165], v[52:55]
	v_mfma_f32_16x16x32_bf16 v[48:51], v[194:197], v[178:181], v[48:51]
	v_mfma_f32_16x16x32_bf16 v[44:47], v[202:205], v[162:165], v[44:47]
	v_mfma_f32_16x16x32_bf16 v[40:43], v[202:205], v[178:181], v[40:43]
	v_mfma_f32_16x16x32_bf16 v[36:39], v[210:213], v[162:165], v[36:39]
	v_mfma_f32_16x16x32_bf16 v[32:35], v[210:213], v[178:181], v[32:35]
	v_mfma_f32_16x16x32_bf16 v[60:63], v[190:193], v[174:177], v[60:63]
	v_mfma_f32_16x16x32_bf16 v[56:59], v[190:193], v[182:185], v[56:59]
	v_mfma_f32_16x16x32_bf16 v[52:55], v[198:201], v[174:177], v[52:55]
	v_mfma_f32_16x16x32_bf16 v[48:51], v[198:201], v[182:185], v[48:51]
	v_mfma_f32_16x16x32_bf16 v[44:47], v[206:209], v[174:177], v[44:47]
	v_mfma_f32_16x16x32_bf16 v[40:43], v[206:209], v[182:185], v[40:43]
	v_mfma_f32_16x16x32_bf16 v[36:39], v[214:217], v[174:177], v[36:39]
	v_mfma_f32_16x16x32_bf16 v[32:35], v[214:217], v[182:185], v[32:35]
	s_setprio 0
	s_barrier
	s_add_u32 m0, s32, 0x1c000
	s_add_u32 s98, s20, 0xb0180
	s_addc_u32 s99, s21, 0
	global_load_lds_dwordx4 v253, s[98:99]
	s_add_u32 m0, s32, 0x1e000
	s_nop 0
	global_load_lds_dwordx4 v252, s[98:99]
	s_waitcnt vmcnt(6)
	s_barrier
	s_setprio 1
	v_mfma_f32_16x16x32_bf16 v[28:31], v[186:189], v[218:221], v[28:31]
	v_mfma_f32_16x16x32_bf16 v[24:27], v[186:189], v[226:229], v[24:27]
	v_mfma_f32_16x16x32_bf16 v[20:23], v[194:197], v[218:221], v[20:23]
	v_mfma_f32_16x16x32_bf16 v[16:19], v[194:197], v[226:229], v[16:19]
	v_mfma_f32_16x16x32_bf16 v[12:15], v[202:205], v[218:221], v[12:15]
	v_mfma_f32_16x16x32_bf16 v[8:11], v[202:205], v[226:229], v[8:11]
	v_mfma_f32_16x16x32_bf16 v[4:7], v[210:213], v[218:221], v[4:7]
	v_mfma_f32_16x16x32_bf16 v[0:3], v[210:213], v[226:229], v[0:3]
	v_mfma_f32_16x16x32_bf16 v[28:31], v[190:193], v[222:225], v[28:31]
	v_mfma_f32_16x16x32_bf16 v[24:27], v[190:193], v[230:233], v[24:27]
	v_mfma_f32_16x16x32_bf16 v[20:23], v[198:201], v[222:225], v[20:23]
	v_mfma_f32_16x16x32_bf16 v[16:19], v[198:201], v[230:233], v[16:19]
	v_mfma_f32_16x16x32_bf16 v[12:15], v[206:209], v[222:225], v[12:15]
	v_mfma_f32_16x16x32_bf16 v[8:11], v[206:209], v[230:233], v[8:11]
	v_mfma_f32_16x16x32_bf16 v[4:7], v[214:217], v[222:225], v[4:7]
	v_mfma_f32_16x16x32_bf16 v[0:3], v[214:217], v[230:233], v[0:3]
	s_setprio 0
	s_add_i32 s70, s70, 2
	s_add_u32 s16, s16, 0x100
	s_addc_u32 s17, s17, 0
	s_cmp_lt_u32 s70, 40
	s_barrier
	s_cbranch_scc1 .LBB0_1779
	s_add_u32 s10, s14, 0x1580
	ds_read_b128 v[142:145], v155
	ds_read_b128 v[162:165], v155 offset:1024
	ds_read_b128 v[174:177], v155 offset:2048
	ds_read_b128 v[178:181], v155 offset:3072
	ds_read_b128 v[182:185], v135
	ds_read_b128 v[186:189], v135 offset:1024
	ds_read_b128 v[190:193], v156
	ds_read_b128 v[194:197], v156 offset:1024
	ds_read_b128 v[198:201], v157
	ds_read_b128 v[202:205], v157 offset:1024
	ds_read_b128 v[206:209], v158
	ds_read_b128 v[210:213], v158 offset:1024
	s_addc_u32 s11, s15, 0
	v_mov_b32_e32 v129, v149
	v_readfirstlane_b32 s12, v159
	v_lshl_add_u64 v[128:129], v[128:129], 1, s[10:11]
	s_mov_b32 m0, s12
	v_mov_b32_e32 v131, v149
	global_load_lds_dwordx4 v[128:129], off
	s_nop 0
	v_lshl_add_u64 v[128:129], v[130:131], 1, s[10:11]
	v_readfirstlane_b32 s10, v160
	s_mov_b32 m0, s10
	s_nop 0
	global_load_lds_dwordx4 v[128:129], off
	s_setprio 1
	s_barrier
	s_waitcnt lgkmcnt(0)
	v_mfma_f32_16x16x32_bf16 v[124:127], v[182:185], v[142:145], v[124:127]
	v_mfma_f32_16x16x32_bf16 v[120:123], v[182:185], v[174:177], v[120:123]
	v_mfma_f32_16x16x32_bf16 v[116:119], v[190:193], v[142:145], v[116:119]
	v_mfma_f32_16x16x32_bf16 v[112:115], v[190:193], v[174:177], v[112:115]
	v_mfma_f32_16x16x32_bf16 v[108:111], v[198:201], v[142:145], v[108:111]
	v_mfma_f32_16x16x32_bf16 v[104:107], v[198:201], v[174:177], v[104:107]
	v_mfma_f32_16x16x32_bf16 v[96:99], v[206:209], v[174:177], v[96:99]
	v_mfma_f32_16x16x32_bf16 v[124:127], v[186:189], v[162:165], v[124:127]
	v_mfma_f32_16x16x32_bf16 v[120:123], v[186:189], v[178:181], v[120:123]
	v_mfma_f32_16x16x32_bf16 v[116:119], v[194:197], v[162:165], v[116:119]
	v_mfma_f32_16x16x32_bf16 v[112:115], v[194:197], v[178:181], v[112:115]
	v_mfma_f32_16x16x32_bf16 v[108:111], v[202:205], v[162:165], v[108:111]
	v_mfma_f32_16x16x32_bf16 v[104:107], v[202:205], v[178:181], v[104:107]
	v_mfma_f32_16x16x32_bf16 v[100:103], v[206:209], v[142:145], v[100:103]
	v_mfma_f32_16x16x32_bf16 v[96:99], v[210:213], v[178:181], v[96:99]
	v_mfma_f32_16x16x32_bf16 v[128:131], v[210:213], v[162:165], v[100:103]
	s_setprio 0
	s_barrier
	s_nop 3
	ds_read_b128 v[100:103], v152
	ds_read_b128 v[214:217], v152 offset:1024
	ds_read_b128 v[218:221], v152 offset:2048
	ds_read_b128 v[152:155], v152 offset:3072
	s_setprio 1
	s_barrier
	s_waitcnt lgkmcnt(0)
	v_mfma_f32_16x16x32_bf16 v[88:91], v[182:185], v[218:221], v[88:91]
	v_mfma_f32_16x16x32_bf16 v[92:95], v[182:185], v[100:103], v[92:95]
	v_mfma_f32_16x16x32_bf16 v[88:91], v[186:189], v[152:155], v[88:91]
	v_mfma_f32_16x16x32_bf16 v[84:87], v[190:193], v[100:103], v[84:87]
	v_mfma_f32_16x16x32_bf16 v[80:83], v[190:193], v[218:221], v[80:83]
	v_mfma_f32_16x16x32_bf16 v[76:79], v[198:201], v[100:103], v[76:79]
	v_mfma_f32_16x16x32_bf16 v[72:75], v[198:201], v[218:221], v[72:75]
	v_mfma_f32_16x16x32_bf16 v[68:71], v[206:209], v[100:103], v[68:71]
	v_mfma_f32_16x16x32_bf16 v[64:67], v[206:209], v[218:221], v[64:67]
	v_mfma_f32_16x16x32_bf16 v[222:225], v[186:189], v[214:217], v[92:95]
	v_mfma_f32_16x16x32_bf16 v[182:185], v[194:197], v[214:217], v[84:87]
	v_mfma_f32_16x16x32_bf16 v[186:189], v[194:197], v[152:155], v[80:83]
	v_mfma_f32_16x16x32_bf16 v[190:193], v[202:205], v[214:217], v[76:79]
	v_mfma_f32_16x16x32_bf16 v[194:197], v[202:205], v[152:155], v[72:75]
	v_mfma_f32_16x16x32_bf16 v[198:201], v[210:213], v[214:217], v[68:71]
	v_mfma_f32_16x16x32_bf16 v[202:205], v[210:213], v[152:155], v[64:67]
	s_setprio 0
	s_barrier
; #define LDA(dst, b, h)                                                                                    \
;   _Pragma("unroll") for (int m = 0; m < 4; ++m) _Pragma("unroll") for (int k = 0; k < 2; ++k)             \
;       dst[m][k] = *reinterpret_cast<const bf16x8*>((char*)SA(b, h) + lds_byte(wr * 64 + m * 16 + fr, k * 32 + fq * 8))
; #define LDB(dst, b, h)                                                                                    \
;   _Pragma("unroll") for (int n = 0; n < 2; ++n) _Pragma("unroll") for (int k = 0; k < 2; ++k)             \
;       dst[n][k] = *reinterpret_cast<const bf16x8*>((char*)SB(b, h) + lds_byte(wc * 32 + n * 16 + fr, k * 32 + fq * 8))
; #define WAIT_V(n) asm volatile("s_waitcnt vmcnt(" #n ")" ::: "memory")
; #define WAIT_L(n) asm volatile("s_waitcnt lgkmcnt(" #n ")" ::: "memory")
; #define BAR __builtin_amdgcn_s_barrier()
; template <int EPI> ...
;     ...
;     LDB(B1, 0, 1); BAR; WAIT_L(0); MMA(0, 1, At, B1); BAR;
;     LDA(At, 0, 1); WAIT_V(4); BAR; WAIT_L(0); MMA(1, 0, At, B0); MMA(1, 1, At, B1); BAR;
;   }
;   {
;     LDB(B0, 1, 0); LDA(At, 1, 0); WAIT_V(2); BAR; WAIT_L(0); MMA(0, 0, At, B0); BAR;
	s_nop 0
	ds_read_b128 v[64:67], v135 offset:16384
	ds_read_b128 v[68:71], v135 offset:17408
	ds_read_b128 v[72:75], v156 offset:16384
	ds_read_b128 v[76:79], v156 offset:17408
	ds_read_b128 v[80:83], v157 offset:16384
	ds_read_b128 v[84:87], v157 offset:17408
	ds_read_b128 v[92:95], v158 offset:16384
	ds_read_b128 v[206:209], v158 offset:17408
	s_waitcnt vmcnt(4)
	s_setprio 1
	s_barrier
	s_waitcnt lgkmcnt(0)
	v_mfma_f32_16x16x32_bf16 v[60:63], v[64:67], v[142:145], v[60:63]
	v_mfma_f32_16x16x32_bf16 v[56:59], v[64:67], v[174:177], v[56:59]
	v_mfma_f32_16x16x32_bf16 v[52:55], v[72:75], v[142:145], v[52:55]
	v_mfma_f32_16x16x32_bf16 v[48:51], v[72:75], v[174:177], v[48:51]
	v_mfma_f32_16x16x32_bf16 v[44:47], v[80:83], v[142:145], v[44:47]
	v_mfma_f32_16x16x32_bf16 v[40:43], v[80:83], v[174:177], v[40:43]
	v_mfma_f32_16x16x32_bf16 v[36:39], v[92:95], v[142:145], v[36:39]
	v_mfma_f32_16x16x32_bf16 v[32:35], v[92:95], v[174:177], v[32:35]
	v_mfma_f32_16x16x32_bf16 v[60:63], v[68:71], v[162:165], v[60:63]
	v_mfma_f32_16x16x32_bf16 v[56:59], v[68:71], v[178:181], v[56:59]
	v_mfma_f32_16x16x32_bf16 v[52:55], v[76:79], v[162:165], v[52:55]
	v_mfma_f32_16x16x32_bf16 v[48:51], v[76:79], v[178:181], v[48:51]
	v_mfma_f32_16x16x32_bf16 v[44:47], v[84:87], v[162:165], v[44:47]
	v_mfma_f32_16x16x32_bf16 v[40:43], v[84:87], v[178:181], v[40:43]
	v_mfma_f32_16x16x32_bf16 v[36:39], v[206:209], v[162:165], v[36:39]
	v_mfma_f32_16x16x32_bf16 v[32:35], v[206:209], v[178:181], v[32:35]
	s_setprio 0
	s_setprio 1
	v_mfma_f32_16x16x32_bf16 v[28:31], v[64:67], v[100:103], v[28:31]
	v_mfma_f32_16x16x32_bf16 v[24:27], v[64:67], v[218:221], v[24:27]
	v_mfma_f32_16x16x32_bf16 v[20:23], v[72:75], v[100:103], v[20:23]
	v_mfma_f32_16x16x32_bf16 v[16:19], v[72:75], v[218:221], v[16:19]
	v_mfma_f32_16x16x32_bf16 v[12:15], v[80:83], v[100:103], v[12:15]
	v_mfma_f32_16x16x32_bf16 v[8:11], v[80:83], v[218:221], v[8:11]
	v_mfma_f32_16x16x32_bf16 v[4:7], v[92:95], v[100:103], v[4:7]
	v_mfma_f32_16x16x32_bf16 v[0:3], v[92:95], v[218:221], v[0:3]
	v_mfma_f32_16x16x32_bf16 v[142:145], v[68:71], v[214:217], v[28:31]
	v_mfma_f32_16x16x32_bf16 v[160:163], v[68:71], v[152:155], v[24:27]
	v_mfma_f32_16x16x32_bf16 v[164:167], v[76:79], v[214:217], v[20:23]
	v_mfma_f32_16x16x32_bf16 v[174:177], v[76:79], v[152:155], v[16:19]
	v_mfma_f32_16x16x32_bf16 v[178:181], v[84:87], v[214:217], v[12:15]
	v_mfma_f32_16x16x32_bf16 v[210:213], v[84:87], v[152:155], v[8:11]
	v_mfma_f32_16x16x32_bf16 v[214:217], v[206:209], v[214:217], v[4:7]
	v_mfma_f32_16x16x32_bf16 v[152:155], v[206:209], v[152:155], v[0:3]
	s_setprio 0
	s_barrier
	s_nop 0
	ds_read_b128 v[0:3], v140
	ds_read_b128 v[4:7], v140 offset:1024
	ds_read_b128 v[206:209], v140 offset:2048
	ds_read_b128 v[138:141], v140 offset:3072
	ds_read_b128 v[8:11], v135 offset:32768
	ds_read_b128 v[12:15], v135 offset:33792
	ds_read_b128 v[16:19], v156 offset:32768
	ds_read_b128 v[20:23], v156 offset:33792
	ds_read_b128 v[24:27], v157 offset:32768
	ds_read_b128 v[28:31], v157 offset:33792
	ds_read_b128 v[218:221], v158 offset:32768
	ds_read_b128 v[226:229], v158 offset:33792
	s_waitcnt vmcnt(2)
	s_setprio 1
	s_barrier
	s_waitcnt lgkmcnt(0)
	v_mfma_f32_16x16x32_bf16 v[64:67], v[8:11], v[0:3], v[124:127]
	v_mfma_f32_16x16x32_bf16 v[92:95], v[12:15], v[4:7], v[64:67]
	v_mfma_f32_16x16x32_bf16 v[64:67], v[8:11], v[206:209], v[120:123]
	v_mfma_f32_16x16x32_bf16 v[100:103], v[12:15], v[138:141], v[64:67]
	v_mfma_f32_16x16x32_bf16 v[64:67], v[16:19], v[0:3], v[116:119]
	v_mfma_f32_16x16x32_bf16 v[80:83], v[20:23], v[4:7], v[64:67]
	v_mfma_f32_16x16x32_bf16 v[64:67], v[16:19], v[206:209], v[112:115]
	v_mfma_f32_16x16x32_bf16 v[84:87], v[20:23], v[138:141], v[64:67]
	v_mfma_f32_16x16x32_bf16 v[64:67], v[24:27], v[0:3], v[108:111]
	v_mfma_f32_16x16x32_bf16 v[72:75], v[28:31], v[4:7], v[64:67]
	v_mfma_f32_16x16x32_bf16 v[64:67], v[24:27], v[206:209], v[104:107]
	v_mfma_f32_16x16x32_bf16 v[76:79], v[28:31], v[138:141], v[64:67]
	v_mfma_f32_16x16x32_bf16 v[64:67], v[218:221], v[0:3], v[128:131]
	v_mfma_f32_16x16x32_bf16 v[68:71], v[218:221], v[206:209], v[96:99]
	v_mfma_f32_16x16x32_bf16 v[64:67], v[226:229], v[4:7], v[64:67]
	v_mfma_f32_16x16x32_bf16 v[68:71], v[226:229], v[138:141], v[68:71]
	s_setprio 0
	s_barrier
; #define LDA(dst, b, h)                                                                                    \
;   _Pragma("unroll") for (int m = 0; m < 4; ++m) _Pragma("unroll") for (int k = 0; k < 2; ++k)             \
;       dst[m][k] = *reinterpret_cast<const bf16x8*>((char*)SA(b, h) + lds_byte(wr * 64 + m * 16 + fr, k * 32 + fq * 8))
; #define LDB(dst, b, h)                                                                                    \
;   _Pragma("unroll") for (int n = 0; n < 2; ++n) _Pragma("unroll") for (int k = 0; k < 2; ++k)             \
;       dst[n][k] = *reinterpret_cast<const bf16x8*>((char*)SB(b, h) + lds_byte(wc * 32 + n * 16 + fr, k * 32 + fq * 8))
; #define WAIT_V(n) asm volatile("s_waitcnt vmcnt(" #n ")" ::: "memory")
; #define WAIT_L(n) asm volatile("s_waitcnt lgkmcnt(" #n ")" ::: "memory")
; #define BAR __builtin_amdgcn_s_barrier()
; template <int EPI> ...
;     ...
;     LDB(B0, 1, 0); LDA(At, 1, 0); WAIT_V(2); BAR; WAIT_L(0); MMA(0, 0, At, B0); BAR;
;     LDB(B1, 1, 1); WAIT_V(0); BAR; WAIT_L(0); MMA(0, 1, At, B1); BAR;
;     LDA(At, 1, 1); BAR; WAIT_L(0); MMA(1, 0, At, B0); MMA(1, 1, At, B1); BAR;
;   }
;   if (wr == 0) BAR;
	ds_read_b128 v[128:131], v137
	ds_read_b128 v[230:233], v137 offset:1024
	ds_read_b128 v[234:237], v137 offset:2048
	ds_read_b128 v[238:241], v137 offset:3072
	s_waitcnt vmcnt(0)
	s_setprio 1
	s_barrier
	s_waitcnt lgkmcnt(0)
	v_mfma_f32_16x16x32_bf16 v[96:99], v[8:11], v[128:131], v[222:225]
	v_mfma_f32_16x16x32_bf16 v[8:11], v[8:11], v[234:237], v[88:91]
	v_mfma_f32_16x16x32_bf16 v[124:127], v[12:15], v[238:241], v[8:11]
	v_mfma_f32_16x16x32_bf16 v[8:11], v[16:19], v[128:131], v[182:185]
	v_mfma_f32_16x16x32_bf16 v[112:115], v[20:23], v[230:233], v[8:11]
	v_mfma_f32_16x16x32_bf16 v[8:11], v[16:19], v[234:237], v[186:189]
	v_mfma_f32_16x16x32_bf16 v[116:119], v[20:23], v[238:241], v[8:11]
	v_mfma_f32_16x16x32_bf16 v[8:11], v[24:27], v[128:131], v[190:193]
	v_mfma_f32_16x16x32_bf16 v[104:107], v[28:31], v[230:233], v[8:11]
	v_mfma_f32_16x16x32_bf16 v[8:11], v[24:27], v[234:237], v[194:197]
	v_mfma_f32_16x16x32_bf16 v[108:111], v[28:31], v[238:241], v[8:11]
	v_mfma_f32_16x16x32_bf16 v[8:11], v[218:221], v[128:131], v[198:201]
	v_mfma_f32_16x16x32_bf16 v[88:91], v[226:229], v[230:233], v[8:11]
	v_mfma_f32_16x16x32_bf16 v[8:11], v[218:221], v[234:237], v[202:205]
	v_mfma_f32_16x16x32_bf16 v[120:123], v[12:15], v[230:233], v[96:99]
	v_mfma_f32_16x16x32_bf16 v[96:99], v[226:229], v[238:241], v[8:11]
	s_setprio 0
	s_barrier
	ds_read_b128 v[182:185], v135 offset:49152
	ds_read_b128 v[134:137], v135 offset:50176
	ds_read_b128 v[186:189], v156 offset:49152
	ds_read_b128 v[190:193], v156 offset:50176
	ds_read_b128 v[194:197], v157 offset:49152
	ds_read_b128 v[198:201], v157 offset:50176
	ds_read_b128 v[202:205], v158 offset:49152
	ds_read_b128 v[156:159], v158 offset:50176
	s_setprio 1
	s_barrier
	s_waitcnt lgkmcnt(0)
	v_mfma_f32_16x16x32_bf16 v[8:11], v[182:185], v[0:3], v[60:63]
	v_mfma_f32_16x16x32_bf16 v[24:27], v[134:137], v[4:7], v[8:11]
	v_mfma_f32_16x16x32_bf16 v[8:11], v[182:185], v[206:209], v[56:59]
	v_mfma_f32_16x16x32_bf16 v[28:31], v[134:137], v[138:141], v[8:11]
	v_mfma_f32_16x16x32_bf16 v[8:11], v[186:189], v[0:3], v[52:55]
	v_mfma_f32_16x16x32_bf16 v[16:19], v[190:193], v[4:7], v[8:11]
	v_mfma_f32_16x16x32_bf16 v[8:11], v[186:189], v[206:209], v[48:51]
	v_mfma_f32_16x16x32_bf16 v[20:23], v[190:193], v[138:141], v[8:11]
	v_mfma_f32_16x16x32_bf16 v[8:11], v[194:197], v[0:3], v[44:47]
	v_mfma_f32_16x16x32_bf16 v[0:3], v[202:205], v[0:3], v[36:39]
	v_mfma_f32_16x16x32_bf16 v[8:11], v[198:201], v[4:7], v[8:11]
	v_mfma_f32_16x16x32_bf16 v[12:15], v[194:197], v[206:209], v[40:43]
	v_mfma_f32_16x16x32_bf16 v[0:3], v[156:159], v[4:7], v[0:3]
	v_mfma_f32_16x16x32_bf16 v[4:7], v[202:205], v[206:209], v[32:35]
	v_mfma_f32_16x16x32_bf16 v[12:15], v[198:201], v[138:141], v[12:15]
	v_mfma_f32_16x16x32_bf16 v[4:7], v[156:159], v[138:141], v[4:7]
	s_setprio 0
	s_setprio 1
	v_mfma_f32_16x16x32_bf16 v[32:35], v[182:185], v[128:131], v[142:145]
	v_mfma_f32_16x16x32_bf16 v[56:59], v[134:137], v[230:233], v[32:35]
	v_mfma_f32_16x16x32_bf16 v[32:35], v[182:185], v[234:237], v[160:163]
	v_mfma_f32_16x16x32_bf16 v[60:63], v[134:137], v[238:241], v[32:35]
	v_mfma_f32_16x16x32_bf16 v[32:35], v[186:189], v[128:131], v[164:167]
	v_mfma_f32_16x16x32_bf16 v[48:51], v[190:193], v[230:233], v[32:35]
	v_mfma_f32_16x16x32_bf16 v[32:35], v[186:189], v[234:237], v[174:177]
	v_mfma_f32_16x16x32_bf16 v[52:55], v[190:193], v[238:241], v[32:35]
	v_mfma_f32_16x16x32_bf16 v[32:35], v[194:197], v[128:131], v[178:181]
	v_mfma_f32_16x16x32_bf16 v[40:43], v[198:201], v[230:233], v[32:35]
	v_mfma_f32_16x16x32_bf16 v[32:35], v[194:197], v[234:237], v[210:213]
	v_mfma_f32_16x16x32_bf16 v[44:47], v[198:201], v[238:241], v[32:35]
	v_mfma_f32_16x16x32_bf16 v[32:35], v[202:205], v[128:131], v[214:217]
	v_mfma_f32_16x16x32_bf16 v[36:39], v[202:205], v[234:237], v[152:155]
	v_mfma_f32_16x16x32_bf16 v[32:35], v[156:159], v[230:233], v[32:35]
	v_mfma_f32_16x16x32_bf16 v[36:39], v[156:159], v[238:241], v[36:39]
	s_setprio 0
	s_cmpk_gt_u32 s30, 0xff
	s_barrier
	s_cbranch_scc1 .LBB0_1782
	s_barrier

; DEVI f32x4 ozero() { float z = 0.f; asm volatile("" : "+v"(z)); return f32x4{z, z, z, z}; }
; #define LDA(dst, b, h)                                                                                    \
;   _Pragma("unroll") for (int m = 0; m < 4; ++m) _Pragma("unroll") for (int k = 0; k < 2; ++k)             \
;       dst[m][k] = *reinterpret_cast<const bf16x8*>((char*)SA(b, h) + lds_byte(wr * 64 + m * 16 + fr, k * 32 + fq * 8))
; #define LDB(dst, b, h)                                                                                    \
;   _Pragma("unroll") for (int n = 0; n < 2; ++n) _Pragma("unroll") for (int k = 0; k < 2; ++k)             \
;       dst[n][k] = *reinterpret_cast<const bf16x8*>((char*)SB(b, h) + lds_byte(wc * 32 + n * 16 + fr, k * 32 + fq * 8))
; #define WAIT_V(n) asm volatile("s_waitcnt vmcnt(" #n ")" ::: "memory")
; #define WAIT_L(n) asm volatile("s_waitcnt lgkmcnt(" #n ")" ::: "memory")
; #define BAR __builtin_amdgcn_s_barrier()
; #define SCHED __builtin_amdgcn_sched_barrier(0)
; template <int EPI> ...
;     ...
;   const int wid = __builtin_amdgcn_readfirstlane(tid >> 6), lane = tid & 63, wr = wid >> 2, wc = wid & 3, fr = lane & 15, fq = lane >> 4;
;   f32x4 acc[2][2][4][2];
;   {
;     const f32x4 zq = ozero();
; #pragma unroll
;     for (int a_ = 0; a_ < 2; ++a_)
; #pragma unroll
;       for (int b_ = 0; b_ < 2; ++b_)
; #pragma unroll
;         for (int m = 0; m < 4; ++m) { acc[a_][b_][m][0] = zq; acc[a_][b_][m][1] = zq; }
;   }
;   bf16x8 At[4][2], B0[2][2], B1[2][2];
;   const int nt = K / BK;
;     ...
;   if (first) {
;     WAIT_V(0);
;     ISSUE_PRO(brow, bcol);
;   }
;   if (wr == 1) BAR;
;   WAIT_V(10); BAR;
;   WAIT_V(6); BAR;
;   for (int t = 0; t < nt - 2; t += 2) {
;     LDB(B0, 0, 0); SCHED; LDA(At, 0, 0); STAGE(SA(1, 1), A, brow + HALF, t + 1);
;     WAIT_L(8); BAR; WAIT_L(0); MMA(0, 0, At, B0); BAR; SCHED;
;     LDB(B1, 0, 1); STAGE(SB(0, 0), Bt, bcol, t + 2);
;     BAR; WAIT_L(0); MMA(0, 1, At, B1); BAR;
;     LDA(At, 0, 1); STAGE(SA(0, 0), A, brow, t + 2);
;     BAR; WAIT_L(0); MMA(1, 0, At, B0); BAR; SCHED;
.LBB0_1856:
	s_ashr_i32 s11, s31, 6
	s_and_b32 s34, s11, 3
	v_and_b32_e32 v129, 15, v128
	v_and_b32_e32 v9, 48, v128
	v_lshlrev_b32_e32 v130, 2, v128
	s_lshl_b32 s35, s34, 12
	v_lshl_or_b32 v8, v129, 6, v9
	v_and_b32_e32 v46, 32, v130
	v_bitop3_b32 v126, s35, v8, v46 bitop3:0xf6
	v_or_b32_e32 v127, 0x10000, v126
	v_or_b32_e32 v222, 0x10800, v126
	s_waitcnt vmcnt(10)
	s_barrier
	s_waitcnt vmcnt(6)
	s_barrier
	v_or_b32_e32 v131, 0x10400, v126
	ds_read_b128 v[22:25], v127
	ds_read_b128 v[26:29], v131
	v_or_b32_e32 v223, 0x10c00, v126
	ds_read_b128 v[30:33], v222
	ds_read_b128 v[34:37], v223
	v_mov_b32_e32 v1, v0
	v_mov_b32_e32 v2, v0
	v_mov_b32_e32 v3, v0
	v_lshlrev_b32_e32 v47, 6, v128
	s_movk_i32 s62, 0x3c0
	s_lshl_b32 s35, s30, 13
	v_and_or_b32 v9, v47, s62, v9
	v_bitop3_b32 v8, s35, v8, v46 bitop3:0xf6
	v_bitop3_b32 v9, s35, v9, v46 bitop3:0xf6
	v_mov_b32_e32 v148, v4
	v_add_u32_e32 v72, 0xc000, v12
	ds_read_b128 v[38:41], v8
	ds_read_b128 v[42:45], v8 offset:1024
	ds_read_b128 v[46:49], v9 offset:2048
	ds_read_b128 v[50:53], v9 offset:3072
	ds_read_b128 v[54:57], v9 offset:4096
	ds_read_b128 v[58:61], v9 offset:5120
	ds_read_b128 v[62:65], v9 offset:6144
	ds_read_b128 v[66:69], v9 offset:7168
	v_readfirstlane_b32 s62, v72
	v_lshl_add_u64 v[70:71], v[148:149], 1, s[12:13]
	v_lshl_add_u64 v[70:71], v[70:71], 0, s[46:47]
	s_mov_b32 m0, s62
	v_mov_b32_e32 v148, v6
	v_add_u32_e32 v72, 0xe000, v12
	global_load_lds_dwordx4 v[70:71], off
	v_readfirstlane_b32 s35, v72
	v_lshl_add_u64 v[70:71], v[148:149], 1, s[12:13]
	v_lshl_add_u64 v[70:71], v[70:71], 0, s[46:47]
	s_mov_b32 m0, s35
	s_nop 0
	global_load_lds_dwordx4 v[70:71], off
	s_waitcnt lgkmcnt(8)
	s_setprio 1
	s_barrier
	s_waitcnt lgkmcnt(0)
	v_mfma_f32_16x16x32_bf16 v[70:73], v[38:41], v[22:25], v[0:3]
	v_mfma_f32_16x16x32_bf16 v[74:77], v[38:41], v[30:33], v[0:3]
	v_mfma_f32_16x16x32_bf16 v[78:81], v[46:49], v[22:25], v[0:3]
	v_mfma_f32_16x16x32_bf16 v[82:85], v[46:49], v[30:33], v[0:3]
	v_mfma_f32_16x16x32_bf16 v[86:89], v[54:57], v[22:25], v[0:3]
	v_mfma_f32_16x16x32_bf16 v[90:93], v[54:57], v[30:33], v[0:3]
	v_mfma_f32_16x16x32_bf16 v[94:97], v[62:65], v[22:25], v[0:3]
	v_mfma_f32_16x16x32_bf16 v[98:101], v[62:65], v[30:33], v[0:3]
	v_mfma_f32_16x16x32_bf16 v[70:73], v[42:45], v[26:29], v[70:73]
	v_mfma_f32_16x16x32_bf16 v[74:77], v[42:45], v[34:37], v[74:77]
	v_mfma_f32_16x16x32_bf16 v[78:81], v[50:53], v[26:29], v[78:81]
	v_mfma_f32_16x16x32_bf16 v[82:85], v[50:53], v[34:37], v[82:85]
	v_mfma_f32_16x16x32_bf16 v[86:89], v[58:61], v[26:29], v[86:89]
	v_mfma_f32_16x16x32_bf16 v[90:93], v[58:61], v[34:37], v[90:93]
	v_mfma_f32_16x16x32_bf16 v[94:97], v[66:69], v[26:29], v[94:97]
	v_mfma_f32_16x16x32_bf16 v[98:101], v[66:69], v[34:37], v[98:101]
	s_setprio 0
	s_barrier
	v_or_b32_e32 v224, 0x14000, v126
	v_or_b32_e32 v226, 0x14800, v126
	v_mov_b32_e32 v148, v4
	v_or_b32_e32 v225, 0x14400, v126
	ds_read_b128 v[102:105], v224
	ds_read_b128 v[106:109], v225
	v_or_b32_e32 v227, 0x14c00, v126
	ds_read_b128 v[110:113], v226
	ds_read_b128 v[114:117], v227
	v_readfirstlane_b32 s63, v20
	v_lshl_add_u64 v[118:119], v[148:149], 1, s[18:19]
	v_lshl_add_u64 v[118:119], v[118:119], 0, s[50:51]
	s_mov_b32 m0, s63
	v_mov_b32_e32 v148, v6
	global_load_lds_dwordx4 v[118:119], off
	v_readfirstlane_b32 s63, v21
	v_lshl_add_u64 v[118:119], v[148:149], 1, s[18:19]
	v_lshl_add_u64 v[118:119], v[118:119], 0, s[50:51]
	s_mov_b32 m0, s63
	s_nop 0
	global_load_lds_dwordx4 v[118:119], off
	s_setprio 1
	s_barrier
	s_waitcnt lgkmcnt(0)
	v_mfma_f32_16x16x32_bf16 v[118:121], v[38:41], v[102:105], v[0:3]
	v_mfma_f32_16x16x32_bf16 v[38:41], v[38:41], v[110:113], v[0:3]
	v_mfma_f32_16x16x32_bf16 v[118:121], v[42:45], v[106:109], v[118:121]
	v_mfma_f32_16x16x32_bf16 v[38:41], v[42:45], v[114:117], v[38:41]
	v_mfma_f32_16x16x32_bf16 v[42:45], v[46:49], v[102:105], v[0:3]
	v_mfma_f32_16x16x32_bf16 v[46:49], v[46:49], v[110:113], v[0:3]
	v_mfma_f32_16x16x32_bf16 v[42:45], v[50:53], v[106:109], v[42:45]
	v_mfma_f32_16x16x32_bf16 v[46:49], v[50:53], v[114:117], v[46:49]
	v_mfma_f32_16x16x32_bf16 v[50:53], v[54:57], v[102:105], v[0:3]
	v_mfma_f32_16x16x32_bf16 v[54:57], v[54:57], v[110:113], v[0:3]
	v_mfma_f32_16x16x32_bf16 v[50:53], v[58:61], v[106:109], v[50:53]
	v_mfma_f32_16x16x32_bf16 v[54:57], v[58:61], v[114:117], v[54:57]
	v_mfma_f32_16x16x32_bf16 v[58:61], v[62:65], v[102:105], v[0:3]
	v_mfma_f32_16x16x32_bf16 v[62:65], v[62:65], v[110:113], v[0:3]
	v_mfma_f32_16x16x32_bf16 v[58:61], v[66:69], v[106:109], v[58:61]
	v_mfma_f32_16x16x32_bf16 v[62:65], v[66:69], v[114:117], v[62:65]
	s_setprio 0
	v_mov_b32_e32 v148, v4
	s_barrier
	ds_read_b128 v[66:69], v8 offset:16384
	ds_read_b128 v[122:125], v8 offset:17408
	ds_read_b128 v[132:135], v9 offset:18432
	ds_read_b128 v[136:139], v9 offset:19456
	ds_read_b128 v[140:143], v9 offset:20480
	ds_read_b128 v[144:147], v9 offset:21504
	ds_read_b128 v[152:155], v9 offset:22528
	ds_read_b128 v[156:159], v9 offset:23552
	v_readfirstlane_b32 s63, v12
	v_lshl_add_u64 v[20:21], v[148:149], 1, s[16:17]
	v_lshl_add_u64 v[20:21], v[20:21], 0, s[50:51]
	s_mov_b32 m0, s63
	v_mov_b32_e32 v148, v6
	global_load_lds_dwordx4 v[20:21], off
	v_readfirstlane_b32 s63, v15
	v_lshl_add_u64 v[20:21], v[148:149], 1, s[16:17]
	v_lshl_add_u64 v[20:21], v[20:21], 0, s[50:51]
	s_mov_b32 m0, s63
	s_nop 0
	global_load_lds_dwordx4 v[20:21], off
	s_setprio 1
	s_barrier
; #define LDA(dst, b, h)                                                                                    \
;   _Pragma("unroll") for (int m = 0; m < 4; ++m) _Pragma("unroll") for (int k = 0; k < 2; ++k)             \
;       dst[m][k] = *reinterpret_cast<const bf16x8*>((char*)SA(b, h) + lds_byte(wr * 64 + m * 16 + fr, k * 32 + fq * 8))
; #define LDB(dst, b, h)                                                                                    \
;   _Pragma("unroll") for (int n = 0; n < 2; ++n) _Pragma("unroll") for (int k = 0; k < 2; ++k)             \
;       dst[n][k] = *reinterpret_cast<const bf16x8*>((char*)SB(b, h) + lds_byte(wc * 32 + n * 16 + fr, k * 32 + fq * 8))
; #define WAIT_V(n) asm volatile("s_waitcnt vmcnt(" #n ")" ::: "memory")
; #define WAIT_L(n) asm volatile("s_waitcnt lgkmcnt(" #n ")" ::: "memory")
; #define BAR __builtin_amdgcn_s_barrier()
; #define SCHED __builtin_amdgcn_sched_barrier(0)
; template <int EPI> ...
;     ...
;     BAR; WAIT_L(0); MMA(1, 0, At, B0); BAR; SCHED;
;     STAGE(SB(0, 1), Bt, bcol + HALF, t + 2);
;     WAIT_V(6); BAR; MMA(1, 1, At, B1); BAR;
;     LDB(B0, 1, 0); SCHED; LDA(At, 1, 0); STAGE(SA(0, 1), A, brow + HALF, t + 2);
;     WAIT_L(8); BAR; WAIT_L(0); MMA(0, 0, At, B0); BAR; SCHED;
;     LDB(B1, 1, 1); STAGE(SB(1, 0), Bt, bcol, t + 3);
;     BAR; WAIT_L(0); MMA(0, 1, At, B1); BAR;
	s_waitcnt lgkmcnt(0)
	v_mfma_f32_16x16x32_bf16 v[160:163], v[66:69], v[22:25], v[0:3]
	v_mfma_f32_16x16x32_bf16 v[174:177], v[132:135], v[22:25], v[0:3]
	v_mfma_f32_16x16x32_bf16 v[182:185], v[140:143], v[22:25], v[0:3]
	v_mfma_f32_16x16x32_bf16 v[20:23], v[152:155], v[22:25], v[0:3]
	v_mfma_f32_16x16x32_bf16 v[160:163], v[122:125], v[26:29], v[160:163]
	v_mfma_f32_16x16x32_bf16 v[174:177], v[136:139], v[26:29], v[174:177]
	v_mfma_f32_16x16x32_bf16 v[182:185], v[144:147], v[26:29], v[182:185]
	v_mfma_f32_16x16x32_bf16 v[20:23], v[156:159], v[26:29], v[20:23]
	v_mfma_f32_16x16x32_bf16 v[24:27], v[152:155], v[30:33], v[0:3]
	v_mfma_f32_16x16x32_bf16 v[164:167], v[66:69], v[30:33], v[0:3]
	v_mfma_f32_16x16x32_bf16 v[178:181], v[132:135], v[30:33], v[0:3]
	v_mfma_f32_16x16x32_bf16 v[186:189], v[140:143], v[30:33], v[0:3]
	v_mfma_f32_16x16x32_bf16 v[24:27], v[156:159], v[34:37], v[24:27]
	v_mfma_f32_16x16x32_bf16 v[164:167], v[122:125], v[34:37], v[164:167]
	v_mfma_f32_16x16x32_bf16 v[178:181], v[136:139], v[34:37], v[178:181]
	v_mfma_f32_16x16x32_bf16 v[186:189], v[144:147], v[34:37], v[186:189]
	s_setprio 0
	s_barrier
	v_mov_b32_e32 v148, v4
	v_readfirstlane_b32 s63, v18
	v_lshl_add_u64 v[28:29], v[148:149], 1, s[14:15]
	v_lshl_add_u64 v[28:29], v[28:29], 0, s[50:51]
	s_mov_b32 m0, s63
	v_mov_b32_e32 v148, v6
	global_load_lds_dwordx4 v[28:29], off
	v_readfirstlane_b32 s63, v19
	v_lshl_add_u64 v[28:29], v[148:149], 1, s[14:15]
	v_lshl_add_u64 v[28:29], v[28:29], 0, s[50:51]
	s_mov_b32 m0, s63
	s_nop 0
	global_load_lds_dwordx4 v[28:29], off
	s_waitcnt vmcnt(6)
	s_barrier
	s_setprio 1
	v_mfma_f32_16x16x32_bf16 v[28:31], v[66:69], v[102:105], v[0:3]
	v_mfma_f32_16x16x32_bf16 v[32:35], v[66:69], v[110:113], v[0:3]
	v_mfma_f32_16x16x32_bf16 v[28:31], v[122:125], v[106:109], v[28:31]
	v_mfma_f32_16x16x32_bf16 v[32:35], v[122:125], v[114:117], v[32:35]
	v_mfma_f32_16x16x32_bf16 v[66:69], v[132:135], v[102:105], v[0:3]
	v_mfma_f32_16x16x32_bf16 v[122:125], v[132:135], v[110:113], v[0:3]
	v_mfma_f32_16x16x32_bf16 v[66:69], v[136:139], v[106:109], v[66:69]
	v_mfma_f32_16x16x32_bf16 v[122:125], v[136:139], v[114:117], v[122:125]
	v_mfma_f32_16x16x32_bf16 v[132:135], v[140:143], v[102:105], v[0:3]
	v_mfma_f32_16x16x32_bf16 v[136:139], v[140:143], v[110:113], v[0:3]
	v_mfma_f32_16x16x32_bf16 v[102:105], v[152:155], v[102:105], v[0:3]
	v_mfma_f32_16x16x32_bf16 v[0:3], v[152:155], v[110:113], v[0:3]
	v_mfma_f32_16x16x32_bf16 v[102:105], v[156:159], v[106:109], v[102:105]
	v_mfma_f32_16x16x32_bf16 v[0:3], v[156:159], v[114:117], v[0:3]
	v_mfma_f32_16x16x32_bf16 v[132:135], v[144:147], v[106:109], v[132:135]
	v_mfma_f32_16x16x32_bf16 v[136:139], v[144:147], v[114:117], v[136:139]
	s_setprio 0
	v_or_b32_e32 v228, 0x18000, v126
	v_or_b32_e32 v230, 0x18800, v126
	s_barrier
	v_or_b32_e32 v229, 0x18400, v126
	ds_read_b128 v[106:109], v228
	ds_read_b128 v[110:113], v229
	v_or_b32_e32 v231, 0x18c00, v126
	ds_read_b128 v[114:117], v230
	ds_read_b128 v[140:143], v231
	v_mov_b32_e32 v148, v4
	ds_read_b128 v[144:147], v8 offset:32768
	ds_read_b128 v[152:155], v8 offset:33792
	ds_read_b128 v[156:159], v9 offset:34816
	ds_read_b128 v[190:193], v9 offset:35840
	ds_read_b128 v[194:197], v9 offset:36864
	ds_read_b128 v[198:201], v9 offset:37888
	ds_read_b128 v[202:205], v9 offset:38912
	ds_read_b128 v[206:209], v9 offset:39936
	v_readfirstlane_b32 s63, v16
	v_lshl_add_u64 v[18:19], v[148:149], 1, s[12:13]
	v_lshl_add_u64 v[18:19], v[18:19], 0, s[50:51]
	s_mov_b32 m0, s63
	v_mov_b32_e32 v148, v6
	global_load_lds_dwordx4 v[18:19], off
	v_readfirstlane_b32 s63, v17
	v_lshl_add_u64 v[18:19], v[148:149], 1, s[12:13]
	v_lshl_add_u64 v[18:19], v[18:19], 0, s[50:51]
	s_mov_b32 m0, s63
	s_nop 0
	global_load_lds_dwordx4 v[18:19], off
	s_waitcnt lgkmcnt(8)
	s_setprio 1
	s_barrier
	s_waitcnt lgkmcnt(0)
	v_mfma_f32_16x16x32_bf16 v[16:19], v[144:147], v[106:109], v[70:73]
	v_mfma_f32_16x16x32_bf16 v[70:73], v[144:147], v[114:117], v[74:77]
	v_mfma_f32_16x16x32_bf16 v[74:77], v[156:159], v[106:109], v[78:81]
	v_mfma_f32_16x16x32_bf16 v[78:81], v[156:159], v[114:117], v[82:85]
	v_mfma_f32_16x16x32_bf16 v[82:85], v[194:197], v[106:109], v[86:89]
	v_mfma_f32_16x16x32_bf16 v[86:89], v[194:197], v[114:117], v[90:93]
	v_mfma_f32_16x16x32_bf16 v[90:93], v[202:205], v[106:109], v[94:97]
	v_mfma_f32_16x16x32_bf16 v[94:97], v[202:205], v[114:117], v[98:101]
	v_mfma_f32_16x16x32_bf16 v[16:19], v[152:155], v[110:113], v[16:19]
	v_mfma_f32_16x16x32_bf16 v[70:73], v[152:155], v[140:143], v[70:73]
	v_mfma_f32_16x16x32_bf16 v[74:77], v[190:193], v[110:113], v[74:77]
	v_mfma_f32_16x16x32_bf16 v[78:81], v[190:193], v[140:143], v[78:81]
	v_mfma_f32_16x16x32_bf16 v[82:85], v[198:201], v[110:113], v[82:85]
	v_mfma_f32_16x16x32_bf16 v[86:89], v[198:201], v[140:143], v[86:89]
	v_mfma_f32_16x16x32_bf16 v[90:93], v[206:209], v[110:113], v[90:93]
	v_mfma_f32_16x16x32_bf16 v[94:97], v[206:209], v[140:143], v[94:97]
	s_setprio 0
	s_barrier
	v_or_b32_e32 v234, 0x1c000, v126
	v_or_b32_e32 v236, 0x1c800, v126
	v_mov_b32_e32 v148, v4
	v_or_b32_e32 v235, 0x1c400, v126
	ds_read_b128 v[98:101], v234
	ds_read_b128 v[210:213], v235
	v_or_b32_e32 v126, 0x1cc00, v126
	ds_read_b128 v[214:217], v236
	ds_read_b128 v[218:221], v126
	v_readfirstlane_b32 s63, v13
	v_lshl_add_u64 v[36:37], v[148:149], 1, s[18:19]
	v_lshl_add_u64 v[36:37], v[36:37], 0, s[54:55]
	s_mov_b32 m0, s63
	v_mov_b32_e32 v148, v6
	global_load_lds_dwordx4 v[36:37], off
	s_nop 0
	v_lshl_add_u64 v[12:13], v[148:149], 1, s[18:19]
	v_readfirstlane_b32 s18, v14
	v_lshl_add_u64 v[12:13], v[12:13], 0, s[54:55]
	s_mov_b32 m0, s18
	s_nop 0
	global_load_lds_dwordx4 v[12:13], off
	s_setprio 1
	s_barrier
; #define LDA(dst, b, h)                                                                                    \
;   _Pragma("unroll") for (int m = 0; m < 4; ++m) _Pragma("unroll") for (int k = 0; k < 2; ++k)             \
;       dst[m][k] = *reinterpret_cast<const bf16x8*>((char*)SA(b, h) + lds_byte(wr * 64 + m * 16 + fr, k * 32 + fq * 8))
; #define LDB(dst, b, h)                                                                                    \
;   _Pragma("unroll") for (int n = 0; n < 2; ++n) _Pragma("unroll") for (int k = 0; k < 2; ++k)             \
;       dst[n][k] = *reinterpret_cast<const bf16x8*>((char*)SB(b, h) + lds_byte(wc * 32 + n * 16 + fr, k * 32 + fq * 8))
; #define WAIT_V(n) asm volatile("s_waitcnt vmcnt(" #n ")" ::: "memory")
; #define WAIT_L(n) asm volatile("s_waitcnt lgkmcnt(" #n ")" ::: "memory")
; #define BAR __builtin_amdgcn_s_barrier()
; #define SCHED __builtin_amdgcn_sched_barrier(0)
; template <int EPI> ...
;     ...
;     BAR; WAIT_L(0); MMA(0, 1, At, B1); BAR;
;     LDA(At, 1, 1); STAGE(SA(1, 0), A, brow, t + 3);
;     BAR; WAIT_L(0); MMA(1, 0, At, B0); BAR; SCHED;
;     STAGE(SB(1, 1), Bt, bcol + HALF, t + 3);
;     WAIT_V(6); BAR; MMA(1, 1, At, B1); BAR;
;   }
;   {
;     LDB(B0, 0, 0); LDA(At, 0, 0); STAGE(SA(1, 1), A, brow + HALF, nt - 1);
;     BAR; WAIT_L(0); MMA(0, 0, At, B0); BAR;
	s_waitcnt lgkmcnt(0)
	v_mfma_f32_16x16x32_bf16 v[12:15], v[144:147], v[98:101], v[118:121]
	v_mfma_f32_16x16x32_bf16 v[36:39], v[144:147], v[214:217], v[38:41]
	v_mfma_f32_16x16x32_bf16 v[40:43], v[156:159], v[98:101], v[42:45]
	v_mfma_f32_16x16x32_bf16 v[44:47], v[156:159], v[214:217], v[46:49]
	v_mfma_f32_16x16x32_bf16 v[48:51], v[194:197], v[98:101], v[50:53]
	v_mfma_f32_16x16x32_bf16 v[52:55], v[194:197], v[214:217], v[54:57]
	v_mfma_f32_16x16x32_bf16 v[56:59], v[202:205], v[98:101], v[58:61]
	v_mfma_f32_16x16x32_bf16 v[60:63], v[202:205], v[214:217], v[62:65]
	v_mfma_f32_16x16x32_bf16 v[12:15], v[152:155], v[210:213], v[12:15]
	v_mfma_f32_16x16x32_bf16 v[36:39], v[152:155], v[218:221], v[36:39]
	v_mfma_f32_16x16x32_bf16 v[40:43], v[190:193], v[210:213], v[40:43]
	v_mfma_f32_16x16x32_bf16 v[44:47], v[190:193], v[218:221], v[44:47]
	v_mfma_f32_16x16x32_bf16 v[48:51], v[198:201], v[210:213], v[48:51]
	v_mfma_f32_16x16x32_bf16 v[52:55], v[198:201], v[218:221], v[52:55]
	v_mfma_f32_16x16x32_bf16 v[56:59], v[206:209], v[210:213], v[56:59]
	v_mfma_f32_16x16x32_bf16 v[60:63], v[206:209], v[218:221], v[60:63]
	s_setprio 0
	v_mov_b32_e32 v148, v4
	s_barrier
	ds_read_b128 v[118:121], v8 offset:49152
	ds_read_b128 v[144:147], v8 offset:50176
	ds_read_b128 v[152:155], v9 offset:51200
	ds_read_b128 v[156:159], v9 offset:52224
	ds_read_b128 v[190:193], v9 offset:53248
	ds_read_b128 v[194:197], v9 offset:54272
	ds_read_b128 v[198:201], v9 offset:55296
	ds_read_b128 v[202:205], v9 offset:56320
	v_readfirstlane_b32 s18, v10
	v_lshl_add_u64 v[64:65], v[148:149], 1, s[16:17]
	v_lshl_add_u64 v[64:65], v[64:65], 0, s[54:55]
	s_mov_b32 m0, s18
	v_mov_b32_e32 v148, v6
	global_load_lds_dwordx4 v[64:65], off
	s_nop 0
	v_lshl_add_u64 v[64:65], v[148:149], 1, s[16:17]
	v_readfirstlane_b32 s16, v11
	v_lshl_add_u64 v[64:65], v[64:65], 0, s[54:55]
	s_mov_b32 m0, s16
	s_nop 0
	global_load_lds_dwordx4 v[64:65], off
	s_setprio 1
	s_barrier
	s_waitcnt lgkmcnt(0)
	v_mfma_f32_16x16x32_bf16 v[20:23], v[198:201], v[106:109], v[20:23]
	v_mfma_f32_16x16x32_bf16 v[24:27], v[198:201], v[114:117], v[24:27]
	v_mfma_f32_16x16x32_bf16 v[160:163], v[118:121], v[106:109], v[160:163]
	v_mfma_f32_16x16x32_bf16 v[164:167], v[118:121], v[114:117], v[164:167]
	v_mfma_f32_16x16x32_bf16 v[174:177], v[152:155], v[106:109], v[174:177]
	v_mfma_f32_16x16x32_bf16 v[178:181], v[152:155], v[114:117], v[178:181]
	v_mfma_f32_16x16x32_bf16 v[182:185], v[190:193], v[106:109], v[182:185]
	v_mfma_f32_16x16x32_bf16 v[186:189], v[190:193], v[114:117], v[186:189]
	v_mfma_f32_16x16x32_bf16 v[20:23], v[202:205], v[110:113], v[20:23]
	v_mfma_f32_16x16x32_bf16 v[24:27], v[202:205], v[140:143], v[24:27]
	v_mfma_f32_16x16x32_bf16 v[160:163], v[144:147], v[110:113], v[160:163]
	v_mfma_f32_16x16x32_bf16 v[164:167], v[144:147], v[140:143], v[164:167]
	v_mfma_f32_16x16x32_bf16 v[174:177], v[156:159], v[110:113], v[174:177]
	v_mfma_f32_16x16x32_bf16 v[178:181], v[156:159], v[140:143], v[178:181]
	v_mfma_f32_16x16x32_bf16 v[182:185], v[194:197], v[110:113], v[182:185]
	v_mfma_f32_16x16x32_bf16 v[186:189], v[194:197], v[140:143], v[186:189]
	s_setprio 0
	s_barrier
	v_mov_b32_e32 v148, v4
	v_readfirstlane_b32 s16, v5
	v_lshl_add_u64 v[10:11], v[148:149], 1, s[14:15]
	v_lshl_add_u64 v[10:11], v[10:11], 0, s[54:55]
	s_mov_b32 m0, s16
	v_mov_b32_e32 v148, v6
	global_load_lds_dwordx4 v[10:11], off
	s_nop 0
	v_lshl_add_u64 v[10:11], v[148:149], 1, s[14:15]
	v_readfirstlane_b32 s14, v7
	v_lshl_add_u64 v[10:11], v[10:11], 0, s[54:55]
	s_mov_b32 m0, s14
	s_nop 0
	global_load_lds_dwordx4 v[10:11], off
	s_waitcnt vmcnt(6)
	s_barrier
	s_setprio 1
	v_mfma_f32_16x16x32_bf16 v[28:31], v[118:121], v[98:101], v[28:31]
	v_mfma_f32_16x16x32_bf16 v[32:35], v[118:121], v[214:217], v[32:35]
	v_mfma_f32_16x16x32_bf16 v[64:67], v[152:155], v[98:101], v[66:69]
	v_mfma_f32_16x16x32_bf16 v[106:109], v[152:155], v[214:217], v[122:125]
	v_mfma_f32_16x16x32_bf16 v[110:113], v[190:193], v[98:101], v[132:135]
	v_mfma_f32_16x16x32_bf16 v[114:117], v[190:193], v[214:217], v[136:139]
	v_mfma_f32_16x16x32_bf16 v[98:101], v[198:201], v[98:101], v[102:105]
	v_mfma_f32_16x16x32_bf16 v[0:3], v[198:201], v[214:217], v[0:3]
	v_mfma_f32_16x16x32_bf16 v[28:31], v[144:147], v[210:213], v[28:31]
	v_mfma_f32_16x16x32_bf16 v[32:35], v[144:147], v[218:221], v[32:35]
	v_mfma_f32_16x16x32_bf16 v[64:67], v[156:159], v[210:213], v[64:67]
	v_mfma_f32_16x16x32_bf16 v[106:109], v[156:159], v[218:221], v[106:109]
	v_mfma_f32_16x16x32_bf16 v[110:113], v[194:197], v[210:213], v[110:113]
	v_mfma_f32_16x16x32_bf16 v[114:117], v[194:197], v[218:221], v[114:117]
	v_mfma_f32_16x16x32_bf16 v[98:101], v[202:205], v[210:213], v[98:101]
	v_mfma_f32_16x16x32_bf16 v[0:3], v[202:205], v[218:221], v[0:3]
	s_setprio 0
	s_barrier
	ds_read_b128 v[102:105], v127
	ds_read_b128 v[118:121], v131
	ds_read_b128 v[122:125], v222
	ds_read_b128 v[132:135], v223
	ds_read_b128 v[136:139], v8
	ds_read_b128 v[140:143], v8 offset:1024
	ds_read_b128 v[144:147], v9 offset:2048
	ds_read_b128 v[152:155], v9 offset:3072
	ds_read_b128 v[156:159], v9 offset:4096
	ds_read_b128 v[190:193], v9 offset:5120
	ds_read_b128 v[194:197], v9 offset:6144
	ds_read_b128 v[198:201], v9 offset:7168
	v_mov_b32_e32 v5, v149
	v_lshl_add_u64 v[4:5], v[4:5], 1, s[12:13]
	s_mov_b32 m0, s62
	v_lshl_add_u64 v[4:5], v[4:5], 0, s[54:55]
	v_mov_b32_e32 v7, v149
	global_load_lds_dwordx4 v[4:5], off
	s_mov_b32 m0, s35
	v_lshl_add_u64 v[4:5], v[6:7], 1, s[12:13]
	v_lshl_add_u64 v[4:5], v[4:5], 0, s[54:55]
	global_load_lds_dwordx4 v[4:5], off
	s_setprio 1
	s_barrier
; #define LDA(dst, b, h)                                                                                    \
;   _Pragma("unroll") for (int m = 0; m < 4; ++m) _Pragma("unroll") for (int k = 0; k < 2; ++k)             \
;       dst[m][k] = *reinterpret_cast<const bf16x8*>((char*)SA(b, h) + lds_byte(wr * 64 + m * 16 + fr, k * 32 + fq * 8))
; #define LDB(dst, b, h)                                                                                    \
;   _Pragma("unroll") for (int n = 0; n < 2; ++n) _Pragma("unroll") for (int k = 0; k < 2; ++k)             \
;       dst[n][k] = *reinterpret_cast<const bf16x8*>((char*)SB(b, h) + lds_byte(wc * 32 + n * 16 + fr, k * 32 + fq * 8))
; #define WAIT_V(n) asm volatile("s_waitcnt vmcnt(" #n ")" ::: "memory")
; #define WAIT_L(n) asm volatile("s_waitcnt lgkmcnt(" #n ")" ::: "memory")
; #define BAR __builtin_amdgcn_s_barrier()
; template <int EPI> ...
;     ...
;     BAR; WAIT_L(0); MMA(0, 0, At, B0); BAR;
;     LDB(B1, 0, 1); BAR; WAIT_L(0); MMA(0, 1, At, B1); BAR;
;     LDA(At, 0, 1); WAIT_V(4); BAR; WAIT_L(0); MMA(1, 0, At, B0); MMA(1, 1, At, B1); BAR;
	s_waitcnt lgkmcnt(0)
	v_mfma_f32_16x16x32_bf16 v[4:7], v[136:139], v[102:105], v[16:19]
	v_mfma_f32_16x16x32_bf16 v[16:19], v[136:139], v[122:125], v[70:73]
	v_mfma_f32_16x16x32_bf16 v[68:71], v[144:147], v[102:105], v[74:77]
	v_mfma_f32_16x16x32_bf16 v[72:75], v[144:147], v[122:125], v[78:81]
	v_mfma_f32_16x16x32_bf16 v[76:79], v[156:159], v[102:105], v[82:85]
	v_mfma_f32_16x16x32_bf16 v[80:83], v[156:159], v[122:125], v[86:89]
	v_mfma_f32_16x16x32_bf16 v[202:205], v[190:193], v[132:135], v[80:83]
	v_mfma_f32_16x16x32_bf16 v[80:83], v[194:197], v[102:105], v[90:93]
	v_mfma_f32_16x16x32_bf16 v[4:7], v[140:143], v[118:121], v[4:7]
	v_mfma_f32_16x16x32_bf16 v[16:19], v[140:143], v[132:135], v[16:19]
	v_mfma_f32_16x16x32_bf16 v[68:71], v[152:155], v[118:121], v[68:71]
	v_mfma_f32_16x16x32_bf16 v[72:75], v[152:155], v[132:135], v[72:75]
	v_mfma_f32_16x16x32_bf16 v[76:79], v[190:193], v[118:121], v[76:79]
	v_mfma_f32_16x16x32_bf16 v[88:91], v[198:201], v[118:121], v[80:83]
	v_mfma_f32_16x16x32_bf16 v[80:83], v[194:197], v[122:125], v[94:97]
	v_mfma_f32_16x16x32_bf16 v[206:209], v[198:201], v[132:135], v[80:83]
	s_setprio 0
	s_barrier
	s_nop 4
	ds_read_b128 v[80:83], v224
	ds_read_b128 v[84:87], v225
	ds_read_b128 v[92:95], v226
	ds_read_b128 v[210:213], v227
	s_setprio 1
	s_barrier
	s_waitcnt lgkmcnt(0)
	v_mfma_f32_16x16x32_bf16 v[10:13], v[136:139], v[80:83], v[12:15]
	v_mfma_f32_16x16x32_bf16 v[36:39], v[136:139], v[92:95], v[36:39]
	v_mfma_f32_16x16x32_bf16 v[40:43], v[144:147], v[80:83], v[40:43]
	v_mfma_f32_16x16x32_bf16 v[44:47], v[144:147], v[92:95], v[44:47]
	v_mfma_f32_16x16x32_bf16 v[48:51], v[156:159], v[80:83], v[48:51]
	v_mfma_f32_16x16x32_bf16 v[52:55], v[156:159], v[92:95], v[52:55]
	v_mfma_f32_16x16x32_bf16 v[56:59], v[194:197], v[80:83], v[56:59]
	v_mfma_f32_16x16x32_bf16 v[60:63], v[194:197], v[92:95], v[60:63]
	v_mfma_f32_16x16x32_bf16 v[10:13], v[140:143], v[84:87], v[10:13]
	v_mfma_f32_16x16x32_bf16 v[36:39], v[140:143], v[210:213], v[36:39]
	v_mfma_f32_16x16x32_bf16 v[40:43], v[152:155], v[84:87], v[40:43]
	v_mfma_f32_16x16x32_bf16 v[44:47], v[152:155], v[210:213], v[44:47]
	v_mfma_f32_16x16x32_bf16 v[48:51], v[190:193], v[84:87], v[48:51]
	v_mfma_f32_16x16x32_bf16 v[52:55], v[190:193], v[210:213], v[52:55]
	v_mfma_f32_16x16x32_bf16 v[56:59], v[198:201], v[84:87], v[56:59]
	v_mfma_f32_16x16x32_bf16 v[60:63], v[198:201], v[210:213], v[60:63]
	s_setprio 0
	s_barrier
	ds_read_b128 v[136:139], v8 offset:16384
	ds_read_b128 v[140:143], v8 offset:17408
	ds_read_b128 v[144:147], v9 offset:18432
	ds_read_b128 v[152:155], v9 offset:19456
	ds_read_b128 v[156:159], v9 offset:20480
	ds_read_b128 v[190:193], v9 offset:21504
	ds_read_b128 v[194:197], v9 offset:22528
	ds_read_b128 v[198:201], v9 offset:23552
	s_waitcnt vmcnt(4)
	s_setprio 1
	s_barrier
	s_waitcnt lgkmcnt(0)
	v_mfma_f32_16x16x32_bf16 v[20:23], v[194:197], v[102:105], v[20:23]
	v_mfma_f32_16x16x32_bf16 v[160:163], v[136:139], v[102:105], v[160:163]
	v_mfma_f32_16x16x32_bf16 v[164:167], v[136:139], v[122:125], v[164:167]
	v_mfma_f32_16x16x32_bf16 v[174:177], v[144:147], v[102:105], v[174:177]
	v_mfma_f32_16x16x32_bf16 v[178:181], v[144:147], v[122:125], v[178:181]
	v_mfma_f32_16x16x32_bf16 v[182:185], v[156:159], v[102:105], v[182:185]
	v_mfma_f32_16x16x32_bf16 v[186:189], v[156:159], v[122:125], v[186:189]
	v_mfma_f32_16x16x32_bf16 v[214:217], v[198:201], v[118:121], v[20:23]
	v_mfma_f32_16x16x32_bf16 v[20:23], v[194:197], v[122:125], v[24:27]
	v_mfma_f32_16x16x32_bf16 v[160:163], v[140:143], v[118:121], v[160:163]
	v_mfma_f32_16x16x32_bf16 v[164:167], v[140:143], v[132:135], v[164:167]
	v_mfma_f32_16x16x32_bf16 v[174:177], v[152:155], v[118:121], v[174:177]
	v_mfma_f32_16x16x32_bf16 v[178:181], v[152:155], v[132:135], v[178:181]
	v_mfma_f32_16x16x32_bf16 v[182:185], v[190:193], v[118:121], v[182:185]
	v_mfma_f32_16x16x32_bf16 v[186:189], v[190:193], v[132:135], v[186:189]
	v_mfma_f32_16x16x32_bf16 v[132:135], v[198:201], v[132:135], v[20:23]
	s_setprio 0
	s_setprio 1
	v_mfma_f32_16x16x32_bf16 v[20:23], v[136:139], v[80:83], v[28:31]
	v_mfma_f32_16x16x32_bf16 v[218:221], v[140:143], v[84:87], v[20:23]
	v_mfma_f32_16x16x32_bf16 v[20:23], v[136:139], v[92:95], v[32:35]
	v_mfma_f32_16x16x32_bf16 v[32:35], v[140:143], v[210:213], v[20:23]
	v_mfma_f32_16x16x32_bf16 v[20:23], v[144:147], v[80:83], v[64:67]
	v_mfma_f32_16x16x32_bf16 v[136:139], v[152:155], v[84:87], v[20:23]
	v_mfma_f32_16x16x32_bf16 v[20:23], v[144:147], v[92:95], v[106:109]
	v_mfma_f32_16x16x32_bf16 v[140:143], v[152:155], v[210:213], v[20:23]
	v_mfma_f32_16x16x32_bf16 v[20:23], v[156:159], v[80:83], v[110:113]
	v_mfma_f32_16x16x32_bf16 v[144:147], v[190:193], v[84:87], v[20:23]
	v_mfma_f32_16x16x32_bf16 v[20:23], v[156:159], v[92:95], v[114:117]
	v_mfma_f32_16x16x32_bf16 v[152:155], v[190:193], v[210:213], v[20:23]
	v_mfma_f32_16x16x32_bf16 v[20:23], v[194:197], v[80:83], v[98:101]
	v_mfma_f32_16x16x32_bf16 v[0:3], v[194:197], v[92:95], v[0:3]
	v_mfma_f32_16x16x32_bf16 v[156:159], v[198:201], v[84:87], v[20:23]
	v_mfma_f32_16x16x32_bf16 v[190:193], v[198:201], v[210:213], v[0:3]
	s_setprio 0
	s_barrier
; #define LDA(dst, b, h)                                                                                    \
;   _Pragma("unroll") for (int m = 0; m < 4; ++m) _Pragma("unroll") for (int k = 0; k < 2; ++k)             \
;       dst[m][k] = *reinterpret_cast<const bf16x8*>((char*)SA(b, h) + lds_byte(wr * 64 + m * 16 + fr, k * 32 + fq * 8))
; #define LDB(dst, b, h)                                                                                    \
;   _Pragma("unroll") for (int n = 0; n < 2; ++n) _Pragma("unroll") for (int k = 0; k < 2; ++k)             \
;       dst[n][k] = *reinterpret_cast<const bf16x8*>((char*)SB(b, h) + lds_byte(wc * 32 + n * 16 + fr, k * 32 + fq * 8))
; #define WAIT_V(n) asm volatile("s_waitcnt vmcnt(" #n ")" ::: "memory")
; #define WAIT_L(n) asm volatile("s_waitcnt lgkmcnt(" #n ")" ::: "memory")
; #define BAR __builtin_amdgcn_s_barrier()
; template <int EPI> ...
;     ...
;     LDB(B0, 1, 0); LDA(At, 1, 0); WAIT_V(2); BAR; WAIT_L(0); MMA(0, 0, At, B0); BAR;
;     LDB(B1, 1, 1); WAIT_V(0); BAR; WAIT_L(0); MMA(0, 1, At, B1); BAR;
;     LDA(At, 1, 1); BAR; WAIT_L(0); MMA(1, 0, At, B0); MMA(1, 1, At, B1); BAR;
;   }
;   if (wr == 0) BAR;
	s_nop 3
	ds_read_b128 v[0:3], v228
	ds_read_b128 v[194:197], v229
	ds_read_b128 v[198:201], v230
	ds_read_b128 v[210:213], v231
	ds_read_b128 v[20:23], v8 offset:32768
	ds_read_b128 v[24:27], v8 offset:33792
	ds_read_b128 v[28:31], v9 offset:34816
	ds_read_b128 v[96:99], v9 offset:35840
	ds_read_b128 v[108:111], v9 offset:36864
	ds_read_b128 v[222:225], v9 offset:37888
	ds_read_b128 v[226:229], v9 offset:38912
	ds_read_b128 v[230:233], v9 offset:39936
	s_waitcnt vmcnt(2)
	s_setprio 1
	s_barrier
	s_waitcnt lgkmcnt(0)
	v_mfma_f32_16x16x32_bf16 v[4:7], v[20:23], v[0:3], v[4:7]
	v_mfma_f32_16x16x32_bf16 v[92:95], v[24:27], v[194:197], v[4:7]
	v_mfma_f32_16x16x32_bf16 v[4:7], v[20:23], v[198:201], v[16:19]
	v_mfma_f32_16x16x32_bf16 v[100:103], v[24:27], v[210:213], v[4:7]
	v_mfma_f32_16x16x32_bf16 v[4:7], v[28:31], v[0:3], v[68:71]
	v_mfma_f32_16x16x32_bf16 v[80:83], v[96:99], v[194:197], v[4:7]
	v_mfma_f32_16x16x32_bf16 v[4:7], v[28:31], v[198:201], v[72:75]
	v_mfma_f32_16x16x32_bf16 v[84:87], v[96:99], v[210:213], v[4:7]
	v_mfma_f32_16x16x32_bf16 v[4:7], v[108:111], v[0:3], v[76:79]
	v_mfma_f32_16x16x32_bf16 v[72:75], v[222:225], v[194:197], v[4:7]
	v_mfma_f32_16x16x32_bf16 v[4:7], v[108:111], v[198:201], v[202:205]
	v_mfma_f32_16x16x32_bf16 v[76:79], v[222:225], v[210:213], v[4:7]
	v_mfma_f32_16x16x32_bf16 v[4:7], v[226:229], v[0:3], v[88:91]
	v_mfma_f32_16x16x32_bf16 v[64:67], v[230:233], v[194:197], v[4:7]
	v_mfma_f32_16x16x32_bf16 v[4:7], v[226:229], v[198:201], v[206:209]
	v_mfma_f32_16x16x32_bf16 v[68:71], v[230:233], v[210:213], v[4:7]
	s_setprio 0
	s_barrier
	ds_read_b128 v[202:205], v234
	ds_read_b128 v[206:209], v235
	ds_read_b128 v[234:237], v236
	ds_read_b128 v[238:241], v126
	s_waitcnt vmcnt(0)
	s_setprio 1
	s_barrier
	s_waitcnt lgkmcnt(0)
	v_mfma_f32_16x16x32_bf16 v[4:7], v[20:23], v[202:205], v[10:13]
	v_mfma_f32_16x16x32_bf16 v[120:123], v[24:27], v[206:209], v[4:7]
	v_mfma_f32_16x16x32_bf16 v[4:7], v[20:23], v[234:237], v[36:39]
	v_mfma_f32_16x16x32_bf16 v[124:127], v[24:27], v[238:241], v[4:7]
	v_mfma_f32_16x16x32_bf16 v[4:7], v[28:31], v[202:205], v[40:43]
	v_mfma_f32_16x16x32_bf16 v[112:115], v[96:99], v[206:209], v[4:7]
	v_mfma_f32_16x16x32_bf16 v[4:7], v[28:31], v[234:237], v[44:47]
	v_mfma_f32_16x16x32_bf16 v[116:119], v[96:99], v[238:241], v[4:7]
	v_mfma_f32_16x16x32_bf16 v[4:7], v[108:111], v[202:205], v[48:51]
	v_mfma_f32_16x16x32_bf16 v[104:107], v[222:225], v[206:209], v[4:7]
	v_mfma_f32_16x16x32_bf16 v[4:7], v[108:111], v[234:237], v[52:55]
	v_mfma_f32_16x16x32_bf16 v[108:111], v[222:225], v[238:241], v[4:7]
	v_mfma_f32_16x16x32_bf16 v[4:7], v[226:229], v[202:205], v[56:59]
	v_mfma_f32_16x16x32_bf16 v[88:91], v[230:233], v[206:209], v[4:7]
	v_mfma_f32_16x16x32_bf16 v[4:7], v[226:229], v[234:237], v[60:63]
	v_mfma_f32_16x16x32_bf16 v[96:99], v[230:233], v[238:241], v[4:7]
	s_setprio 0
	s_barrier
	ds_read_b128 v[36:39], v8 offset:49152
	ds_read_b128 v[40:43], v8 offset:50176
	ds_read_b128 v[44:47], v9 offset:51200
	ds_read_b128 v[52:55], v9 offset:52224
	ds_read_b128 v[222:225], v9 offset:53248
	ds_read_b128 v[226:229], v9 offset:54272
	ds_read_b128 v[230:233], v9 offset:55296
	ds_read_b128 v[242:245], v9 offset:56320
	s_setprio 1
	s_barrier
	s_waitcnt lgkmcnt(0)
	v_mfma_f32_16x16x32_bf16 v[4:7], v[36:39], v[0:3], v[160:163]
	v_mfma_f32_16x16x32_bf16 v[24:27], v[40:43], v[194:197], v[4:7]
	v_mfma_f32_16x16x32_bf16 v[4:7], v[36:39], v[198:201], v[164:167]
	v_mfma_f32_16x16x32_bf16 v[28:31], v[40:43], v[210:213], v[4:7]
	v_mfma_f32_16x16x32_bf16 v[4:7], v[44:47], v[0:3], v[174:177]
	v_mfma_f32_16x16x32_bf16 v[16:19], v[52:55], v[194:197], v[4:7]
	v_mfma_f32_16x16x32_bf16 v[4:7], v[44:47], v[198:201], v[178:181]
	v_mfma_f32_16x16x32_bf16 v[20:23], v[52:55], v[210:213], v[4:7]
	v_mfma_f32_16x16x32_bf16 v[4:7], v[222:225], v[0:3], v[182:185]
	v_mfma_f32_16x16x32_bf16 v[8:11], v[226:229], v[194:197], v[4:7]
	v_mfma_f32_16x16x32_bf16 v[4:7], v[222:225], v[198:201], v[186:189]
	v_mfma_f32_16x16x32_bf16 v[12:15], v[226:229], v[210:213], v[4:7]
	v_mfma_f32_16x16x32_bf16 v[0:3], v[230:233], v[0:3], v[214:217]
	v_mfma_f32_16x16x32_bf16 v[4:7], v[230:233], v[198:201], v[132:135]
	v_mfma_f32_16x16x32_bf16 v[0:3], v[242:245], v[194:197], v[0:3]
	v_mfma_f32_16x16x32_bf16 v[4:7], v[242:245], v[210:213], v[4:7]
	s_setprio 0
	s_setprio 1
	v_mfma_f32_16x16x32_bf16 v[32:35], v[36:39], v[234:237], v[32:35]
	v_mfma_f32_16x16x32_bf16 v[48:51], v[36:39], v[202:205], v[218:221]
	v_mfma_f32_16x16x32_bf16 v[60:63], v[40:43], v[238:241], v[32:35]
	v_mfma_f32_16x16x32_bf16 v[32:35], v[44:47], v[202:205], v[136:139]
	v_mfma_f32_16x16x32_bf16 v[56:59], v[40:43], v[206:209], v[48:51]
	v_mfma_f32_16x16x32_bf16 v[48:51], v[52:55], v[206:209], v[32:35]
	v_mfma_f32_16x16x32_bf16 v[32:35], v[44:47], v[234:237], v[140:143]
	v_mfma_f32_16x16x32_bf16 v[52:55], v[52:55], v[238:241], v[32:35]
	v_mfma_f32_16x16x32_bf16 v[32:35], v[222:225], v[202:205], v[144:147]
	v_mfma_f32_16x16x32_bf16 v[40:43], v[226:229], v[206:209], v[32:35]
	v_mfma_f32_16x16x32_bf16 v[32:35], v[222:225], v[234:237], v[152:155]
	v_mfma_f32_16x16x32_bf16 v[44:47], v[226:229], v[238:241], v[32:35]
	v_mfma_f32_16x16x32_bf16 v[32:35], v[230:233], v[202:205], v[156:159]
	v_mfma_f32_16x16x32_bf16 v[36:39], v[230:233], v[234:237], v[190:193]
	v_mfma_f32_16x16x32_bf16 v[32:35], v[242:245], v[206:209], v[32:35]
	v_mfma_f32_16x16x32_bf16 v[36:39], v[242:245], v[238:241], v[36:39]
	s_setprio 0
	s_cmpk_gt_u32 s31, 0xff
	s_barrier
	s_cbranch_scc1 .LBB0_1851
	s_barrier
	s_branch .LBB0_1851

; #define LDA(dst, b, h)                                                                                    \
;   _Pragma("unroll") for (int m = 0; m < 4; ++m) _Pragma("unroll") for (int k = 0; k < 2; ++k)             \
;       dst[m][k] = *reinterpret_cast<const bf16x8*>((char*)SA(b, h) + lds_byte(wr * 64 + m * 16 + fr, k * 32 + fq * 8))
; #define LDB(dst, b, h)                                                                                    \
;   _Pragma("unroll") for (int n = 0; n < 2; ++n) _Pragma("unroll") for (int k = 0; k < 2; ++k)             \
;       dst[n][k] = *reinterpret_cast<const bf16x8*>((char*)SB(b, h) + lds_byte(wc * 32 + n * 16 + fr, k * 32 + fq * 8))
; #define WAIT_V(n) asm volatile("s_waitcnt vmcnt(" #n ")" ::: "memory")
; #define WAIT_L(n) asm volatile("s_waitcnt lgkmcnt(" #n ")" ::: "memory")
; #define BAR __builtin_amdgcn_s_barrier()
; #define SCHED __builtin_amdgcn_sched_barrier(0)
; template <int EPI> ...
;     ...
;   for (int t = 0; t < nt - 2; t += 2) {
;     LDB(B0, 0, 0); SCHED; LDA(At, 0, 0); STAGE(SA(1, 1), A, brow + HALF, t + 1);
;     WAIT_L(8); BAR; WAIT_L(0); MMA(0, 0, At, B0); BAR; SCHED;
;     LDB(B1, 0, 1); STAGE(SB(0, 0), Bt, bcol, t + 2);
;     BAR; WAIT_L(0); MMA(0, 1, At, B1); BAR;
;     LDA(At, 0, 1); STAGE(SA(0, 0), A, brow, t + 2);
;     BAR; WAIT_L(0); MMA(1, 0, At, B0); BAR; SCHED;
;     STAGE(SB(0, 1), Bt, bcol + HALF, t + 2);
;     WAIT_V(6); BAR; MMA(1, 1, At, B1); BAR;
.LBB0_1883:
	ds_read_b128 v[162:165], v155
	ds_read_b128 v[174:177], v155 offset:1024
	ds_read_b128 v[178:181], v155 offset:2048
	ds_read_b128 v[182:185], v155 offset:3072
	s_add_u32 s34, s20, s30
	v_add_u32_e32 v156, s67, v154
	v_add_u32_e32 v157, s68, v154
	v_add_u32_e32 v158, s69, v154
	s_addc_u32 s35, s21, s31
	ds_read_b128 v[186:189], v134
	ds_read_b128 v[190:193], v134 offset:1024
	ds_read_b128 v[194:197], v156
	ds_read_b128 v[198:201], v156 offset:1024
	ds_read_b128 v[202:205], v157
	ds_read_b128 v[206:209], v157 offset:1024
	ds_read_b128 v[210:213], v158
	ds_read_b128 v[214:217], v158 offset:1024
	v_add_u32_e32 v159, 0xe000, v129
	v_add_u32_e32 v160, 0xc000, v129
	s_add_u32 m0, s32, 0xc000
	s_add_u32 s98, s34, 0x40080
	s_addc_u32 s99, s35, 0
	global_load_lds_dwordx4 v253, s[98:99]
	s_add_u32 m0, s32, 0xe000
	s_nop 0
	global_load_lds_dwordx4 v252, s[98:99]
	s_waitcnt lgkmcnt(8)
	s_setprio 1
	s_barrier
	s_waitcnt lgkmcnt(0)
	v_mfma_f32_16x16x32_bf16 v[124:127], v[186:189], v[162:165], v[124:127]
	v_mfma_f32_16x16x32_bf16 v[120:123], v[186:189], v[178:181], v[120:123]
	v_mfma_f32_16x16x32_bf16 v[116:119], v[194:197], v[162:165], v[116:119]
	v_mfma_f32_16x16x32_bf16 v[112:115], v[194:197], v[178:181], v[112:115]
	v_mfma_f32_16x16x32_bf16 v[108:111], v[202:205], v[162:165], v[108:111]
	v_mfma_f32_16x16x32_bf16 v[104:107], v[202:205], v[178:181], v[104:107]
	v_mfma_f32_16x16x32_bf16 v[100:103], v[210:213], v[162:165], v[100:103]
	v_mfma_f32_16x16x32_bf16 v[96:99], v[210:213], v[178:181], v[96:99]
	v_mfma_f32_16x16x32_bf16 v[124:127], v[190:193], v[174:177], v[124:127]
	v_mfma_f32_16x16x32_bf16 v[120:123], v[190:193], v[182:185], v[120:123]
	v_mfma_f32_16x16x32_bf16 v[116:119], v[198:201], v[174:177], v[116:119]
	v_mfma_f32_16x16x32_bf16 v[112:115], v[198:201], v[182:185], v[112:115]
	v_mfma_f32_16x16x32_bf16 v[108:111], v[206:209], v[174:177], v[108:111]
	v_mfma_f32_16x16x32_bf16 v[104:107], v[206:209], v[182:185], v[104:107]
	v_mfma_f32_16x16x32_bf16 v[100:103], v[214:217], v[174:177], v[100:103]
	v_mfma_f32_16x16x32_bf16 v[96:99], v[214:217], v[182:185], v[96:99]
	s_setprio 0
	s_barrier
	s_add_u32 s62, s18, s30
	s_addc_u32 s63, s19, s31
	ds_read_b128 v[218:221], v152
	ds_read_b128 v[222:225], v152 offset:1024
	ds_read_b128 v[226:229], v152 offset:2048
	ds_read_b128 v[230:233], v152 offset:3072
	s_add_u32 m0, s32, 0x10000
	s_add_u32 s98, s62, 0x100
	s_addc_u32 s99, s63, 0
	global_load_lds_dwordx4 v253, s[98:99]
	s_add_u32 m0, s32, 0x12000
	s_nop 0
	global_load_lds_dwordx4 v252, s[98:99]
	s_setprio 1
	s_barrier
	s_waitcnt lgkmcnt(0)
	v_mfma_f32_16x16x32_bf16 v[92:95], v[186:189], v[218:221], v[92:95]
	v_mfma_f32_16x16x32_bf16 v[88:91], v[186:189], v[226:229], v[88:91]
	v_mfma_f32_16x16x32_bf16 v[84:87], v[194:197], v[218:221], v[84:87]
	v_mfma_f32_16x16x32_bf16 v[80:83], v[194:197], v[226:229], v[80:83]
	v_mfma_f32_16x16x32_bf16 v[76:79], v[202:205], v[218:221], v[76:79]
	v_mfma_f32_16x16x32_bf16 v[72:75], v[202:205], v[226:229], v[72:75]
	v_mfma_f32_16x16x32_bf16 v[68:71], v[210:213], v[218:221], v[68:71]
	v_mfma_f32_16x16x32_bf16 v[64:67], v[210:213], v[226:229], v[64:67]
	v_mfma_f32_16x16x32_bf16 v[92:95], v[190:193], v[222:225], v[92:95]
	v_mfma_f32_16x16x32_bf16 v[88:91], v[190:193], v[230:233], v[88:91]
	v_mfma_f32_16x16x32_bf16 v[84:87], v[198:201], v[222:225], v[84:87]
	v_mfma_f32_16x16x32_bf16 v[80:83], v[198:201], v[230:233], v[80:83]
	v_mfma_f32_16x16x32_bf16 v[76:79], v[206:209], v[222:225], v[76:79]
	v_mfma_f32_16x16x32_bf16 v[72:75], v[206:209], v[230:233], v[72:75]
	v_mfma_f32_16x16x32_bf16 v[68:71], v[214:217], v[222:225], v[68:71]
	v_mfma_f32_16x16x32_bf16 v[64:67], v[214:217], v[230:233], v[64:67]
	s_setprio 0
	s_barrier
	ds_read_b128 v[186:189], v134 offset:16384
	ds_read_b128 v[190:193], v134 offset:17408
	ds_read_b128 v[194:197], v156 offset:16384
	ds_read_b128 v[198:201], v156 offset:17408
	ds_read_b128 v[202:205], v157 offset:16384
	ds_read_b128 v[206:209], v157 offset:17408
	ds_read_b128 v[210:213], v158 offset:16384
	ds_read_b128 v[214:217], v158 offset:17408
	s_mov_b32 m0, s32
	s_add_u32 s98, s34, 0x100
	s_addc_u32 s99, s35, 0
	global_load_lds_dwordx4 v253, s[98:99]
	s_add_u32 m0, s32, 0x2000
	s_nop 0
	global_load_lds_dwordx4 v252, s[98:99]
	s_setprio 1
	s_barrier
	s_waitcnt lgkmcnt(0)
	v_mfma_f32_16x16x32_bf16 v[60:63], v[186:189], v[162:165], v[60:63]
	v_mfma_f32_16x16x32_bf16 v[56:59], v[186:189], v[178:181], v[56:59]
	v_mfma_f32_16x16x32_bf16 v[52:55], v[194:197], v[162:165], v[52:55]
	v_mfma_f32_16x16x32_bf16 v[48:51], v[194:197], v[178:181], v[48:51]
	v_mfma_f32_16x16x32_bf16 v[44:47], v[202:205], v[162:165], v[44:47]
	v_mfma_f32_16x16x32_bf16 v[40:43], v[202:205], v[178:181], v[40:43]
	v_mfma_f32_16x16x32_bf16 v[36:39], v[210:213], v[162:165], v[36:39]
	v_mfma_f32_16x16x32_bf16 v[32:35], v[210:213], v[178:181], v[32:35]
	v_mfma_f32_16x16x32_bf16 v[60:63], v[190:193], v[174:177], v[60:63]
	v_mfma_f32_16x16x32_bf16 v[56:59], v[190:193], v[182:185], v[56:59]
	v_mfma_f32_16x16x32_bf16 v[52:55], v[198:201], v[174:177], v[52:55]
	v_mfma_f32_16x16x32_bf16 v[48:51], v[198:201], v[182:185], v[48:51]
	v_mfma_f32_16x16x32_bf16 v[44:47], v[206:209], v[174:177], v[44:47]
	v_mfma_f32_16x16x32_bf16 v[40:43], v[206:209], v[182:185], v[40:43]
	v_mfma_f32_16x16x32_bf16 v[36:39], v[214:217], v[174:177], v[36:39]
	v_mfma_f32_16x16x32_bf16 v[32:35], v[214:217], v[182:185], v[32:35]
	s_setprio 0
	s_barrier
	s_add_u32 m0, s32, 0x14000
	s_add_u32 s98, s62, 0x40100
	s_addc_u32 s99, s63, 0
	global_load_lds_dwordx4 v253, s[98:99]
	s_add_u32 m0, s32, 0x16000
	s_nop 0
	global_load_lds_dwordx4 v252, s[98:99]
	s_waitcnt vmcnt(6)
	s_barrier
; #define LDA(dst, b, h)                                                                                    \
;   _Pragma("unroll") for (int m = 0; m < 4; ++m) _Pragma("unroll") for (int k = 0; k < 2; ++k)             \
;       dst[m][k] = *reinterpret_cast<const bf16x8*>((char*)SA(b, h) + lds_byte(wr * 64 + m * 16 + fr, k * 32 + fq * 8))
; #define LDB(dst, b, h)                                                                                    \
;   _Pragma("unroll") for (int n = 0; n < 2; ++n) _Pragma("unroll") for (int k = 0; k < 2; ++k)             \
;       dst[n][k] = *reinterpret_cast<const bf16x8*>((char*)SB(b, h) + lds_byte(wc * 32 + n * 16 + fr, k * 32 + fq * 8))
; #define WAIT_V(n) asm volatile("s_waitcnt vmcnt(" #n ")" ::: "memory")
; #define WAIT_L(n) asm volatile("s_waitcnt lgkmcnt(" #n ")" ::: "memory")
; #define BAR __builtin_amdgcn_s_barrier()
; #define SCHED __builtin_amdgcn_sched_barrier(0)
; template <int EPI> ...
;     ...
;     WAIT_V(6); BAR; MMA(1, 1, At, B1); BAR;
;     LDB(B0, 1, 0); SCHED; LDA(At, 1, 0); STAGE(SA(0, 1), A, brow + HALF, t + 2);
;     WAIT_L(8); BAR; WAIT_L(0); MMA(0, 0, At, B0); BAR; SCHED;
;     LDB(B1, 1, 1); STAGE(SB(1, 0), Bt, bcol, t + 3);
;     BAR; WAIT_L(0); MMA(0, 1, At, B1); BAR;
;     LDA(At, 1, 1); STAGE(SA(1, 0), A, brow, t + 3);
;     BAR; WAIT_L(0); MMA(1, 0, At, B0); BAR; SCHED;
;     STAGE(SB(1, 1), Bt, bcol + HALF, t + 3);
;     WAIT_V(6); BAR; MMA(1, 1, At, B1); BAR;
	s_setprio 1
	v_mfma_f32_16x16x32_bf16 v[28:31], v[186:189], v[218:221], v[28:31]
	v_mfma_f32_16x16x32_bf16 v[24:27], v[186:189], v[226:229], v[24:27]
	v_mfma_f32_16x16x32_bf16 v[20:23], v[194:197], v[218:221], v[20:23]
	v_mfma_f32_16x16x32_bf16 v[16:19], v[194:197], v[226:229], v[16:19]
	v_mfma_f32_16x16x32_bf16 v[12:15], v[202:205], v[218:221], v[12:15]
	v_mfma_f32_16x16x32_bf16 v[8:11], v[202:205], v[226:229], v[8:11]
	v_mfma_f32_16x16x32_bf16 v[4:7], v[210:213], v[218:221], v[4:7]
	v_mfma_f32_16x16x32_bf16 v[0:3], v[210:213], v[226:229], v[0:3]
	v_mfma_f32_16x16x32_bf16 v[28:31], v[190:193], v[222:225], v[28:31]
	v_mfma_f32_16x16x32_bf16 v[24:27], v[190:193], v[230:233], v[24:27]
	v_mfma_f32_16x16x32_bf16 v[20:23], v[198:201], v[222:225], v[20:23]
	v_mfma_f32_16x16x32_bf16 v[16:19], v[198:201], v[230:233], v[16:19]
	v_mfma_f32_16x16x32_bf16 v[12:15], v[206:209], v[222:225], v[12:15]
	v_mfma_f32_16x16x32_bf16 v[8:11], v[206:209], v[230:233], v[8:11]
	v_mfma_f32_16x16x32_bf16 v[4:7], v[214:217], v[222:225], v[4:7]
	v_mfma_f32_16x16x32_bf16 v[0:3], v[214:217], v[230:233], v[0:3]
	s_setprio 0
	s_barrier
	ds_read_b128 v[162:165], v139
	ds_read_b128 v[174:177], v139 offset:1024
	ds_read_b128 v[178:181], v139 offset:2048
	ds_read_b128 v[182:185], v139 offset:3072
	ds_read_b128 v[186:189], v134 offset:32768
	ds_read_b128 v[190:193], v134 offset:33792
	ds_read_b128 v[194:197], v156 offset:32768
	ds_read_b128 v[198:201], v156 offset:33792
	ds_read_b128 v[202:205], v157 offset:32768
	ds_read_b128 v[206:209], v157 offset:33792
	ds_read_b128 v[210:213], v158 offset:32768
	ds_read_b128 v[214:217], v158 offset:33792
	s_add_u32 m0, s32, 0x4000
	s_add_u32 s98, s34, 0x40100
	s_addc_u32 s99, s35, 0
	global_load_lds_dwordx4 v253, s[98:99]
	s_add_u32 m0, s32, 0x6000
	s_nop 0
	global_load_lds_dwordx4 v252, s[98:99]
	s_waitcnt lgkmcnt(8)
	s_setprio 1
	s_barrier
	s_waitcnt lgkmcnt(0)
	v_mfma_f32_16x16x32_bf16 v[124:127], v[186:189], v[162:165], v[124:127]
	v_mfma_f32_16x16x32_bf16 v[120:123], v[186:189], v[178:181], v[120:123]
	v_mfma_f32_16x16x32_bf16 v[116:119], v[194:197], v[162:165], v[116:119]
	v_mfma_f32_16x16x32_bf16 v[112:115], v[194:197], v[178:181], v[112:115]
	v_mfma_f32_16x16x32_bf16 v[108:111], v[202:205], v[162:165], v[108:111]
	v_mfma_f32_16x16x32_bf16 v[104:107], v[202:205], v[178:181], v[104:107]
	v_mfma_f32_16x16x32_bf16 v[100:103], v[210:213], v[162:165], v[100:103]
	v_mfma_f32_16x16x32_bf16 v[96:99], v[210:213], v[178:181], v[96:99]
	v_mfma_f32_16x16x32_bf16 v[124:127], v[190:193], v[174:177], v[124:127]
	v_mfma_f32_16x16x32_bf16 v[120:123], v[190:193], v[182:185], v[120:123]
	v_mfma_f32_16x16x32_bf16 v[116:119], v[198:201], v[174:177], v[116:119]
	v_mfma_f32_16x16x32_bf16 v[112:115], v[198:201], v[182:185], v[112:115]
	v_mfma_f32_16x16x32_bf16 v[108:111], v[206:209], v[174:177], v[108:111]
	v_mfma_f32_16x16x32_bf16 v[104:107], v[206:209], v[182:185], v[104:107]
	v_mfma_f32_16x16x32_bf16 v[100:103], v[214:217], v[174:177], v[100:103]
	v_mfma_f32_16x16x32_bf16 v[96:99], v[214:217], v[182:185], v[96:99]
	s_setprio 0
	s_barrier
	ds_read_b128 v[218:221], v136
	ds_read_b128 v[222:225], v136 offset:1024
	ds_read_b128 v[226:229], v136 offset:2048
	ds_read_b128 v[230:233], v136 offset:3072
	s_add_u32 m0, s32, 0x18000
	s_add_u32 s98, s62, 0x180
	s_addc_u32 s99, s63, 0
	global_load_lds_dwordx4 v253, s[98:99]
	s_add_u32 m0, s32, 0x1a000
	s_nop 0
	global_load_lds_dwordx4 v252, s[98:99]
	s_setprio 1
	s_barrier
	s_waitcnt lgkmcnt(0)
	v_mfma_f32_16x16x32_bf16 v[92:95], v[186:189], v[218:221], v[92:95]
	v_mfma_f32_16x16x32_bf16 v[88:91], v[186:189], v[226:229], v[88:91]
	v_mfma_f32_16x16x32_bf16 v[84:87], v[194:197], v[218:221], v[84:87]
	v_mfma_f32_16x16x32_bf16 v[80:83], v[194:197], v[226:229], v[80:83]
	v_mfma_f32_16x16x32_bf16 v[76:79], v[202:205], v[218:221], v[76:79]
	v_mfma_f32_16x16x32_bf16 v[72:75], v[202:205], v[226:229], v[72:75]
	v_mfma_f32_16x16x32_bf16 v[68:71], v[210:213], v[218:221], v[68:71]
	v_mfma_f32_16x16x32_bf16 v[64:67], v[210:213], v[226:229], v[64:67]
	v_mfma_f32_16x16x32_bf16 v[92:95], v[190:193], v[222:225], v[92:95]
	v_mfma_f32_16x16x32_bf16 v[88:91], v[190:193], v[230:233], v[88:91]
	v_mfma_f32_16x16x32_bf16 v[84:87], v[198:201], v[222:225], v[84:87]
	v_mfma_f32_16x16x32_bf16 v[80:83], v[198:201], v[230:233], v[80:83]
	v_mfma_f32_16x16x32_bf16 v[76:79], v[206:209], v[222:225], v[76:79]
	v_mfma_f32_16x16x32_bf16 v[72:75], v[206:209], v[230:233], v[72:75]
	v_mfma_f32_16x16x32_bf16 v[68:71], v[214:217], v[222:225], v[68:71]
	v_mfma_f32_16x16x32_bf16 v[64:67], v[214:217], v[230:233], v[64:67]
	s_setprio 0
	s_barrier
	ds_read_b128 v[186:189], v134 offset:49152
	ds_read_b128 v[190:193], v134 offset:50176
	ds_read_b128 v[194:197], v156 offset:49152
	ds_read_b128 v[198:201], v156 offset:50176
	ds_read_b128 v[202:205], v157 offset:49152
	ds_read_b128 v[206:209], v157 offset:50176
	ds_read_b128 v[210:213], v158 offset:49152
	ds_read_b128 v[214:217], v158 offset:50176
	s_add_u32 m0, s32, 0x8000
	s_add_u32 s98, s34, 0x180
	s_addc_u32 s99, s35, 0
	global_load_lds_dwordx4 v253, s[98:99]
	s_nop 0
	s_add_u32 m0, s32, 0xa000
	s_nop 0
	global_load_lds_dwordx4 v252, s[98:99]
	s_setprio 1
	s_barrier
; #define LDA(dst, b, h)                                                                                    \
;   _Pragma("unroll") for (int m = 0; m < 4; ++m) _Pragma("unroll") for (int k = 0; k < 2; ++k)             \
;       dst[m][k] = *reinterpret_cast<const bf16x8*>((char*)SA(b, h) + lds_byte(wr * 64 + m * 16 + fr, k * 32 + fq * 8))
; #define LDB(dst, b, h)                                                                                    \
;   _Pragma("unroll") for (int n = 0; n < 2; ++n) _Pragma("unroll") for (int k = 0; k < 2; ++k)             \
;       dst[n][k] = *reinterpret_cast<const bf16x8*>((char*)SB(b, h) + lds_byte(wc * 32 + n * 16 + fr, k * 32 + fq * 8))
; #define WAIT_V(n) asm volatile("s_waitcnt vmcnt(" #n ")" ::: "memory")
; #define WAIT_L(n) asm volatile("s_waitcnt lgkmcnt(" #n ")" ::: "memory")
; #define BAR __builtin_amdgcn_s_barrier()
; #define SCHED __builtin_amdgcn_sched_barrier(0)
; template <int EPI> ...
;     ...
;     BAR; WAIT_L(0); MMA(0, 1, At, B1); BAR;
;     LDA(At, 1, 1); STAGE(SA(1, 0), A, brow, t + 3);
;     BAR; WAIT_L(0); MMA(1, 0, At, B0); BAR; SCHED;
;     STAGE(SB(1, 1), Bt, bcol + HALF, t + 3);
;     WAIT_V(6); BAR; MMA(1, 1, At, B1); BAR;
;   }
;   {
;     LDB(B0, 0, 0); LDA(At, 0, 0); STAGE(SA(1, 1), A, brow + HALF, nt - 1);
;     BAR; WAIT_L(0); MMA(0, 0, At, B0); BAR;
;     LDB(B1, 0, 1); BAR; WAIT_L(0); MMA(0, 1, At, B1); BAR;
	s_waitcnt lgkmcnt(0)
	v_mfma_f32_16x16x32_bf16 v[60:63], v[186:189], v[162:165], v[60:63]
	v_mfma_f32_16x16x32_bf16 v[56:59], v[186:189], v[178:181], v[56:59]
	v_mfma_f32_16x16x32_bf16 v[52:55], v[194:197], v[162:165], v[52:55]
	v_mfma_f32_16x16x32_bf16 v[48:51], v[194:197], v[178:181], v[48:51]
	v_mfma_f32_16x16x32_bf16 v[44:47], v[202:205], v[162:165], v[44:47]
	v_mfma_f32_16x16x32_bf16 v[40:43], v[202:205], v[178:181], v[40:43]
	v_mfma_f32_16x16x32_bf16 v[36:39], v[210:213], v[162:165], v[36:39]
	v_mfma_f32_16x16x32_bf16 v[32:35], v[210:213], v[178:181], v[32:35]
	v_mfma_f32_16x16x32_bf16 v[60:63], v[190:193], v[174:177], v[60:63]
	v_mfma_f32_16x16x32_bf16 v[56:59], v[190:193], v[182:185], v[56:59]
	v_mfma_f32_16x16x32_bf16 v[52:55], v[198:201], v[174:177], v[52:55]
	v_mfma_f32_16x16x32_bf16 v[48:51], v[198:201], v[182:185], v[48:51]
	v_mfma_f32_16x16x32_bf16 v[44:47], v[206:209], v[174:177], v[44:47]
	v_mfma_f32_16x16x32_bf16 v[40:43], v[206:209], v[182:185], v[40:43]
	v_mfma_f32_16x16x32_bf16 v[36:39], v[214:217], v[174:177], v[36:39]
	v_mfma_f32_16x16x32_bf16 v[32:35], v[214:217], v[182:185], v[32:35]
	s_setprio 0
	s_barrier
	s_add_u32 m0, s32, 0x1c000
	s_add_u32 s98, s62, 0x40180
	s_addc_u32 s99, s63, 0
	global_load_lds_dwordx4 v253, s[98:99]
	s_add_u32 m0, s32, 0x1e000
	s_nop 0
	global_load_lds_dwordx4 v252, s[98:99]
	s_waitcnt vmcnt(6)
	s_barrier
	s_setprio 1
	v_mfma_f32_16x16x32_bf16 v[28:31], v[186:189], v[218:221], v[28:31]
	v_mfma_f32_16x16x32_bf16 v[24:27], v[186:189], v[226:229], v[24:27]
	v_mfma_f32_16x16x32_bf16 v[20:23], v[194:197], v[218:221], v[20:23]
	v_mfma_f32_16x16x32_bf16 v[16:19], v[194:197], v[226:229], v[16:19]
	v_mfma_f32_16x16x32_bf16 v[12:15], v[202:205], v[218:221], v[12:15]
	v_mfma_f32_16x16x32_bf16 v[8:11], v[202:205], v[226:229], v[8:11]
	v_mfma_f32_16x16x32_bf16 v[4:7], v[210:213], v[218:221], v[4:7]
	v_mfma_f32_16x16x32_bf16 v[0:3], v[210:213], v[226:229], v[0:3]
	v_mfma_f32_16x16x32_bf16 v[28:31], v[190:193], v[222:225], v[28:31]
	v_mfma_f32_16x16x32_bf16 v[24:27], v[190:193], v[230:233], v[24:27]
	v_mfma_f32_16x16x32_bf16 v[20:23], v[198:201], v[222:225], v[20:23]
	v_mfma_f32_16x16x32_bf16 v[16:19], v[198:201], v[230:233], v[16:19]
	v_mfma_f32_16x16x32_bf16 v[12:15], v[206:209], v[222:225], v[12:15]
	v_mfma_f32_16x16x32_bf16 v[8:11], v[206:209], v[230:233], v[8:11]
	v_mfma_f32_16x16x32_bf16 v[4:7], v[214:217], v[222:225], v[4:7]
	v_mfma_f32_16x16x32_bf16 v[0:3], v[214:217], v[230:233], v[0:3]
	s_setprio 0
	s_add_i32 s70, s70, 2
	s_add_u32 s30, s30, 0x100
	s_addc_u32 s31, s31, 0
	s_cmp_lt_u32 s70, 12
	s_barrier
	s_cbranch_scc1 .LBB0_1883
	ds_read_b128 v[144:147], v155
	ds_read_b128 v[162:165], v155 offset:1024
	ds_read_b128 v[174:177], v155 offset:2048
	ds_read_b128 v[178:181], v155 offset:3072
	ds_read_b128 v[182:185], v134
	ds_read_b128 v[186:189], v134 offset:1024
	ds_read_b128 v[190:193], v156
	ds_read_b128 v[194:197], v156 offset:1024
	ds_read_b128 v[198:201], v157
	ds_read_b128 v[202:205], v157 offset:1024
	ds_read_b128 v[206:209], v158
	ds_read_b128 v[210:213], v158 offset:1024
	v_mov_b32_e32 v129, v149
	v_lshl_add_u64 v[128:129], v[128:129], 1, s[22:23]
	s_mov_b64 s[20:21], 0x780
	v_readfirstlane_b32 s18, v160
	v_lshl_add_u64 v[128:129], v[128:129], 0, s[20:21]
	s_mov_b32 m0, s18
	v_mov_b32_e32 v131, v149
	global_load_lds_dwordx4 v[128:129], off
	v_readfirstlane_b32 s18, v159
	v_lshl_add_u64 v[128:129], v[130:131], 1, s[22:23]
	v_lshl_add_u64 v[128:129], v[128:129], 0, s[20:21]
	s_mov_b32 m0, s18
	s_nop 0
	global_load_lds_dwordx4 v[128:129], off
	s_setprio 1
	s_barrier
	s_waitcnt lgkmcnt(0)
	v_mfma_f32_16x16x32_bf16 v[124:127], v[182:185], v[144:147], v[124:127]
	v_mfma_f32_16x16x32_bf16 v[120:123], v[182:185], v[174:177], v[120:123]
	v_mfma_f32_16x16x32_bf16 v[116:119], v[190:193], v[144:147], v[116:119]
	v_mfma_f32_16x16x32_bf16 v[112:115], v[190:193], v[174:177], v[112:115]
	v_mfma_f32_16x16x32_bf16 v[108:111], v[198:201], v[144:147], v[108:111]
	v_mfma_f32_16x16x32_bf16 v[104:107], v[198:201], v[174:177], v[104:107]
	v_mfma_f32_16x16x32_bf16 v[96:99], v[206:209], v[174:177], v[96:99]
	v_mfma_f32_16x16x32_bf16 v[124:127], v[186:189], v[162:165], v[124:127]
	v_mfma_f32_16x16x32_bf16 v[120:123], v[186:189], v[178:181], v[120:123]
	v_mfma_f32_16x16x32_bf16 v[116:119], v[194:197], v[162:165], v[116:119]
	v_mfma_f32_16x16x32_bf16 v[112:115], v[194:197], v[178:181], v[112:115]
	v_mfma_f32_16x16x32_bf16 v[108:111], v[202:205], v[162:165], v[108:111]
	v_mfma_f32_16x16x32_bf16 v[104:107], v[202:205], v[178:181], v[104:107]
	v_mfma_f32_16x16x32_bf16 v[100:103], v[206:209], v[144:147], v[100:103]
	v_mfma_f32_16x16x32_bf16 v[96:99], v[210:213], v[178:181], v[96:99]
	v_mfma_f32_16x16x32_bf16 v[128:131], v[210:213], v[162:165], v[100:103]
	s_setprio 0
	s_barrier
	s_nop 3
	ds_read_b128 v[100:103], v152
	ds_read_b128 v[214:217], v152 offset:1024
	ds_read_b128 v[218:221], v152 offset:2048
	ds_read_b128 v[152:155], v152 offset:3072
	s_setprio 1
	s_barrier
	s_waitcnt lgkmcnt(0)
	v_mfma_f32_16x16x32_bf16 v[88:91], v[182:185], v[218:221], v[88:91]
	v_mfma_f32_16x16x32_bf16 v[92:95], v[182:185], v[100:103], v[92:95]
	v_mfma_f32_16x16x32_bf16 v[88:91], v[186:189], v[152:155], v[88:91]
	v_mfma_f32_16x16x32_bf16 v[84:87], v[190:193], v[100:103], v[84:87]
	v_mfma_f32_16x16x32_bf16 v[80:83], v[190:193], v[218:221], v[80:83]
	v_mfma_f32_16x16x32_bf16 v[76:79], v[198:201], v[100:103], v[76:79]
	v_mfma_f32_16x16x32_bf16 v[72:75], v[198:201], v[218:221], v[72:75]
	v_mfma_f32_16x16x32_bf16 v[68:71], v[206:209], v[100:103], v[68:71]
	v_mfma_f32_16x16x32_bf16 v[64:67], v[206:209], v[218:221], v[64:67]
	v_mfma_f32_16x16x32_bf16 v[222:225], v[186:189], v[214:217], v[92:95]
	v_mfma_f32_16x16x32_bf16 v[182:185], v[194:197], v[214:217], v[84:87]
	v_mfma_f32_16x16x32_bf16 v[186:189], v[194:197], v[152:155], v[80:83]
	v_mfma_f32_16x16x32_bf16 v[190:193], v[202:205], v[214:217], v[76:79]
	v_mfma_f32_16x16x32_bf16 v[194:197], v[202:205], v[152:155], v[72:75]
	v_mfma_f32_16x16x32_bf16 v[198:201], v[210:213], v[214:217], v[68:71]
	v_mfma_f32_16x16x32_bf16 v[202:205], v[210:213], v[152:155], v[64:67]
	s_setprio 0
	s_barrier
; #define LDA(dst, b, h)                                                                                    \
;   _Pragma("unroll") for (int m = 0; m < 4; ++m) _Pragma("unroll") for (int k = 0; k < 2; ++k)             \
;       dst[m][k] = *reinterpret_cast<const bf16x8*>((char*)SA(b, h) + lds_byte(wr * 64 + m * 16 + fr, k * 32 + fq * 8))
; #define LDB(dst, b, h)                                                                                    \
;   _Pragma("unroll") for (int n = 0; n < 2; ++n) _Pragma("unroll") for (int k = 0; k < 2; ++k)             \
;       dst[n][k] = *reinterpret_cast<const bf16x8*>((char*)SB(b, h) + lds_byte(wc * 32 + n * 16 + fr, k * 32 + fq * 8))
; #define WAIT_V(n) asm volatile("s_waitcnt vmcnt(" #n ")" ::: "memory")
; #define WAIT_L(n) asm volatile("s_waitcnt lgkmcnt(" #n ")" ::: "memory")
; #define BAR __builtin_amdgcn_s_barrier()
; template <int EPI> ...
;     ...
;     LDA(At, 0, 1); WAIT_V(4); BAR; WAIT_L(0); MMA(1, 0, At, B0); MMA(1, 1, At, B1); BAR;
;   }
;   {
;     LDB(B0, 1, 0); LDA(At, 1, 0); WAIT_V(2); BAR; WAIT_L(0); MMA(0, 0, At, B0); BAR;
	s_nop 0
	ds_read_b128 v[64:67], v134 offset:16384
	ds_read_b128 v[68:71], v134 offset:17408
	ds_read_b128 v[72:75], v156 offset:16384
	ds_read_b128 v[76:79], v156 offset:17408
	ds_read_b128 v[80:83], v157 offset:16384
	ds_read_b128 v[84:87], v157 offset:17408
	ds_read_b128 v[92:95], v158 offset:16384
	ds_read_b128 v[206:209], v158 offset:17408
	s_waitcnt vmcnt(4)
	s_setprio 1
	s_barrier
	s_waitcnt lgkmcnt(0)
	v_mfma_f32_16x16x32_bf16 v[60:63], v[64:67], v[144:147], v[60:63]
	v_mfma_f32_16x16x32_bf16 v[56:59], v[64:67], v[174:177], v[56:59]
	v_mfma_f32_16x16x32_bf16 v[52:55], v[72:75], v[144:147], v[52:55]
	v_mfma_f32_16x16x32_bf16 v[48:51], v[72:75], v[174:177], v[48:51]
	v_mfma_f32_16x16x32_bf16 v[44:47], v[80:83], v[144:147], v[44:47]
	v_mfma_f32_16x16x32_bf16 v[40:43], v[80:83], v[174:177], v[40:43]
	v_mfma_f32_16x16x32_bf16 v[36:39], v[92:95], v[144:147], v[36:39]
	v_mfma_f32_16x16x32_bf16 v[32:35], v[92:95], v[174:177], v[32:35]
	v_mfma_f32_16x16x32_bf16 v[60:63], v[68:71], v[162:165], v[60:63]
	v_mfma_f32_16x16x32_bf16 v[56:59], v[68:71], v[178:181], v[56:59]
	v_mfma_f32_16x16x32_bf16 v[52:55], v[76:79], v[162:165], v[52:55]
	v_mfma_f32_16x16x32_bf16 v[48:51], v[76:79], v[178:181], v[48:51]
	v_mfma_f32_16x16x32_bf16 v[44:47], v[84:87], v[162:165], v[44:47]
	v_mfma_f32_16x16x32_bf16 v[40:43], v[84:87], v[178:181], v[40:43]
	v_mfma_f32_16x16x32_bf16 v[36:39], v[206:209], v[162:165], v[36:39]
	v_mfma_f32_16x16x32_bf16 v[32:35], v[206:209], v[178:181], v[32:35]
	s_setprio 0
	s_setprio 1
	v_mfma_f32_16x16x32_bf16 v[28:31], v[64:67], v[100:103], v[28:31]
	v_mfma_f32_16x16x32_bf16 v[24:27], v[64:67], v[218:221], v[24:27]
	v_mfma_f32_16x16x32_bf16 v[20:23], v[72:75], v[100:103], v[20:23]
	v_mfma_f32_16x16x32_bf16 v[16:19], v[72:75], v[218:221], v[16:19]
	v_mfma_f32_16x16x32_bf16 v[12:15], v[80:83], v[100:103], v[12:15]
	v_mfma_f32_16x16x32_bf16 v[8:11], v[80:83], v[218:221], v[8:11]
	v_mfma_f32_16x16x32_bf16 v[4:7], v[92:95], v[100:103], v[4:7]
	v_mfma_f32_16x16x32_bf16 v[0:3], v[92:95], v[218:221], v[0:3]
	v_mfma_f32_16x16x32_bf16 v[144:147], v[68:71], v[214:217], v[28:31]
	v_mfma_f32_16x16x32_bf16 v[160:163], v[68:71], v[152:155], v[24:27]
	v_mfma_f32_16x16x32_bf16 v[164:167], v[76:79], v[214:217], v[20:23]
	v_mfma_f32_16x16x32_bf16 v[174:177], v[76:79], v[152:155], v[16:19]
	v_mfma_f32_16x16x32_bf16 v[178:181], v[84:87], v[214:217], v[12:15]
	v_mfma_f32_16x16x32_bf16 v[210:213], v[84:87], v[152:155], v[8:11]
	v_mfma_f32_16x16x32_bf16 v[214:217], v[206:209], v[214:217], v[4:7]
	v_mfma_f32_16x16x32_bf16 v[152:155], v[206:209], v[152:155], v[0:3]
	s_setprio 0
	s_barrier
	s_nop 0
	ds_read_b128 v[0:3], v139
	ds_read_b128 v[4:7], v139 offset:1024
	ds_read_b128 v[206:209], v139 offset:2048
	ds_read_b128 v[138:141], v139 offset:3072
	ds_read_b128 v[8:11], v134 offset:32768
	ds_read_b128 v[12:15], v134 offset:33792
	ds_read_b128 v[16:19], v156 offset:32768
	ds_read_b128 v[20:23], v156 offset:33792
	ds_read_b128 v[24:27], v157 offset:32768
	ds_read_b128 v[28:31], v157 offset:33792
	ds_read_b128 v[218:221], v158 offset:32768
	ds_read_b128 v[226:229], v158 offset:33792
	s_waitcnt vmcnt(2)
	s_setprio 1
	s_barrier
	s_waitcnt lgkmcnt(0)
	v_mfma_f32_16x16x32_bf16 v[64:67], v[8:11], v[0:3], v[124:127]
	v_mfma_f32_16x16x32_bf16 v[92:95], v[12:15], v[4:7], v[64:67]
	v_mfma_f32_16x16x32_bf16 v[64:67], v[8:11], v[206:209], v[120:123]
	v_mfma_f32_16x16x32_bf16 v[100:103], v[12:15], v[138:141], v[64:67]
	v_mfma_f32_16x16x32_bf16 v[64:67], v[16:19], v[0:3], v[116:119]
	v_mfma_f32_16x16x32_bf16 v[80:83], v[20:23], v[4:7], v[64:67]
	v_mfma_f32_16x16x32_bf16 v[64:67], v[16:19], v[206:209], v[112:115]
	v_mfma_f32_16x16x32_bf16 v[84:87], v[20:23], v[138:141], v[64:67]
	v_mfma_f32_16x16x32_bf16 v[64:67], v[24:27], v[0:3], v[108:111]
	v_mfma_f32_16x16x32_bf16 v[72:75], v[28:31], v[4:7], v[64:67]
	v_mfma_f32_16x16x32_bf16 v[64:67], v[24:27], v[206:209], v[104:107]
	v_mfma_f32_16x16x32_bf16 v[76:79], v[28:31], v[138:141], v[64:67]
	v_mfma_f32_16x16x32_bf16 v[64:67], v[218:221], v[0:3], v[128:131]
	v_mfma_f32_16x16x32_bf16 v[68:71], v[218:221], v[206:209], v[96:99]
	v_mfma_f32_16x16x32_bf16 v[64:67], v[226:229], v[4:7], v[64:67]
	v_mfma_f32_16x16x32_bf16 v[68:71], v[226:229], v[138:141], v[68:71]
	s_setprio 0
	s_barrier
; #define LDA(dst, b, h)                                                                                    \
;   _Pragma("unroll") for (int m = 0; m < 4; ++m) _Pragma("unroll") for (int k = 0; k < 2; ++k)             \
;       dst[m][k] = *reinterpret_cast<const bf16x8*>((char*)SA(b, h) + lds_byte(wr * 64 + m * 16 + fr, k * 32 + fq * 8))
; #define LDB(dst, b, h)                                                                                    \
;   _Pragma("unroll") for (int n = 0; n < 2; ++n) _Pragma("unroll") for (int k = 0; k < 2; ++k)             \
;       dst[n][k] = *reinterpret_cast<const bf16x8*>((char*)SB(b, h) + lds_byte(wc * 32 + n * 16 + fr, k * 32 + fq * 8))
; #define WAIT_V(n) asm volatile("s_waitcnt vmcnt(" #n ")" ::: "memory")
; #define WAIT_L(n) asm volatile("s_waitcnt lgkmcnt(" #n ")" ::: "memory")
; #define BAR __builtin_amdgcn_s_barrier()
; template <int EPI> ...
;     ...
;     LDB(B0, 1, 0); LDA(At, 1, 0); WAIT_V(2); BAR; WAIT_L(0); MMA(0, 0, At, B0); BAR;
;     LDB(B1, 1, 1); WAIT_V(0); BAR; WAIT_L(0); MMA(0, 1, At, B1); BAR;
;     LDA(At, 1, 1); BAR; WAIT_L(0); MMA(1, 0, At, B0); MMA(1, 1, At, B1); BAR;
;   }
;   if (wr == 0) BAR;
	ds_read_b128 v[128:131], v136
	ds_read_b128 v[230:233], v136 offset:1024
	ds_read_b128 v[234:237], v136 offset:2048
	ds_read_b128 v[238:241], v136 offset:3072
	s_waitcnt vmcnt(0)
	s_setprio 1
	s_barrier
	s_waitcnt lgkmcnt(0)
	v_mfma_f32_16x16x32_bf16 v[96:99], v[8:11], v[128:131], v[222:225]
	v_mfma_f32_16x16x32_bf16 v[8:11], v[8:11], v[234:237], v[88:91]
	v_mfma_f32_16x16x32_bf16 v[124:127], v[12:15], v[238:241], v[8:11]
	v_mfma_f32_16x16x32_bf16 v[8:11], v[16:19], v[128:131], v[182:185]
	v_mfma_f32_16x16x32_bf16 v[112:115], v[20:23], v[230:233], v[8:11]
	v_mfma_f32_16x16x32_bf16 v[8:11], v[16:19], v[234:237], v[186:189]
	v_mfma_f32_16x16x32_bf16 v[116:119], v[20:23], v[238:241], v[8:11]
	v_mfma_f32_16x16x32_bf16 v[8:11], v[24:27], v[128:131], v[190:193]
	v_mfma_f32_16x16x32_bf16 v[104:107], v[28:31], v[230:233], v[8:11]
	v_mfma_f32_16x16x32_bf16 v[8:11], v[24:27], v[234:237], v[194:197]
	v_mfma_f32_16x16x32_bf16 v[108:111], v[28:31], v[238:241], v[8:11]
	v_mfma_f32_16x16x32_bf16 v[8:11], v[218:221], v[128:131], v[198:201]
	v_mfma_f32_16x16x32_bf16 v[88:91], v[226:229], v[230:233], v[8:11]
	v_mfma_f32_16x16x32_bf16 v[8:11], v[218:221], v[234:237], v[202:205]
	v_mfma_f32_16x16x32_bf16 v[120:123], v[12:15], v[230:233], v[96:99]
	v_mfma_f32_16x16x32_bf16 v[96:99], v[226:229], v[238:241], v[8:11]
	s_setprio 0
	s_barrier
	ds_read_b128 v[182:185], v134 offset:49152
	ds_read_b128 v[134:137], v134 offset:50176
	ds_read_b128 v[186:189], v156 offset:49152
	ds_read_b128 v[190:193], v156 offset:50176
	ds_read_b128 v[194:197], v157 offset:49152
	ds_read_b128 v[198:201], v157 offset:50176
	ds_read_b128 v[202:205], v158 offset:49152
	ds_read_b128 v[156:159], v158 offset:50176
	s_setprio 1
	s_barrier
	s_waitcnt lgkmcnt(0)
	v_mfma_f32_16x16x32_bf16 v[8:11], v[182:185], v[0:3], v[60:63]
	v_mfma_f32_16x16x32_bf16 v[24:27], v[134:137], v[4:7], v[8:11]
	v_mfma_f32_16x16x32_bf16 v[8:11], v[182:185], v[206:209], v[56:59]
	v_mfma_f32_16x16x32_bf16 v[28:31], v[134:137], v[138:141], v[8:11]
	v_mfma_f32_16x16x32_bf16 v[8:11], v[186:189], v[0:3], v[52:55]
	v_mfma_f32_16x16x32_bf16 v[16:19], v[190:193], v[4:7], v[8:11]
	v_mfma_f32_16x16x32_bf16 v[8:11], v[186:189], v[206:209], v[48:51]
	v_mfma_f32_16x16x32_bf16 v[20:23], v[190:193], v[138:141], v[8:11]
	v_mfma_f32_16x16x32_bf16 v[8:11], v[194:197], v[0:3], v[44:47]
	v_mfma_f32_16x16x32_bf16 v[0:3], v[202:205], v[0:3], v[36:39]
	v_mfma_f32_16x16x32_bf16 v[8:11], v[198:201], v[4:7], v[8:11]
	v_mfma_f32_16x16x32_bf16 v[12:15], v[194:197], v[206:209], v[40:43]
	v_mfma_f32_16x16x32_bf16 v[0:3], v[156:159], v[4:7], v[0:3]
	v_mfma_f32_16x16x32_bf16 v[4:7], v[202:205], v[206:209], v[32:35]
	v_mfma_f32_16x16x32_bf16 v[12:15], v[198:201], v[138:141], v[12:15]
	v_mfma_f32_16x16x32_bf16 v[4:7], v[156:159], v[138:141], v[4:7]
	s_setprio 0
	s_setprio 1
	v_mfma_f32_16x16x32_bf16 v[32:35], v[182:185], v[128:131], v[144:147]
	v_mfma_f32_16x16x32_bf16 v[56:59], v[134:137], v[230:233], v[32:35]
	v_mfma_f32_16x16x32_bf16 v[32:35], v[182:185], v[234:237], v[160:163]
	v_mfma_f32_16x16x32_bf16 v[60:63], v[134:137], v[238:241], v[32:35]
	v_mfma_f32_16x16x32_bf16 v[32:35], v[186:189], v[128:131], v[164:167]
	v_mfma_f32_16x16x32_bf16 v[48:51], v[190:193], v[230:233], v[32:35]
	v_mfma_f32_16x16x32_bf16 v[32:35], v[186:189], v[234:237], v[174:177]
	v_mfma_f32_16x16x32_bf16 v[52:55], v[190:193], v[238:241], v[32:35]
	v_mfma_f32_16x16x32_bf16 v[32:35], v[194:197], v[128:131], v[178:181]
	v_mfma_f32_16x16x32_bf16 v[40:43], v[198:201], v[230:233], v[32:35]
	v_mfma_f32_16x16x32_bf16 v[32:35], v[194:197], v[234:237], v[210:213]
	v_mfma_f32_16x16x32_bf16 v[44:47], v[198:201], v[238:241], v[32:35]
	v_mfma_f32_16x16x32_bf16 v[32:35], v[202:205], v[128:131], v[214:217]
	v_mfma_f32_16x16x32_bf16 v[36:39], v[202:205], v[234:237], v[152:155]
	v_mfma_f32_16x16x32_bf16 v[32:35], v[156:159], v[230:233], v[32:35]
	v_mfma_f32_16x16x32_bf16 v[36:39], v[156:159], v[238:241], v[36:39]
	s_setprio 0
	s_cmpk_gt_u32 s64, 0xff
	s_barrier
	s_cbranch_scc1 .LBB0_1886
	s_barrier
